# S5 pass 1 and pass 3 inner complex arithmetic on packed f32 ops (planar power tables)
# speedup vs baseline: 1.5117x; 1.0071x over previous
.Lss3_body:
	v_readlane_b32 s58, v247, 28
	s_lshr_b32 s59, s36, 6
	s_mul_i32 s59, s59, 68
	s_and_b32 s10, s36, 63
	s_add_i32 s59, s59, s10
	s_add_i32 s59, s59, 4
	s_cmp_eq_u32 s58, 1
	s_cselect_b32 s58, s59, s36
	s_mul_i32 s10, s58, 0xf0f1
	s_lshr_b32 s10, s10, 22
	s_mul_i32 s11, s10, 68
	s_sub_i32 s8, s58, s11
	s_and_b32 s7, s10, 15
	s_lshr_b32 s6, s10, 4
	s_lshl_b32 s10, s8, 6
	s_lshl_b32 s11, s6, 8
	s_add_i32 s9, s10, s11
	s_lshl_b32 s11, s6, 12
	s_add_i32 s11, s11, s10
	s_add_i32 s11, s11, 0x300
	s_cmp_lt_u32 s8, 4
	s_cselect_b32 s9, s9, s11
	v_mov_b32_e32 v0, 0
	v_mov_b32_e32 v1, 0
	v_mov_b32_e32 v2, 0
	v_mov_b32_e32 v3, 0
	v_mov_b32_e32 v4, 0
	v_mov_b32_e32 v5, 0
	v_mov_b32_e32 v6, 0
	v_mov_b32_e32 v7, 0
	v_mov_b32_e32 v8, 0
	v_mov_b32_e32 v9, 0
	v_mov_b32_e32 v10, 0
	v_mov_b32_e32 v11, 0
	v_mov_b32_e32 v12, 0
	v_mov_b32_e32 v13, 0
	v_mov_b32_e32 v14, 0
	v_mov_b32_e32 v15, 0
	v_and_b32_e32 v207, 15, v205
	v_mul_u32_u24_e32 v207, 0xe00, v207
	v_and_b32_e32 v208, 16, v205
	v_add_u32_e32 v207, v207, v208
	s_mul_i32 s18, s9, 0xe00
	s_lshl_b32 s19, s7, 5
	s_add_i32 s18, s18, s19
	s_add_u32 s18, s18, 0x5e00c00
	s_add_u32 s18, s4, s18
	s_addc_u32 s19, s5, 0
	s_mov_b32 exec_hi, 0
	global_load_dwordx4 v[0:3], v207, s[18:19]
	s_add_u32 s18, s18, 0xe000
	s_addc_u32 s19, s19, 0
	global_load_dwordx4 v[4:7], v207, s[18:19]
	s_add_u32 s18, s18, 0xe000
	s_addc_u32 s19, s19, 0
	global_load_dwordx4 v[8:11], v207, s[18:19]
	s_add_u32 s18, s18, 0xe000
	s_addc_u32 s19, s19, 0
	global_load_dwordx4 v[12:15], v207, s[18:19]
	s_mov_b64 exec, -1
	v_lshlrev_b32_e32 v134, 4, v205
	v_add_u32_e32 v208, 0x1000, v134
	v_and_b32_e32 v135, 15, v205
	v_lshlrev_b32_e32 v136, 8, v135
	v_lshlrev_b32_e32 v135, 6, v135
	v_and_b32_e32 v207, 16, v205
	v_lshl_add_u32 v135, v207, 1, v135
	v_lshrrev_b32_e32 v207, 4, v205
	v_lshl_add_u32 v136, v207, 4, v136
	v_lshlrev_b32_e32 v206, 5, v207
	v_readlane_b32 s10, v247, 28
	s_mov_b32 s11, s8
	s_lshl_b32 s16, s10, 1
	s_add_i32 s16, s16, 0
	s_lshl_b32 s16, s16, 4
	s_add_i32 s16, s16, s7
	s_lshl_b32 s17, s6, 1
	s_add_i32 s17, s17, 0
	s_lshl_b32 s17, s17, 4
	s_add_i32 s17, s17, s7
	s_mul_i32 s17, s17, 68
	s_add_i32 s17, s17, s11
	s_lshl_b32 s17, s17, 6
	s_lshl_b32 s20, s16, 13
	s_add_u32 s20, s20, 0xfd00000
	s_add_u32 s20, s4, s20
	s_addc_u32 s21, s5, 0
	s_lshl_b32 s38, s16, 12
	s_add_u32 s38, s38, 0xfd80000
	s_add_u32 s38, s4, s38
	s_addc_u32 s39, s5, 0
	s_lshl_b32 s42, s16, 15
	s_add_u32 s42, s42, 0xf900000
	s_add_u32 s42, s4, s42
	s_addc_u32 s43, s5, 0
	s_lshl_b32 s44, s17, 3
	s_add_u32 s44, s44, 0x740000
	s_add_u32 s44, s4, s44
	s_addc_u32 s45, s5, 0
	global_load_dwordx4 v[64:67], v134, s[20:21]
	global_load_dwordx4 v[72:75], v134, s[20:21] offset:1024
	s_add_u32 s20, s20, 0x800
	s_addc_u32 s21, s21, 0
	global_load_dwordx4 v[138:141], v134, s[42:43] offset:0
	global_load_dwordx4 v[142:145], v134, s[42:43] offset:1024
	global_load_dwordx4 v[146:149], v134, s[42:43] offset:2048
	global_load_dwordx4 v[150:153], v134, s[42:43] offset:3072
	global_load_dwordx4 v[154:157], v208, s[42:43] offset:0
	global_load_dwordx4 v[158:161], v208, s[42:43] offset:1024
	global_load_dwordx4 v[162:165], v208, s[42:43] offset:2048
	global_load_dwordx4 v[166:169], v208, s[42:43] offset:3072
	global_load_dwordx4 v[170:173], v206, s[44:45]
	global_load_dwordx4 v[174:177], v206, s[44:45] offset:16
	s_add_u32 s42, s42, 0x2000
	s_addc_u32 s43, s43, 0
	s_add_u32 s44, s44, 0x80
	s_addc_u32 s45, s45, 0
	s_waitcnt vmcnt(12)
	s_waitcnt vmcnt(10)
	global_load_dwordx4 v[80:83], v134, s[38:39]
	s_add_u32 s38, s38, 0x400
	s_addc_u32 s39, s39, 0
	v_mfma_f32_16x16x32_bf16 v[32:35], v[64:67], v[0:3], 0
	v_mfma_f32_16x16x32_bf16 v[36:39], v[72:75], v[0:3], 0
	v_mfma_f32_16x16x32_bf16 v[40:43], v[64:67], v[4:7], 0
	v_mfma_f32_16x16x32_bf16 v[44:47], v[72:75], v[4:7], 0
	v_mfma_f32_16x16x32_bf16 v[48:51], v[64:67], v[8:11], 0
	v_mfma_f32_16x16x32_bf16 v[52:55], v[72:75], v[8:11], 0
	v_mfma_f32_16x16x32_bf16 v[56:59], v[64:67], v[12:15], 0
	v_mfma_f32_16x16x32_bf16 v[60:63], v[72:75], v[12:15], 0
	global_load_dwordx4 v[64:67], v134, s[20:21]
	global_load_dwordx4 v[72:75], v134, s[20:21] offset:1024
	s_add_u32 s20, s20, 0x800
	s_addc_u32 s21, s21, 0
	global_load_dwordx4 v[100:103], v134, s[42:43] offset:0
	global_load_dwordx4 v[104:107], v134, s[42:43] offset:1024
	global_load_dwordx4 v[108:111], v134, s[42:43] offset:2048
	global_load_dwordx4 v[112:115], v134, s[42:43] offset:3072
	global_load_dwordx4 v[116:119], v208, s[42:43] offset:0
	global_load_dwordx4 v[120:123], v208, s[42:43] offset:1024
	global_load_dwordx4 v[124:127], v208, s[42:43] offset:2048
	global_load_dwordx4 v[128:131], v208, s[42:43] offset:3072
	global_load_dwordx4 v[178:181], v206, s[44:45]
	global_load_dwordx4 v[182:185], v206, s[44:45] offset:16
	s_add_u32 s42, s42, 0x2000
	s_addc_u32 s43, s43, 0
	s_add_u32 s44, s44, 0x80
	s_addc_u32 s45, s45, 0
	s_waitcnt vmcnt(13)
	v_mul_f32_e32 v132, v171, v166
	v_mul_f32_e32 v133, v170, v166
	v_fma_f32 v68, v170, v162, -v132
	v_fma_f32 v76, v171, v162, v133
	v_mul_f32_e32 v132, v173, v167
	v_mul_f32_e32 v133, v172, v167
	v_fma_f32 v69, v172, v163, -v132
	v_fma_f32 v77, v173, v163, v133
	v_mul_f32_e32 v132, v175, v168
	v_mul_f32_e32 v133, v174, v168
	v_fma_f32 v70, v174, v164, -v132
	v_fma_f32 v78, v175, v164, v133
	v_mul_f32_e32 v132, v177, v169
	v_mul_f32_e32 v133, v176, v169
	v_fma_f32 v71, v176, v165, -v132
	v_fma_f32 v79, v177, v165, v133
	v_pk_mul_f32 v[132:133], v[32:33], v[142:143]
	v_pk_mul_f32 v[32:33], v[32:33], v[138:139]
	v_pk_fma_f32 v[32:33], v[36:37], v[142:143], v[32:33] neg_lo:[1,0,0] neg_hi:[1,0,0]
	v_pk_fma_f32 v[36:37], v[36:37], v[138:139], v[132:133]
	v_pk_mul_f32 v[132:133], v[34:35], v[144:145]
	v_pk_mul_f32 v[34:35], v[34:35], v[140:141]
	v_pk_fma_f32 v[34:35], v[38:39], v[144:145], v[34:35] neg_lo:[1,0,0] neg_hi:[1,0,0]
	v_pk_fma_f32 v[38:39], v[38:39], v[140:141], v[132:133]
	v_add_f32_dpp v32, v32, v32 row_shr:1 row_mask:0xf bank_mask:0xf bound_ctrl:1
	v_add_f32_dpp v33, v33, v33 row_shr:1 row_mask:0xf bank_mask:0xf bound_ctrl:1
	v_add_f32_dpp v34, v34, v34 row_shr:1 row_mask:0xf bank_mask:0xf bound_ctrl:1
	v_add_f32_dpp v35, v35, v35 row_shr:1 row_mask:0xf bank_mask:0xf bound_ctrl:1
	v_add_f32_dpp v36, v36, v36 row_shr:1 row_mask:0xf bank_mask:0xf bound_ctrl:1
	v_add_f32_dpp v37, v37, v37 row_shr:1 row_mask:0xf bank_mask:0xf bound_ctrl:1
	v_add_f32_dpp v38, v38, v38 row_shr:1 row_mask:0xf bank_mask:0xf bound_ctrl:1
	v_add_f32_dpp v39, v39, v39 row_shr:1 row_mask:0xf bank_mask:0xf bound_ctrl:1
	v_add_f32_dpp v32, v32, v32 row_shr:2 row_mask:0xf bank_mask:0xf bound_ctrl:1
	v_add_f32_dpp v33, v33, v33 row_shr:2 row_mask:0xf bank_mask:0xf bound_ctrl:1
	v_add_f32_dpp v34, v34, v34 row_shr:2 row_mask:0xf bank_mask:0xf bound_ctrl:1
	v_add_f32_dpp v35, v35, v35 row_shr:2 row_mask:0xf bank_mask:0xf bound_ctrl:1
	v_add_f32_dpp v36, v36, v36 row_shr:2 row_mask:0xf bank_mask:0xf bound_ctrl:1
	v_add_f32_dpp v37, v37, v37 row_shr:2 row_mask:0xf bank_mask:0xf bound_ctrl:1
	v_add_f32_dpp v38, v38, v38 row_shr:2 row_mask:0xf bank_mask:0xf bound_ctrl:1
	v_add_f32_dpp v39, v39, v39 row_shr:2 row_mask:0xf bank_mask:0xf bound_ctrl:1
	v_add_f32_dpp v32, v32, v32 row_shr:4 row_mask:0xf bank_mask:0xf bound_ctrl:1
	v_add_f32_dpp v33, v33, v33 row_shr:4 row_mask:0xf bank_mask:0xf bound_ctrl:1
	v_add_f32_dpp v34, v34, v34 row_shr:4 row_mask:0xf bank_mask:0xf bound_ctrl:1
	v_add_f32_dpp v35, v35, v35 row_shr:4 row_mask:0xf bank_mask:0xf bound_ctrl:1
	v_add_f32_dpp v36, v36, v36 row_shr:4 row_mask:0xf bank_mask:0xf bound_ctrl:1
	v_add_f32_dpp v37, v37, v37 row_shr:4 row_mask:0xf bank_mask:0xf bound_ctrl:1
	v_add_f32_dpp v38, v38, v38 row_shr:4 row_mask:0xf bank_mask:0xf bound_ctrl:1
	v_add_f32_dpp v39, v39, v39 row_shr:4 row_mask:0xf bank_mask:0xf bound_ctrl:1
	v_add_f32_dpp v32, v32, v32 row_shr:8 row_mask:0xf bank_mask:0xf bound_ctrl:1
	v_add_f32_dpp v33, v33, v33 row_shr:8 row_mask:0xf bank_mask:0xf bound_ctrl:1
	v_add_f32_dpp v34, v34, v34 row_shr:8 row_mask:0xf bank_mask:0xf bound_ctrl:1
	v_add_f32_dpp v35, v35, v35 row_shr:8 row_mask:0xf bank_mask:0xf bound_ctrl:1
	v_add_f32_dpp v36, v36, v36 row_shr:8 row_mask:0xf bank_mask:0xf bound_ctrl:1
	v_add_f32_dpp v37, v37, v37 row_shr:8 row_mask:0xf bank_mask:0xf bound_ctrl:1
	v_add_f32_dpp v38, v38, v38 row_shr:8 row_mask:0xf bank_mask:0xf bound_ctrl:1
	v_add_f32_dpp v39, v39, v39 row_shr:8 row_mask:0xf bank_mask:0xf bound_ctrl:1
	v_mov_b32_dpp v88, v32 row_newbcast:15 row_mask:0xf bank_mask:0xf
	v_mov_b32_dpp v89, v33 row_newbcast:15 row_mask:0xf bank_mask:0xf
	v_mov_b32_dpp v90, v34 row_newbcast:15 row_mask:0xf bank_mask:0xf
	v_mov_b32_dpp v91, v35 row_newbcast:15 row_mask:0xf bank_mask:0xf
	v_mov_b32_dpp v92, v36 row_newbcast:15 row_mask:0xf bank_mask:0xf
	v_mov_b32_dpp v93, v37 row_newbcast:15 row_mask:0xf bank_mask:0xf
	v_mov_b32_dpp v94, v38 row_newbcast:15 row_mask:0xf bank_mask:0xf
	v_mov_b32_dpp v95, v39 row_newbcast:15 row_mask:0xf bank_mask:0xf
	v_pk_add_f32 v[32:33], v[32:33], v[68:69]
	v_pk_add_f32 v[36:37], v[36:37], v[76:77]
	v_pk_add_f32 v[34:35], v[34:35], v[70:71]
	v_pk_add_f32 v[38:39], v[38:39], v[78:79]
	v_pk_mul_f32 v[132:133], v[32:33], v[150:151]
	v_pk_mul_f32 v[32:33], v[32:33], v[146:147]
	v_pk_fma_f32 v[32:33], v[36:37], v[150:151], v[32:33] neg_lo:[1,0,0] neg_hi:[1,0,0]
	v_pk_fma_f32 v[36:37], v[36:37], v[146:147], v[132:133]
	v_pk_mul_f32 v[132:133], v[34:35], v[152:153]
	v_pk_mul_f32 v[34:35], v[34:35], v[148:149]
	v_pk_fma_f32 v[34:35], v[38:39], v[152:153], v[34:35] neg_lo:[1,0,0] neg_hi:[1,0,0]
	v_pk_fma_f32 v[38:39], v[38:39], v[148:149], v[132:133]
	v_pk_add_f32 v[88:89], v[88:89], v[68:69]
	v_pk_add_f32 v[92:93], v[92:93], v[76:77]
	v_pk_mul_f32 v[132:133], v[92:93], v[158:159]
	v_pk_mul_f32 v[76:77], v[88:89], v[158:159]
	v_pk_fma_f32 v[68:69], v[88:89], v[154:155], v[132:133] neg_lo:[0,0,1] neg_hi:[0,0,1]
	v_pk_fma_f32 v[76:77], v[92:93], v[154:155], v[76:77]
	v_pk_add_f32 v[90:91], v[90:91], v[70:71]
	v_pk_add_f32 v[94:95], v[94:95], v[78:79]
	v_pk_mul_f32 v[132:133], v[94:95], v[160:161]
	v_pk_mul_f32 v[78:79], v[90:91], v[160:161]
	v_pk_fma_f32 v[70:71], v[90:91], v[156:157], v[132:133] neg_lo:[0,0,1] neg_hi:[0,0,1]
	v_pk_fma_f32 v[78:79], v[94:95], v[156:157], v[78:79]
	v_pk_mul_f32 v[132:133], v[40:41], v[142:143]
	v_pk_mul_f32 v[40:41], v[40:41], v[138:139]
	v_pk_fma_f32 v[40:41], v[44:45], v[142:143], v[40:41] neg_lo:[1,0,0] neg_hi:[1,0,0]
	v_pk_fma_f32 v[44:45], v[44:45], v[138:139], v[132:133]
	v_pk_mul_f32 v[132:133], v[42:43], v[144:145]
	v_pk_mul_f32 v[42:43], v[42:43], v[140:141]
	v_pk_fma_f32 v[42:43], v[46:47], v[144:145], v[42:43] neg_lo:[1,0,0] neg_hi:[1,0,0]
	v_pk_fma_f32 v[46:47], v[46:47], v[140:141], v[132:133]
	v_add_f32_dpp v40, v40, v40 row_shr:1 row_mask:0xf bank_mask:0xf bound_ctrl:1
	v_add_f32_dpp v41, v41, v41 row_shr:1 row_mask:0xf bank_mask:0xf bound_ctrl:1
	v_add_f32_dpp v42, v42, v42 row_shr:1 row_mask:0xf bank_mask:0xf bound_ctrl:1
	v_add_f32_dpp v43, v43, v43 row_shr:1 row_mask:0xf bank_mask:0xf bound_ctrl:1
	v_add_f32_dpp v44, v44, v44 row_shr:1 row_mask:0xf bank_mask:0xf bound_ctrl:1
	v_add_f32_dpp v45, v45, v45 row_shr:1 row_mask:0xf bank_mask:0xf bound_ctrl:1
	v_add_f32_dpp v46, v46, v46 row_shr:1 row_mask:0xf bank_mask:0xf bound_ctrl:1
	v_add_f32_dpp v47, v47, v47 row_shr:1 row_mask:0xf bank_mask:0xf bound_ctrl:1
	v_add_f32_dpp v40, v40, v40 row_shr:2 row_mask:0xf bank_mask:0xf bound_ctrl:1
	v_add_f32_dpp v41, v41, v41 row_shr:2 row_mask:0xf bank_mask:0xf bound_ctrl:1
	v_add_f32_dpp v42, v42, v42 row_shr:2 row_mask:0xf bank_mask:0xf bound_ctrl:1
	v_add_f32_dpp v43, v43, v43 row_shr:2 row_mask:0xf bank_mask:0xf bound_ctrl:1
	v_add_f32_dpp v44, v44, v44 row_shr:2 row_mask:0xf bank_mask:0xf bound_ctrl:1
	v_add_f32_dpp v45, v45, v45 row_shr:2 row_mask:0xf bank_mask:0xf bound_ctrl:1
	v_add_f32_dpp v46, v46, v46 row_shr:2 row_mask:0xf bank_mask:0xf bound_ctrl:1
	v_add_f32_dpp v47, v47, v47 row_shr:2 row_mask:0xf bank_mask:0xf bound_ctrl:1
	v_add_f32_dpp v40, v40, v40 row_shr:4 row_mask:0xf bank_mask:0xf bound_ctrl:1
	v_add_f32_dpp v41, v41, v41 row_shr:4 row_mask:0xf bank_mask:0xf bound_ctrl:1
	v_add_f32_dpp v42, v42, v42 row_shr:4 row_mask:0xf bank_mask:0xf bound_ctrl:1
	v_add_f32_dpp v43, v43, v43 row_shr:4 row_mask:0xf bank_mask:0xf bound_ctrl:1
	v_add_f32_dpp v44, v44, v44 row_shr:4 row_mask:0xf bank_mask:0xf bound_ctrl:1
	v_add_f32_dpp v45, v45, v45 row_shr:4 row_mask:0xf bank_mask:0xf bound_ctrl:1
	v_add_f32_dpp v46, v46, v46 row_shr:4 row_mask:0xf bank_mask:0xf bound_ctrl:1
	v_add_f32_dpp v47, v47, v47 row_shr:4 row_mask:0xf bank_mask:0xf bound_ctrl:1
	v_add_f32_dpp v40, v40, v40 row_shr:8 row_mask:0xf bank_mask:0xf bound_ctrl:1
	v_add_f32_dpp v41, v41, v41 row_shr:8 row_mask:0xf bank_mask:0xf bound_ctrl:1
	v_add_f32_dpp v42, v42, v42 row_shr:8 row_mask:0xf bank_mask:0xf bound_ctrl:1
	v_add_f32_dpp v43, v43, v43 row_shr:8 row_mask:0xf bank_mask:0xf bound_ctrl:1
	v_add_f32_dpp v44, v44, v44 row_shr:8 row_mask:0xf bank_mask:0xf bound_ctrl:1
	v_add_f32_dpp v45, v45, v45 row_shr:8 row_mask:0xf bank_mask:0xf bound_ctrl:1
	v_add_f32_dpp v46, v46, v46 row_shr:8 row_mask:0xf bank_mask:0xf bound_ctrl:1
	v_add_f32_dpp v47, v47, v47 row_shr:8 row_mask:0xf bank_mask:0xf bound_ctrl:1
	v_mov_b32_dpp v88, v40 row_newbcast:15 row_mask:0xf bank_mask:0xf
	v_mov_b32_dpp v89, v41 row_newbcast:15 row_mask:0xf bank_mask:0xf
	v_mov_b32_dpp v90, v42 row_newbcast:15 row_mask:0xf bank_mask:0xf
	v_mov_b32_dpp v91, v43 row_newbcast:15 row_mask:0xf bank_mask:0xf
	v_mov_b32_dpp v92, v44 row_newbcast:15 row_mask:0xf bank_mask:0xf
	v_mov_b32_dpp v93, v45 row_newbcast:15 row_mask:0xf bank_mask:0xf
	v_mov_b32_dpp v94, v46 row_newbcast:15 row_mask:0xf bank_mask:0xf
	v_mov_b32_dpp v95, v47 row_newbcast:15 row_mask:0xf bank_mask:0xf
	v_pk_add_f32 v[40:41], v[40:41], v[68:69]
	v_pk_add_f32 v[44:45], v[44:45], v[76:77]
	v_pk_add_f32 v[42:43], v[42:43], v[70:71]
	v_pk_add_f32 v[46:47], v[46:47], v[78:79]
	v_pk_mul_f32 v[132:133], v[40:41], v[150:151]
	v_pk_mul_f32 v[40:41], v[40:41], v[146:147]
	v_pk_fma_f32 v[40:41], v[44:45], v[150:151], v[40:41] neg_lo:[1,0,0] neg_hi:[1,0,0]
	v_pk_fma_f32 v[44:45], v[44:45], v[146:147], v[132:133]
	v_pk_mul_f32 v[132:133], v[42:43], v[152:153]
	v_pk_mul_f32 v[42:43], v[42:43], v[148:149]
	v_pk_fma_f32 v[42:43], v[46:47], v[152:153], v[42:43] neg_lo:[1,0,0] neg_hi:[1,0,0]
	v_pk_fma_f32 v[46:47], v[46:47], v[148:149], v[132:133]
	v_pk_add_f32 v[88:89], v[88:89], v[68:69]
	v_pk_add_f32 v[92:93], v[92:93], v[76:77]
	v_pk_mul_f32 v[132:133], v[92:93], v[158:159]
	v_pk_mul_f32 v[76:77], v[88:89], v[158:159]
	v_pk_fma_f32 v[68:69], v[88:89], v[154:155], v[132:133] neg_lo:[0,0,1] neg_hi:[0,0,1]
	v_pk_fma_f32 v[76:77], v[92:93], v[154:155], v[76:77]
	v_pk_add_f32 v[90:91], v[90:91], v[70:71]
	v_pk_add_f32 v[94:95], v[94:95], v[78:79]
	v_pk_mul_f32 v[132:133], v[94:95], v[160:161]
	v_pk_mul_f32 v[78:79], v[90:91], v[160:161]
	v_pk_fma_f32 v[70:71], v[90:91], v[156:157], v[132:133] neg_lo:[0,0,1] neg_hi:[0,0,1]
	v_pk_fma_f32 v[78:79], v[94:95], v[156:157], v[78:79]
	v_pk_mul_f32 v[132:133], v[48:49], v[142:143]
	v_pk_mul_f32 v[48:49], v[48:49], v[138:139]
	v_pk_fma_f32 v[48:49], v[52:53], v[142:143], v[48:49] neg_lo:[1,0,0] neg_hi:[1,0,0]
	v_pk_fma_f32 v[52:53], v[52:53], v[138:139], v[132:133]
	v_pk_mul_f32 v[132:133], v[50:51], v[144:145]
	v_pk_mul_f32 v[50:51], v[50:51], v[140:141]
	v_pk_fma_f32 v[50:51], v[54:55], v[144:145], v[50:51] neg_lo:[1,0,0] neg_hi:[1,0,0]
	v_pk_fma_f32 v[54:55], v[54:55], v[140:141], v[132:133]
	v_add_f32_dpp v48, v48, v48 row_shr:1 row_mask:0xf bank_mask:0xf bound_ctrl:1
	v_add_f32_dpp v49, v49, v49 row_shr:1 row_mask:0xf bank_mask:0xf bound_ctrl:1
	v_add_f32_dpp v50, v50, v50 row_shr:1 row_mask:0xf bank_mask:0xf bound_ctrl:1
	v_add_f32_dpp v51, v51, v51 row_shr:1 row_mask:0xf bank_mask:0xf bound_ctrl:1
	v_add_f32_dpp v52, v52, v52 row_shr:1 row_mask:0xf bank_mask:0xf bound_ctrl:1
	v_add_f32_dpp v53, v53, v53 row_shr:1 row_mask:0xf bank_mask:0xf bound_ctrl:1
	v_add_f32_dpp v54, v54, v54 row_shr:1 row_mask:0xf bank_mask:0xf bound_ctrl:1
	v_add_f32_dpp v55, v55, v55 row_shr:1 row_mask:0xf bank_mask:0xf bound_ctrl:1
	v_add_f32_dpp v48, v48, v48 row_shr:2 row_mask:0xf bank_mask:0xf bound_ctrl:1
	v_add_f32_dpp v49, v49, v49 row_shr:2 row_mask:0xf bank_mask:0xf bound_ctrl:1
	v_add_f32_dpp v50, v50, v50 row_shr:2 row_mask:0xf bank_mask:0xf bound_ctrl:1
	v_add_f32_dpp v51, v51, v51 row_shr:2 row_mask:0xf bank_mask:0xf bound_ctrl:1
	v_add_f32_dpp v52, v52, v52 row_shr:2 row_mask:0xf bank_mask:0xf bound_ctrl:1
	v_add_f32_dpp v53, v53, v53 row_shr:2 row_mask:0xf bank_mask:0xf bound_ctrl:1
	v_add_f32_dpp v54, v54, v54 row_shr:2 row_mask:0xf bank_mask:0xf bound_ctrl:1
	v_add_f32_dpp v55, v55, v55 row_shr:2 row_mask:0xf bank_mask:0xf bound_ctrl:1
	v_add_f32_dpp v48, v48, v48 row_shr:4 row_mask:0xf bank_mask:0xf bound_ctrl:1
	v_add_f32_dpp v49, v49, v49 row_shr:4 row_mask:0xf bank_mask:0xf bound_ctrl:1
	v_add_f32_dpp v50, v50, v50 row_shr:4 row_mask:0xf bank_mask:0xf bound_ctrl:1
	v_add_f32_dpp v51, v51, v51 row_shr:4 row_mask:0xf bank_mask:0xf bound_ctrl:1
	v_add_f32_dpp v52, v52, v52 row_shr:4 row_mask:0xf bank_mask:0xf bound_ctrl:1
	v_add_f32_dpp v53, v53, v53 row_shr:4 row_mask:0xf bank_mask:0xf bound_ctrl:1
	v_add_f32_dpp v54, v54, v54 row_shr:4 row_mask:0xf bank_mask:0xf bound_ctrl:1
	v_add_f32_dpp v55, v55, v55 row_shr:4 row_mask:0xf bank_mask:0xf bound_ctrl:1
	v_add_f32_dpp v48, v48, v48 row_shr:8 row_mask:0xf bank_mask:0xf bound_ctrl:1
	v_add_f32_dpp v49, v49, v49 row_shr:8 row_mask:0xf bank_mask:0xf bound_ctrl:1
	v_add_f32_dpp v50, v50, v50 row_shr:8 row_mask:0xf bank_mask:0xf bound_ctrl:1
	v_add_f32_dpp v51, v51, v51 row_shr:8 row_mask:0xf bank_mask:0xf bound_ctrl:1
	v_add_f32_dpp v52, v52, v52 row_shr:8 row_mask:0xf bank_mask:0xf bound_ctrl:1
	v_add_f32_dpp v53, v53, v53 row_shr:8 row_mask:0xf bank_mask:0xf bound_ctrl:1
	v_add_f32_dpp v54, v54, v54 row_shr:8 row_mask:0xf bank_mask:0xf bound_ctrl:1
	v_add_f32_dpp v55, v55, v55 row_shr:8 row_mask:0xf bank_mask:0xf bound_ctrl:1
	v_mov_b32_dpp v88, v48 row_newbcast:15 row_mask:0xf bank_mask:0xf
	v_mov_b32_dpp v89, v49 row_newbcast:15 row_mask:0xf bank_mask:0xf
	v_mov_b32_dpp v90, v50 row_newbcast:15 row_mask:0xf bank_mask:0xf
	v_mov_b32_dpp v91, v51 row_newbcast:15 row_mask:0xf bank_mask:0xf
	v_mov_b32_dpp v92, v52 row_newbcast:15 row_mask:0xf bank_mask:0xf
	v_mov_b32_dpp v93, v53 row_newbcast:15 row_mask:0xf bank_mask:0xf
	v_mov_b32_dpp v94, v54 row_newbcast:15 row_mask:0xf bank_mask:0xf
	v_mov_b32_dpp v95, v55 row_newbcast:15 row_mask:0xf bank_mask:0xf
	v_pk_add_f32 v[48:49], v[48:49], v[68:69]
	v_pk_add_f32 v[52:53], v[52:53], v[76:77]
	v_pk_add_f32 v[50:51], v[50:51], v[70:71]
	v_pk_add_f32 v[54:55], v[54:55], v[78:79]
	v_pk_mul_f32 v[132:133], v[48:49], v[150:151]
	v_pk_mul_f32 v[48:49], v[48:49], v[146:147]
	v_pk_fma_f32 v[48:49], v[52:53], v[150:151], v[48:49] neg_lo:[1,0,0] neg_hi:[1,0,0]
	v_pk_fma_f32 v[52:53], v[52:53], v[146:147], v[132:133]
	v_pk_mul_f32 v[132:133], v[50:51], v[152:153]
	v_pk_mul_f32 v[50:51], v[50:51], v[148:149]
	v_pk_fma_f32 v[50:51], v[54:55], v[152:153], v[50:51] neg_lo:[1,0,0] neg_hi:[1,0,0]
	v_pk_fma_f32 v[54:55], v[54:55], v[148:149], v[132:133]
	v_pk_add_f32 v[88:89], v[88:89], v[68:69]
	v_pk_add_f32 v[92:93], v[92:93], v[76:77]
	v_pk_mul_f32 v[132:133], v[92:93], v[158:159]
	v_pk_mul_f32 v[76:77], v[88:89], v[158:159]
	v_pk_fma_f32 v[68:69], v[88:89], v[154:155], v[132:133] neg_lo:[0,0,1] neg_hi:[0,0,1]
	v_pk_fma_f32 v[76:77], v[92:93], v[154:155], v[76:77]
	v_pk_add_f32 v[90:91], v[90:91], v[70:71]
	v_pk_add_f32 v[94:95], v[94:95], v[78:79]
	v_pk_mul_f32 v[132:133], v[94:95], v[160:161]
	v_pk_mul_f32 v[78:79], v[90:91], v[160:161]
	v_pk_fma_f32 v[70:71], v[90:91], v[156:157], v[132:133] neg_lo:[0,0,1] neg_hi:[0,0,1]
	v_pk_fma_f32 v[78:79], v[94:95], v[156:157], v[78:79]
	v_pk_mul_f32 v[132:133], v[56:57], v[142:143]
	v_pk_mul_f32 v[56:57], v[56:57], v[138:139]
	v_pk_fma_f32 v[56:57], v[60:61], v[142:143], v[56:57] neg_lo:[1,0,0] neg_hi:[1,0,0]
	v_pk_fma_f32 v[60:61], v[60:61], v[138:139], v[132:133]
	v_pk_mul_f32 v[132:133], v[58:59], v[144:145]
	v_pk_mul_f32 v[58:59], v[58:59], v[140:141]
	v_pk_fma_f32 v[58:59], v[62:63], v[144:145], v[58:59] neg_lo:[1,0,0] neg_hi:[1,0,0]
	v_pk_fma_f32 v[62:63], v[62:63], v[140:141], v[132:133]
	v_add_f32_dpp v56, v56, v56 row_shr:1 row_mask:0xf bank_mask:0xf bound_ctrl:1
	v_add_f32_dpp v57, v57, v57 row_shr:1 row_mask:0xf bank_mask:0xf bound_ctrl:1
	v_add_f32_dpp v58, v58, v58 row_shr:1 row_mask:0xf bank_mask:0xf bound_ctrl:1
	v_add_f32_dpp v59, v59, v59 row_shr:1 row_mask:0xf bank_mask:0xf bound_ctrl:1
	v_add_f32_dpp v60, v60, v60 row_shr:1 row_mask:0xf bank_mask:0xf bound_ctrl:1
	v_add_f32_dpp v61, v61, v61 row_shr:1 row_mask:0xf bank_mask:0xf bound_ctrl:1
	v_add_f32_dpp v62, v62, v62 row_shr:1 row_mask:0xf bank_mask:0xf bound_ctrl:1
	v_add_f32_dpp v63, v63, v63 row_shr:1 row_mask:0xf bank_mask:0xf bound_ctrl:1
	v_add_f32_dpp v56, v56, v56 row_shr:2 row_mask:0xf bank_mask:0xf bound_ctrl:1
	v_add_f32_dpp v57, v57, v57 row_shr:2 row_mask:0xf bank_mask:0xf bound_ctrl:1
	v_add_f32_dpp v58, v58, v58 row_shr:2 row_mask:0xf bank_mask:0xf bound_ctrl:1
	v_add_f32_dpp v59, v59, v59 row_shr:2 row_mask:0xf bank_mask:0xf bound_ctrl:1
	v_add_f32_dpp v60, v60, v60 row_shr:2 row_mask:0xf bank_mask:0xf bound_ctrl:1
	v_add_f32_dpp v61, v61, v61 row_shr:2 row_mask:0xf bank_mask:0xf bound_ctrl:1
	v_add_f32_dpp v62, v62, v62 row_shr:2 row_mask:0xf bank_mask:0xf bound_ctrl:1
	v_add_f32_dpp v63, v63, v63 row_shr:2 row_mask:0xf bank_mask:0xf bound_ctrl:1
	v_add_f32_dpp v56, v56, v56 row_shr:4 row_mask:0xf bank_mask:0xf bound_ctrl:1
	v_add_f32_dpp v57, v57, v57 row_shr:4 row_mask:0xf bank_mask:0xf bound_ctrl:1
	v_add_f32_dpp v58, v58, v58 row_shr:4 row_mask:0xf bank_mask:0xf bound_ctrl:1
	v_add_f32_dpp v59, v59, v59 row_shr:4 row_mask:0xf bank_mask:0xf bound_ctrl:1
	v_add_f32_dpp v60, v60, v60 row_shr:4 row_mask:0xf bank_mask:0xf bound_ctrl:1
	v_add_f32_dpp v61, v61, v61 row_shr:4 row_mask:0xf bank_mask:0xf bound_ctrl:1
	v_add_f32_dpp v62, v62, v62 row_shr:4 row_mask:0xf bank_mask:0xf bound_ctrl:1
	v_add_f32_dpp v63, v63, v63 row_shr:4 row_mask:0xf bank_mask:0xf bound_ctrl:1
	v_add_f32_dpp v56, v56, v56 row_shr:8 row_mask:0xf bank_mask:0xf bound_ctrl:1
	v_add_f32_dpp v57, v57, v57 row_shr:8 row_mask:0xf bank_mask:0xf bound_ctrl:1
	v_add_f32_dpp v58, v58, v58 row_shr:8 row_mask:0xf bank_mask:0xf bound_ctrl:1
	v_add_f32_dpp v59, v59, v59 row_shr:8 row_mask:0xf bank_mask:0xf bound_ctrl:1
	v_add_f32_dpp v60, v60, v60 row_shr:8 row_mask:0xf bank_mask:0xf bound_ctrl:1
	v_add_f32_dpp v61, v61, v61 row_shr:8 row_mask:0xf bank_mask:0xf bound_ctrl:1
	v_add_f32_dpp v62, v62, v62 row_shr:8 row_mask:0xf bank_mask:0xf bound_ctrl:1
	v_add_f32_dpp v63, v63, v63 row_shr:8 row_mask:0xf bank_mask:0xf bound_ctrl:1
	v_mov_b32_dpp v88, v56 row_newbcast:15 row_mask:0xf bank_mask:0xf
	v_mov_b32_dpp v89, v57 row_newbcast:15 row_mask:0xf bank_mask:0xf
	v_mov_b32_dpp v90, v58 row_newbcast:15 row_mask:0xf bank_mask:0xf
	v_mov_b32_dpp v91, v59 row_newbcast:15 row_mask:0xf bank_mask:0xf
	v_mov_b32_dpp v92, v60 row_newbcast:15 row_mask:0xf bank_mask:0xf
	v_mov_b32_dpp v93, v61 row_newbcast:15 row_mask:0xf bank_mask:0xf
	v_mov_b32_dpp v94, v62 row_newbcast:15 row_mask:0xf bank_mask:0xf
	v_mov_b32_dpp v95, v63 row_newbcast:15 row_mask:0xf bank_mask:0xf
	v_pk_add_f32 v[56:57], v[56:57], v[68:69]
	v_pk_add_f32 v[60:61], v[60:61], v[76:77]
	v_pk_add_f32 v[58:59], v[58:59], v[70:71]
	v_pk_add_f32 v[62:63], v[62:63], v[78:79]
	v_pk_mul_f32 v[132:133], v[56:57], v[150:151]
	v_pk_mul_f32 v[56:57], v[56:57], v[146:147]
	v_pk_fma_f32 v[56:57], v[60:61], v[150:151], v[56:57] neg_lo:[1,0,0] neg_hi:[1,0,0]
	v_pk_fma_f32 v[60:61], v[60:61], v[146:147], v[132:133]
	v_pk_mul_f32 v[132:133], v[58:59], v[152:153]
	v_pk_mul_f32 v[58:59], v[58:59], v[148:149]
	v_pk_fma_f32 v[58:59], v[62:63], v[152:153], v[58:59] neg_lo:[1,0,0] neg_hi:[1,0,0]
	v_pk_fma_f32 v[62:63], v[62:63], v[148:149], v[132:133]
	v_pk_add_f32 v[88:89], v[88:89], v[68:69]
	v_pk_add_f32 v[92:93], v[92:93], v[76:77]
	v_pk_mul_f32 v[132:133], v[92:93], v[158:159]
	v_pk_mul_f32 v[76:77], v[88:89], v[158:159]
	v_pk_fma_f32 v[68:69], v[88:89], v[154:155], v[132:133] neg_lo:[0,0,1] neg_hi:[0,0,1]
	v_pk_fma_f32 v[76:77], v[92:93], v[154:155], v[76:77]
	v_pk_add_f32 v[90:91], v[90:91], v[70:71]
	v_pk_add_f32 v[94:95], v[94:95], v[78:79]
	v_pk_mul_f32 v[132:133], v[94:95], v[160:161]
	v_pk_mul_f32 v[78:79], v[90:91], v[160:161]
	v_pk_fma_f32 v[70:71], v[90:91], v[156:157], v[132:133] neg_lo:[0,0,1] neg_hi:[0,0,1]
	v_pk_fma_f32 v[78:79], v[94:95], v[156:157], v[78:79]
	s_waitcnt vmcnt(12)
	v_cvt_pk_bf16_f32 v96, v32, v33
	v_cvt_pk_bf16_f32 v97, v34, v35
	v_cvt_pk_bf16_f32 v98, v36, v37
	v_cvt_pk_bf16_f32 v99, v38, v39
	s_nop 1
	v_mfma_f32_16x16x32_bf16 v[16:19], v[80:83], v[96:99], 0
	v_cvt_pk_bf16_f32 v96, v40, v41
	v_cvt_pk_bf16_f32 v97, v42, v43
	v_cvt_pk_bf16_f32 v98, v44, v45
	v_cvt_pk_bf16_f32 v99, v46, v47
	s_nop 1
	v_mfma_f32_16x16x32_bf16 v[20:23], v[80:83], v[96:99], 0
	v_cvt_pk_bf16_f32 v96, v48, v49
	v_cvt_pk_bf16_f32 v97, v50, v51
	v_cvt_pk_bf16_f32 v98, v52, v53
	v_cvt_pk_bf16_f32 v99, v54, v55
	s_nop 1
	v_mfma_f32_16x16x32_bf16 v[24:27], v[80:83], v[96:99], 0
	v_cvt_pk_bf16_f32 v96, v56, v57
	v_cvt_pk_bf16_f32 v97, v58, v59
	v_cvt_pk_bf16_f32 v98, v60, v61
	v_cvt_pk_bf16_f32 v99, v62, v63
	s_nop 1
	v_mfma_f32_16x16x32_bf16 v[28:31], v[80:83], v[96:99], 0
	s_waitcnt vmcnt(10)
	global_load_dwordx4 v[80:83], v134, s[38:39]
	s_add_u32 s38, s38, 0x400
	s_addc_u32 s39, s39, 0
	v_mfma_f32_16x16x32_bf16 v[32:35], v[64:67], v[0:3], 0
	v_mfma_f32_16x16x32_bf16 v[36:39], v[72:75], v[0:3], 0
	v_mfma_f32_16x16x32_bf16 v[40:43], v[64:67], v[4:7], 0
	v_mfma_f32_16x16x32_bf16 v[44:47], v[72:75], v[4:7], 0
	v_mfma_f32_16x16x32_bf16 v[48:51], v[64:67], v[8:11], 0
	v_mfma_f32_16x16x32_bf16 v[52:55], v[72:75], v[8:11], 0
	v_mfma_f32_16x16x32_bf16 v[56:59], v[64:67], v[12:15], 0
	v_mfma_f32_16x16x32_bf16 v[60:63], v[72:75], v[12:15], 0
	global_load_dwordx4 v[64:67], v134, s[20:21]
	global_load_dwordx4 v[72:75], v134, s[20:21] offset:1024
	s_add_u32 s20, s20, 0x800
	s_addc_u32 s21, s21, 0
	global_load_dwordx4 v[138:141], v134, s[42:43] offset:0
	global_load_dwordx4 v[142:145], v134, s[42:43] offset:1024
	global_load_dwordx4 v[146:149], v134, s[42:43] offset:2048
	global_load_dwordx4 v[150:153], v134, s[42:43] offset:3072
	global_load_dwordx4 v[154:157], v208, s[42:43] offset:0
	global_load_dwordx4 v[158:161], v208, s[42:43] offset:1024
	global_load_dwordx4 v[162:165], v208, s[42:43] offset:2048
	global_load_dwordx4 v[166:169], v208, s[42:43] offset:3072
	global_load_dwordx4 v[170:173], v206, s[44:45]
	global_load_dwordx4 v[174:177], v206, s[44:45] offset:16
	s_add_u32 s42, s42, 0x2000
	s_addc_u32 s43, s43, 0
	s_add_u32 s44, s44, 0x80
	s_addc_u32 s45, s45, 0
	s_waitcnt vmcnt(13)
	v_mul_f32_e32 v132, v179, v128
	v_mul_f32_e32 v133, v178, v128
	v_fma_f32 v68, v178, v124, -v132
	v_fma_f32 v76, v179, v124, v133
	v_mul_f32_e32 v132, v181, v129
	v_mul_f32_e32 v133, v180, v129
	v_fma_f32 v69, v180, v125, -v132
	v_fma_f32 v77, v181, v125, v133
	v_mul_f32_e32 v132, v183, v130
	v_mul_f32_e32 v133, v182, v130
	v_fma_f32 v70, v182, v126, -v132
	v_fma_f32 v78, v183, v126, v133
	v_mul_f32_e32 v132, v185, v131
	v_mul_f32_e32 v133, v184, v131
	v_fma_f32 v71, v184, v127, -v132
	v_fma_f32 v79, v185, v127, v133
	v_pk_mul_f32 v[132:133], v[32:33], v[104:105]
	v_pk_mul_f32 v[32:33], v[32:33], v[100:101]
	v_pk_fma_f32 v[32:33], v[36:37], v[104:105], v[32:33] neg_lo:[1,0,0] neg_hi:[1,0,0]
	v_pk_fma_f32 v[36:37], v[36:37], v[100:101], v[132:133]
	v_pk_mul_f32 v[132:133], v[34:35], v[106:107]
	v_pk_mul_f32 v[34:35], v[34:35], v[102:103]
	v_pk_fma_f32 v[34:35], v[38:39], v[106:107], v[34:35] neg_lo:[1,0,0] neg_hi:[1,0,0]
	v_pk_fma_f32 v[38:39], v[38:39], v[102:103], v[132:133]
	v_add_f32_dpp v32, v32, v32 row_shr:1 row_mask:0xf bank_mask:0xf bound_ctrl:1
	v_add_f32_dpp v33, v33, v33 row_shr:1 row_mask:0xf bank_mask:0xf bound_ctrl:1
	v_add_f32_dpp v34, v34, v34 row_shr:1 row_mask:0xf bank_mask:0xf bound_ctrl:1
	v_add_f32_dpp v35, v35, v35 row_shr:1 row_mask:0xf bank_mask:0xf bound_ctrl:1
	v_add_f32_dpp v36, v36, v36 row_shr:1 row_mask:0xf bank_mask:0xf bound_ctrl:1
	v_add_f32_dpp v37, v37, v37 row_shr:1 row_mask:0xf bank_mask:0xf bound_ctrl:1
	v_add_f32_dpp v38, v38, v38 row_shr:1 row_mask:0xf bank_mask:0xf bound_ctrl:1
	v_add_f32_dpp v39, v39, v39 row_shr:1 row_mask:0xf bank_mask:0xf bound_ctrl:1
	v_add_f32_dpp v32, v32, v32 row_shr:2 row_mask:0xf bank_mask:0xf bound_ctrl:1
	v_add_f32_dpp v33, v33, v33 row_shr:2 row_mask:0xf bank_mask:0xf bound_ctrl:1
	v_add_f32_dpp v34, v34, v34 row_shr:2 row_mask:0xf bank_mask:0xf bound_ctrl:1
	v_add_f32_dpp v35, v35, v35 row_shr:2 row_mask:0xf bank_mask:0xf bound_ctrl:1
	v_add_f32_dpp v36, v36, v36 row_shr:2 row_mask:0xf bank_mask:0xf bound_ctrl:1
	v_add_f32_dpp v37, v37, v37 row_shr:2 row_mask:0xf bank_mask:0xf bound_ctrl:1
	v_add_f32_dpp v38, v38, v38 row_shr:2 row_mask:0xf bank_mask:0xf bound_ctrl:1
	v_add_f32_dpp v39, v39, v39 row_shr:2 row_mask:0xf bank_mask:0xf bound_ctrl:1
	v_add_f32_dpp v32, v32, v32 row_shr:4 row_mask:0xf bank_mask:0xf bound_ctrl:1
	v_add_f32_dpp v33, v33, v33 row_shr:4 row_mask:0xf bank_mask:0xf bound_ctrl:1
	v_add_f32_dpp v34, v34, v34 row_shr:4 row_mask:0xf bank_mask:0xf bound_ctrl:1
	v_add_f32_dpp v35, v35, v35 row_shr:4 row_mask:0xf bank_mask:0xf bound_ctrl:1
	v_add_f32_dpp v36, v36, v36 row_shr:4 row_mask:0xf bank_mask:0xf bound_ctrl:1
	v_add_f32_dpp v37, v37, v37 row_shr:4 row_mask:0xf bank_mask:0xf bound_ctrl:1
	v_add_f32_dpp v38, v38, v38 row_shr:4 row_mask:0xf bank_mask:0xf bound_ctrl:1
	v_add_f32_dpp v39, v39, v39 row_shr:4 row_mask:0xf bank_mask:0xf bound_ctrl:1
	v_add_f32_dpp v32, v32, v32 row_shr:8 row_mask:0xf bank_mask:0xf bound_ctrl:1
	v_add_f32_dpp v33, v33, v33 row_shr:8 row_mask:0xf bank_mask:0xf bound_ctrl:1
	v_add_f32_dpp v34, v34, v34 row_shr:8 row_mask:0xf bank_mask:0xf bound_ctrl:1
	v_add_f32_dpp v35, v35, v35 row_shr:8 row_mask:0xf bank_mask:0xf bound_ctrl:1
	v_add_f32_dpp v36, v36, v36 row_shr:8 row_mask:0xf bank_mask:0xf bound_ctrl:1
	v_add_f32_dpp v37, v37, v37 row_shr:8 row_mask:0xf bank_mask:0xf bound_ctrl:1
	v_add_f32_dpp v38, v38, v38 row_shr:8 row_mask:0xf bank_mask:0xf bound_ctrl:1
	v_add_f32_dpp v39, v39, v39 row_shr:8 row_mask:0xf bank_mask:0xf bound_ctrl:1
	v_mov_b32_dpp v88, v32 row_newbcast:15 row_mask:0xf bank_mask:0xf
	v_mov_b32_dpp v89, v33 row_newbcast:15 row_mask:0xf bank_mask:0xf
	v_mov_b32_dpp v90, v34 row_newbcast:15 row_mask:0xf bank_mask:0xf
	v_mov_b32_dpp v91, v35 row_newbcast:15 row_mask:0xf bank_mask:0xf
	v_mov_b32_dpp v92, v36 row_newbcast:15 row_mask:0xf bank_mask:0xf
	v_mov_b32_dpp v93, v37 row_newbcast:15 row_mask:0xf bank_mask:0xf
	v_mov_b32_dpp v94, v38 row_newbcast:15 row_mask:0xf bank_mask:0xf
	v_mov_b32_dpp v95, v39 row_newbcast:15 row_mask:0xf bank_mask:0xf
	v_pk_add_f32 v[32:33], v[32:33], v[68:69]
	v_pk_add_f32 v[36:37], v[36:37], v[76:77]
	v_pk_add_f32 v[34:35], v[34:35], v[70:71]
	v_pk_add_f32 v[38:39], v[38:39], v[78:79]
	v_pk_mul_f32 v[132:133], v[32:33], v[112:113]
	v_pk_mul_f32 v[32:33], v[32:33], v[108:109]
	v_pk_fma_f32 v[32:33], v[36:37], v[112:113], v[32:33] neg_lo:[1,0,0] neg_hi:[1,0,0]
	v_pk_fma_f32 v[36:37], v[36:37], v[108:109], v[132:133]
	v_pk_mul_f32 v[132:133], v[34:35], v[114:115]
	v_pk_mul_f32 v[34:35], v[34:35], v[110:111]
	v_pk_fma_f32 v[34:35], v[38:39], v[114:115], v[34:35] neg_lo:[1,0,0] neg_hi:[1,0,0]
	v_pk_fma_f32 v[38:39], v[38:39], v[110:111], v[132:133]
	v_pk_add_f32 v[88:89], v[88:89], v[68:69]
	v_pk_add_f32 v[92:93], v[92:93], v[76:77]
	v_pk_mul_f32 v[132:133], v[92:93], v[120:121]
	v_pk_mul_f32 v[76:77], v[88:89], v[120:121]
	v_pk_fma_f32 v[68:69], v[88:89], v[116:117], v[132:133] neg_lo:[0,0,1] neg_hi:[0,0,1]
	v_pk_fma_f32 v[76:77], v[92:93], v[116:117], v[76:77]
	v_pk_add_f32 v[90:91], v[90:91], v[70:71]
	v_pk_add_f32 v[94:95], v[94:95], v[78:79]
	v_pk_mul_f32 v[132:133], v[94:95], v[122:123]
	v_pk_mul_f32 v[78:79], v[90:91], v[122:123]
	v_pk_fma_f32 v[70:71], v[90:91], v[118:119], v[132:133] neg_lo:[0,0,1] neg_hi:[0,0,1]
	v_pk_fma_f32 v[78:79], v[94:95], v[118:119], v[78:79]
	v_pk_mul_f32 v[132:133], v[40:41], v[104:105]
	v_pk_mul_f32 v[40:41], v[40:41], v[100:101]
	v_pk_fma_f32 v[40:41], v[44:45], v[104:105], v[40:41] neg_lo:[1,0,0] neg_hi:[1,0,0]
	v_pk_fma_f32 v[44:45], v[44:45], v[100:101], v[132:133]
	v_pk_mul_f32 v[132:133], v[42:43], v[106:107]
	v_pk_mul_f32 v[42:43], v[42:43], v[102:103]
	v_pk_fma_f32 v[42:43], v[46:47], v[106:107], v[42:43] neg_lo:[1,0,0] neg_hi:[1,0,0]
	v_pk_fma_f32 v[46:47], v[46:47], v[102:103], v[132:133]
	v_add_f32_dpp v40, v40, v40 row_shr:1 row_mask:0xf bank_mask:0xf bound_ctrl:1
	v_add_f32_dpp v41, v41, v41 row_shr:1 row_mask:0xf bank_mask:0xf bound_ctrl:1
	v_add_f32_dpp v42, v42, v42 row_shr:1 row_mask:0xf bank_mask:0xf bound_ctrl:1
	v_add_f32_dpp v43, v43, v43 row_shr:1 row_mask:0xf bank_mask:0xf bound_ctrl:1
	v_add_f32_dpp v44, v44, v44 row_shr:1 row_mask:0xf bank_mask:0xf bound_ctrl:1
	v_add_f32_dpp v45, v45, v45 row_shr:1 row_mask:0xf bank_mask:0xf bound_ctrl:1
	v_add_f32_dpp v46, v46, v46 row_shr:1 row_mask:0xf bank_mask:0xf bound_ctrl:1
	v_add_f32_dpp v47, v47, v47 row_shr:1 row_mask:0xf bank_mask:0xf bound_ctrl:1
	v_add_f32_dpp v40, v40, v40 row_shr:2 row_mask:0xf bank_mask:0xf bound_ctrl:1
	v_add_f32_dpp v41, v41, v41 row_shr:2 row_mask:0xf bank_mask:0xf bound_ctrl:1
	v_add_f32_dpp v42, v42, v42 row_shr:2 row_mask:0xf bank_mask:0xf bound_ctrl:1
	v_add_f32_dpp v43, v43, v43 row_shr:2 row_mask:0xf bank_mask:0xf bound_ctrl:1
	v_add_f32_dpp v44, v44, v44 row_shr:2 row_mask:0xf bank_mask:0xf bound_ctrl:1
	v_add_f32_dpp v45, v45, v45 row_shr:2 row_mask:0xf bank_mask:0xf bound_ctrl:1
	v_add_f32_dpp v46, v46, v46 row_shr:2 row_mask:0xf bank_mask:0xf bound_ctrl:1
	v_add_f32_dpp v47, v47, v47 row_shr:2 row_mask:0xf bank_mask:0xf bound_ctrl:1
	v_add_f32_dpp v40, v40, v40 row_shr:4 row_mask:0xf bank_mask:0xf bound_ctrl:1
	v_add_f32_dpp v41, v41, v41 row_shr:4 row_mask:0xf bank_mask:0xf bound_ctrl:1
	v_add_f32_dpp v42, v42, v42 row_shr:4 row_mask:0xf bank_mask:0xf bound_ctrl:1
	v_add_f32_dpp v43, v43, v43 row_shr:4 row_mask:0xf bank_mask:0xf bound_ctrl:1
	v_add_f32_dpp v44, v44, v44 row_shr:4 row_mask:0xf bank_mask:0xf bound_ctrl:1
	v_add_f32_dpp v45, v45, v45 row_shr:4 row_mask:0xf bank_mask:0xf bound_ctrl:1
	v_add_f32_dpp v46, v46, v46 row_shr:4 row_mask:0xf bank_mask:0xf bound_ctrl:1
	v_add_f32_dpp v47, v47, v47 row_shr:4 row_mask:0xf bank_mask:0xf bound_ctrl:1
	v_add_f32_dpp v40, v40, v40 row_shr:8 row_mask:0xf bank_mask:0xf bound_ctrl:1
	v_add_f32_dpp v41, v41, v41 row_shr:8 row_mask:0xf bank_mask:0xf bound_ctrl:1
	v_add_f32_dpp v42, v42, v42 row_shr:8 row_mask:0xf bank_mask:0xf bound_ctrl:1
	v_add_f32_dpp v43, v43, v43 row_shr:8 row_mask:0xf bank_mask:0xf bound_ctrl:1
	v_add_f32_dpp v44, v44, v44 row_shr:8 row_mask:0xf bank_mask:0xf bound_ctrl:1
	v_add_f32_dpp v45, v45, v45 row_shr:8 row_mask:0xf bank_mask:0xf bound_ctrl:1
	v_add_f32_dpp v46, v46, v46 row_shr:8 row_mask:0xf bank_mask:0xf bound_ctrl:1
	v_add_f32_dpp v47, v47, v47 row_shr:8 row_mask:0xf bank_mask:0xf bound_ctrl:1
	v_mov_b32_dpp v88, v40 row_newbcast:15 row_mask:0xf bank_mask:0xf
	v_mov_b32_dpp v89, v41 row_newbcast:15 row_mask:0xf bank_mask:0xf
	v_mov_b32_dpp v90, v42 row_newbcast:15 row_mask:0xf bank_mask:0xf
	v_mov_b32_dpp v91, v43 row_newbcast:15 row_mask:0xf bank_mask:0xf
	v_mov_b32_dpp v92, v44 row_newbcast:15 row_mask:0xf bank_mask:0xf
	v_mov_b32_dpp v93, v45 row_newbcast:15 row_mask:0xf bank_mask:0xf
	v_mov_b32_dpp v94, v46 row_newbcast:15 row_mask:0xf bank_mask:0xf
	v_mov_b32_dpp v95, v47 row_newbcast:15 row_mask:0xf bank_mask:0xf
	v_pk_add_f32 v[40:41], v[40:41], v[68:69]
	v_pk_add_f32 v[44:45], v[44:45], v[76:77]
	v_pk_add_f32 v[42:43], v[42:43], v[70:71]
	v_pk_add_f32 v[46:47], v[46:47], v[78:79]
	v_pk_mul_f32 v[132:133], v[40:41], v[112:113]
	v_pk_mul_f32 v[40:41], v[40:41], v[108:109]
	v_pk_fma_f32 v[40:41], v[44:45], v[112:113], v[40:41] neg_lo:[1,0,0] neg_hi:[1,0,0]
	v_pk_fma_f32 v[44:45], v[44:45], v[108:109], v[132:133]
	v_pk_mul_f32 v[132:133], v[42:43], v[114:115]
	v_pk_mul_f32 v[42:43], v[42:43], v[110:111]
	v_pk_fma_f32 v[42:43], v[46:47], v[114:115], v[42:43] neg_lo:[1,0,0] neg_hi:[1,0,0]
	v_pk_fma_f32 v[46:47], v[46:47], v[110:111], v[132:133]
	v_pk_add_f32 v[88:89], v[88:89], v[68:69]
	v_pk_add_f32 v[92:93], v[92:93], v[76:77]
	v_pk_mul_f32 v[132:133], v[92:93], v[120:121]
	v_pk_mul_f32 v[76:77], v[88:89], v[120:121]
	v_pk_fma_f32 v[68:69], v[88:89], v[116:117], v[132:133] neg_lo:[0,0,1] neg_hi:[0,0,1]
	v_pk_fma_f32 v[76:77], v[92:93], v[116:117], v[76:77]
	v_pk_add_f32 v[90:91], v[90:91], v[70:71]
	v_pk_add_f32 v[94:95], v[94:95], v[78:79]
	v_pk_mul_f32 v[132:133], v[94:95], v[122:123]
	v_pk_mul_f32 v[78:79], v[90:91], v[122:123]
	v_pk_fma_f32 v[70:71], v[90:91], v[118:119], v[132:133] neg_lo:[0,0,1] neg_hi:[0,0,1]
	v_pk_fma_f32 v[78:79], v[94:95], v[118:119], v[78:79]
	v_pk_mul_f32 v[132:133], v[48:49], v[104:105]
	v_pk_mul_f32 v[48:49], v[48:49], v[100:101]
	v_pk_fma_f32 v[48:49], v[52:53], v[104:105], v[48:49] neg_lo:[1,0,0] neg_hi:[1,0,0]
	v_pk_fma_f32 v[52:53], v[52:53], v[100:101], v[132:133]
	v_pk_mul_f32 v[132:133], v[50:51], v[106:107]
	v_pk_mul_f32 v[50:51], v[50:51], v[102:103]
	v_pk_fma_f32 v[50:51], v[54:55], v[106:107], v[50:51] neg_lo:[1,0,0] neg_hi:[1,0,0]
	v_pk_fma_f32 v[54:55], v[54:55], v[102:103], v[132:133]
	v_add_f32_dpp v48, v48, v48 row_shr:1 row_mask:0xf bank_mask:0xf bound_ctrl:1
	v_add_f32_dpp v49, v49, v49 row_shr:1 row_mask:0xf bank_mask:0xf bound_ctrl:1
	v_add_f32_dpp v50, v50, v50 row_shr:1 row_mask:0xf bank_mask:0xf bound_ctrl:1
	v_add_f32_dpp v51, v51, v51 row_shr:1 row_mask:0xf bank_mask:0xf bound_ctrl:1
	v_add_f32_dpp v52, v52, v52 row_shr:1 row_mask:0xf bank_mask:0xf bound_ctrl:1
	v_add_f32_dpp v53, v53, v53 row_shr:1 row_mask:0xf bank_mask:0xf bound_ctrl:1
	v_add_f32_dpp v54, v54, v54 row_shr:1 row_mask:0xf bank_mask:0xf bound_ctrl:1
	v_add_f32_dpp v55, v55, v55 row_shr:1 row_mask:0xf bank_mask:0xf bound_ctrl:1
	v_add_f32_dpp v48, v48, v48 row_shr:2 row_mask:0xf bank_mask:0xf bound_ctrl:1
	v_add_f32_dpp v49, v49, v49 row_shr:2 row_mask:0xf bank_mask:0xf bound_ctrl:1
	v_add_f32_dpp v50, v50, v50 row_shr:2 row_mask:0xf bank_mask:0xf bound_ctrl:1
	v_add_f32_dpp v51, v51, v51 row_shr:2 row_mask:0xf bank_mask:0xf bound_ctrl:1
	v_add_f32_dpp v52, v52, v52 row_shr:2 row_mask:0xf bank_mask:0xf bound_ctrl:1
	v_add_f32_dpp v53, v53, v53 row_shr:2 row_mask:0xf bank_mask:0xf bound_ctrl:1
	v_add_f32_dpp v54, v54, v54 row_shr:2 row_mask:0xf bank_mask:0xf bound_ctrl:1
	v_add_f32_dpp v55, v55, v55 row_shr:2 row_mask:0xf bank_mask:0xf bound_ctrl:1
	v_add_f32_dpp v48, v48, v48 row_shr:4 row_mask:0xf bank_mask:0xf bound_ctrl:1
	v_add_f32_dpp v49, v49, v49 row_shr:4 row_mask:0xf bank_mask:0xf bound_ctrl:1
	v_add_f32_dpp v50, v50, v50 row_shr:4 row_mask:0xf bank_mask:0xf bound_ctrl:1
	v_add_f32_dpp v51, v51, v51 row_shr:4 row_mask:0xf bank_mask:0xf bound_ctrl:1
	v_add_f32_dpp v52, v52, v52 row_shr:4 row_mask:0xf bank_mask:0xf bound_ctrl:1
	v_add_f32_dpp v53, v53, v53 row_shr:4 row_mask:0xf bank_mask:0xf bound_ctrl:1
	v_add_f32_dpp v54, v54, v54 row_shr:4 row_mask:0xf bank_mask:0xf bound_ctrl:1
	v_add_f32_dpp v55, v55, v55 row_shr:4 row_mask:0xf bank_mask:0xf bound_ctrl:1
	v_add_f32_dpp v48, v48, v48 row_shr:8 row_mask:0xf bank_mask:0xf bound_ctrl:1
	v_add_f32_dpp v49, v49, v49 row_shr:8 row_mask:0xf bank_mask:0xf bound_ctrl:1
	v_add_f32_dpp v50, v50, v50 row_shr:8 row_mask:0xf bank_mask:0xf bound_ctrl:1
	v_add_f32_dpp v51, v51, v51 row_shr:8 row_mask:0xf bank_mask:0xf bound_ctrl:1
	v_add_f32_dpp v52, v52, v52 row_shr:8 row_mask:0xf bank_mask:0xf bound_ctrl:1
	v_add_f32_dpp v53, v53, v53 row_shr:8 row_mask:0xf bank_mask:0xf bound_ctrl:1
	v_add_f32_dpp v54, v54, v54 row_shr:8 row_mask:0xf bank_mask:0xf bound_ctrl:1
	v_add_f32_dpp v55, v55, v55 row_shr:8 row_mask:0xf bank_mask:0xf bound_ctrl:1
	v_mov_b32_dpp v88, v48 row_newbcast:15 row_mask:0xf bank_mask:0xf
	v_mov_b32_dpp v89, v49 row_newbcast:15 row_mask:0xf bank_mask:0xf
	v_mov_b32_dpp v90, v50 row_newbcast:15 row_mask:0xf bank_mask:0xf
	v_mov_b32_dpp v91, v51 row_newbcast:15 row_mask:0xf bank_mask:0xf
	v_mov_b32_dpp v92, v52 row_newbcast:15 row_mask:0xf bank_mask:0xf
	v_mov_b32_dpp v93, v53 row_newbcast:15 row_mask:0xf bank_mask:0xf
	v_mov_b32_dpp v94, v54 row_newbcast:15 row_mask:0xf bank_mask:0xf
	v_mov_b32_dpp v95, v55 row_newbcast:15 row_mask:0xf bank_mask:0xf
	v_pk_add_f32 v[48:49], v[48:49], v[68:69]
	v_pk_add_f32 v[52:53], v[52:53], v[76:77]
	v_pk_add_f32 v[50:51], v[50:51], v[70:71]
	v_pk_add_f32 v[54:55], v[54:55], v[78:79]
	v_pk_mul_f32 v[132:133], v[48:49], v[112:113]
	v_pk_mul_f32 v[48:49], v[48:49], v[108:109]
	v_pk_fma_f32 v[48:49], v[52:53], v[112:113], v[48:49] neg_lo:[1,0,0] neg_hi:[1,0,0]
	v_pk_fma_f32 v[52:53], v[52:53], v[108:109], v[132:133]
	v_pk_mul_f32 v[132:133], v[50:51], v[114:115]
	v_pk_mul_f32 v[50:51], v[50:51], v[110:111]
	v_pk_fma_f32 v[50:51], v[54:55], v[114:115], v[50:51] neg_lo:[1,0,0] neg_hi:[1,0,0]
	v_pk_fma_f32 v[54:55], v[54:55], v[110:111], v[132:133]
	v_pk_add_f32 v[88:89], v[88:89], v[68:69]
	v_pk_add_f32 v[92:93], v[92:93], v[76:77]
	v_pk_mul_f32 v[132:133], v[92:93], v[120:121]
	v_pk_mul_f32 v[76:77], v[88:89], v[120:121]
	v_pk_fma_f32 v[68:69], v[88:89], v[116:117], v[132:133] neg_lo:[0,0,1] neg_hi:[0,0,1]
	v_pk_fma_f32 v[76:77], v[92:93], v[116:117], v[76:77]
	v_pk_add_f32 v[90:91], v[90:91], v[70:71]
	v_pk_add_f32 v[94:95], v[94:95], v[78:79]
	v_pk_mul_f32 v[132:133], v[94:95], v[122:123]
	v_pk_mul_f32 v[78:79], v[90:91], v[122:123]
	v_pk_fma_f32 v[70:71], v[90:91], v[118:119], v[132:133] neg_lo:[0,0,1] neg_hi:[0,0,1]
	v_pk_fma_f32 v[78:79], v[94:95], v[118:119], v[78:79]
	v_pk_mul_f32 v[132:133], v[56:57], v[104:105]
	v_pk_mul_f32 v[56:57], v[56:57], v[100:101]
	v_pk_fma_f32 v[56:57], v[60:61], v[104:105], v[56:57] neg_lo:[1,0,0] neg_hi:[1,0,0]
	v_pk_fma_f32 v[60:61], v[60:61], v[100:101], v[132:133]
	v_pk_mul_f32 v[132:133], v[58:59], v[106:107]
	v_pk_mul_f32 v[58:59], v[58:59], v[102:103]
	v_pk_fma_f32 v[58:59], v[62:63], v[106:107], v[58:59] neg_lo:[1,0,0] neg_hi:[1,0,0]
	v_pk_fma_f32 v[62:63], v[62:63], v[102:103], v[132:133]
	v_add_f32_dpp v56, v56, v56 row_shr:1 row_mask:0xf bank_mask:0xf bound_ctrl:1
	v_add_f32_dpp v57, v57, v57 row_shr:1 row_mask:0xf bank_mask:0xf bound_ctrl:1
	v_add_f32_dpp v58, v58, v58 row_shr:1 row_mask:0xf bank_mask:0xf bound_ctrl:1
	v_add_f32_dpp v59, v59, v59 row_shr:1 row_mask:0xf bank_mask:0xf bound_ctrl:1
	v_add_f32_dpp v60, v60, v60 row_shr:1 row_mask:0xf bank_mask:0xf bound_ctrl:1
	v_add_f32_dpp v61, v61, v61 row_shr:1 row_mask:0xf bank_mask:0xf bound_ctrl:1
	v_add_f32_dpp v62, v62, v62 row_shr:1 row_mask:0xf bank_mask:0xf bound_ctrl:1
	v_add_f32_dpp v63, v63, v63 row_shr:1 row_mask:0xf bank_mask:0xf bound_ctrl:1
	v_add_f32_dpp v56, v56, v56 row_shr:2 row_mask:0xf bank_mask:0xf bound_ctrl:1
	v_add_f32_dpp v57, v57, v57 row_shr:2 row_mask:0xf bank_mask:0xf bound_ctrl:1
	v_add_f32_dpp v58, v58, v58 row_shr:2 row_mask:0xf bank_mask:0xf bound_ctrl:1
	v_add_f32_dpp v59, v59, v59 row_shr:2 row_mask:0xf bank_mask:0xf bound_ctrl:1
	v_add_f32_dpp v60, v60, v60 row_shr:2 row_mask:0xf bank_mask:0xf bound_ctrl:1
	v_add_f32_dpp v61, v61, v61 row_shr:2 row_mask:0xf bank_mask:0xf bound_ctrl:1
	v_add_f32_dpp v62, v62, v62 row_shr:2 row_mask:0xf bank_mask:0xf bound_ctrl:1
	v_add_f32_dpp v63, v63, v63 row_shr:2 row_mask:0xf bank_mask:0xf bound_ctrl:1
	v_add_f32_dpp v56, v56, v56 row_shr:4 row_mask:0xf bank_mask:0xf bound_ctrl:1
	v_add_f32_dpp v57, v57, v57 row_shr:4 row_mask:0xf bank_mask:0xf bound_ctrl:1
	v_add_f32_dpp v58, v58, v58 row_shr:4 row_mask:0xf bank_mask:0xf bound_ctrl:1
	v_add_f32_dpp v59, v59, v59 row_shr:4 row_mask:0xf bank_mask:0xf bound_ctrl:1
	v_add_f32_dpp v60, v60, v60 row_shr:4 row_mask:0xf bank_mask:0xf bound_ctrl:1
	v_add_f32_dpp v61, v61, v61 row_shr:4 row_mask:0xf bank_mask:0xf bound_ctrl:1
	v_add_f32_dpp v62, v62, v62 row_shr:4 row_mask:0xf bank_mask:0xf bound_ctrl:1
	v_add_f32_dpp v63, v63, v63 row_shr:4 row_mask:0xf bank_mask:0xf bound_ctrl:1
	v_add_f32_dpp v56, v56, v56 row_shr:8 row_mask:0xf bank_mask:0xf bound_ctrl:1
	v_add_f32_dpp v57, v57, v57 row_shr:8 row_mask:0xf bank_mask:0xf bound_ctrl:1
	v_add_f32_dpp v58, v58, v58 row_shr:8 row_mask:0xf bank_mask:0xf bound_ctrl:1
	v_add_f32_dpp v59, v59, v59 row_shr:8 row_mask:0xf bank_mask:0xf bound_ctrl:1
	v_add_f32_dpp v60, v60, v60 row_shr:8 row_mask:0xf bank_mask:0xf bound_ctrl:1
	v_add_f32_dpp v61, v61, v61 row_shr:8 row_mask:0xf bank_mask:0xf bound_ctrl:1
	v_add_f32_dpp v62, v62, v62 row_shr:8 row_mask:0xf bank_mask:0xf bound_ctrl:1
	v_add_f32_dpp v63, v63, v63 row_shr:8 row_mask:0xf bank_mask:0xf bound_ctrl:1
	v_mov_b32_dpp v88, v56 row_newbcast:15 row_mask:0xf bank_mask:0xf
	v_mov_b32_dpp v89, v57 row_newbcast:15 row_mask:0xf bank_mask:0xf
	v_mov_b32_dpp v90, v58 row_newbcast:15 row_mask:0xf bank_mask:0xf
	v_mov_b32_dpp v91, v59 row_newbcast:15 row_mask:0xf bank_mask:0xf
	v_mov_b32_dpp v92, v60 row_newbcast:15 row_mask:0xf bank_mask:0xf
	v_mov_b32_dpp v93, v61 row_newbcast:15 row_mask:0xf bank_mask:0xf
	v_mov_b32_dpp v94, v62 row_newbcast:15 row_mask:0xf bank_mask:0xf
	v_mov_b32_dpp v95, v63 row_newbcast:15 row_mask:0xf bank_mask:0xf
	v_pk_add_f32 v[56:57], v[56:57], v[68:69]
	v_pk_add_f32 v[60:61], v[60:61], v[76:77]
	v_pk_add_f32 v[58:59], v[58:59], v[70:71]
	v_pk_add_f32 v[62:63], v[62:63], v[78:79]
	v_pk_mul_f32 v[132:133], v[56:57], v[112:113]
	v_pk_mul_f32 v[56:57], v[56:57], v[108:109]
	v_pk_fma_f32 v[56:57], v[60:61], v[112:113], v[56:57] neg_lo:[1,0,0] neg_hi:[1,0,0]
	v_pk_fma_f32 v[60:61], v[60:61], v[108:109], v[132:133]
	v_pk_mul_f32 v[132:133], v[58:59], v[114:115]
	v_pk_mul_f32 v[58:59], v[58:59], v[110:111]
	v_pk_fma_f32 v[58:59], v[62:63], v[114:115], v[58:59] neg_lo:[1,0,0] neg_hi:[1,0,0]
	v_pk_fma_f32 v[62:63], v[62:63], v[110:111], v[132:133]
	v_pk_add_f32 v[88:89], v[88:89], v[68:69]
	v_pk_add_f32 v[92:93], v[92:93], v[76:77]
	v_pk_mul_f32 v[132:133], v[92:93], v[120:121]
	v_pk_mul_f32 v[76:77], v[88:89], v[120:121]
	v_pk_fma_f32 v[68:69], v[88:89], v[116:117], v[132:133] neg_lo:[0,0,1] neg_hi:[0,0,1]
	v_pk_fma_f32 v[76:77], v[92:93], v[116:117], v[76:77]
	v_pk_add_f32 v[90:91], v[90:91], v[70:71]
	v_pk_add_f32 v[94:95], v[94:95], v[78:79]
	v_pk_mul_f32 v[132:133], v[94:95], v[122:123]
	v_pk_mul_f32 v[78:79], v[90:91], v[122:123]
	v_pk_fma_f32 v[70:71], v[90:91], v[118:119], v[132:133] neg_lo:[0,0,1] neg_hi:[0,0,1]
	v_pk_fma_f32 v[78:79], v[94:95], v[118:119], v[78:79]
	s_waitcnt vmcnt(12)
	v_cvt_pk_bf16_f32 v96, v32, v33
	v_cvt_pk_bf16_f32 v97, v34, v35
	v_cvt_pk_bf16_f32 v98, v36, v37
	v_cvt_pk_bf16_f32 v99, v38, v39
	s_nop 1
	v_mfma_f32_16x16x32_bf16 v[16:19], v[80:83], v[96:99], v[16:19]
	v_cvt_pk_bf16_f32 v96, v40, v41
	v_cvt_pk_bf16_f32 v97, v42, v43
	v_cvt_pk_bf16_f32 v98, v44, v45
	v_cvt_pk_bf16_f32 v99, v46, v47
	s_nop 1
	v_mfma_f32_16x16x32_bf16 v[20:23], v[80:83], v[96:99], v[20:23]
	v_cvt_pk_bf16_f32 v96, v48, v49
	v_cvt_pk_bf16_f32 v97, v50, v51
	v_cvt_pk_bf16_f32 v98, v52, v53
	v_cvt_pk_bf16_f32 v99, v54, v55
	s_nop 1
	v_mfma_f32_16x16x32_bf16 v[24:27], v[80:83], v[96:99], v[24:27]
	v_cvt_pk_bf16_f32 v96, v56, v57
	v_cvt_pk_bf16_f32 v97, v58, v59
	v_cvt_pk_bf16_f32 v98, v60, v61
	v_cvt_pk_bf16_f32 v99, v62, v63
	s_nop 1
	v_mfma_f32_16x16x32_bf16 v[28:31], v[80:83], v[96:99], v[28:31]
	s_waitcnt vmcnt(10)
	global_load_dwordx4 v[80:83], v134, s[38:39]
	s_add_u32 s38, s38, 0x400
	s_addc_u32 s39, s39, 0
	v_mfma_f32_16x16x32_bf16 v[32:35], v[64:67], v[0:3], 0
	v_mfma_f32_16x16x32_bf16 v[36:39], v[72:75], v[0:3], 0
	v_mfma_f32_16x16x32_bf16 v[40:43], v[64:67], v[4:7], 0
	v_mfma_f32_16x16x32_bf16 v[44:47], v[72:75], v[4:7], 0
	v_mfma_f32_16x16x32_bf16 v[48:51], v[64:67], v[8:11], 0
	v_mfma_f32_16x16x32_bf16 v[52:55], v[72:75], v[8:11], 0
	v_mfma_f32_16x16x32_bf16 v[56:59], v[64:67], v[12:15], 0
	v_mfma_f32_16x16x32_bf16 v[60:63], v[72:75], v[12:15], 0
	global_load_dwordx4 v[64:67], v134, s[20:21]
	global_load_dwordx4 v[72:75], v134, s[20:21] offset:1024
	global_load_dwordx4 v[100:103], v134, s[42:43] offset:0
	global_load_dwordx4 v[104:107], v134, s[42:43] offset:1024
	global_load_dwordx4 v[108:111], v134, s[42:43] offset:2048
	global_load_dwordx4 v[112:115], v134, s[42:43] offset:3072
	global_load_dwordx4 v[116:119], v208, s[42:43] offset:0
	global_load_dwordx4 v[120:123], v208, s[42:43] offset:1024
	global_load_dwordx4 v[124:127], v208, s[42:43] offset:2048
	global_load_dwordx4 v[128:131], v208, s[42:43] offset:3072
	global_load_dwordx4 v[178:181], v206, s[44:45]
	global_load_dwordx4 v[182:185], v206, s[44:45] offset:16
	s_waitcnt vmcnt(13)
	v_mul_f32_e32 v132, v171, v166
	v_mul_f32_e32 v133, v170, v166
	v_fma_f32 v68, v170, v162, -v132
	v_fma_f32 v76, v171, v162, v133
	v_mul_f32_e32 v132, v173, v167
	v_mul_f32_e32 v133, v172, v167
	v_fma_f32 v69, v172, v163, -v132
	v_fma_f32 v77, v173, v163, v133
	v_mul_f32_e32 v132, v175, v168
	v_mul_f32_e32 v133, v174, v168
	v_fma_f32 v70, v174, v164, -v132
	v_fma_f32 v78, v175, v164, v133
	v_mul_f32_e32 v132, v177, v169
	v_mul_f32_e32 v133, v176, v169
	v_fma_f32 v71, v176, v165, -v132
	v_fma_f32 v79, v177, v165, v133
	v_pk_mul_f32 v[132:133], v[32:33], v[142:143]
	v_pk_mul_f32 v[32:33], v[32:33], v[138:139]
	v_pk_fma_f32 v[32:33], v[36:37], v[142:143], v[32:33] neg_lo:[1,0,0] neg_hi:[1,0,0]
	v_pk_fma_f32 v[36:37], v[36:37], v[138:139], v[132:133]
	v_pk_mul_f32 v[132:133], v[34:35], v[144:145]
	v_pk_mul_f32 v[34:35], v[34:35], v[140:141]
	v_pk_fma_f32 v[34:35], v[38:39], v[144:145], v[34:35] neg_lo:[1,0,0] neg_hi:[1,0,0]
	v_pk_fma_f32 v[38:39], v[38:39], v[140:141], v[132:133]
	v_add_f32_dpp v32, v32, v32 row_shr:1 row_mask:0xf bank_mask:0xf bound_ctrl:1
	v_add_f32_dpp v33, v33, v33 row_shr:1 row_mask:0xf bank_mask:0xf bound_ctrl:1
	v_add_f32_dpp v34, v34, v34 row_shr:1 row_mask:0xf bank_mask:0xf bound_ctrl:1
	v_add_f32_dpp v35, v35, v35 row_shr:1 row_mask:0xf bank_mask:0xf bound_ctrl:1
	v_add_f32_dpp v36, v36, v36 row_shr:1 row_mask:0xf bank_mask:0xf bound_ctrl:1
	v_add_f32_dpp v37, v37, v37 row_shr:1 row_mask:0xf bank_mask:0xf bound_ctrl:1
	v_add_f32_dpp v38, v38, v38 row_shr:1 row_mask:0xf bank_mask:0xf bound_ctrl:1
	v_add_f32_dpp v39, v39, v39 row_shr:1 row_mask:0xf bank_mask:0xf bound_ctrl:1
	v_add_f32_dpp v32, v32, v32 row_shr:2 row_mask:0xf bank_mask:0xf bound_ctrl:1
	v_add_f32_dpp v33, v33, v33 row_shr:2 row_mask:0xf bank_mask:0xf bound_ctrl:1
	v_add_f32_dpp v34, v34, v34 row_shr:2 row_mask:0xf bank_mask:0xf bound_ctrl:1
	v_add_f32_dpp v35, v35, v35 row_shr:2 row_mask:0xf bank_mask:0xf bound_ctrl:1
	v_add_f32_dpp v36, v36, v36 row_shr:2 row_mask:0xf bank_mask:0xf bound_ctrl:1
	v_add_f32_dpp v37, v37, v37 row_shr:2 row_mask:0xf bank_mask:0xf bound_ctrl:1
	v_add_f32_dpp v38, v38, v38 row_shr:2 row_mask:0xf bank_mask:0xf bound_ctrl:1
	v_add_f32_dpp v39, v39, v39 row_shr:2 row_mask:0xf bank_mask:0xf bound_ctrl:1
	v_add_f32_dpp v32, v32, v32 row_shr:4 row_mask:0xf bank_mask:0xf bound_ctrl:1
	v_add_f32_dpp v33, v33, v33 row_shr:4 row_mask:0xf bank_mask:0xf bound_ctrl:1
	v_add_f32_dpp v34, v34, v34 row_shr:4 row_mask:0xf bank_mask:0xf bound_ctrl:1
	v_add_f32_dpp v35, v35, v35 row_shr:4 row_mask:0xf bank_mask:0xf bound_ctrl:1
	v_add_f32_dpp v36, v36, v36 row_shr:4 row_mask:0xf bank_mask:0xf bound_ctrl:1
	v_add_f32_dpp v37, v37, v37 row_shr:4 row_mask:0xf bank_mask:0xf bound_ctrl:1
	v_add_f32_dpp v38, v38, v38 row_shr:4 row_mask:0xf bank_mask:0xf bound_ctrl:1
	v_add_f32_dpp v39, v39, v39 row_shr:4 row_mask:0xf bank_mask:0xf bound_ctrl:1
	v_add_f32_dpp v32, v32, v32 row_shr:8 row_mask:0xf bank_mask:0xf bound_ctrl:1
	v_add_f32_dpp v33, v33, v33 row_shr:8 row_mask:0xf bank_mask:0xf bound_ctrl:1
	v_add_f32_dpp v34, v34, v34 row_shr:8 row_mask:0xf bank_mask:0xf bound_ctrl:1
	v_add_f32_dpp v35, v35, v35 row_shr:8 row_mask:0xf bank_mask:0xf bound_ctrl:1
	v_add_f32_dpp v36, v36, v36 row_shr:8 row_mask:0xf bank_mask:0xf bound_ctrl:1
	v_add_f32_dpp v37, v37, v37 row_shr:8 row_mask:0xf bank_mask:0xf bound_ctrl:1
	v_add_f32_dpp v38, v38, v38 row_shr:8 row_mask:0xf bank_mask:0xf bound_ctrl:1
	v_add_f32_dpp v39, v39, v39 row_shr:8 row_mask:0xf bank_mask:0xf bound_ctrl:1
	v_mov_b32_dpp v88, v32 row_newbcast:15 row_mask:0xf bank_mask:0xf
	v_mov_b32_dpp v89, v33 row_newbcast:15 row_mask:0xf bank_mask:0xf
	v_mov_b32_dpp v90, v34 row_newbcast:15 row_mask:0xf bank_mask:0xf
	v_mov_b32_dpp v91, v35 row_newbcast:15 row_mask:0xf bank_mask:0xf
	v_mov_b32_dpp v92, v36 row_newbcast:15 row_mask:0xf bank_mask:0xf
	v_mov_b32_dpp v93, v37 row_newbcast:15 row_mask:0xf bank_mask:0xf
	v_mov_b32_dpp v94, v38 row_newbcast:15 row_mask:0xf bank_mask:0xf
	v_mov_b32_dpp v95, v39 row_newbcast:15 row_mask:0xf bank_mask:0xf
	v_pk_add_f32 v[32:33], v[32:33], v[68:69]
	v_pk_add_f32 v[36:37], v[36:37], v[76:77]
	v_pk_add_f32 v[34:35], v[34:35], v[70:71]
	v_pk_add_f32 v[38:39], v[38:39], v[78:79]
	v_pk_mul_f32 v[132:133], v[32:33], v[150:151]
	v_pk_mul_f32 v[32:33], v[32:33], v[146:147]
	v_pk_fma_f32 v[32:33], v[36:37], v[150:151], v[32:33] neg_lo:[1,0,0] neg_hi:[1,0,0]
	v_pk_fma_f32 v[36:37], v[36:37], v[146:147], v[132:133]
	v_pk_mul_f32 v[132:133], v[34:35], v[152:153]
	v_pk_mul_f32 v[34:35], v[34:35], v[148:149]
	v_pk_fma_f32 v[34:35], v[38:39], v[152:153], v[34:35] neg_lo:[1,0,0] neg_hi:[1,0,0]
	v_pk_fma_f32 v[38:39], v[38:39], v[148:149], v[132:133]
	v_pk_add_f32 v[88:89], v[88:89], v[68:69]
	v_pk_add_f32 v[92:93], v[92:93], v[76:77]
	v_pk_mul_f32 v[132:133], v[92:93], v[158:159]
	v_pk_mul_f32 v[76:77], v[88:89], v[158:159]
	v_pk_fma_f32 v[68:69], v[88:89], v[154:155], v[132:133] neg_lo:[0,0,1] neg_hi:[0,0,1]
	v_pk_fma_f32 v[76:77], v[92:93], v[154:155], v[76:77]
	v_pk_add_f32 v[90:91], v[90:91], v[70:71]
	v_pk_add_f32 v[94:95], v[94:95], v[78:79]
	v_pk_mul_f32 v[132:133], v[94:95], v[160:161]
	v_pk_mul_f32 v[78:79], v[90:91], v[160:161]
	v_pk_fma_f32 v[70:71], v[90:91], v[156:157], v[132:133] neg_lo:[0,0,1] neg_hi:[0,0,1]
	v_pk_fma_f32 v[78:79], v[94:95], v[156:157], v[78:79]
	v_pk_mul_f32 v[132:133], v[40:41], v[142:143]
	v_pk_mul_f32 v[40:41], v[40:41], v[138:139]
	v_pk_fma_f32 v[40:41], v[44:45], v[142:143], v[40:41] neg_lo:[1,0,0] neg_hi:[1,0,0]
	v_pk_fma_f32 v[44:45], v[44:45], v[138:139], v[132:133]
	v_pk_mul_f32 v[132:133], v[42:43], v[144:145]
	v_pk_mul_f32 v[42:43], v[42:43], v[140:141]
	v_pk_fma_f32 v[42:43], v[46:47], v[144:145], v[42:43] neg_lo:[1,0,0] neg_hi:[1,0,0]
	v_pk_fma_f32 v[46:47], v[46:47], v[140:141], v[132:133]
	v_add_f32_dpp v40, v40, v40 row_shr:1 row_mask:0xf bank_mask:0xf bound_ctrl:1
	v_add_f32_dpp v41, v41, v41 row_shr:1 row_mask:0xf bank_mask:0xf bound_ctrl:1
	v_add_f32_dpp v42, v42, v42 row_shr:1 row_mask:0xf bank_mask:0xf bound_ctrl:1
	v_add_f32_dpp v43, v43, v43 row_shr:1 row_mask:0xf bank_mask:0xf bound_ctrl:1
	v_add_f32_dpp v44, v44, v44 row_shr:1 row_mask:0xf bank_mask:0xf bound_ctrl:1
	v_add_f32_dpp v45, v45, v45 row_shr:1 row_mask:0xf bank_mask:0xf bound_ctrl:1
	v_add_f32_dpp v46, v46, v46 row_shr:1 row_mask:0xf bank_mask:0xf bound_ctrl:1
	v_add_f32_dpp v47, v47, v47 row_shr:1 row_mask:0xf bank_mask:0xf bound_ctrl:1
	v_add_f32_dpp v40, v40, v40 row_shr:2 row_mask:0xf bank_mask:0xf bound_ctrl:1
	v_add_f32_dpp v41, v41, v41 row_shr:2 row_mask:0xf bank_mask:0xf bound_ctrl:1
	v_add_f32_dpp v42, v42, v42 row_shr:2 row_mask:0xf bank_mask:0xf bound_ctrl:1
	v_add_f32_dpp v43, v43, v43 row_shr:2 row_mask:0xf bank_mask:0xf bound_ctrl:1
	v_add_f32_dpp v44, v44, v44 row_shr:2 row_mask:0xf bank_mask:0xf bound_ctrl:1
	v_add_f32_dpp v45, v45, v45 row_shr:2 row_mask:0xf bank_mask:0xf bound_ctrl:1
	v_add_f32_dpp v46, v46, v46 row_shr:2 row_mask:0xf bank_mask:0xf bound_ctrl:1
	v_add_f32_dpp v47, v47, v47 row_shr:2 row_mask:0xf bank_mask:0xf bound_ctrl:1
	v_add_f32_dpp v40, v40, v40 row_shr:4 row_mask:0xf bank_mask:0xf bound_ctrl:1
	v_add_f32_dpp v41, v41, v41 row_shr:4 row_mask:0xf bank_mask:0xf bound_ctrl:1
	v_add_f32_dpp v42, v42, v42 row_shr:4 row_mask:0xf bank_mask:0xf bound_ctrl:1
	v_add_f32_dpp v43, v43, v43 row_shr:4 row_mask:0xf bank_mask:0xf bound_ctrl:1
	v_add_f32_dpp v44, v44, v44 row_shr:4 row_mask:0xf bank_mask:0xf bound_ctrl:1
	v_add_f32_dpp v45, v45, v45 row_shr:4 row_mask:0xf bank_mask:0xf bound_ctrl:1
	v_add_f32_dpp v46, v46, v46 row_shr:4 row_mask:0xf bank_mask:0xf bound_ctrl:1
	v_add_f32_dpp v47, v47, v47 row_shr:4 row_mask:0xf bank_mask:0xf bound_ctrl:1
	v_add_f32_dpp v40, v40, v40 row_shr:8 row_mask:0xf bank_mask:0xf bound_ctrl:1
	v_add_f32_dpp v41, v41, v41 row_shr:8 row_mask:0xf bank_mask:0xf bound_ctrl:1
	v_add_f32_dpp v42, v42, v42 row_shr:8 row_mask:0xf bank_mask:0xf bound_ctrl:1
	v_add_f32_dpp v43, v43, v43 row_shr:8 row_mask:0xf bank_mask:0xf bound_ctrl:1
	v_add_f32_dpp v44, v44, v44 row_shr:8 row_mask:0xf bank_mask:0xf bound_ctrl:1
	v_add_f32_dpp v45, v45, v45 row_shr:8 row_mask:0xf bank_mask:0xf bound_ctrl:1
	v_add_f32_dpp v46, v46, v46 row_shr:8 row_mask:0xf bank_mask:0xf bound_ctrl:1
	v_add_f32_dpp v47, v47, v47 row_shr:8 row_mask:0xf bank_mask:0xf bound_ctrl:1
	v_mov_b32_dpp v88, v40 row_newbcast:15 row_mask:0xf bank_mask:0xf
	v_mov_b32_dpp v89, v41 row_newbcast:15 row_mask:0xf bank_mask:0xf
	v_mov_b32_dpp v90, v42 row_newbcast:15 row_mask:0xf bank_mask:0xf
	v_mov_b32_dpp v91, v43 row_newbcast:15 row_mask:0xf bank_mask:0xf
	v_mov_b32_dpp v92, v44 row_newbcast:15 row_mask:0xf bank_mask:0xf
	v_mov_b32_dpp v93, v45 row_newbcast:15 row_mask:0xf bank_mask:0xf
	v_mov_b32_dpp v94, v46 row_newbcast:15 row_mask:0xf bank_mask:0xf
	v_mov_b32_dpp v95, v47 row_newbcast:15 row_mask:0xf bank_mask:0xf
	v_pk_add_f32 v[40:41], v[40:41], v[68:69]
	v_pk_add_f32 v[44:45], v[44:45], v[76:77]
	v_pk_add_f32 v[42:43], v[42:43], v[70:71]
	v_pk_add_f32 v[46:47], v[46:47], v[78:79]
	v_pk_mul_f32 v[132:133], v[40:41], v[150:151]
	v_pk_mul_f32 v[40:41], v[40:41], v[146:147]
	v_pk_fma_f32 v[40:41], v[44:45], v[150:151], v[40:41] neg_lo:[1,0,0] neg_hi:[1,0,0]
	v_pk_fma_f32 v[44:45], v[44:45], v[146:147], v[132:133]
	v_pk_mul_f32 v[132:133], v[42:43], v[152:153]
	v_pk_mul_f32 v[42:43], v[42:43], v[148:149]
	v_pk_fma_f32 v[42:43], v[46:47], v[152:153], v[42:43] neg_lo:[1,0,0] neg_hi:[1,0,0]
	v_pk_fma_f32 v[46:47], v[46:47], v[148:149], v[132:133]
	v_pk_add_f32 v[88:89], v[88:89], v[68:69]
	v_pk_add_f32 v[92:93], v[92:93], v[76:77]
	v_pk_mul_f32 v[132:133], v[92:93], v[158:159]
	v_pk_mul_f32 v[76:77], v[88:89], v[158:159]
	v_pk_fma_f32 v[68:69], v[88:89], v[154:155], v[132:133] neg_lo:[0,0,1] neg_hi:[0,0,1]
	v_pk_fma_f32 v[76:77], v[92:93], v[154:155], v[76:77]
	v_pk_add_f32 v[90:91], v[90:91], v[70:71]
	v_pk_add_f32 v[94:95], v[94:95], v[78:79]
	v_pk_mul_f32 v[132:133], v[94:95], v[160:161]
	v_pk_mul_f32 v[78:79], v[90:91], v[160:161]
	v_pk_fma_f32 v[70:71], v[90:91], v[156:157], v[132:133] neg_lo:[0,0,1] neg_hi:[0,0,1]
	v_pk_fma_f32 v[78:79], v[94:95], v[156:157], v[78:79]
	v_pk_mul_f32 v[132:133], v[48:49], v[142:143]
	v_pk_mul_f32 v[48:49], v[48:49], v[138:139]
	v_pk_fma_f32 v[48:49], v[52:53], v[142:143], v[48:49] neg_lo:[1,0,0] neg_hi:[1,0,0]
	v_pk_fma_f32 v[52:53], v[52:53], v[138:139], v[132:133]
	v_pk_mul_f32 v[132:133], v[50:51], v[144:145]
	v_pk_mul_f32 v[50:51], v[50:51], v[140:141]
	v_pk_fma_f32 v[50:51], v[54:55], v[144:145], v[50:51] neg_lo:[1,0,0] neg_hi:[1,0,0]
	v_pk_fma_f32 v[54:55], v[54:55], v[140:141], v[132:133]
	v_add_f32_dpp v48, v48, v48 row_shr:1 row_mask:0xf bank_mask:0xf bound_ctrl:1
	v_add_f32_dpp v49, v49, v49 row_shr:1 row_mask:0xf bank_mask:0xf bound_ctrl:1
	v_add_f32_dpp v50, v50, v50 row_shr:1 row_mask:0xf bank_mask:0xf bound_ctrl:1
	v_add_f32_dpp v51, v51, v51 row_shr:1 row_mask:0xf bank_mask:0xf bound_ctrl:1
	v_add_f32_dpp v52, v52, v52 row_shr:1 row_mask:0xf bank_mask:0xf bound_ctrl:1
	v_add_f32_dpp v53, v53, v53 row_shr:1 row_mask:0xf bank_mask:0xf bound_ctrl:1
	v_add_f32_dpp v54, v54, v54 row_shr:1 row_mask:0xf bank_mask:0xf bound_ctrl:1
	v_add_f32_dpp v55, v55, v55 row_shr:1 row_mask:0xf bank_mask:0xf bound_ctrl:1
	v_add_f32_dpp v48, v48, v48 row_shr:2 row_mask:0xf bank_mask:0xf bound_ctrl:1
	v_add_f32_dpp v49, v49, v49 row_shr:2 row_mask:0xf bank_mask:0xf bound_ctrl:1
	v_add_f32_dpp v50, v50, v50 row_shr:2 row_mask:0xf bank_mask:0xf bound_ctrl:1
	v_add_f32_dpp v51, v51, v51 row_shr:2 row_mask:0xf bank_mask:0xf bound_ctrl:1
	v_add_f32_dpp v52, v52, v52 row_shr:2 row_mask:0xf bank_mask:0xf bound_ctrl:1
	v_add_f32_dpp v53, v53, v53 row_shr:2 row_mask:0xf bank_mask:0xf bound_ctrl:1
	v_add_f32_dpp v54, v54, v54 row_shr:2 row_mask:0xf bank_mask:0xf bound_ctrl:1
	v_add_f32_dpp v55, v55, v55 row_shr:2 row_mask:0xf bank_mask:0xf bound_ctrl:1
	v_add_f32_dpp v48, v48, v48 row_shr:4 row_mask:0xf bank_mask:0xf bound_ctrl:1
	v_add_f32_dpp v49, v49, v49 row_shr:4 row_mask:0xf bank_mask:0xf bound_ctrl:1
	v_add_f32_dpp v50, v50, v50 row_shr:4 row_mask:0xf bank_mask:0xf bound_ctrl:1
	v_add_f32_dpp v51, v51, v51 row_shr:4 row_mask:0xf bank_mask:0xf bound_ctrl:1
	v_add_f32_dpp v52, v52, v52 row_shr:4 row_mask:0xf bank_mask:0xf bound_ctrl:1
	v_add_f32_dpp v53, v53, v53 row_shr:4 row_mask:0xf bank_mask:0xf bound_ctrl:1
	v_add_f32_dpp v54, v54, v54 row_shr:4 row_mask:0xf bank_mask:0xf bound_ctrl:1
	v_add_f32_dpp v55, v55, v55 row_shr:4 row_mask:0xf bank_mask:0xf bound_ctrl:1
	v_add_f32_dpp v48, v48, v48 row_shr:8 row_mask:0xf bank_mask:0xf bound_ctrl:1
	v_add_f32_dpp v49, v49, v49 row_shr:8 row_mask:0xf bank_mask:0xf bound_ctrl:1
	v_add_f32_dpp v50, v50, v50 row_shr:8 row_mask:0xf bank_mask:0xf bound_ctrl:1
	v_add_f32_dpp v51, v51, v51 row_shr:8 row_mask:0xf bank_mask:0xf bound_ctrl:1
	v_add_f32_dpp v52, v52, v52 row_shr:8 row_mask:0xf bank_mask:0xf bound_ctrl:1
	v_add_f32_dpp v53, v53, v53 row_shr:8 row_mask:0xf bank_mask:0xf bound_ctrl:1
	v_add_f32_dpp v54, v54, v54 row_shr:8 row_mask:0xf bank_mask:0xf bound_ctrl:1
	v_add_f32_dpp v55, v55, v55 row_shr:8 row_mask:0xf bank_mask:0xf bound_ctrl:1
	v_mov_b32_dpp v88, v48 row_newbcast:15 row_mask:0xf bank_mask:0xf
	v_mov_b32_dpp v89, v49 row_newbcast:15 row_mask:0xf bank_mask:0xf
	v_mov_b32_dpp v90, v50 row_newbcast:15 row_mask:0xf bank_mask:0xf
	v_mov_b32_dpp v91, v51 row_newbcast:15 row_mask:0xf bank_mask:0xf
	v_mov_b32_dpp v92, v52 row_newbcast:15 row_mask:0xf bank_mask:0xf
	v_mov_b32_dpp v93, v53 row_newbcast:15 row_mask:0xf bank_mask:0xf
	v_mov_b32_dpp v94, v54 row_newbcast:15 row_mask:0xf bank_mask:0xf
	v_mov_b32_dpp v95, v55 row_newbcast:15 row_mask:0xf bank_mask:0xf
	v_pk_add_f32 v[48:49], v[48:49], v[68:69]
	v_pk_add_f32 v[52:53], v[52:53], v[76:77]
	v_pk_add_f32 v[50:51], v[50:51], v[70:71]
	v_pk_add_f32 v[54:55], v[54:55], v[78:79]
	v_pk_mul_f32 v[132:133], v[48:49], v[150:151]
	v_pk_mul_f32 v[48:49], v[48:49], v[146:147]
	v_pk_fma_f32 v[48:49], v[52:53], v[150:151], v[48:49] neg_lo:[1,0,0] neg_hi:[1,0,0]
	v_pk_fma_f32 v[52:53], v[52:53], v[146:147], v[132:133]
	v_pk_mul_f32 v[132:133], v[50:51], v[152:153]
	v_pk_mul_f32 v[50:51], v[50:51], v[148:149]
	v_pk_fma_f32 v[50:51], v[54:55], v[152:153], v[50:51] neg_lo:[1,0,0] neg_hi:[1,0,0]
	v_pk_fma_f32 v[54:55], v[54:55], v[148:149], v[132:133]
	v_pk_add_f32 v[88:89], v[88:89], v[68:69]
	v_pk_add_f32 v[92:93], v[92:93], v[76:77]
	v_pk_mul_f32 v[132:133], v[92:93], v[158:159]
	v_pk_mul_f32 v[76:77], v[88:89], v[158:159]
	v_pk_fma_f32 v[68:69], v[88:89], v[154:155], v[132:133] neg_lo:[0,0,1] neg_hi:[0,0,1]
	v_pk_fma_f32 v[76:77], v[92:93], v[154:155], v[76:77]
	v_pk_add_f32 v[90:91], v[90:91], v[70:71]
	v_pk_add_f32 v[94:95], v[94:95], v[78:79]
	v_pk_mul_f32 v[132:133], v[94:95], v[160:161]
	v_pk_mul_f32 v[78:79], v[90:91], v[160:161]
	v_pk_fma_f32 v[70:71], v[90:91], v[156:157], v[132:133] neg_lo:[0,0,1] neg_hi:[0,0,1]
	v_pk_fma_f32 v[78:79], v[94:95], v[156:157], v[78:79]
	v_pk_mul_f32 v[132:133], v[56:57], v[142:143]
	v_pk_mul_f32 v[56:57], v[56:57], v[138:139]
	v_pk_fma_f32 v[56:57], v[60:61], v[142:143], v[56:57] neg_lo:[1,0,0] neg_hi:[1,0,0]
	v_pk_fma_f32 v[60:61], v[60:61], v[138:139], v[132:133]
	v_pk_mul_f32 v[132:133], v[58:59], v[144:145]
	v_pk_mul_f32 v[58:59], v[58:59], v[140:141]
	v_pk_fma_f32 v[58:59], v[62:63], v[144:145], v[58:59] neg_lo:[1,0,0] neg_hi:[1,0,0]
	v_pk_fma_f32 v[62:63], v[62:63], v[140:141], v[132:133]
	v_add_f32_dpp v56, v56, v56 row_shr:1 row_mask:0xf bank_mask:0xf bound_ctrl:1
	v_add_f32_dpp v57, v57, v57 row_shr:1 row_mask:0xf bank_mask:0xf bound_ctrl:1
	v_add_f32_dpp v58, v58, v58 row_shr:1 row_mask:0xf bank_mask:0xf bound_ctrl:1
	v_add_f32_dpp v59, v59, v59 row_shr:1 row_mask:0xf bank_mask:0xf bound_ctrl:1
	v_add_f32_dpp v60, v60, v60 row_shr:1 row_mask:0xf bank_mask:0xf bound_ctrl:1
	v_add_f32_dpp v61, v61, v61 row_shr:1 row_mask:0xf bank_mask:0xf bound_ctrl:1
	v_add_f32_dpp v62, v62, v62 row_shr:1 row_mask:0xf bank_mask:0xf bound_ctrl:1
	v_add_f32_dpp v63, v63, v63 row_shr:1 row_mask:0xf bank_mask:0xf bound_ctrl:1
	v_add_f32_dpp v56, v56, v56 row_shr:2 row_mask:0xf bank_mask:0xf bound_ctrl:1
	v_add_f32_dpp v57, v57, v57 row_shr:2 row_mask:0xf bank_mask:0xf bound_ctrl:1
	v_add_f32_dpp v58, v58, v58 row_shr:2 row_mask:0xf bank_mask:0xf bound_ctrl:1
	v_add_f32_dpp v59, v59, v59 row_shr:2 row_mask:0xf bank_mask:0xf bound_ctrl:1
	v_add_f32_dpp v60, v60, v60 row_shr:2 row_mask:0xf bank_mask:0xf bound_ctrl:1
	v_add_f32_dpp v61, v61, v61 row_shr:2 row_mask:0xf bank_mask:0xf bound_ctrl:1
	v_add_f32_dpp v62, v62, v62 row_shr:2 row_mask:0xf bank_mask:0xf bound_ctrl:1
	v_add_f32_dpp v63, v63, v63 row_shr:2 row_mask:0xf bank_mask:0xf bound_ctrl:1
	v_add_f32_dpp v56, v56, v56 row_shr:4 row_mask:0xf bank_mask:0xf bound_ctrl:1
	v_add_f32_dpp v57, v57, v57 row_shr:4 row_mask:0xf bank_mask:0xf bound_ctrl:1
	v_add_f32_dpp v58, v58, v58 row_shr:4 row_mask:0xf bank_mask:0xf bound_ctrl:1
	v_add_f32_dpp v59, v59, v59 row_shr:4 row_mask:0xf bank_mask:0xf bound_ctrl:1
	v_add_f32_dpp v60, v60, v60 row_shr:4 row_mask:0xf bank_mask:0xf bound_ctrl:1
	v_add_f32_dpp v61, v61, v61 row_shr:4 row_mask:0xf bank_mask:0xf bound_ctrl:1
	v_add_f32_dpp v62, v62, v62 row_shr:4 row_mask:0xf bank_mask:0xf bound_ctrl:1
	v_add_f32_dpp v63, v63, v63 row_shr:4 row_mask:0xf bank_mask:0xf bound_ctrl:1
	v_add_f32_dpp v56, v56, v56 row_shr:8 row_mask:0xf bank_mask:0xf bound_ctrl:1
	v_add_f32_dpp v57, v57, v57 row_shr:8 row_mask:0xf bank_mask:0xf bound_ctrl:1
	v_add_f32_dpp v58, v58, v58 row_shr:8 row_mask:0xf bank_mask:0xf bound_ctrl:1
	v_add_f32_dpp v59, v59, v59 row_shr:8 row_mask:0xf bank_mask:0xf bound_ctrl:1
	v_add_f32_dpp v60, v60, v60 row_shr:8 row_mask:0xf bank_mask:0xf bound_ctrl:1
	v_add_f32_dpp v61, v61, v61 row_shr:8 row_mask:0xf bank_mask:0xf bound_ctrl:1
	v_add_f32_dpp v62, v62, v62 row_shr:8 row_mask:0xf bank_mask:0xf bound_ctrl:1
	v_add_f32_dpp v63, v63, v63 row_shr:8 row_mask:0xf bank_mask:0xf bound_ctrl:1
	v_mov_b32_dpp v88, v56 row_newbcast:15 row_mask:0xf bank_mask:0xf
	v_mov_b32_dpp v89, v57 row_newbcast:15 row_mask:0xf bank_mask:0xf
	v_mov_b32_dpp v90, v58 row_newbcast:15 row_mask:0xf bank_mask:0xf
	v_mov_b32_dpp v91, v59 row_newbcast:15 row_mask:0xf bank_mask:0xf
	v_mov_b32_dpp v92, v60 row_newbcast:15 row_mask:0xf bank_mask:0xf
	v_mov_b32_dpp v93, v61 row_newbcast:15 row_mask:0xf bank_mask:0xf
	v_mov_b32_dpp v94, v62 row_newbcast:15 row_mask:0xf bank_mask:0xf
	v_mov_b32_dpp v95, v63 row_newbcast:15 row_mask:0xf bank_mask:0xf
	v_pk_add_f32 v[56:57], v[56:57], v[68:69]
	v_pk_add_f32 v[60:61], v[60:61], v[76:77]
	v_pk_add_f32 v[58:59], v[58:59], v[70:71]
	v_pk_add_f32 v[62:63], v[62:63], v[78:79]
	v_pk_mul_f32 v[132:133], v[56:57], v[150:151]
	v_pk_mul_f32 v[56:57], v[56:57], v[146:147]
	v_pk_fma_f32 v[56:57], v[60:61], v[150:151], v[56:57] neg_lo:[1,0,0] neg_hi:[1,0,0]
	v_pk_fma_f32 v[60:61], v[60:61], v[146:147], v[132:133]
	v_pk_mul_f32 v[132:133], v[58:59], v[152:153]
	v_pk_mul_f32 v[58:59], v[58:59], v[148:149]
	v_pk_fma_f32 v[58:59], v[62:63], v[152:153], v[58:59] neg_lo:[1,0,0] neg_hi:[1,0,0]
	v_pk_fma_f32 v[62:63], v[62:63], v[148:149], v[132:133]
	v_pk_add_f32 v[88:89], v[88:89], v[68:69]
	v_pk_add_f32 v[92:93], v[92:93], v[76:77]
	v_pk_mul_f32 v[132:133], v[92:93], v[158:159]
	v_pk_mul_f32 v[76:77], v[88:89], v[158:159]
	v_pk_fma_f32 v[68:69], v[88:89], v[154:155], v[132:133] neg_lo:[0,0,1] neg_hi:[0,0,1]
	v_pk_fma_f32 v[76:77], v[92:93], v[154:155], v[76:77]
	v_pk_add_f32 v[90:91], v[90:91], v[70:71]
	v_pk_add_f32 v[94:95], v[94:95], v[78:79]
	v_pk_mul_f32 v[132:133], v[94:95], v[160:161]
	v_pk_mul_f32 v[78:79], v[90:91], v[160:161]
	v_pk_fma_f32 v[70:71], v[90:91], v[156:157], v[132:133] neg_lo:[0,0,1] neg_hi:[0,0,1]
	v_pk_fma_f32 v[78:79], v[94:95], v[156:157], v[78:79]
	s_waitcnt vmcnt(12)
	v_cvt_pk_bf16_f32 v96, v32, v33
	v_cvt_pk_bf16_f32 v97, v34, v35
	v_cvt_pk_bf16_f32 v98, v36, v37
	v_cvt_pk_bf16_f32 v99, v38, v39
	s_nop 1
	v_mfma_f32_16x16x32_bf16 v[16:19], v[80:83], v[96:99], v[16:19]
	v_cvt_pk_bf16_f32 v96, v40, v41
	v_cvt_pk_bf16_f32 v97, v42, v43
	v_cvt_pk_bf16_f32 v98, v44, v45
	v_cvt_pk_bf16_f32 v99, v46, v47
	s_nop 1
	v_mfma_f32_16x16x32_bf16 v[20:23], v[80:83], v[96:99], v[20:23]
	v_cvt_pk_bf16_f32 v96, v48, v49
	v_cvt_pk_bf16_f32 v97, v50, v51
	v_cvt_pk_bf16_f32 v98, v52, v53
	v_cvt_pk_bf16_f32 v99, v54, v55
	s_nop 1
	v_mfma_f32_16x16x32_bf16 v[24:27], v[80:83], v[96:99], v[24:27]
	v_cvt_pk_bf16_f32 v96, v56, v57
	v_cvt_pk_bf16_f32 v97, v58, v59
	v_cvt_pk_bf16_f32 v98, v60, v61
	v_cvt_pk_bf16_f32 v99, v62, v63
	s_nop 1
	v_mfma_f32_16x16x32_bf16 v[28:31], v[80:83], v[96:99], v[28:31]
	s_waitcnt vmcnt(10)
	global_load_dwordx4 v[80:83], v134, s[38:39]
	v_mfma_f32_16x16x32_bf16 v[32:35], v[64:67], v[0:3], 0
	v_mfma_f32_16x16x32_bf16 v[36:39], v[72:75], v[0:3], 0
	v_mfma_f32_16x16x32_bf16 v[40:43], v[64:67], v[4:7], 0
	v_mfma_f32_16x16x32_bf16 v[44:47], v[72:75], v[4:7], 0
	v_mfma_f32_16x16x32_bf16 v[48:51], v[64:67], v[8:11], 0
	v_mfma_f32_16x16x32_bf16 v[52:55], v[72:75], v[8:11], 0
	v_mfma_f32_16x16x32_bf16 v[56:59], v[64:67], v[12:15], 0
	v_mfma_f32_16x16x32_bf16 v[60:63], v[72:75], v[12:15], 0
	v_readlane_b32 s10, v247, 28
	s_sub_i32 s11, 3, s8
	s_sub_i32 s17, 71, s8
	s_cmp_lt_u32 s8, 4
	s_cselect_b32 s11, s11, s17
	s_lshl_b32 s16, s10, 1
	s_add_i32 s16, s16, 1
	s_lshl_b32 s16, s16, 4
	s_add_i32 s16, s16, s7
	s_lshl_b32 s17, s6, 1
	s_add_i32 s17, s17, 1
	s_lshl_b32 s17, s17, 4
	s_add_i32 s17, s17, s7
	s_mul_i32 s17, s17, 68
	s_add_i32 s17, s17, s11
	s_lshl_b32 s17, s17, 6
	s_lshl_b32 s20, s16, 13
	s_add_u32 s20, s20, 0xfd00000
	s_add_u32 s20, s4, s20
	s_addc_u32 s21, s5, 0
	s_lshl_b32 s38, s16, 12
	s_add_u32 s38, s38, 0xfd80000
	s_add_u32 s38, s4, s38
	s_addc_u32 s39, s5, 0
	s_lshl_b32 s42, s16, 15
	s_add_u32 s42, s42, 0xf900000
	s_add_u32 s42, s4, s42
	s_addc_u32 s43, s5, 0
	s_lshl_b32 s44, s17, 3
	s_add_u32 s44, s44, 0x740000
	s_add_u32 s44, s4, s44
	s_addc_u32 s45, s5, 0
	global_load_dwordx4 v[64:67], v134, s[20:21]
	global_load_dwordx4 v[72:75], v134, s[20:21] offset:1024
	s_add_u32 s20, s20, 0x800
	s_addc_u32 s21, s21, 0
	global_load_dwordx4 v[138:141], v134, s[42:43] offset:0
	global_load_dwordx4 v[142:145], v134, s[42:43] offset:1024
	global_load_dwordx4 v[146:149], v134, s[42:43] offset:2048
	global_load_dwordx4 v[150:153], v134, s[42:43] offset:3072
	global_load_dwordx4 v[154:157], v208, s[42:43] offset:0
	global_load_dwordx4 v[158:161], v208, s[42:43] offset:1024
	global_load_dwordx4 v[162:165], v208, s[42:43] offset:2048
	global_load_dwordx4 v[166:169], v208, s[42:43] offset:3072
	global_load_dwordx4 v[170:173], v206, s[44:45]
	global_load_dwordx4 v[174:177], v206, s[44:45] offset:16
	s_add_u32 s42, s42, 0x2000
	s_addc_u32 s43, s43, 0
	s_add_u32 s44, s44, 0x80
	s_addc_u32 s45, s45, 0
	s_waitcnt vmcnt(13)
	v_mul_f32_e32 v132, v179, v128
	v_mul_f32_e32 v133, v178, v128
	v_fma_f32 v68, v178, v124, -v132
	v_fma_f32 v76, v179, v124, v133
	v_mul_f32_e32 v132, v181, v129
	v_mul_f32_e32 v133, v180, v129
	v_fma_f32 v69, v180, v125, -v132
	v_fma_f32 v77, v181, v125, v133
	v_mul_f32_e32 v132, v183, v130
	v_mul_f32_e32 v133, v182, v130
	v_fma_f32 v70, v182, v126, -v132
	v_fma_f32 v78, v183, v126, v133
	v_mul_f32_e32 v132, v185, v131
	v_mul_f32_e32 v133, v184, v131
	v_fma_f32 v71, v184, v127, -v132
	v_fma_f32 v79, v185, v127, v133
	v_pk_mul_f32 v[132:133], v[32:33], v[104:105]
	v_pk_mul_f32 v[32:33], v[32:33], v[100:101]
	v_pk_fma_f32 v[32:33], v[36:37], v[104:105], v[32:33] neg_lo:[1,0,0] neg_hi:[1,0,0]
	v_pk_fma_f32 v[36:37], v[36:37], v[100:101], v[132:133]
	v_pk_mul_f32 v[132:133], v[34:35], v[106:107]
	v_pk_mul_f32 v[34:35], v[34:35], v[102:103]
	v_pk_fma_f32 v[34:35], v[38:39], v[106:107], v[34:35] neg_lo:[1,0,0] neg_hi:[1,0,0]
	v_pk_fma_f32 v[38:39], v[38:39], v[102:103], v[132:133]
	v_add_f32_dpp v32, v32, v32 row_shr:1 row_mask:0xf bank_mask:0xf bound_ctrl:1
	v_add_f32_dpp v33, v33, v33 row_shr:1 row_mask:0xf bank_mask:0xf bound_ctrl:1
	v_add_f32_dpp v34, v34, v34 row_shr:1 row_mask:0xf bank_mask:0xf bound_ctrl:1
	v_add_f32_dpp v35, v35, v35 row_shr:1 row_mask:0xf bank_mask:0xf bound_ctrl:1
	v_add_f32_dpp v36, v36, v36 row_shr:1 row_mask:0xf bank_mask:0xf bound_ctrl:1
	v_add_f32_dpp v37, v37, v37 row_shr:1 row_mask:0xf bank_mask:0xf bound_ctrl:1
	v_add_f32_dpp v38, v38, v38 row_shr:1 row_mask:0xf bank_mask:0xf bound_ctrl:1
	v_add_f32_dpp v39, v39, v39 row_shr:1 row_mask:0xf bank_mask:0xf bound_ctrl:1
	v_add_f32_dpp v32, v32, v32 row_shr:2 row_mask:0xf bank_mask:0xf bound_ctrl:1
	v_add_f32_dpp v33, v33, v33 row_shr:2 row_mask:0xf bank_mask:0xf bound_ctrl:1
	v_add_f32_dpp v34, v34, v34 row_shr:2 row_mask:0xf bank_mask:0xf bound_ctrl:1
	v_add_f32_dpp v35, v35, v35 row_shr:2 row_mask:0xf bank_mask:0xf bound_ctrl:1
	v_add_f32_dpp v36, v36, v36 row_shr:2 row_mask:0xf bank_mask:0xf bound_ctrl:1
	v_add_f32_dpp v37, v37, v37 row_shr:2 row_mask:0xf bank_mask:0xf bound_ctrl:1
	v_add_f32_dpp v38, v38, v38 row_shr:2 row_mask:0xf bank_mask:0xf bound_ctrl:1
	v_add_f32_dpp v39, v39, v39 row_shr:2 row_mask:0xf bank_mask:0xf bound_ctrl:1
	v_add_f32_dpp v32, v32, v32 row_shr:4 row_mask:0xf bank_mask:0xf bound_ctrl:1
	v_add_f32_dpp v33, v33, v33 row_shr:4 row_mask:0xf bank_mask:0xf bound_ctrl:1
	v_add_f32_dpp v34, v34, v34 row_shr:4 row_mask:0xf bank_mask:0xf bound_ctrl:1
	v_add_f32_dpp v35, v35, v35 row_shr:4 row_mask:0xf bank_mask:0xf bound_ctrl:1
	v_add_f32_dpp v36, v36, v36 row_shr:4 row_mask:0xf bank_mask:0xf bound_ctrl:1
	v_add_f32_dpp v37, v37, v37 row_shr:4 row_mask:0xf bank_mask:0xf bound_ctrl:1
	v_add_f32_dpp v38, v38, v38 row_shr:4 row_mask:0xf bank_mask:0xf bound_ctrl:1
	v_add_f32_dpp v39, v39, v39 row_shr:4 row_mask:0xf bank_mask:0xf bound_ctrl:1
	v_add_f32_dpp v32, v32, v32 row_shr:8 row_mask:0xf bank_mask:0xf bound_ctrl:1
	v_add_f32_dpp v33, v33, v33 row_shr:8 row_mask:0xf bank_mask:0xf bound_ctrl:1
	v_add_f32_dpp v34, v34, v34 row_shr:8 row_mask:0xf bank_mask:0xf bound_ctrl:1
	v_add_f32_dpp v35, v35, v35 row_shr:8 row_mask:0xf bank_mask:0xf bound_ctrl:1
	v_add_f32_dpp v36, v36, v36 row_shr:8 row_mask:0xf bank_mask:0xf bound_ctrl:1
	v_add_f32_dpp v37, v37, v37 row_shr:8 row_mask:0xf bank_mask:0xf bound_ctrl:1
	v_add_f32_dpp v38, v38, v38 row_shr:8 row_mask:0xf bank_mask:0xf bound_ctrl:1
	v_add_f32_dpp v39, v39, v39 row_shr:8 row_mask:0xf bank_mask:0xf bound_ctrl:1
	v_mov_b32_dpp v88, v32 row_newbcast:15 row_mask:0xf bank_mask:0xf
	v_mov_b32_dpp v89, v33 row_newbcast:15 row_mask:0xf bank_mask:0xf
	v_mov_b32_dpp v90, v34 row_newbcast:15 row_mask:0xf bank_mask:0xf
	v_mov_b32_dpp v91, v35 row_newbcast:15 row_mask:0xf bank_mask:0xf
	v_mov_b32_dpp v92, v36 row_newbcast:15 row_mask:0xf bank_mask:0xf
	v_mov_b32_dpp v93, v37 row_newbcast:15 row_mask:0xf bank_mask:0xf
	v_mov_b32_dpp v94, v38 row_newbcast:15 row_mask:0xf bank_mask:0xf
	v_mov_b32_dpp v95, v39 row_newbcast:15 row_mask:0xf bank_mask:0xf
	v_pk_add_f32 v[32:33], v[32:33], v[68:69]
	v_pk_add_f32 v[36:37], v[36:37], v[76:77]
	v_pk_add_f32 v[34:35], v[34:35], v[70:71]
	v_pk_add_f32 v[38:39], v[38:39], v[78:79]
	v_pk_mul_f32 v[132:133], v[32:33], v[112:113]
	v_pk_mul_f32 v[32:33], v[32:33], v[108:109]
	v_pk_fma_f32 v[32:33], v[36:37], v[112:113], v[32:33] neg_lo:[1,0,0] neg_hi:[1,0,0]
	v_pk_fma_f32 v[36:37], v[36:37], v[108:109], v[132:133]
	v_pk_mul_f32 v[132:133], v[34:35], v[114:115]
	v_pk_mul_f32 v[34:35], v[34:35], v[110:111]
	v_pk_fma_f32 v[34:35], v[38:39], v[114:115], v[34:35] neg_lo:[1,0,0] neg_hi:[1,0,0]
	v_pk_fma_f32 v[38:39], v[38:39], v[110:111], v[132:133]
	v_pk_add_f32 v[88:89], v[88:89], v[68:69]
	v_pk_add_f32 v[92:93], v[92:93], v[76:77]
	v_pk_mul_f32 v[132:133], v[92:93], v[120:121]
	v_pk_mul_f32 v[76:77], v[88:89], v[120:121]
	v_pk_fma_f32 v[68:69], v[88:89], v[116:117], v[132:133] neg_lo:[0,0,1] neg_hi:[0,0,1]
	v_pk_fma_f32 v[76:77], v[92:93], v[116:117], v[76:77]
	v_pk_add_f32 v[90:91], v[90:91], v[70:71]
	v_pk_add_f32 v[94:95], v[94:95], v[78:79]
	v_pk_mul_f32 v[132:133], v[94:95], v[122:123]
	v_pk_mul_f32 v[78:79], v[90:91], v[122:123]
	v_pk_fma_f32 v[70:71], v[90:91], v[118:119], v[132:133] neg_lo:[0,0,1] neg_hi:[0,0,1]
	v_pk_fma_f32 v[78:79], v[94:95], v[118:119], v[78:79]
	v_pk_mul_f32 v[132:133], v[40:41], v[104:105]
	v_pk_mul_f32 v[40:41], v[40:41], v[100:101]
	v_pk_fma_f32 v[40:41], v[44:45], v[104:105], v[40:41] neg_lo:[1,0,0] neg_hi:[1,0,0]
	v_pk_fma_f32 v[44:45], v[44:45], v[100:101], v[132:133]
	v_pk_mul_f32 v[132:133], v[42:43], v[106:107]
	v_pk_mul_f32 v[42:43], v[42:43], v[102:103]
	v_pk_fma_f32 v[42:43], v[46:47], v[106:107], v[42:43] neg_lo:[1,0,0] neg_hi:[1,0,0]
	v_pk_fma_f32 v[46:47], v[46:47], v[102:103], v[132:133]
	v_add_f32_dpp v40, v40, v40 row_shr:1 row_mask:0xf bank_mask:0xf bound_ctrl:1
	v_add_f32_dpp v41, v41, v41 row_shr:1 row_mask:0xf bank_mask:0xf bound_ctrl:1
	v_add_f32_dpp v42, v42, v42 row_shr:1 row_mask:0xf bank_mask:0xf bound_ctrl:1
	v_add_f32_dpp v43, v43, v43 row_shr:1 row_mask:0xf bank_mask:0xf bound_ctrl:1
	v_add_f32_dpp v44, v44, v44 row_shr:1 row_mask:0xf bank_mask:0xf bound_ctrl:1
	v_add_f32_dpp v45, v45, v45 row_shr:1 row_mask:0xf bank_mask:0xf bound_ctrl:1
	v_add_f32_dpp v46, v46, v46 row_shr:1 row_mask:0xf bank_mask:0xf bound_ctrl:1
	v_add_f32_dpp v47, v47, v47 row_shr:1 row_mask:0xf bank_mask:0xf bound_ctrl:1
	v_add_f32_dpp v40, v40, v40 row_shr:2 row_mask:0xf bank_mask:0xf bound_ctrl:1
	v_add_f32_dpp v41, v41, v41 row_shr:2 row_mask:0xf bank_mask:0xf bound_ctrl:1
	v_add_f32_dpp v42, v42, v42 row_shr:2 row_mask:0xf bank_mask:0xf bound_ctrl:1
	v_add_f32_dpp v43, v43, v43 row_shr:2 row_mask:0xf bank_mask:0xf bound_ctrl:1
	v_add_f32_dpp v44, v44, v44 row_shr:2 row_mask:0xf bank_mask:0xf bound_ctrl:1
	v_add_f32_dpp v45, v45, v45 row_shr:2 row_mask:0xf bank_mask:0xf bound_ctrl:1
	v_add_f32_dpp v46, v46, v46 row_shr:2 row_mask:0xf bank_mask:0xf bound_ctrl:1
	v_add_f32_dpp v47, v47, v47 row_shr:2 row_mask:0xf bank_mask:0xf bound_ctrl:1
	v_add_f32_dpp v40, v40, v40 row_shr:4 row_mask:0xf bank_mask:0xf bound_ctrl:1
	v_add_f32_dpp v41, v41, v41 row_shr:4 row_mask:0xf bank_mask:0xf bound_ctrl:1
	v_add_f32_dpp v42, v42, v42 row_shr:4 row_mask:0xf bank_mask:0xf bound_ctrl:1
	v_add_f32_dpp v43, v43, v43 row_shr:4 row_mask:0xf bank_mask:0xf bound_ctrl:1
	v_add_f32_dpp v44, v44, v44 row_shr:4 row_mask:0xf bank_mask:0xf bound_ctrl:1
	v_add_f32_dpp v45, v45, v45 row_shr:4 row_mask:0xf bank_mask:0xf bound_ctrl:1
	v_add_f32_dpp v46, v46, v46 row_shr:4 row_mask:0xf bank_mask:0xf bound_ctrl:1
	v_add_f32_dpp v47, v47, v47 row_shr:4 row_mask:0xf bank_mask:0xf bound_ctrl:1
	v_add_f32_dpp v40, v40, v40 row_shr:8 row_mask:0xf bank_mask:0xf bound_ctrl:1
	v_add_f32_dpp v41, v41, v41 row_shr:8 row_mask:0xf bank_mask:0xf bound_ctrl:1
	v_add_f32_dpp v42, v42, v42 row_shr:8 row_mask:0xf bank_mask:0xf bound_ctrl:1
	v_add_f32_dpp v43, v43, v43 row_shr:8 row_mask:0xf bank_mask:0xf bound_ctrl:1
	v_add_f32_dpp v44, v44, v44 row_shr:8 row_mask:0xf bank_mask:0xf bound_ctrl:1
	v_add_f32_dpp v45, v45, v45 row_shr:8 row_mask:0xf bank_mask:0xf bound_ctrl:1
	v_add_f32_dpp v46, v46, v46 row_shr:8 row_mask:0xf bank_mask:0xf bound_ctrl:1
	v_add_f32_dpp v47, v47, v47 row_shr:8 row_mask:0xf bank_mask:0xf bound_ctrl:1
	v_mov_b32_dpp v88, v40 row_newbcast:15 row_mask:0xf bank_mask:0xf
	v_mov_b32_dpp v89, v41 row_newbcast:15 row_mask:0xf bank_mask:0xf
	v_mov_b32_dpp v90, v42 row_newbcast:15 row_mask:0xf bank_mask:0xf
	v_mov_b32_dpp v91, v43 row_newbcast:15 row_mask:0xf bank_mask:0xf
	v_mov_b32_dpp v92, v44 row_newbcast:15 row_mask:0xf bank_mask:0xf
	v_mov_b32_dpp v93, v45 row_newbcast:15 row_mask:0xf bank_mask:0xf
	v_mov_b32_dpp v94, v46 row_newbcast:15 row_mask:0xf bank_mask:0xf
	v_mov_b32_dpp v95, v47 row_newbcast:15 row_mask:0xf bank_mask:0xf
	v_pk_add_f32 v[40:41], v[40:41], v[68:69]
	v_pk_add_f32 v[44:45], v[44:45], v[76:77]
	v_pk_add_f32 v[42:43], v[42:43], v[70:71]
	v_pk_add_f32 v[46:47], v[46:47], v[78:79]
	v_pk_mul_f32 v[132:133], v[40:41], v[112:113]
	v_pk_mul_f32 v[40:41], v[40:41], v[108:109]
	v_pk_fma_f32 v[40:41], v[44:45], v[112:113], v[40:41] neg_lo:[1,0,0] neg_hi:[1,0,0]
	v_pk_fma_f32 v[44:45], v[44:45], v[108:109], v[132:133]
	v_pk_mul_f32 v[132:133], v[42:43], v[114:115]
	v_pk_mul_f32 v[42:43], v[42:43], v[110:111]
	v_pk_fma_f32 v[42:43], v[46:47], v[114:115], v[42:43] neg_lo:[1,0,0] neg_hi:[1,0,0]
	v_pk_fma_f32 v[46:47], v[46:47], v[110:111], v[132:133]
	v_pk_add_f32 v[88:89], v[88:89], v[68:69]
	v_pk_add_f32 v[92:93], v[92:93], v[76:77]
	v_pk_mul_f32 v[132:133], v[92:93], v[120:121]
	v_pk_mul_f32 v[76:77], v[88:89], v[120:121]
	v_pk_fma_f32 v[68:69], v[88:89], v[116:117], v[132:133] neg_lo:[0,0,1] neg_hi:[0,0,1]
	v_pk_fma_f32 v[76:77], v[92:93], v[116:117], v[76:77]
	v_pk_add_f32 v[90:91], v[90:91], v[70:71]
	v_pk_add_f32 v[94:95], v[94:95], v[78:79]
	v_pk_mul_f32 v[132:133], v[94:95], v[122:123]
	v_pk_mul_f32 v[78:79], v[90:91], v[122:123]
	v_pk_fma_f32 v[70:71], v[90:91], v[118:119], v[132:133] neg_lo:[0,0,1] neg_hi:[0,0,1]
	v_pk_fma_f32 v[78:79], v[94:95], v[118:119], v[78:79]
	v_pk_mul_f32 v[132:133], v[48:49], v[104:105]
	v_pk_mul_f32 v[48:49], v[48:49], v[100:101]
	v_pk_fma_f32 v[48:49], v[52:53], v[104:105], v[48:49] neg_lo:[1,0,0] neg_hi:[1,0,0]
	v_pk_fma_f32 v[52:53], v[52:53], v[100:101], v[132:133]
	v_pk_mul_f32 v[132:133], v[50:51], v[106:107]
	v_pk_mul_f32 v[50:51], v[50:51], v[102:103]
	v_pk_fma_f32 v[50:51], v[54:55], v[106:107], v[50:51] neg_lo:[1,0,0] neg_hi:[1,0,0]
	v_pk_fma_f32 v[54:55], v[54:55], v[102:103], v[132:133]
	v_add_f32_dpp v48, v48, v48 row_shr:1 row_mask:0xf bank_mask:0xf bound_ctrl:1
	v_add_f32_dpp v49, v49, v49 row_shr:1 row_mask:0xf bank_mask:0xf bound_ctrl:1
	v_add_f32_dpp v50, v50, v50 row_shr:1 row_mask:0xf bank_mask:0xf bound_ctrl:1
	v_add_f32_dpp v51, v51, v51 row_shr:1 row_mask:0xf bank_mask:0xf bound_ctrl:1
	v_add_f32_dpp v52, v52, v52 row_shr:1 row_mask:0xf bank_mask:0xf bound_ctrl:1
	v_add_f32_dpp v53, v53, v53 row_shr:1 row_mask:0xf bank_mask:0xf bound_ctrl:1
	v_add_f32_dpp v54, v54, v54 row_shr:1 row_mask:0xf bank_mask:0xf bound_ctrl:1
	v_add_f32_dpp v55, v55, v55 row_shr:1 row_mask:0xf bank_mask:0xf bound_ctrl:1
	v_add_f32_dpp v48, v48, v48 row_shr:2 row_mask:0xf bank_mask:0xf bound_ctrl:1
	v_add_f32_dpp v49, v49, v49 row_shr:2 row_mask:0xf bank_mask:0xf bound_ctrl:1
	v_add_f32_dpp v50, v50, v50 row_shr:2 row_mask:0xf bank_mask:0xf bound_ctrl:1
	v_add_f32_dpp v51, v51, v51 row_shr:2 row_mask:0xf bank_mask:0xf bound_ctrl:1
	v_add_f32_dpp v52, v52, v52 row_shr:2 row_mask:0xf bank_mask:0xf bound_ctrl:1
	v_add_f32_dpp v53, v53, v53 row_shr:2 row_mask:0xf bank_mask:0xf bound_ctrl:1
	v_add_f32_dpp v54, v54, v54 row_shr:2 row_mask:0xf bank_mask:0xf bound_ctrl:1
	v_add_f32_dpp v55, v55, v55 row_shr:2 row_mask:0xf bank_mask:0xf bound_ctrl:1
	v_add_f32_dpp v48, v48, v48 row_shr:4 row_mask:0xf bank_mask:0xf bound_ctrl:1
	v_add_f32_dpp v49, v49, v49 row_shr:4 row_mask:0xf bank_mask:0xf bound_ctrl:1
	v_add_f32_dpp v50, v50, v50 row_shr:4 row_mask:0xf bank_mask:0xf bound_ctrl:1
	v_add_f32_dpp v51, v51, v51 row_shr:4 row_mask:0xf bank_mask:0xf bound_ctrl:1
	v_add_f32_dpp v52, v52, v52 row_shr:4 row_mask:0xf bank_mask:0xf bound_ctrl:1
	v_add_f32_dpp v53, v53, v53 row_shr:4 row_mask:0xf bank_mask:0xf bound_ctrl:1
	v_add_f32_dpp v54, v54, v54 row_shr:4 row_mask:0xf bank_mask:0xf bound_ctrl:1
	v_add_f32_dpp v55, v55, v55 row_shr:4 row_mask:0xf bank_mask:0xf bound_ctrl:1
	v_add_f32_dpp v48, v48, v48 row_shr:8 row_mask:0xf bank_mask:0xf bound_ctrl:1
	v_add_f32_dpp v49, v49, v49 row_shr:8 row_mask:0xf bank_mask:0xf bound_ctrl:1
	v_add_f32_dpp v50, v50, v50 row_shr:8 row_mask:0xf bank_mask:0xf bound_ctrl:1
	v_add_f32_dpp v51, v51, v51 row_shr:8 row_mask:0xf bank_mask:0xf bound_ctrl:1
	v_add_f32_dpp v52, v52, v52 row_shr:8 row_mask:0xf bank_mask:0xf bound_ctrl:1
	v_add_f32_dpp v53, v53, v53 row_shr:8 row_mask:0xf bank_mask:0xf bound_ctrl:1
	v_add_f32_dpp v54, v54, v54 row_shr:8 row_mask:0xf bank_mask:0xf bound_ctrl:1
	v_add_f32_dpp v55, v55, v55 row_shr:8 row_mask:0xf bank_mask:0xf bound_ctrl:1
	v_mov_b32_dpp v88, v48 row_newbcast:15 row_mask:0xf bank_mask:0xf
	v_mov_b32_dpp v89, v49 row_newbcast:15 row_mask:0xf bank_mask:0xf
	v_mov_b32_dpp v90, v50 row_newbcast:15 row_mask:0xf bank_mask:0xf
	v_mov_b32_dpp v91, v51 row_newbcast:15 row_mask:0xf bank_mask:0xf
	v_mov_b32_dpp v92, v52 row_newbcast:15 row_mask:0xf bank_mask:0xf
	v_mov_b32_dpp v93, v53 row_newbcast:15 row_mask:0xf bank_mask:0xf
	v_mov_b32_dpp v94, v54 row_newbcast:15 row_mask:0xf bank_mask:0xf
	v_mov_b32_dpp v95, v55 row_newbcast:15 row_mask:0xf bank_mask:0xf
	v_pk_add_f32 v[48:49], v[48:49], v[68:69]
	v_pk_add_f32 v[52:53], v[52:53], v[76:77]
	v_pk_add_f32 v[50:51], v[50:51], v[70:71]
	v_pk_add_f32 v[54:55], v[54:55], v[78:79]
	v_pk_mul_f32 v[132:133], v[48:49], v[112:113]
	v_pk_mul_f32 v[48:49], v[48:49], v[108:109]
	v_pk_fma_f32 v[48:49], v[52:53], v[112:113], v[48:49] neg_lo:[1,0,0] neg_hi:[1,0,0]
	v_pk_fma_f32 v[52:53], v[52:53], v[108:109], v[132:133]
	v_pk_mul_f32 v[132:133], v[50:51], v[114:115]
	v_pk_mul_f32 v[50:51], v[50:51], v[110:111]
	v_pk_fma_f32 v[50:51], v[54:55], v[114:115], v[50:51] neg_lo:[1,0,0] neg_hi:[1,0,0]
	v_pk_fma_f32 v[54:55], v[54:55], v[110:111], v[132:133]
	v_pk_add_f32 v[88:89], v[88:89], v[68:69]
	v_pk_add_f32 v[92:93], v[92:93], v[76:77]
	v_pk_mul_f32 v[132:133], v[92:93], v[120:121]
	v_pk_mul_f32 v[76:77], v[88:89], v[120:121]
	v_pk_fma_f32 v[68:69], v[88:89], v[116:117], v[132:133] neg_lo:[0,0,1] neg_hi:[0,0,1]
	v_pk_fma_f32 v[76:77], v[92:93], v[116:117], v[76:77]
	v_pk_add_f32 v[90:91], v[90:91], v[70:71]
	v_pk_add_f32 v[94:95], v[94:95], v[78:79]
	v_pk_mul_f32 v[132:133], v[94:95], v[122:123]
	v_pk_mul_f32 v[78:79], v[90:91], v[122:123]
	v_pk_fma_f32 v[70:71], v[90:91], v[118:119], v[132:133] neg_lo:[0,0,1] neg_hi:[0,0,1]
	v_pk_fma_f32 v[78:79], v[94:95], v[118:119], v[78:79]
	v_pk_mul_f32 v[132:133], v[56:57], v[104:105]
	v_pk_mul_f32 v[56:57], v[56:57], v[100:101]
	v_pk_fma_f32 v[56:57], v[60:61], v[104:105], v[56:57] neg_lo:[1,0,0] neg_hi:[1,0,0]
	v_pk_fma_f32 v[60:61], v[60:61], v[100:101], v[132:133]
	v_pk_mul_f32 v[132:133], v[58:59], v[106:107]
	v_pk_mul_f32 v[58:59], v[58:59], v[102:103]
	v_pk_fma_f32 v[58:59], v[62:63], v[106:107], v[58:59] neg_lo:[1,0,0] neg_hi:[1,0,0]
	v_pk_fma_f32 v[62:63], v[62:63], v[102:103], v[132:133]
	v_add_f32_dpp v56, v56, v56 row_shr:1 row_mask:0xf bank_mask:0xf bound_ctrl:1
	v_add_f32_dpp v57, v57, v57 row_shr:1 row_mask:0xf bank_mask:0xf bound_ctrl:1
	v_add_f32_dpp v58, v58, v58 row_shr:1 row_mask:0xf bank_mask:0xf bound_ctrl:1
	v_add_f32_dpp v59, v59, v59 row_shr:1 row_mask:0xf bank_mask:0xf bound_ctrl:1
	v_add_f32_dpp v60, v60, v60 row_shr:1 row_mask:0xf bank_mask:0xf bound_ctrl:1
	v_add_f32_dpp v61, v61, v61 row_shr:1 row_mask:0xf bank_mask:0xf bound_ctrl:1
	v_add_f32_dpp v62, v62, v62 row_shr:1 row_mask:0xf bank_mask:0xf bound_ctrl:1
	v_add_f32_dpp v63, v63, v63 row_shr:1 row_mask:0xf bank_mask:0xf bound_ctrl:1
	v_add_f32_dpp v56, v56, v56 row_shr:2 row_mask:0xf bank_mask:0xf bound_ctrl:1
	v_add_f32_dpp v57, v57, v57 row_shr:2 row_mask:0xf bank_mask:0xf bound_ctrl:1
	v_add_f32_dpp v58, v58, v58 row_shr:2 row_mask:0xf bank_mask:0xf bound_ctrl:1
	v_add_f32_dpp v59, v59, v59 row_shr:2 row_mask:0xf bank_mask:0xf bound_ctrl:1
	v_add_f32_dpp v60, v60, v60 row_shr:2 row_mask:0xf bank_mask:0xf bound_ctrl:1
	v_add_f32_dpp v61, v61, v61 row_shr:2 row_mask:0xf bank_mask:0xf bound_ctrl:1
	v_add_f32_dpp v62, v62, v62 row_shr:2 row_mask:0xf bank_mask:0xf bound_ctrl:1
	v_add_f32_dpp v63, v63, v63 row_shr:2 row_mask:0xf bank_mask:0xf bound_ctrl:1
	v_add_f32_dpp v56, v56, v56 row_shr:4 row_mask:0xf bank_mask:0xf bound_ctrl:1
	v_add_f32_dpp v57, v57, v57 row_shr:4 row_mask:0xf bank_mask:0xf bound_ctrl:1
	v_add_f32_dpp v58, v58, v58 row_shr:4 row_mask:0xf bank_mask:0xf bound_ctrl:1
	v_add_f32_dpp v59, v59, v59 row_shr:4 row_mask:0xf bank_mask:0xf bound_ctrl:1
	v_add_f32_dpp v60, v60, v60 row_shr:4 row_mask:0xf bank_mask:0xf bound_ctrl:1
	v_add_f32_dpp v61, v61, v61 row_shr:4 row_mask:0xf bank_mask:0xf bound_ctrl:1
	v_add_f32_dpp v62, v62, v62 row_shr:4 row_mask:0xf bank_mask:0xf bound_ctrl:1
	v_add_f32_dpp v63, v63, v63 row_shr:4 row_mask:0xf bank_mask:0xf bound_ctrl:1
	v_add_f32_dpp v56, v56, v56 row_shr:8 row_mask:0xf bank_mask:0xf bound_ctrl:1
	v_add_f32_dpp v57, v57, v57 row_shr:8 row_mask:0xf bank_mask:0xf bound_ctrl:1
	v_add_f32_dpp v58, v58, v58 row_shr:8 row_mask:0xf bank_mask:0xf bound_ctrl:1
	v_add_f32_dpp v59, v59, v59 row_shr:8 row_mask:0xf bank_mask:0xf bound_ctrl:1
	v_add_f32_dpp v60, v60, v60 row_shr:8 row_mask:0xf bank_mask:0xf bound_ctrl:1
	v_add_f32_dpp v61, v61, v61 row_shr:8 row_mask:0xf bank_mask:0xf bound_ctrl:1
	v_add_f32_dpp v62, v62, v62 row_shr:8 row_mask:0xf bank_mask:0xf bound_ctrl:1
	v_add_f32_dpp v63, v63, v63 row_shr:8 row_mask:0xf bank_mask:0xf bound_ctrl:1
	v_mov_b32_dpp v88, v56 row_newbcast:15 row_mask:0xf bank_mask:0xf
	v_mov_b32_dpp v89, v57 row_newbcast:15 row_mask:0xf bank_mask:0xf
	v_mov_b32_dpp v90, v58 row_newbcast:15 row_mask:0xf bank_mask:0xf
	v_mov_b32_dpp v91, v59 row_newbcast:15 row_mask:0xf bank_mask:0xf
	v_mov_b32_dpp v92, v60 row_newbcast:15 row_mask:0xf bank_mask:0xf
	v_mov_b32_dpp v93, v61 row_newbcast:15 row_mask:0xf bank_mask:0xf
	v_mov_b32_dpp v94, v62 row_newbcast:15 row_mask:0xf bank_mask:0xf
	v_mov_b32_dpp v95, v63 row_newbcast:15 row_mask:0xf bank_mask:0xf
	v_pk_add_f32 v[56:57], v[56:57], v[68:69]
	v_pk_add_f32 v[60:61], v[60:61], v[76:77]
	v_pk_add_f32 v[58:59], v[58:59], v[70:71]
	v_pk_add_f32 v[62:63], v[62:63], v[78:79]
	v_pk_mul_f32 v[132:133], v[56:57], v[112:113]
	v_pk_mul_f32 v[56:57], v[56:57], v[108:109]
	v_pk_fma_f32 v[56:57], v[60:61], v[112:113], v[56:57] neg_lo:[1,0,0] neg_hi:[1,0,0]
	v_pk_fma_f32 v[60:61], v[60:61], v[108:109], v[132:133]
	v_pk_mul_f32 v[132:133], v[58:59], v[114:115]
	v_pk_mul_f32 v[58:59], v[58:59], v[110:111]
	v_pk_fma_f32 v[58:59], v[62:63], v[114:115], v[58:59] neg_lo:[1,0,0] neg_hi:[1,0,0]
	v_pk_fma_f32 v[62:63], v[62:63], v[110:111], v[132:133]
	v_pk_add_f32 v[88:89], v[88:89], v[68:69]
	v_pk_add_f32 v[92:93], v[92:93], v[76:77]
	v_pk_mul_f32 v[132:133], v[92:93], v[120:121]
	v_pk_mul_f32 v[76:77], v[88:89], v[120:121]
	v_pk_fma_f32 v[68:69], v[88:89], v[116:117], v[132:133] neg_lo:[0,0,1] neg_hi:[0,0,1]
	v_pk_fma_f32 v[76:77], v[92:93], v[116:117], v[76:77]
	v_pk_add_f32 v[90:91], v[90:91], v[70:71]
	v_pk_add_f32 v[94:95], v[94:95], v[78:79]
	v_pk_mul_f32 v[132:133], v[94:95], v[122:123]
	v_pk_mul_f32 v[78:79], v[90:91], v[122:123]
	v_pk_fma_f32 v[70:71], v[90:91], v[118:119], v[132:133] neg_lo:[0,0,1] neg_hi:[0,0,1]
	v_pk_fma_f32 v[78:79], v[94:95], v[118:119], v[78:79]
	s_waitcnt vmcnt(12)
	v_cvt_pk_bf16_f32 v96, v32, v33
	v_cvt_pk_bf16_f32 v97, v34, v35
	v_cvt_pk_bf16_f32 v98, v36, v37
	v_cvt_pk_bf16_f32 v99, v38, v39
	s_nop 1
	v_mfma_f32_16x16x32_bf16 v[16:19], v[80:83], v[96:99], v[16:19]
	v_cvt_pk_bf16_f32 v96, v40, v41
	v_cvt_pk_bf16_f32 v97, v42, v43
	v_cvt_pk_bf16_f32 v98, v44, v45
	v_cvt_pk_bf16_f32 v99, v46, v47
	s_nop 1
	v_mfma_f32_16x16x32_bf16 v[20:23], v[80:83], v[96:99], v[20:23]
	v_cvt_pk_bf16_f32 v96, v48, v49
	v_cvt_pk_bf16_f32 v97, v50, v51
	v_cvt_pk_bf16_f32 v98, v52, v53
	v_cvt_pk_bf16_f32 v99, v54, v55
	s_nop 1
	v_mfma_f32_16x16x32_bf16 v[24:27], v[80:83], v[96:99], v[24:27]
	v_cvt_pk_bf16_f32 v96, v56, v57
	v_cvt_pk_bf16_f32 v97, v58, v59
	v_cvt_pk_bf16_f32 v98, v60, v61
	v_cvt_pk_bf16_f32 v99, v62, v63
	s_nop 1
	v_mfma_f32_16x16x32_bf16 v[28:31], v[80:83], v[96:99], v[28:31]
	s_waitcnt vmcnt(10)
	global_load_dwordx4 v[80:83], v134, s[38:39]
	s_add_u32 s38, s38, 0x400
	s_addc_u32 s39, s39, 0
	v_mfma_f32_16x16x32_bf16 v[32:35], v[64:67], v[0:3], 0
	v_mfma_f32_16x16x32_bf16 v[36:39], v[72:75], v[0:3], 0
	v_mfma_f32_16x16x32_bf16 v[40:43], v[64:67], v[4:7], 0
	v_mfma_f32_16x16x32_bf16 v[44:47], v[72:75], v[4:7], 0
	v_mfma_f32_16x16x32_bf16 v[48:51], v[64:67], v[8:11], 0
	v_mfma_f32_16x16x32_bf16 v[52:55], v[72:75], v[8:11], 0
	v_mfma_f32_16x16x32_bf16 v[56:59], v[64:67], v[12:15], 0
	v_mfma_f32_16x16x32_bf16 v[60:63], v[72:75], v[12:15], 0
	global_load_dwordx4 v[64:67], v134, s[20:21]
	global_load_dwordx4 v[72:75], v134, s[20:21] offset:1024
	s_add_u32 s20, s20, 0x800
	s_addc_u32 s21, s21, 0
	global_load_dwordx4 v[100:103], v134, s[42:43] offset:0
	global_load_dwordx4 v[104:107], v134, s[42:43] offset:1024
	global_load_dwordx4 v[108:111], v134, s[42:43] offset:2048
	global_load_dwordx4 v[112:115], v134, s[42:43] offset:3072
	global_load_dwordx4 v[116:119], v208, s[42:43] offset:0
	global_load_dwordx4 v[120:123], v208, s[42:43] offset:1024
	global_load_dwordx4 v[124:127], v208, s[42:43] offset:2048
	global_load_dwordx4 v[128:131], v208, s[42:43] offset:3072
	global_load_dwordx4 v[178:181], v206, s[44:45]
	global_load_dwordx4 v[182:185], v206, s[44:45] offset:16
	s_add_u32 s42, s42, 0x2000
	s_addc_u32 s43, s43, 0
	s_add_u32 s44, s44, 0x80
	s_addc_u32 s45, s45, 0
	s_waitcnt vmcnt(13)
	v_mul_f32_e32 v132, v171, v166
	v_mul_f32_e32 v133, v170, v166
	v_fma_f32 v68, v170, v162, -v132
	v_fma_f32 v76, v171, v162, v133
	v_mul_f32_e32 v132, v173, v167
	v_mul_f32_e32 v133, v172, v167
	v_fma_f32 v69, v172, v163, -v132
	v_fma_f32 v77, v173, v163, v133
	v_mul_f32_e32 v132, v175, v168
	v_mul_f32_e32 v133, v174, v168
	v_fma_f32 v70, v174, v164, -v132
	v_fma_f32 v78, v175, v164, v133
	v_mul_f32_e32 v132, v177, v169
	v_mul_f32_e32 v133, v176, v169
	v_fma_f32 v71, v176, v165, -v132
	v_fma_f32 v79, v177, v165, v133
	v_pk_mul_f32 v[132:133], v[56:57], v[142:143]
	v_pk_mul_f32 v[56:57], v[56:57], v[138:139]
	v_pk_fma_f32 v[56:57], v[60:61], v[142:143], v[56:57] neg_lo:[1,0,0] neg_hi:[1,0,0]
	v_pk_fma_f32 v[60:61], v[60:61], v[138:139], v[132:133]
	v_pk_mul_f32 v[132:133], v[58:59], v[144:145]
	v_pk_mul_f32 v[58:59], v[58:59], v[140:141]
	v_pk_fma_f32 v[58:59], v[62:63], v[144:145], v[58:59] neg_lo:[1,0,0] neg_hi:[1,0,0]
	v_pk_fma_f32 v[62:63], v[62:63], v[140:141], v[132:133]
	v_add_f32_dpp v56, v56, v56 row_shl:1 row_mask:0xf bank_mask:0xf bound_ctrl:1
	v_add_f32_dpp v57, v57, v57 row_shl:1 row_mask:0xf bank_mask:0xf bound_ctrl:1
	v_add_f32_dpp v58, v58, v58 row_shl:1 row_mask:0xf bank_mask:0xf bound_ctrl:1
	v_add_f32_dpp v59, v59, v59 row_shl:1 row_mask:0xf bank_mask:0xf bound_ctrl:1
	v_add_f32_dpp v60, v60, v60 row_shl:1 row_mask:0xf bank_mask:0xf bound_ctrl:1
	v_add_f32_dpp v61, v61, v61 row_shl:1 row_mask:0xf bank_mask:0xf bound_ctrl:1
	v_add_f32_dpp v62, v62, v62 row_shl:1 row_mask:0xf bank_mask:0xf bound_ctrl:1
	v_add_f32_dpp v63, v63, v63 row_shl:1 row_mask:0xf bank_mask:0xf bound_ctrl:1
	v_add_f32_dpp v56, v56, v56 row_shl:2 row_mask:0xf bank_mask:0xf bound_ctrl:1
	v_add_f32_dpp v57, v57, v57 row_shl:2 row_mask:0xf bank_mask:0xf bound_ctrl:1
	v_add_f32_dpp v58, v58, v58 row_shl:2 row_mask:0xf bank_mask:0xf bound_ctrl:1
	v_add_f32_dpp v59, v59, v59 row_shl:2 row_mask:0xf bank_mask:0xf bound_ctrl:1
	v_add_f32_dpp v60, v60, v60 row_shl:2 row_mask:0xf bank_mask:0xf bound_ctrl:1
	v_add_f32_dpp v61, v61, v61 row_shl:2 row_mask:0xf bank_mask:0xf bound_ctrl:1
	v_add_f32_dpp v62, v62, v62 row_shl:2 row_mask:0xf bank_mask:0xf bound_ctrl:1
	v_add_f32_dpp v63, v63, v63 row_shl:2 row_mask:0xf bank_mask:0xf bound_ctrl:1
	v_add_f32_dpp v56, v56, v56 row_shl:4 row_mask:0xf bank_mask:0xf bound_ctrl:1
	v_add_f32_dpp v57, v57, v57 row_shl:4 row_mask:0xf bank_mask:0xf bound_ctrl:1
	v_add_f32_dpp v58, v58, v58 row_shl:4 row_mask:0xf bank_mask:0xf bound_ctrl:1
	v_add_f32_dpp v59, v59, v59 row_shl:4 row_mask:0xf bank_mask:0xf bound_ctrl:1
	v_add_f32_dpp v60, v60, v60 row_shl:4 row_mask:0xf bank_mask:0xf bound_ctrl:1
	v_add_f32_dpp v61, v61, v61 row_shl:4 row_mask:0xf bank_mask:0xf bound_ctrl:1
	v_add_f32_dpp v62, v62, v62 row_shl:4 row_mask:0xf bank_mask:0xf bound_ctrl:1
	v_add_f32_dpp v63, v63, v63 row_shl:4 row_mask:0xf bank_mask:0xf bound_ctrl:1
	v_add_f32_dpp v56, v56, v56 row_shl:8 row_mask:0xf bank_mask:0xf bound_ctrl:1
	v_add_f32_dpp v57, v57, v57 row_shl:8 row_mask:0xf bank_mask:0xf bound_ctrl:1
	v_add_f32_dpp v58, v58, v58 row_shl:8 row_mask:0xf bank_mask:0xf bound_ctrl:1
	v_add_f32_dpp v59, v59, v59 row_shl:8 row_mask:0xf bank_mask:0xf bound_ctrl:1
	v_add_f32_dpp v60, v60, v60 row_shl:8 row_mask:0xf bank_mask:0xf bound_ctrl:1
	v_add_f32_dpp v61, v61, v61 row_shl:8 row_mask:0xf bank_mask:0xf bound_ctrl:1
	v_add_f32_dpp v62, v62, v62 row_shl:8 row_mask:0xf bank_mask:0xf bound_ctrl:1
	v_add_f32_dpp v63, v63, v63 row_shl:8 row_mask:0xf bank_mask:0xf bound_ctrl:1
	v_mov_b32_dpp v88, v56 row_newbcast:0 row_mask:0xf bank_mask:0xf
	v_mov_b32_dpp v89, v57 row_newbcast:0 row_mask:0xf bank_mask:0xf
	v_mov_b32_dpp v90, v58 row_newbcast:0 row_mask:0xf bank_mask:0xf
	v_mov_b32_dpp v91, v59 row_newbcast:0 row_mask:0xf bank_mask:0xf
	v_mov_b32_dpp v92, v60 row_newbcast:0 row_mask:0xf bank_mask:0xf
	v_mov_b32_dpp v93, v61 row_newbcast:0 row_mask:0xf bank_mask:0xf
	v_mov_b32_dpp v94, v62 row_newbcast:0 row_mask:0xf bank_mask:0xf
	v_mov_b32_dpp v95, v63 row_newbcast:0 row_mask:0xf bank_mask:0xf
	v_pk_add_f32 v[56:57], v[56:57], v[68:69]
	v_pk_add_f32 v[60:61], v[60:61], v[76:77]
	v_pk_add_f32 v[58:59], v[58:59], v[70:71]
	v_pk_add_f32 v[62:63], v[62:63], v[78:79]
	v_pk_mul_f32 v[132:133], v[56:57], v[150:151]
	v_pk_mul_f32 v[56:57], v[56:57], v[146:147]
	v_pk_fma_f32 v[56:57], v[60:61], v[150:151], v[56:57] neg_lo:[1,0,0] neg_hi:[1,0,0]
	v_pk_fma_f32 v[60:61], v[60:61], v[146:147], v[132:133]
	v_pk_mul_f32 v[132:133], v[58:59], v[152:153]
	v_pk_mul_f32 v[58:59], v[58:59], v[148:149]
	v_pk_fma_f32 v[58:59], v[62:63], v[152:153], v[58:59] neg_lo:[1,0,0] neg_hi:[1,0,0]
	v_pk_fma_f32 v[62:63], v[62:63], v[148:149], v[132:133]
	v_pk_add_f32 v[88:89], v[88:89], v[68:69]
	v_pk_add_f32 v[92:93], v[92:93], v[76:77]
	v_pk_mul_f32 v[132:133], v[92:93], v[158:159]
	v_pk_mul_f32 v[76:77], v[88:89], v[158:159]
	v_pk_fma_f32 v[68:69], v[88:89], v[154:155], v[132:133] neg_lo:[0,0,1] neg_hi:[0,0,1]
	v_pk_fma_f32 v[76:77], v[92:93], v[154:155], v[76:77]
	v_pk_add_f32 v[90:91], v[90:91], v[70:71]
	v_pk_add_f32 v[94:95], v[94:95], v[78:79]
	v_pk_mul_f32 v[132:133], v[94:95], v[160:161]
	v_pk_mul_f32 v[78:79], v[90:91], v[160:161]
	v_pk_fma_f32 v[70:71], v[90:91], v[156:157], v[132:133] neg_lo:[0,0,1] neg_hi:[0,0,1]
	v_pk_fma_f32 v[78:79], v[94:95], v[156:157], v[78:79]
	v_pk_mul_f32 v[132:133], v[48:49], v[142:143]
	v_pk_mul_f32 v[48:49], v[48:49], v[138:139]
	v_pk_fma_f32 v[48:49], v[52:53], v[142:143], v[48:49] neg_lo:[1,0,0] neg_hi:[1,0,0]
	v_pk_fma_f32 v[52:53], v[52:53], v[138:139], v[132:133]
	v_pk_mul_f32 v[132:133], v[50:51], v[144:145]
	v_pk_mul_f32 v[50:51], v[50:51], v[140:141]
	v_pk_fma_f32 v[50:51], v[54:55], v[144:145], v[50:51] neg_lo:[1,0,0] neg_hi:[1,0,0]
	v_pk_fma_f32 v[54:55], v[54:55], v[140:141], v[132:133]
	v_add_f32_dpp v48, v48, v48 row_shl:1 row_mask:0xf bank_mask:0xf bound_ctrl:1
	v_add_f32_dpp v49, v49, v49 row_shl:1 row_mask:0xf bank_mask:0xf bound_ctrl:1
	v_add_f32_dpp v50, v50, v50 row_shl:1 row_mask:0xf bank_mask:0xf bound_ctrl:1
	v_add_f32_dpp v51, v51, v51 row_shl:1 row_mask:0xf bank_mask:0xf bound_ctrl:1
	v_add_f32_dpp v52, v52, v52 row_shl:1 row_mask:0xf bank_mask:0xf bound_ctrl:1
	v_add_f32_dpp v53, v53, v53 row_shl:1 row_mask:0xf bank_mask:0xf bound_ctrl:1
	v_add_f32_dpp v54, v54, v54 row_shl:1 row_mask:0xf bank_mask:0xf bound_ctrl:1
	v_add_f32_dpp v55, v55, v55 row_shl:1 row_mask:0xf bank_mask:0xf bound_ctrl:1
	v_add_f32_dpp v48, v48, v48 row_shl:2 row_mask:0xf bank_mask:0xf bound_ctrl:1
	v_add_f32_dpp v49, v49, v49 row_shl:2 row_mask:0xf bank_mask:0xf bound_ctrl:1
	v_add_f32_dpp v50, v50, v50 row_shl:2 row_mask:0xf bank_mask:0xf bound_ctrl:1
	v_add_f32_dpp v51, v51, v51 row_shl:2 row_mask:0xf bank_mask:0xf bound_ctrl:1
	v_add_f32_dpp v52, v52, v52 row_shl:2 row_mask:0xf bank_mask:0xf bound_ctrl:1
	v_add_f32_dpp v53, v53, v53 row_shl:2 row_mask:0xf bank_mask:0xf bound_ctrl:1
	v_add_f32_dpp v54, v54, v54 row_shl:2 row_mask:0xf bank_mask:0xf bound_ctrl:1
	v_add_f32_dpp v55, v55, v55 row_shl:2 row_mask:0xf bank_mask:0xf bound_ctrl:1
	v_add_f32_dpp v48, v48, v48 row_shl:4 row_mask:0xf bank_mask:0xf bound_ctrl:1
	v_add_f32_dpp v49, v49, v49 row_shl:4 row_mask:0xf bank_mask:0xf bound_ctrl:1
	v_add_f32_dpp v50, v50, v50 row_shl:4 row_mask:0xf bank_mask:0xf bound_ctrl:1
	v_add_f32_dpp v51, v51, v51 row_shl:4 row_mask:0xf bank_mask:0xf bound_ctrl:1
	v_add_f32_dpp v52, v52, v52 row_shl:4 row_mask:0xf bank_mask:0xf bound_ctrl:1
	v_add_f32_dpp v53, v53, v53 row_shl:4 row_mask:0xf bank_mask:0xf bound_ctrl:1
	v_add_f32_dpp v54, v54, v54 row_shl:4 row_mask:0xf bank_mask:0xf bound_ctrl:1
	v_add_f32_dpp v55, v55, v55 row_shl:4 row_mask:0xf bank_mask:0xf bound_ctrl:1
	v_add_f32_dpp v48, v48, v48 row_shl:8 row_mask:0xf bank_mask:0xf bound_ctrl:1
	v_add_f32_dpp v49, v49, v49 row_shl:8 row_mask:0xf bank_mask:0xf bound_ctrl:1
	v_add_f32_dpp v50, v50, v50 row_shl:8 row_mask:0xf bank_mask:0xf bound_ctrl:1
	v_add_f32_dpp v51, v51, v51 row_shl:8 row_mask:0xf bank_mask:0xf bound_ctrl:1
	v_add_f32_dpp v52, v52, v52 row_shl:8 row_mask:0xf bank_mask:0xf bound_ctrl:1
	v_add_f32_dpp v53, v53, v53 row_shl:8 row_mask:0xf bank_mask:0xf bound_ctrl:1
	v_add_f32_dpp v54, v54, v54 row_shl:8 row_mask:0xf bank_mask:0xf bound_ctrl:1
	v_add_f32_dpp v55, v55, v55 row_shl:8 row_mask:0xf bank_mask:0xf bound_ctrl:1
	v_mov_b32_dpp v88, v48 row_newbcast:0 row_mask:0xf bank_mask:0xf
	v_mov_b32_dpp v89, v49 row_newbcast:0 row_mask:0xf bank_mask:0xf
	v_mov_b32_dpp v90, v50 row_newbcast:0 row_mask:0xf bank_mask:0xf
	v_mov_b32_dpp v91, v51 row_newbcast:0 row_mask:0xf bank_mask:0xf
	v_mov_b32_dpp v92, v52 row_newbcast:0 row_mask:0xf bank_mask:0xf
	v_mov_b32_dpp v93, v53 row_newbcast:0 row_mask:0xf bank_mask:0xf
	v_mov_b32_dpp v94, v54 row_newbcast:0 row_mask:0xf bank_mask:0xf
	v_mov_b32_dpp v95, v55 row_newbcast:0 row_mask:0xf bank_mask:0xf
	v_pk_add_f32 v[48:49], v[48:49], v[68:69]
	v_pk_add_f32 v[52:53], v[52:53], v[76:77]
	v_pk_add_f32 v[50:51], v[50:51], v[70:71]
	v_pk_add_f32 v[54:55], v[54:55], v[78:79]
	v_pk_mul_f32 v[132:133], v[48:49], v[150:151]
	v_pk_mul_f32 v[48:49], v[48:49], v[146:147]
	v_pk_fma_f32 v[48:49], v[52:53], v[150:151], v[48:49] neg_lo:[1,0,0] neg_hi:[1,0,0]
	v_pk_fma_f32 v[52:53], v[52:53], v[146:147], v[132:133]
	v_pk_mul_f32 v[132:133], v[50:51], v[152:153]
	v_pk_mul_f32 v[50:51], v[50:51], v[148:149]
	v_pk_fma_f32 v[50:51], v[54:55], v[152:153], v[50:51] neg_lo:[1,0,0] neg_hi:[1,0,0]
	v_pk_fma_f32 v[54:55], v[54:55], v[148:149], v[132:133]
	v_pk_add_f32 v[88:89], v[88:89], v[68:69]
	v_pk_add_f32 v[92:93], v[92:93], v[76:77]
	v_pk_mul_f32 v[132:133], v[92:93], v[158:159]
	v_pk_mul_f32 v[76:77], v[88:89], v[158:159]
	v_pk_fma_f32 v[68:69], v[88:89], v[154:155], v[132:133] neg_lo:[0,0,1] neg_hi:[0,0,1]
	v_pk_fma_f32 v[76:77], v[92:93], v[154:155], v[76:77]
	v_pk_add_f32 v[90:91], v[90:91], v[70:71]
	v_pk_add_f32 v[94:95], v[94:95], v[78:79]
	v_pk_mul_f32 v[132:133], v[94:95], v[160:161]
	v_pk_mul_f32 v[78:79], v[90:91], v[160:161]
	v_pk_fma_f32 v[70:71], v[90:91], v[156:157], v[132:133] neg_lo:[0,0,1] neg_hi:[0,0,1]
	v_pk_fma_f32 v[78:79], v[94:95], v[156:157], v[78:79]
	v_pk_mul_f32 v[132:133], v[40:41], v[142:143]
	v_pk_mul_f32 v[40:41], v[40:41], v[138:139]
	v_pk_fma_f32 v[40:41], v[44:45], v[142:143], v[40:41] neg_lo:[1,0,0] neg_hi:[1,0,0]
	v_pk_fma_f32 v[44:45], v[44:45], v[138:139], v[132:133]
	v_pk_mul_f32 v[132:133], v[42:43], v[144:145]
	v_pk_mul_f32 v[42:43], v[42:43], v[140:141]
	v_pk_fma_f32 v[42:43], v[46:47], v[144:145], v[42:43] neg_lo:[1,0,0] neg_hi:[1,0,0]
	v_pk_fma_f32 v[46:47], v[46:47], v[140:141], v[132:133]
	v_add_f32_dpp v40, v40, v40 row_shl:1 row_mask:0xf bank_mask:0xf bound_ctrl:1
	v_add_f32_dpp v41, v41, v41 row_shl:1 row_mask:0xf bank_mask:0xf bound_ctrl:1
	v_add_f32_dpp v42, v42, v42 row_shl:1 row_mask:0xf bank_mask:0xf bound_ctrl:1
	v_add_f32_dpp v43, v43, v43 row_shl:1 row_mask:0xf bank_mask:0xf bound_ctrl:1
	v_add_f32_dpp v44, v44, v44 row_shl:1 row_mask:0xf bank_mask:0xf bound_ctrl:1
	v_add_f32_dpp v45, v45, v45 row_shl:1 row_mask:0xf bank_mask:0xf bound_ctrl:1
	v_add_f32_dpp v46, v46, v46 row_shl:1 row_mask:0xf bank_mask:0xf bound_ctrl:1
	v_add_f32_dpp v47, v47, v47 row_shl:1 row_mask:0xf bank_mask:0xf bound_ctrl:1
	v_add_f32_dpp v40, v40, v40 row_shl:2 row_mask:0xf bank_mask:0xf bound_ctrl:1
	v_add_f32_dpp v41, v41, v41 row_shl:2 row_mask:0xf bank_mask:0xf bound_ctrl:1
	v_add_f32_dpp v42, v42, v42 row_shl:2 row_mask:0xf bank_mask:0xf bound_ctrl:1
	v_add_f32_dpp v43, v43, v43 row_shl:2 row_mask:0xf bank_mask:0xf bound_ctrl:1
	v_add_f32_dpp v44, v44, v44 row_shl:2 row_mask:0xf bank_mask:0xf bound_ctrl:1
	v_add_f32_dpp v45, v45, v45 row_shl:2 row_mask:0xf bank_mask:0xf bound_ctrl:1
	v_add_f32_dpp v46, v46, v46 row_shl:2 row_mask:0xf bank_mask:0xf bound_ctrl:1
	v_add_f32_dpp v47, v47, v47 row_shl:2 row_mask:0xf bank_mask:0xf bound_ctrl:1
	v_add_f32_dpp v40, v40, v40 row_shl:4 row_mask:0xf bank_mask:0xf bound_ctrl:1
	v_add_f32_dpp v41, v41, v41 row_shl:4 row_mask:0xf bank_mask:0xf bound_ctrl:1
	v_add_f32_dpp v42, v42, v42 row_shl:4 row_mask:0xf bank_mask:0xf bound_ctrl:1
	v_add_f32_dpp v43, v43, v43 row_shl:4 row_mask:0xf bank_mask:0xf bound_ctrl:1
	v_add_f32_dpp v44, v44, v44 row_shl:4 row_mask:0xf bank_mask:0xf bound_ctrl:1
	v_add_f32_dpp v45, v45, v45 row_shl:4 row_mask:0xf bank_mask:0xf bound_ctrl:1
	v_add_f32_dpp v46, v46, v46 row_shl:4 row_mask:0xf bank_mask:0xf bound_ctrl:1
	v_add_f32_dpp v47, v47, v47 row_shl:4 row_mask:0xf bank_mask:0xf bound_ctrl:1
	v_add_f32_dpp v40, v40, v40 row_shl:8 row_mask:0xf bank_mask:0xf bound_ctrl:1
	v_add_f32_dpp v41, v41, v41 row_shl:8 row_mask:0xf bank_mask:0xf bound_ctrl:1
	v_add_f32_dpp v42, v42, v42 row_shl:8 row_mask:0xf bank_mask:0xf bound_ctrl:1
	v_add_f32_dpp v43, v43, v43 row_shl:8 row_mask:0xf bank_mask:0xf bound_ctrl:1
	v_add_f32_dpp v44, v44, v44 row_shl:8 row_mask:0xf bank_mask:0xf bound_ctrl:1
	v_add_f32_dpp v45, v45, v45 row_shl:8 row_mask:0xf bank_mask:0xf bound_ctrl:1
	v_add_f32_dpp v46, v46, v46 row_shl:8 row_mask:0xf bank_mask:0xf bound_ctrl:1
	v_add_f32_dpp v47, v47, v47 row_shl:8 row_mask:0xf bank_mask:0xf bound_ctrl:1
	v_mov_b32_dpp v88, v40 row_newbcast:0 row_mask:0xf bank_mask:0xf
	v_mov_b32_dpp v89, v41 row_newbcast:0 row_mask:0xf bank_mask:0xf
	v_mov_b32_dpp v90, v42 row_newbcast:0 row_mask:0xf bank_mask:0xf
	v_mov_b32_dpp v91, v43 row_newbcast:0 row_mask:0xf bank_mask:0xf
	v_mov_b32_dpp v92, v44 row_newbcast:0 row_mask:0xf bank_mask:0xf
	v_mov_b32_dpp v93, v45 row_newbcast:0 row_mask:0xf bank_mask:0xf
	v_mov_b32_dpp v94, v46 row_newbcast:0 row_mask:0xf bank_mask:0xf
	v_mov_b32_dpp v95, v47 row_newbcast:0 row_mask:0xf bank_mask:0xf
	v_pk_add_f32 v[40:41], v[40:41], v[68:69]
	v_pk_add_f32 v[44:45], v[44:45], v[76:77]
	v_pk_add_f32 v[42:43], v[42:43], v[70:71]
	v_pk_add_f32 v[46:47], v[46:47], v[78:79]
	v_pk_mul_f32 v[132:133], v[40:41], v[150:151]
	v_pk_mul_f32 v[40:41], v[40:41], v[146:147]
	v_pk_fma_f32 v[40:41], v[44:45], v[150:151], v[40:41] neg_lo:[1,0,0] neg_hi:[1,0,0]
	v_pk_fma_f32 v[44:45], v[44:45], v[146:147], v[132:133]
	v_pk_mul_f32 v[132:133], v[42:43], v[152:153]
	v_pk_mul_f32 v[42:43], v[42:43], v[148:149]
	v_pk_fma_f32 v[42:43], v[46:47], v[152:153], v[42:43] neg_lo:[1,0,0] neg_hi:[1,0,0]
	v_pk_fma_f32 v[46:47], v[46:47], v[148:149], v[132:133]
	v_pk_add_f32 v[88:89], v[88:89], v[68:69]
	v_pk_add_f32 v[92:93], v[92:93], v[76:77]
	v_pk_mul_f32 v[132:133], v[92:93], v[158:159]
	v_pk_mul_f32 v[76:77], v[88:89], v[158:159]
	v_pk_fma_f32 v[68:69], v[88:89], v[154:155], v[132:133] neg_lo:[0,0,1] neg_hi:[0,0,1]
	v_pk_fma_f32 v[76:77], v[92:93], v[154:155], v[76:77]
	v_pk_add_f32 v[90:91], v[90:91], v[70:71]
	v_pk_add_f32 v[94:95], v[94:95], v[78:79]
	v_pk_mul_f32 v[132:133], v[94:95], v[160:161]
	v_pk_mul_f32 v[78:79], v[90:91], v[160:161]
	v_pk_fma_f32 v[70:71], v[90:91], v[156:157], v[132:133] neg_lo:[0,0,1] neg_hi:[0,0,1]
	v_pk_fma_f32 v[78:79], v[94:95], v[156:157], v[78:79]
	v_pk_mul_f32 v[132:133], v[32:33], v[142:143]
	v_pk_mul_f32 v[32:33], v[32:33], v[138:139]
	v_pk_fma_f32 v[32:33], v[36:37], v[142:143], v[32:33] neg_lo:[1,0,0] neg_hi:[1,0,0]
	v_pk_fma_f32 v[36:37], v[36:37], v[138:139], v[132:133]
	v_pk_mul_f32 v[132:133], v[34:35], v[144:145]
	v_pk_mul_f32 v[34:35], v[34:35], v[140:141]
	v_pk_fma_f32 v[34:35], v[38:39], v[144:145], v[34:35] neg_lo:[1,0,0] neg_hi:[1,0,0]
	v_pk_fma_f32 v[38:39], v[38:39], v[140:141], v[132:133]
	v_add_f32_dpp v32, v32, v32 row_shl:1 row_mask:0xf bank_mask:0xf bound_ctrl:1
	v_add_f32_dpp v33, v33, v33 row_shl:1 row_mask:0xf bank_mask:0xf bound_ctrl:1
	v_add_f32_dpp v34, v34, v34 row_shl:1 row_mask:0xf bank_mask:0xf bound_ctrl:1
	v_add_f32_dpp v35, v35, v35 row_shl:1 row_mask:0xf bank_mask:0xf bound_ctrl:1
	v_add_f32_dpp v36, v36, v36 row_shl:1 row_mask:0xf bank_mask:0xf bound_ctrl:1
	v_add_f32_dpp v37, v37, v37 row_shl:1 row_mask:0xf bank_mask:0xf bound_ctrl:1
	v_add_f32_dpp v38, v38, v38 row_shl:1 row_mask:0xf bank_mask:0xf bound_ctrl:1
	v_add_f32_dpp v39, v39, v39 row_shl:1 row_mask:0xf bank_mask:0xf bound_ctrl:1
	v_add_f32_dpp v32, v32, v32 row_shl:2 row_mask:0xf bank_mask:0xf bound_ctrl:1
	v_add_f32_dpp v33, v33, v33 row_shl:2 row_mask:0xf bank_mask:0xf bound_ctrl:1
	v_add_f32_dpp v34, v34, v34 row_shl:2 row_mask:0xf bank_mask:0xf bound_ctrl:1
	v_add_f32_dpp v35, v35, v35 row_shl:2 row_mask:0xf bank_mask:0xf bound_ctrl:1
	v_add_f32_dpp v36, v36, v36 row_shl:2 row_mask:0xf bank_mask:0xf bound_ctrl:1
	v_add_f32_dpp v37, v37, v37 row_shl:2 row_mask:0xf bank_mask:0xf bound_ctrl:1
	v_add_f32_dpp v38, v38, v38 row_shl:2 row_mask:0xf bank_mask:0xf bound_ctrl:1
	v_add_f32_dpp v39, v39, v39 row_shl:2 row_mask:0xf bank_mask:0xf bound_ctrl:1
	v_add_f32_dpp v32, v32, v32 row_shl:4 row_mask:0xf bank_mask:0xf bound_ctrl:1
	v_add_f32_dpp v33, v33, v33 row_shl:4 row_mask:0xf bank_mask:0xf bound_ctrl:1
	v_add_f32_dpp v34, v34, v34 row_shl:4 row_mask:0xf bank_mask:0xf bound_ctrl:1
	v_add_f32_dpp v35, v35, v35 row_shl:4 row_mask:0xf bank_mask:0xf bound_ctrl:1
	v_add_f32_dpp v36, v36, v36 row_shl:4 row_mask:0xf bank_mask:0xf bound_ctrl:1
	v_add_f32_dpp v37, v37, v37 row_shl:4 row_mask:0xf bank_mask:0xf bound_ctrl:1
	v_add_f32_dpp v38, v38, v38 row_shl:4 row_mask:0xf bank_mask:0xf bound_ctrl:1
	v_add_f32_dpp v39, v39, v39 row_shl:4 row_mask:0xf bank_mask:0xf bound_ctrl:1
	v_add_f32_dpp v32, v32, v32 row_shl:8 row_mask:0xf bank_mask:0xf bound_ctrl:1
	v_add_f32_dpp v33, v33, v33 row_shl:8 row_mask:0xf bank_mask:0xf bound_ctrl:1
	v_add_f32_dpp v34, v34, v34 row_shl:8 row_mask:0xf bank_mask:0xf bound_ctrl:1
	v_add_f32_dpp v35, v35, v35 row_shl:8 row_mask:0xf bank_mask:0xf bound_ctrl:1
	v_add_f32_dpp v36, v36, v36 row_shl:8 row_mask:0xf bank_mask:0xf bound_ctrl:1
	v_add_f32_dpp v37, v37, v37 row_shl:8 row_mask:0xf bank_mask:0xf bound_ctrl:1
	v_add_f32_dpp v38, v38, v38 row_shl:8 row_mask:0xf bank_mask:0xf bound_ctrl:1
	v_add_f32_dpp v39, v39, v39 row_shl:8 row_mask:0xf bank_mask:0xf bound_ctrl:1
	v_mov_b32_dpp v88, v32 row_newbcast:0 row_mask:0xf bank_mask:0xf
	v_mov_b32_dpp v89, v33 row_newbcast:0 row_mask:0xf bank_mask:0xf
	v_mov_b32_dpp v90, v34 row_newbcast:0 row_mask:0xf bank_mask:0xf
	v_mov_b32_dpp v91, v35 row_newbcast:0 row_mask:0xf bank_mask:0xf
	v_mov_b32_dpp v92, v36 row_newbcast:0 row_mask:0xf bank_mask:0xf
	v_mov_b32_dpp v93, v37 row_newbcast:0 row_mask:0xf bank_mask:0xf
	v_mov_b32_dpp v94, v38 row_newbcast:0 row_mask:0xf bank_mask:0xf
	v_mov_b32_dpp v95, v39 row_newbcast:0 row_mask:0xf bank_mask:0xf
	v_pk_add_f32 v[32:33], v[32:33], v[68:69]
	v_pk_add_f32 v[36:37], v[36:37], v[76:77]
	v_pk_add_f32 v[34:35], v[34:35], v[70:71]
	v_pk_add_f32 v[38:39], v[38:39], v[78:79]
	v_pk_mul_f32 v[132:133], v[32:33], v[150:151]
	v_pk_mul_f32 v[32:33], v[32:33], v[146:147]
	v_pk_fma_f32 v[32:33], v[36:37], v[150:151], v[32:33] neg_lo:[1,0,0] neg_hi:[1,0,0]
	v_pk_fma_f32 v[36:37], v[36:37], v[146:147], v[132:133]
	v_pk_mul_f32 v[132:133], v[34:35], v[152:153]
	v_pk_mul_f32 v[34:35], v[34:35], v[148:149]
	v_pk_fma_f32 v[34:35], v[38:39], v[152:153], v[34:35] neg_lo:[1,0,0] neg_hi:[1,0,0]
	v_pk_fma_f32 v[38:39], v[38:39], v[148:149], v[132:133]
	v_pk_add_f32 v[88:89], v[88:89], v[68:69]
	v_pk_add_f32 v[92:93], v[92:93], v[76:77]
	v_pk_mul_f32 v[132:133], v[92:93], v[158:159]
	v_pk_mul_f32 v[76:77], v[88:89], v[158:159]
	v_pk_fma_f32 v[68:69], v[88:89], v[154:155], v[132:133] neg_lo:[0,0,1] neg_hi:[0,0,1]
	v_pk_fma_f32 v[76:77], v[92:93], v[154:155], v[76:77]
	v_pk_add_f32 v[90:91], v[90:91], v[70:71]
	v_pk_add_f32 v[94:95], v[94:95], v[78:79]
	v_pk_mul_f32 v[132:133], v[94:95], v[160:161]
	v_pk_mul_f32 v[78:79], v[90:91], v[160:161]
	v_pk_fma_f32 v[70:71], v[90:91], v[156:157], v[132:133] neg_lo:[0,0,1] neg_hi:[0,0,1]
	v_pk_fma_f32 v[78:79], v[94:95], v[156:157], v[78:79]
	s_waitcnt vmcnt(12)
	v_cvt_pk_bf16_f32 v96, v32, v33
	v_cvt_pk_bf16_f32 v97, v34, v35
	v_cvt_pk_bf16_f32 v98, v36, v37
	v_cvt_pk_bf16_f32 v99, v38, v39
	s_nop 1
	v_mfma_f32_16x16x32_bf16 v[16:19], v[80:83], v[96:99], v[16:19]
	v_cvt_pk_bf16_f32 v96, v40, v41
	v_cvt_pk_bf16_f32 v97, v42, v43
	v_cvt_pk_bf16_f32 v98, v44, v45
	v_cvt_pk_bf16_f32 v99, v46, v47
	s_nop 1
	v_mfma_f32_16x16x32_bf16 v[20:23], v[80:83], v[96:99], v[20:23]
	v_cvt_pk_bf16_f32 v96, v48, v49
	v_cvt_pk_bf16_f32 v97, v50, v51
	v_cvt_pk_bf16_f32 v98, v52, v53
	v_cvt_pk_bf16_f32 v99, v54, v55
	s_nop 1
	v_mfma_f32_16x16x32_bf16 v[24:27], v[80:83], v[96:99], v[24:27]
	v_cvt_pk_bf16_f32 v96, v56, v57
	v_cvt_pk_bf16_f32 v97, v58, v59
	v_cvt_pk_bf16_f32 v98, v60, v61
	v_cvt_pk_bf16_f32 v99, v62, v63
	s_nop 1
	v_mfma_f32_16x16x32_bf16 v[28:31], v[80:83], v[96:99], v[28:31]
	s_waitcnt vmcnt(10)
	global_load_dwordx4 v[80:83], v134, s[38:39]
	s_add_u32 s38, s38, 0x400
	s_addc_u32 s39, s39, 0
	v_mfma_f32_16x16x32_bf16 v[32:35], v[64:67], v[0:3], 0
	v_mfma_f32_16x16x32_bf16 v[36:39], v[72:75], v[0:3], 0
	v_mfma_f32_16x16x32_bf16 v[40:43], v[64:67], v[4:7], 0
	v_mfma_f32_16x16x32_bf16 v[44:47], v[72:75], v[4:7], 0
	v_mfma_f32_16x16x32_bf16 v[48:51], v[64:67], v[8:11], 0
	v_mfma_f32_16x16x32_bf16 v[52:55], v[72:75], v[8:11], 0
	v_mfma_f32_16x16x32_bf16 v[56:59], v[64:67], v[12:15], 0
	v_mfma_f32_16x16x32_bf16 v[60:63], v[72:75], v[12:15], 0
	global_load_dwordx4 v[64:67], v134, s[20:21]
	global_load_dwordx4 v[72:75], v134, s[20:21] offset:1024
	s_add_u32 s20, s20, 0x800
	s_addc_u32 s21, s21, 0
	global_load_dwordx4 v[138:141], v134, s[42:43] offset:0
	global_load_dwordx4 v[142:145], v134, s[42:43] offset:1024
	global_load_dwordx4 v[146:149], v134, s[42:43] offset:2048
	global_load_dwordx4 v[150:153], v134, s[42:43] offset:3072
	global_load_dwordx4 v[154:157], v208, s[42:43] offset:0
	global_load_dwordx4 v[158:161], v208, s[42:43] offset:1024
	global_load_dwordx4 v[162:165], v208, s[42:43] offset:2048
	global_load_dwordx4 v[166:169], v208, s[42:43] offset:3072
	global_load_dwordx4 v[170:173], v206, s[44:45]
	global_load_dwordx4 v[174:177], v206, s[44:45] offset:16
	s_add_u32 s42, s42, 0x2000
	s_addc_u32 s43, s43, 0
	s_add_u32 s44, s44, 0x80
	s_addc_u32 s45, s45, 0
	s_waitcnt vmcnt(13)
	v_mul_f32_e32 v132, v179, v128
	v_mul_f32_e32 v133, v178, v128
	v_fma_f32 v68, v178, v124, -v132
	v_fma_f32 v76, v179, v124, v133
	v_mul_f32_e32 v132, v181, v129
	v_mul_f32_e32 v133, v180, v129
	v_fma_f32 v69, v180, v125, -v132
	v_fma_f32 v77, v181, v125, v133
	v_mul_f32_e32 v132, v183, v130
	v_mul_f32_e32 v133, v182, v130
	v_fma_f32 v70, v182, v126, -v132
	v_fma_f32 v78, v183, v126, v133
	v_mul_f32_e32 v132, v185, v131
	v_mul_f32_e32 v133, v184, v131
	v_fma_f32 v71, v184, v127, -v132
	v_fma_f32 v79, v185, v127, v133
	v_pk_mul_f32 v[132:133], v[56:57], v[104:105]
	v_pk_mul_f32 v[56:57], v[56:57], v[100:101]
	v_pk_fma_f32 v[56:57], v[60:61], v[104:105], v[56:57] neg_lo:[1,0,0] neg_hi:[1,0,0]
	v_pk_fma_f32 v[60:61], v[60:61], v[100:101], v[132:133]
	v_pk_mul_f32 v[132:133], v[58:59], v[106:107]
	v_pk_mul_f32 v[58:59], v[58:59], v[102:103]
	v_pk_fma_f32 v[58:59], v[62:63], v[106:107], v[58:59] neg_lo:[1,0,0] neg_hi:[1,0,0]
	v_pk_fma_f32 v[62:63], v[62:63], v[102:103], v[132:133]
	v_add_f32_dpp v56, v56, v56 row_shl:1 row_mask:0xf bank_mask:0xf bound_ctrl:1
	v_add_f32_dpp v57, v57, v57 row_shl:1 row_mask:0xf bank_mask:0xf bound_ctrl:1
	v_add_f32_dpp v58, v58, v58 row_shl:1 row_mask:0xf bank_mask:0xf bound_ctrl:1
	v_add_f32_dpp v59, v59, v59 row_shl:1 row_mask:0xf bank_mask:0xf bound_ctrl:1
	v_add_f32_dpp v60, v60, v60 row_shl:1 row_mask:0xf bank_mask:0xf bound_ctrl:1
	v_add_f32_dpp v61, v61, v61 row_shl:1 row_mask:0xf bank_mask:0xf bound_ctrl:1
	v_add_f32_dpp v62, v62, v62 row_shl:1 row_mask:0xf bank_mask:0xf bound_ctrl:1
	v_add_f32_dpp v63, v63, v63 row_shl:1 row_mask:0xf bank_mask:0xf bound_ctrl:1
	v_add_f32_dpp v56, v56, v56 row_shl:2 row_mask:0xf bank_mask:0xf bound_ctrl:1
	v_add_f32_dpp v57, v57, v57 row_shl:2 row_mask:0xf bank_mask:0xf bound_ctrl:1
	v_add_f32_dpp v58, v58, v58 row_shl:2 row_mask:0xf bank_mask:0xf bound_ctrl:1
	v_add_f32_dpp v59, v59, v59 row_shl:2 row_mask:0xf bank_mask:0xf bound_ctrl:1
	v_add_f32_dpp v60, v60, v60 row_shl:2 row_mask:0xf bank_mask:0xf bound_ctrl:1
	v_add_f32_dpp v61, v61, v61 row_shl:2 row_mask:0xf bank_mask:0xf bound_ctrl:1
	v_add_f32_dpp v62, v62, v62 row_shl:2 row_mask:0xf bank_mask:0xf bound_ctrl:1
	v_add_f32_dpp v63, v63, v63 row_shl:2 row_mask:0xf bank_mask:0xf bound_ctrl:1
	v_add_f32_dpp v56, v56, v56 row_shl:4 row_mask:0xf bank_mask:0xf bound_ctrl:1
	v_add_f32_dpp v57, v57, v57 row_shl:4 row_mask:0xf bank_mask:0xf bound_ctrl:1
	v_add_f32_dpp v58, v58, v58 row_shl:4 row_mask:0xf bank_mask:0xf bound_ctrl:1
	v_add_f32_dpp v59, v59, v59 row_shl:4 row_mask:0xf bank_mask:0xf bound_ctrl:1
	v_add_f32_dpp v60, v60, v60 row_shl:4 row_mask:0xf bank_mask:0xf bound_ctrl:1
	v_add_f32_dpp v61, v61, v61 row_shl:4 row_mask:0xf bank_mask:0xf bound_ctrl:1
	v_add_f32_dpp v62, v62, v62 row_shl:4 row_mask:0xf bank_mask:0xf bound_ctrl:1
	v_add_f32_dpp v63, v63, v63 row_shl:4 row_mask:0xf bank_mask:0xf bound_ctrl:1
	v_add_f32_dpp v56, v56, v56 row_shl:8 row_mask:0xf bank_mask:0xf bound_ctrl:1
	v_add_f32_dpp v57, v57, v57 row_shl:8 row_mask:0xf bank_mask:0xf bound_ctrl:1
	v_add_f32_dpp v58, v58, v58 row_shl:8 row_mask:0xf bank_mask:0xf bound_ctrl:1
	v_add_f32_dpp v59, v59, v59 row_shl:8 row_mask:0xf bank_mask:0xf bound_ctrl:1
	v_add_f32_dpp v60, v60, v60 row_shl:8 row_mask:0xf bank_mask:0xf bound_ctrl:1
	v_add_f32_dpp v61, v61, v61 row_shl:8 row_mask:0xf bank_mask:0xf bound_ctrl:1
	v_add_f32_dpp v62, v62, v62 row_shl:8 row_mask:0xf bank_mask:0xf bound_ctrl:1
	v_add_f32_dpp v63, v63, v63 row_shl:8 row_mask:0xf bank_mask:0xf bound_ctrl:1
	v_mov_b32_dpp v88, v56 row_newbcast:0 row_mask:0xf bank_mask:0xf
	v_mov_b32_dpp v89, v57 row_newbcast:0 row_mask:0xf bank_mask:0xf
	v_mov_b32_dpp v90, v58 row_newbcast:0 row_mask:0xf bank_mask:0xf
	v_mov_b32_dpp v91, v59 row_newbcast:0 row_mask:0xf bank_mask:0xf
	v_mov_b32_dpp v92, v60 row_newbcast:0 row_mask:0xf bank_mask:0xf
	v_mov_b32_dpp v93, v61 row_newbcast:0 row_mask:0xf bank_mask:0xf
	v_mov_b32_dpp v94, v62 row_newbcast:0 row_mask:0xf bank_mask:0xf
	v_mov_b32_dpp v95, v63 row_newbcast:0 row_mask:0xf bank_mask:0xf
	v_pk_add_f32 v[56:57], v[56:57], v[68:69]
	v_pk_add_f32 v[60:61], v[60:61], v[76:77]
	v_pk_add_f32 v[58:59], v[58:59], v[70:71]
	v_pk_add_f32 v[62:63], v[62:63], v[78:79]
	v_pk_mul_f32 v[132:133], v[56:57], v[112:113]
	v_pk_mul_f32 v[56:57], v[56:57], v[108:109]
	v_pk_fma_f32 v[56:57], v[60:61], v[112:113], v[56:57] neg_lo:[1,0,0] neg_hi:[1,0,0]
	v_pk_fma_f32 v[60:61], v[60:61], v[108:109], v[132:133]
	v_pk_mul_f32 v[132:133], v[58:59], v[114:115]
	v_pk_mul_f32 v[58:59], v[58:59], v[110:111]
	v_pk_fma_f32 v[58:59], v[62:63], v[114:115], v[58:59] neg_lo:[1,0,0] neg_hi:[1,0,0]
	v_pk_fma_f32 v[62:63], v[62:63], v[110:111], v[132:133]
	v_pk_add_f32 v[88:89], v[88:89], v[68:69]
	v_pk_add_f32 v[92:93], v[92:93], v[76:77]
	v_pk_mul_f32 v[132:133], v[92:93], v[120:121]
	v_pk_mul_f32 v[76:77], v[88:89], v[120:121]
	v_pk_fma_f32 v[68:69], v[88:89], v[116:117], v[132:133] neg_lo:[0,0,1] neg_hi:[0,0,1]
	v_pk_fma_f32 v[76:77], v[92:93], v[116:117], v[76:77]
	v_pk_add_f32 v[90:91], v[90:91], v[70:71]
	v_pk_add_f32 v[94:95], v[94:95], v[78:79]
	v_pk_mul_f32 v[132:133], v[94:95], v[122:123]
	v_pk_mul_f32 v[78:79], v[90:91], v[122:123]
	v_pk_fma_f32 v[70:71], v[90:91], v[118:119], v[132:133] neg_lo:[0,0,1] neg_hi:[0,0,1]
	v_pk_fma_f32 v[78:79], v[94:95], v[118:119], v[78:79]
	v_pk_mul_f32 v[132:133], v[48:49], v[104:105]
	v_pk_mul_f32 v[48:49], v[48:49], v[100:101]
	v_pk_fma_f32 v[48:49], v[52:53], v[104:105], v[48:49] neg_lo:[1,0,0] neg_hi:[1,0,0]
	v_pk_fma_f32 v[52:53], v[52:53], v[100:101], v[132:133]
	v_pk_mul_f32 v[132:133], v[50:51], v[106:107]
	v_pk_mul_f32 v[50:51], v[50:51], v[102:103]
	v_pk_fma_f32 v[50:51], v[54:55], v[106:107], v[50:51] neg_lo:[1,0,0] neg_hi:[1,0,0]
	v_pk_fma_f32 v[54:55], v[54:55], v[102:103], v[132:133]
	v_add_f32_dpp v48, v48, v48 row_shl:1 row_mask:0xf bank_mask:0xf bound_ctrl:1
	v_add_f32_dpp v49, v49, v49 row_shl:1 row_mask:0xf bank_mask:0xf bound_ctrl:1
	v_add_f32_dpp v50, v50, v50 row_shl:1 row_mask:0xf bank_mask:0xf bound_ctrl:1
	v_add_f32_dpp v51, v51, v51 row_shl:1 row_mask:0xf bank_mask:0xf bound_ctrl:1
	v_add_f32_dpp v52, v52, v52 row_shl:1 row_mask:0xf bank_mask:0xf bound_ctrl:1
	v_add_f32_dpp v53, v53, v53 row_shl:1 row_mask:0xf bank_mask:0xf bound_ctrl:1
	v_add_f32_dpp v54, v54, v54 row_shl:1 row_mask:0xf bank_mask:0xf bound_ctrl:1
	v_add_f32_dpp v55, v55, v55 row_shl:1 row_mask:0xf bank_mask:0xf bound_ctrl:1
	v_add_f32_dpp v48, v48, v48 row_shl:2 row_mask:0xf bank_mask:0xf bound_ctrl:1
	v_add_f32_dpp v49, v49, v49 row_shl:2 row_mask:0xf bank_mask:0xf bound_ctrl:1
	v_add_f32_dpp v50, v50, v50 row_shl:2 row_mask:0xf bank_mask:0xf bound_ctrl:1
	v_add_f32_dpp v51, v51, v51 row_shl:2 row_mask:0xf bank_mask:0xf bound_ctrl:1
	v_add_f32_dpp v52, v52, v52 row_shl:2 row_mask:0xf bank_mask:0xf bound_ctrl:1
	v_add_f32_dpp v53, v53, v53 row_shl:2 row_mask:0xf bank_mask:0xf bound_ctrl:1
	v_add_f32_dpp v54, v54, v54 row_shl:2 row_mask:0xf bank_mask:0xf bound_ctrl:1
	v_add_f32_dpp v55, v55, v55 row_shl:2 row_mask:0xf bank_mask:0xf bound_ctrl:1
	v_add_f32_dpp v48, v48, v48 row_shl:4 row_mask:0xf bank_mask:0xf bound_ctrl:1
	v_add_f32_dpp v49, v49, v49 row_shl:4 row_mask:0xf bank_mask:0xf bound_ctrl:1
	v_add_f32_dpp v50, v50, v50 row_shl:4 row_mask:0xf bank_mask:0xf bound_ctrl:1
	v_add_f32_dpp v51, v51, v51 row_shl:4 row_mask:0xf bank_mask:0xf bound_ctrl:1
	v_add_f32_dpp v52, v52, v52 row_shl:4 row_mask:0xf bank_mask:0xf bound_ctrl:1
	v_add_f32_dpp v53, v53, v53 row_shl:4 row_mask:0xf bank_mask:0xf bound_ctrl:1
	v_add_f32_dpp v54, v54, v54 row_shl:4 row_mask:0xf bank_mask:0xf bound_ctrl:1
	v_add_f32_dpp v55, v55, v55 row_shl:4 row_mask:0xf bank_mask:0xf bound_ctrl:1
	v_add_f32_dpp v48, v48, v48 row_shl:8 row_mask:0xf bank_mask:0xf bound_ctrl:1
	v_add_f32_dpp v49, v49, v49 row_shl:8 row_mask:0xf bank_mask:0xf bound_ctrl:1
	v_add_f32_dpp v50, v50, v50 row_shl:8 row_mask:0xf bank_mask:0xf bound_ctrl:1
	v_add_f32_dpp v51, v51, v51 row_shl:8 row_mask:0xf bank_mask:0xf bound_ctrl:1
	v_add_f32_dpp v52, v52, v52 row_shl:8 row_mask:0xf bank_mask:0xf bound_ctrl:1
	v_add_f32_dpp v53, v53, v53 row_shl:8 row_mask:0xf bank_mask:0xf bound_ctrl:1
	v_add_f32_dpp v54, v54, v54 row_shl:8 row_mask:0xf bank_mask:0xf bound_ctrl:1
	v_add_f32_dpp v55, v55, v55 row_shl:8 row_mask:0xf bank_mask:0xf bound_ctrl:1
	v_mov_b32_dpp v88, v48 row_newbcast:0 row_mask:0xf bank_mask:0xf
	v_mov_b32_dpp v89, v49 row_newbcast:0 row_mask:0xf bank_mask:0xf
	v_mov_b32_dpp v90, v50 row_newbcast:0 row_mask:0xf bank_mask:0xf
	v_mov_b32_dpp v91, v51 row_newbcast:0 row_mask:0xf bank_mask:0xf
	v_mov_b32_dpp v92, v52 row_newbcast:0 row_mask:0xf bank_mask:0xf
	v_mov_b32_dpp v93, v53 row_newbcast:0 row_mask:0xf bank_mask:0xf
	v_mov_b32_dpp v94, v54 row_newbcast:0 row_mask:0xf bank_mask:0xf
	v_mov_b32_dpp v95, v55 row_newbcast:0 row_mask:0xf bank_mask:0xf
	v_pk_add_f32 v[48:49], v[48:49], v[68:69]
	v_pk_add_f32 v[52:53], v[52:53], v[76:77]
	v_pk_add_f32 v[50:51], v[50:51], v[70:71]
	v_pk_add_f32 v[54:55], v[54:55], v[78:79]
	v_pk_mul_f32 v[132:133], v[48:49], v[112:113]
	v_pk_mul_f32 v[48:49], v[48:49], v[108:109]
	v_pk_fma_f32 v[48:49], v[52:53], v[112:113], v[48:49] neg_lo:[1,0,0] neg_hi:[1,0,0]
	v_pk_fma_f32 v[52:53], v[52:53], v[108:109], v[132:133]
	v_pk_mul_f32 v[132:133], v[50:51], v[114:115]
	v_pk_mul_f32 v[50:51], v[50:51], v[110:111]
	v_pk_fma_f32 v[50:51], v[54:55], v[114:115], v[50:51] neg_lo:[1,0,0] neg_hi:[1,0,0]
	v_pk_fma_f32 v[54:55], v[54:55], v[110:111], v[132:133]
	v_pk_add_f32 v[88:89], v[88:89], v[68:69]
	v_pk_add_f32 v[92:93], v[92:93], v[76:77]
	v_pk_mul_f32 v[132:133], v[92:93], v[120:121]
	v_pk_mul_f32 v[76:77], v[88:89], v[120:121]
	v_pk_fma_f32 v[68:69], v[88:89], v[116:117], v[132:133] neg_lo:[0,0,1] neg_hi:[0,0,1]
	v_pk_fma_f32 v[76:77], v[92:93], v[116:117], v[76:77]
	v_pk_add_f32 v[90:91], v[90:91], v[70:71]
	v_pk_add_f32 v[94:95], v[94:95], v[78:79]
	v_pk_mul_f32 v[132:133], v[94:95], v[122:123]
	v_pk_mul_f32 v[78:79], v[90:91], v[122:123]
	v_pk_fma_f32 v[70:71], v[90:91], v[118:119], v[132:133] neg_lo:[0,0,1] neg_hi:[0,0,1]
	v_pk_fma_f32 v[78:79], v[94:95], v[118:119], v[78:79]
	v_pk_mul_f32 v[132:133], v[40:41], v[104:105]
	v_pk_mul_f32 v[40:41], v[40:41], v[100:101]
	v_pk_fma_f32 v[40:41], v[44:45], v[104:105], v[40:41] neg_lo:[1,0,0] neg_hi:[1,0,0]
	v_pk_fma_f32 v[44:45], v[44:45], v[100:101], v[132:133]
	v_pk_mul_f32 v[132:133], v[42:43], v[106:107]
	v_pk_mul_f32 v[42:43], v[42:43], v[102:103]
	v_pk_fma_f32 v[42:43], v[46:47], v[106:107], v[42:43] neg_lo:[1,0,0] neg_hi:[1,0,0]
	v_pk_fma_f32 v[46:47], v[46:47], v[102:103], v[132:133]
	v_add_f32_dpp v40, v40, v40 row_shl:1 row_mask:0xf bank_mask:0xf bound_ctrl:1
	v_add_f32_dpp v41, v41, v41 row_shl:1 row_mask:0xf bank_mask:0xf bound_ctrl:1
	v_add_f32_dpp v42, v42, v42 row_shl:1 row_mask:0xf bank_mask:0xf bound_ctrl:1
	v_add_f32_dpp v43, v43, v43 row_shl:1 row_mask:0xf bank_mask:0xf bound_ctrl:1
	v_add_f32_dpp v44, v44, v44 row_shl:1 row_mask:0xf bank_mask:0xf bound_ctrl:1
	v_add_f32_dpp v45, v45, v45 row_shl:1 row_mask:0xf bank_mask:0xf bound_ctrl:1
	v_add_f32_dpp v46, v46, v46 row_shl:1 row_mask:0xf bank_mask:0xf bound_ctrl:1
	v_add_f32_dpp v47, v47, v47 row_shl:1 row_mask:0xf bank_mask:0xf bound_ctrl:1
	v_add_f32_dpp v40, v40, v40 row_shl:2 row_mask:0xf bank_mask:0xf bound_ctrl:1
	v_add_f32_dpp v41, v41, v41 row_shl:2 row_mask:0xf bank_mask:0xf bound_ctrl:1
	v_add_f32_dpp v42, v42, v42 row_shl:2 row_mask:0xf bank_mask:0xf bound_ctrl:1
	v_add_f32_dpp v43, v43, v43 row_shl:2 row_mask:0xf bank_mask:0xf bound_ctrl:1
	v_add_f32_dpp v44, v44, v44 row_shl:2 row_mask:0xf bank_mask:0xf bound_ctrl:1
	v_add_f32_dpp v45, v45, v45 row_shl:2 row_mask:0xf bank_mask:0xf bound_ctrl:1
	v_add_f32_dpp v46, v46, v46 row_shl:2 row_mask:0xf bank_mask:0xf bound_ctrl:1
	v_add_f32_dpp v47, v47, v47 row_shl:2 row_mask:0xf bank_mask:0xf bound_ctrl:1
	v_add_f32_dpp v40, v40, v40 row_shl:4 row_mask:0xf bank_mask:0xf bound_ctrl:1
	v_add_f32_dpp v41, v41, v41 row_shl:4 row_mask:0xf bank_mask:0xf bound_ctrl:1
	v_add_f32_dpp v42, v42, v42 row_shl:4 row_mask:0xf bank_mask:0xf bound_ctrl:1
	v_add_f32_dpp v43, v43, v43 row_shl:4 row_mask:0xf bank_mask:0xf bound_ctrl:1
	v_add_f32_dpp v44, v44, v44 row_shl:4 row_mask:0xf bank_mask:0xf bound_ctrl:1
	v_add_f32_dpp v45, v45, v45 row_shl:4 row_mask:0xf bank_mask:0xf bound_ctrl:1
	v_add_f32_dpp v46, v46, v46 row_shl:4 row_mask:0xf bank_mask:0xf bound_ctrl:1
	v_add_f32_dpp v47, v47, v47 row_shl:4 row_mask:0xf bank_mask:0xf bound_ctrl:1
	v_add_f32_dpp v40, v40, v40 row_shl:8 row_mask:0xf bank_mask:0xf bound_ctrl:1
	v_add_f32_dpp v41, v41, v41 row_shl:8 row_mask:0xf bank_mask:0xf bound_ctrl:1
	v_add_f32_dpp v42, v42, v42 row_shl:8 row_mask:0xf bank_mask:0xf bound_ctrl:1
	v_add_f32_dpp v43, v43, v43 row_shl:8 row_mask:0xf bank_mask:0xf bound_ctrl:1
	v_add_f32_dpp v44, v44, v44 row_shl:8 row_mask:0xf bank_mask:0xf bound_ctrl:1
	v_add_f32_dpp v45, v45, v45 row_shl:8 row_mask:0xf bank_mask:0xf bound_ctrl:1
	v_add_f32_dpp v46, v46, v46 row_shl:8 row_mask:0xf bank_mask:0xf bound_ctrl:1
	v_add_f32_dpp v47, v47, v47 row_shl:8 row_mask:0xf bank_mask:0xf bound_ctrl:1
	v_mov_b32_dpp v88, v40 row_newbcast:0 row_mask:0xf bank_mask:0xf
	v_mov_b32_dpp v89, v41 row_newbcast:0 row_mask:0xf bank_mask:0xf
	v_mov_b32_dpp v90, v42 row_newbcast:0 row_mask:0xf bank_mask:0xf
	v_mov_b32_dpp v91, v43 row_newbcast:0 row_mask:0xf bank_mask:0xf
	v_mov_b32_dpp v92, v44 row_newbcast:0 row_mask:0xf bank_mask:0xf
	v_mov_b32_dpp v93, v45 row_newbcast:0 row_mask:0xf bank_mask:0xf
	v_mov_b32_dpp v94, v46 row_newbcast:0 row_mask:0xf bank_mask:0xf
	v_mov_b32_dpp v95, v47 row_newbcast:0 row_mask:0xf bank_mask:0xf
	v_pk_add_f32 v[40:41], v[40:41], v[68:69]
	v_pk_add_f32 v[44:45], v[44:45], v[76:77]
	v_pk_add_f32 v[42:43], v[42:43], v[70:71]
	v_pk_add_f32 v[46:47], v[46:47], v[78:79]
	v_pk_mul_f32 v[132:133], v[40:41], v[112:113]
	v_pk_mul_f32 v[40:41], v[40:41], v[108:109]
	v_pk_fma_f32 v[40:41], v[44:45], v[112:113], v[40:41] neg_lo:[1,0,0] neg_hi:[1,0,0]
	v_pk_fma_f32 v[44:45], v[44:45], v[108:109], v[132:133]
	v_pk_mul_f32 v[132:133], v[42:43], v[114:115]
	v_pk_mul_f32 v[42:43], v[42:43], v[110:111]
	v_pk_fma_f32 v[42:43], v[46:47], v[114:115], v[42:43] neg_lo:[1,0,0] neg_hi:[1,0,0]
	v_pk_fma_f32 v[46:47], v[46:47], v[110:111], v[132:133]
	v_pk_add_f32 v[88:89], v[88:89], v[68:69]
	v_pk_add_f32 v[92:93], v[92:93], v[76:77]
	v_pk_mul_f32 v[132:133], v[92:93], v[120:121]
	v_pk_mul_f32 v[76:77], v[88:89], v[120:121]
	v_pk_fma_f32 v[68:69], v[88:89], v[116:117], v[132:133] neg_lo:[0,0,1] neg_hi:[0,0,1]
	v_pk_fma_f32 v[76:77], v[92:93], v[116:117], v[76:77]
	v_pk_add_f32 v[90:91], v[90:91], v[70:71]
	v_pk_add_f32 v[94:95], v[94:95], v[78:79]
	v_pk_mul_f32 v[132:133], v[94:95], v[122:123]
	v_pk_mul_f32 v[78:79], v[90:91], v[122:123]
	v_pk_fma_f32 v[70:71], v[90:91], v[118:119], v[132:133] neg_lo:[0,0,1] neg_hi:[0,0,1]
	v_pk_fma_f32 v[78:79], v[94:95], v[118:119], v[78:79]
	v_pk_mul_f32 v[132:133], v[32:33], v[104:105]
	v_pk_mul_f32 v[32:33], v[32:33], v[100:101]
	v_pk_fma_f32 v[32:33], v[36:37], v[104:105], v[32:33] neg_lo:[1,0,0] neg_hi:[1,0,0]
	v_pk_fma_f32 v[36:37], v[36:37], v[100:101], v[132:133]
	v_pk_mul_f32 v[132:133], v[34:35], v[106:107]
	v_pk_mul_f32 v[34:35], v[34:35], v[102:103]
	v_pk_fma_f32 v[34:35], v[38:39], v[106:107], v[34:35] neg_lo:[1,0,0] neg_hi:[1,0,0]
	v_pk_fma_f32 v[38:39], v[38:39], v[102:103], v[132:133]
	v_add_f32_dpp v32, v32, v32 row_shl:1 row_mask:0xf bank_mask:0xf bound_ctrl:1
	v_add_f32_dpp v33, v33, v33 row_shl:1 row_mask:0xf bank_mask:0xf bound_ctrl:1
	v_add_f32_dpp v34, v34, v34 row_shl:1 row_mask:0xf bank_mask:0xf bound_ctrl:1
	v_add_f32_dpp v35, v35, v35 row_shl:1 row_mask:0xf bank_mask:0xf bound_ctrl:1
	v_add_f32_dpp v36, v36, v36 row_shl:1 row_mask:0xf bank_mask:0xf bound_ctrl:1
	v_add_f32_dpp v37, v37, v37 row_shl:1 row_mask:0xf bank_mask:0xf bound_ctrl:1
	v_add_f32_dpp v38, v38, v38 row_shl:1 row_mask:0xf bank_mask:0xf bound_ctrl:1
	v_add_f32_dpp v39, v39, v39 row_shl:1 row_mask:0xf bank_mask:0xf bound_ctrl:1
	v_add_f32_dpp v32, v32, v32 row_shl:2 row_mask:0xf bank_mask:0xf bound_ctrl:1
	v_add_f32_dpp v33, v33, v33 row_shl:2 row_mask:0xf bank_mask:0xf bound_ctrl:1
	v_add_f32_dpp v34, v34, v34 row_shl:2 row_mask:0xf bank_mask:0xf bound_ctrl:1
	v_add_f32_dpp v35, v35, v35 row_shl:2 row_mask:0xf bank_mask:0xf bound_ctrl:1
	v_add_f32_dpp v36, v36, v36 row_shl:2 row_mask:0xf bank_mask:0xf bound_ctrl:1
	v_add_f32_dpp v37, v37, v37 row_shl:2 row_mask:0xf bank_mask:0xf bound_ctrl:1
	v_add_f32_dpp v38, v38, v38 row_shl:2 row_mask:0xf bank_mask:0xf bound_ctrl:1
	v_add_f32_dpp v39, v39, v39 row_shl:2 row_mask:0xf bank_mask:0xf bound_ctrl:1
	v_add_f32_dpp v32, v32, v32 row_shl:4 row_mask:0xf bank_mask:0xf bound_ctrl:1
	v_add_f32_dpp v33, v33, v33 row_shl:4 row_mask:0xf bank_mask:0xf bound_ctrl:1
	v_add_f32_dpp v34, v34, v34 row_shl:4 row_mask:0xf bank_mask:0xf bound_ctrl:1
	v_add_f32_dpp v35, v35, v35 row_shl:4 row_mask:0xf bank_mask:0xf bound_ctrl:1
	v_add_f32_dpp v36, v36, v36 row_shl:4 row_mask:0xf bank_mask:0xf bound_ctrl:1
	v_add_f32_dpp v37, v37, v37 row_shl:4 row_mask:0xf bank_mask:0xf bound_ctrl:1
	v_add_f32_dpp v38, v38, v38 row_shl:4 row_mask:0xf bank_mask:0xf bound_ctrl:1
	v_add_f32_dpp v39, v39, v39 row_shl:4 row_mask:0xf bank_mask:0xf bound_ctrl:1
	v_add_f32_dpp v32, v32, v32 row_shl:8 row_mask:0xf bank_mask:0xf bound_ctrl:1
	v_add_f32_dpp v33, v33, v33 row_shl:8 row_mask:0xf bank_mask:0xf bound_ctrl:1
	v_add_f32_dpp v34, v34, v34 row_shl:8 row_mask:0xf bank_mask:0xf bound_ctrl:1
	v_add_f32_dpp v35, v35, v35 row_shl:8 row_mask:0xf bank_mask:0xf bound_ctrl:1
	v_add_f32_dpp v36, v36, v36 row_shl:8 row_mask:0xf bank_mask:0xf bound_ctrl:1
	v_add_f32_dpp v37, v37, v37 row_shl:8 row_mask:0xf bank_mask:0xf bound_ctrl:1
	v_add_f32_dpp v38, v38, v38 row_shl:8 row_mask:0xf bank_mask:0xf bound_ctrl:1
	v_add_f32_dpp v39, v39, v39 row_shl:8 row_mask:0xf bank_mask:0xf bound_ctrl:1
	v_mov_b32_dpp v88, v32 row_newbcast:0 row_mask:0xf bank_mask:0xf
	v_mov_b32_dpp v89, v33 row_newbcast:0 row_mask:0xf bank_mask:0xf
	v_mov_b32_dpp v90, v34 row_newbcast:0 row_mask:0xf bank_mask:0xf
	v_mov_b32_dpp v91, v35 row_newbcast:0 row_mask:0xf bank_mask:0xf
	v_mov_b32_dpp v92, v36 row_newbcast:0 row_mask:0xf bank_mask:0xf
	v_mov_b32_dpp v93, v37 row_newbcast:0 row_mask:0xf bank_mask:0xf
	v_mov_b32_dpp v94, v38 row_newbcast:0 row_mask:0xf bank_mask:0xf
	v_mov_b32_dpp v95, v39 row_newbcast:0 row_mask:0xf bank_mask:0xf
	v_pk_add_f32 v[32:33], v[32:33], v[68:69]
	v_pk_add_f32 v[36:37], v[36:37], v[76:77]
	v_pk_add_f32 v[34:35], v[34:35], v[70:71]
	v_pk_add_f32 v[38:39], v[38:39], v[78:79]
	v_pk_mul_f32 v[132:133], v[32:33], v[112:113]
	v_pk_mul_f32 v[32:33], v[32:33], v[108:109]
	v_pk_fma_f32 v[32:33], v[36:37], v[112:113], v[32:33] neg_lo:[1,0,0] neg_hi:[1,0,0]
	v_pk_fma_f32 v[36:37], v[36:37], v[108:109], v[132:133]
	v_pk_mul_f32 v[132:133], v[34:35], v[114:115]
	v_pk_mul_f32 v[34:35], v[34:35], v[110:111]
	v_pk_fma_f32 v[34:35], v[38:39], v[114:115], v[34:35] neg_lo:[1,0,0] neg_hi:[1,0,0]
	v_pk_fma_f32 v[38:39], v[38:39], v[110:111], v[132:133]
	v_pk_add_f32 v[88:89], v[88:89], v[68:69]
	v_pk_add_f32 v[92:93], v[92:93], v[76:77]
	v_pk_mul_f32 v[132:133], v[92:93], v[120:121]
	v_pk_mul_f32 v[76:77], v[88:89], v[120:121]
	v_pk_fma_f32 v[68:69], v[88:89], v[116:117], v[132:133] neg_lo:[0,0,1] neg_hi:[0,0,1]
	v_pk_fma_f32 v[76:77], v[92:93], v[116:117], v[76:77]
	v_pk_add_f32 v[90:91], v[90:91], v[70:71]
	v_pk_add_f32 v[94:95], v[94:95], v[78:79]
	v_pk_mul_f32 v[132:133], v[94:95], v[122:123]
	v_pk_mul_f32 v[78:79], v[90:91], v[122:123]
	v_pk_fma_f32 v[70:71], v[90:91], v[118:119], v[132:133] neg_lo:[0,0,1] neg_hi:[0,0,1]
	v_pk_fma_f32 v[78:79], v[94:95], v[118:119], v[78:79]
	s_waitcnt vmcnt(12)
	v_cvt_pk_bf16_f32 v96, v32, v33
	v_cvt_pk_bf16_f32 v97, v34, v35
	v_cvt_pk_bf16_f32 v98, v36, v37
	v_cvt_pk_bf16_f32 v99, v38, v39
	s_nop 1
	v_mfma_f32_16x16x32_bf16 v[16:19], v[80:83], v[96:99], v[16:19]
	v_cvt_pk_bf16_f32 v96, v40, v41
	v_cvt_pk_bf16_f32 v97, v42, v43
	v_cvt_pk_bf16_f32 v98, v44, v45
	v_cvt_pk_bf16_f32 v99, v46, v47
	s_nop 1
	v_mfma_f32_16x16x32_bf16 v[20:23], v[80:83], v[96:99], v[20:23]
	v_cvt_pk_bf16_f32 v96, v48, v49
	v_cvt_pk_bf16_f32 v97, v50, v51
	v_cvt_pk_bf16_f32 v98, v52, v53
	v_cvt_pk_bf16_f32 v99, v54, v55
	s_nop 1
	v_mfma_f32_16x16x32_bf16 v[24:27], v[80:83], v[96:99], v[24:27]
	v_cvt_pk_bf16_f32 v96, v56, v57
	v_cvt_pk_bf16_f32 v97, v58, v59
	v_cvt_pk_bf16_f32 v98, v60, v61
	v_cvt_pk_bf16_f32 v99, v62, v63
	s_nop 1
	v_mfma_f32_16x16x32_bf16 v[28:31], v[80:83], v[96:99], v[28:31]
	s_waitcnt vmcnt(10)
	global_load_dwordx4 v[80:83], v134, s[38:39]
	s_add_u32 s38, s38, 0x400
	s_addc_u32 s39, s39, 0
	v_mfma_f32_16x16x32_bf16 v[32:35], v[64:67], v[0:3], 0
	v_mfma_f32_16x16x32_bf16 v[36:39], v[72:75], v[0:3], 0
	v_mfma_f32_16x16x32_bf16 v[40:43], v[64:67], v[4:7], 0
	v_mfma_f32_16x16x32_bf16 v[44:47], v[72:75], v[4:7], 0
	v_mfma_f32_16x16x32_bf16 v[48:51], v[64:67], v[8:11], 0
	v_mfma_f32_16x16x32_bf16 v[52:55], v[72:75], v[8:11], 0
	v_mfma_f32_16x16x32_bf16 v[56:59], v[64:67], v[12:15], 0
	v_mfma_f32_16x16x32_bf16 v[60:63], v[72:75], v[12:15], 0
	global_load_dwordx4 v[64:67], v134, s[20:21]
	global_load_dwordx4 v[72:75], v134, s[20:21] offset:1024
	global_load_dwordx4 v[100:103], v134, s[42:43] offset:0
	global_load_dwordx4 v[104:107], v134, s[42:43] offset:1024
	global_load_dwordx4 v[108:111], v134, s[42:43] offset:2048
	global_load_dwordx4 v[112:115], v134, s[42:43] offset:3072
	global_load_dwordx4 v[116:119], v208, s[42:43] offset:0
	global_load_dwordx4 v[120:123], v208, s[42:43] offset:1024
	global_load_dwordx4 v[124:127], v208, s[42:43] offset:2048
	global_load_dwordx4 v[128:131], v208, s[42:43] offset:3072
	global_load_dwordx4 v[178:181], v206, s[44:45]
	global_load_dwordx4 v[182:185], v206, s[44:45] offset:16
	s_waitcnt vmcnt(13)
	v_mul_f32_e32 v132, v171, v166
	v_mul_f32_e32 v133, v170, v166
	v_fma_f32 v68, v170, v162, -v132
	v_fma_f32 v76, v171, v162, v133
	v_mul_f32_e32 v132, v173, v167
	v_mul_f32_e32 v133, v172, v167
	v_fma_f32 v69, v172, v163, -v132
	v_fma_f32 v77, v173, v163, v133
	v_mul_f32_e32 v132, v175, v168
	v_mul_f32_e32 v133, v174, v168
	v_fma_f32 v70, v174, v164, -v132
	v_fma_f32 v78, v175, v164, v133
	v_mul_f32_e32 v132, v177, v169
	v_mul_f32_e32 v133, v176, v169
	v_fma_f32 v71, v176, v165, -v132
	v_fma_f32 v79, v177, v165, v133
	v_pk_mul_f32 v[132:133], v[56:57], v[142:143]
	v_pk_mul_f32 v[56:57], v[56:57], v[138:139]
	v_pk_fma_f32 v[56:57], v[60:61], v[142:143], v[56:57] neg_lo:[1,0,0] neg_hi:[1,0,0]
	v_pk_fma_f32 v[60:61], v[60:61], v[138:139], v[132:133]
	v_pk_mul_f32 v[132:133], v[58:59], v[144:145]
	v_pk_mul_f32 v[58:59], v[58:59], v[140:141]
	v_pk_fma_f32 v[58:59], v[62:63], v[144:145], v[58:59] neg_lo:[1,0,0] neg_hi:[1,0,0]
	v_pk_fma_f32 v[62:63], v[62:63], v[140:141], v[132:133]
	v_add_f32_dpp v56, v56, v56 row_shl:1 row_mask:0xf bank_mask:0xf bound_ctrl:1
	v_add_f32_dpp v57, v57, v57 row_shl:1 row_mask:0xf bank_mask:0xf bound_ctrl:1
	v_add_f32_dpp v58, v58, v58 row_shl:1 row_mask:0xf bank_mask:0xf bound_ctrl:1
	v_add_f32_dpp v59, v59, v59 row_shl:1 row_mask:0xf bank_mask:0xf bound_ctrl:1
	v_add_f32_dpp v60, v60, v60 row_shl:1 row_mask:0xf bank_mask:0xf bound_ctrl:1
	v_add_f32_dpp v61, v61, v61 row_shl:1 row_mask:0xf bank_mask:0xf bound_ctrl:1
	v_add_f32_dpp v62, v62, v62 row_shl:1 row_mask:0xf bank_mask:0xf bound_ctrl:1
	v_add_f32_dpp v63, v63, v63 row_shl:1 row_mask:0xf bank_mask:0xf bound_ctrl:1
	v_add_f32_dpp v56, v56, v56 row_shl:2 row_mask:0xf bank_mask:0xf bound_ctrl:1
	v_add_f32_dpp v57, v57, v57 row_shl:2 row_mask:0xf bank_mask:0xf bound_ctrl:1
	v_add_f32_dpp v58, v58, v58 row_shl:2 row_mask:0xf bank_mask:0xf bound_ctrl:1
	v_add_f32_dpp v59, v59, v59 row_shl:2 row_mask:0xf bank_mask:0xf bound_ctrl:1
	v_add_f32_dpp v60, v60, v60 row_shl:2 row_mask:0xf bank_mask:0xf bound_ctrl:1
	v_add_f32_dpp v61, v61, v61 row_shl:2 row_mask:0xf bank_mask:0xf bound_ctrl:1
	v_add_f32_dpp v62, v62, v62 row_shl:2 row_mask:0xf bank_mask:0xf bound_ctrl:1
	v_add_f32_dpp v63, v63, v63 row_shl:2 row_mask:0xf bank_mask:0xf bound_ctrl:1
	v_add_f32_dpp v56, v56, v56 row_shl:4 row_mask:0xf bank_mask:0xf bound_ctrl:1
	v_add_f32_dpp v57, v57, v57 row_shl:4 row_mask:0xf bank_mask:0xf bound_ctrl:1
	v_add_f32_dpp v58, v58, v58 row_shl:4 row_mask:0xf bank_mask:0xf bound_ctrl:1
	v_add_f32_dpp v59, v59, v59 row_shl:4 row_mask:0xf bank_mask:0xf bound_ctrl:1
	v_add_f32_dpp v60, v60, v60 row_shl:4 row_mask:0xf bank_mask:0xf bound_ctrl:1
	v_add_f32_dpp v61, v61, v61 row_shl:4 row_mask:0xf bank_mask:0xf bound_ctrl:1
	v_add_f32_dpp v62, v62, v62 row_shl:4 row_mask:0xf bank_mask:0xf bound_ctrl:1
	v_add_f32_dpp v63, v63, v63 row_shl:4 row_mask:0xf bank_mask:0xf bound_ctrl:1
	v_add_f32_dpp v56, v56, v56 row_shl:8 row_mask:0xf bank_mask:0xf bound_ctrl:1
	v_add_f32_dpp v57, v57, v57 row_shl:8 row_mask:0xf bank_mask:0xf bound_ctrl:1
	v_add_f32_dpp v58, v58, v58 row_shl:8 row_mask:0xf bank_mask:0xf bound_ctrl:1
	v_add_f32_dpp v59, v59, v59 row_shl:8 row_mask:0xf bank_mask:0xf bound_ctrl:1
	v_add_f32_dpp v60, v60, v60 row_shl:8 row_mask:0xf bank_mask:0xf bound_ctrl:1
	v_add_f32_dpp v61, v61, v61 row_shl:8 row_mask:0xf bank_mask:0xf bound_ctrl:1
	v_add_f32_dpp v62, v62, v62 row_shl:8 row_mask:0xf bank_mask:0xf bound_ctrl:1
	v_add_f32_dpp v63, v63, v63 row_shl:8 row_mask:0xf bank_mask:0xf bound_ctrl:1
	v_mov_b32_dpp v88, v56 row_newbcast:0 row_mask:0xf bank_mask:0xf
	v_mov_b32_dpp v89, v57 row_newbcast:0 row_mask:0xf bank_mask:0xf
	v_mov_b32_dpp v90, v58 row_newbcast:0 row_mask:0xf bank_mask:0xf
	v_mov_b32_dpp v91, v59 row_newbcast:0 row_mask:0xf bank_mask:0xf
	v_mov_b32_dpp v92, v60 row_newbcast:0 row_mask:0xf bank_mask:0xf
	v_mov_b32_dpp v93, v61 row_newbcast:0 row_mask:0xf bank_mask:0xf
	v_mov_b32_dpp v94, v62 row_newbcast:0 row_mask:0xf bank_mask:0xf
	v_mov_b32_dpp v95, v63 row_newbcast:0 row_mask:0xf bank_mask:0xf
	v_pk_add_f32 v[56:57], v[56:57], v[68:69]
	v_pk_add_f32 v[60:61], v[60:61], v[76:77]
	v_pk_add_f32 v[58:59], v[58:59], v[70:71]
	v_pk_add_f32 v[62:63], v[62:63], v[78:79]
	v_pk_mul_f32 v[132:133], v[56:57], v[150:151]
	v_pk_mul_f32 v[56:57], v[56:57], v[146:147]
	v_pk_fma_f32 v[56:57], v[60:61], v[150:151], v[56:57] neg_lo:[1,0,0] neg_hi:[1,0,0]
	v_pk_fma_f32 v[60:61], v[60:61], v[146:147], v[132:133]
	v_pk_mul_f32 v[132:133], v[58:59], v[152:153]
	v_pk_mul_f32 v[58:59], v[58:59], v[148:149]
	v_pk_fma_f32 v[58:59], v[62:63], v[152:153], v[58:59] neg_lo:[1,0,0] neg_hi:[1,0,0]
	v_pk_fma_f32 v[62:63], v[62:63], v[148:149], v[132:133]
	v_pk_add_f32 v[88:89], v[88:89], v[68:69]
	v_pk_add_f32 v[92:93], v[92:93], v[76:77]
	v_pk_mul_f32 v[132:133], v[92:93], v[158:159]
	v_pk_mul_f32 v[76:77], v[88:89], v[158:159]
	v_pk_fma_f32 v[68:69], v[88:89], v[154:155], v[132:133] neg_lo:[0,0,1] neg_hi:[0,0,1]
	v_pk_fma_f32 v[76:77], v[92:93], v[154:155], v[76:77]
	v_pk_add_f32 v[90:91], v[90:91], v[70:71]
	v_pk_add_f32 v[94:95], v[94:95], v[78:79]
	v_pk_mul_f32 v[132:133], v[94:95], v[160:161]
	v_pk_mul_f32 v[78:79], v[90:91], v[160:161]
	v_pk_fma_f32 v[70:71], v[90:91], v[156:157], v[132:133] neg_lo:[0,0,1] neg_hi:[0,0,1]
	v_pk_fma_f32 v[78:79], v[94:95], v[156:157], v[78:79]
	v_pk_mul_f32 v[132:133], v[48:49], v[142:143]
	v_pk_mul_f32 v[48:49], v[48:49], v[138:139]
	v_pk_fma_f32 v[48:49], v[52:53], v[142:143], v[48:49] neg_lo:[1,0,0] neg_hi:[1,0,0]
	v_pk_fma_f32 v[52:53], v[52:53], v[138:139], v[132:133]
	v_pk_mul_f32 v[132:133], v[50:51], v[144:145]
	v_pk_mul_f32 v[50:51], v[50:51], v[140:141]
	v_pk_fma_f32 v[50:51], v[54:55], v[144:145], v[50:51] neg_lo:[1,0,0] neg_hi:[1,0,0]
	v_pk_fma_f32 v[54:55], v[54:55], v[140:141], v[132:133]
	v_add_f32_dpp v48, v48, v48 row_shl:1 row_mask:0xf bank_mask:0xf bound_ctrl:1
	v_add_f32_dpp v49, v49, v49 row_shl:1 row_mask:0xf bank_mask:0xf bound_ctrl:1
	v_add_f32_dpp v50, v50, v50 row_shl:1 row_mask:0xf bank_mask:0xf bound_ctrl:1
	v_add_f32_dpp v51, v51, v51 row_shl:1 row_mask:0xf bank_mask:0xf bound_ctrl:1
	v_add_f32_dpp v52, v52, v52 row_shl:1 row_mask:0xf bank_mask:0xf bound_ctrl:1
	v_add_f32_dpp v53, v53, v53 row_shl:1 row_mask:0xf bank_mask:0xf bound_ctrl:1
	v_add_f32_dpp v54, v54, v54 row_shl:1 row_mask:0xf bank_mask:0xf bound_ctrl:1
	v_add_f32_dpp v55, v55, v55 row_shl:1 row_mask:0xf bank_mask:0xf bound_ctrl:1
	v_add_f32_dpp v48, v48, v48 row_shl:2 row_mask:0xf bank_mask:0xf bound_ctrl:1
	v_add_f32_dpp v49, v49, v49 row_shl:2 row_mask:0xf bank_mask:0xf bound_ctrl:1
	v_add_f32_dpp v50, v50, v50 row_shl:2 row_mask:0xf bank_mask:0xf bound_ctrl:1
	v_add_f32_dpp v51, v51, v51 row_shl:2 row_mask:0xf bank_mask:0xf bound_ctrl:1
	v_add_f32_dpp v52, v52, v52 row_shl:2 row_mask:0xf bank_mask:0xf bound_ctrl:1
	v_add_f32_dpp v53, v53, v53 row_shl:2 row_mask:0xf bank_mask:0xf bound_ctrl:1
	v_add_f32_dpp v54, v54, v54 row_shl:2 row_mask:0xf bank_mask:0xf bound_ctrl:1
	v_add_f32_dpp v55, v55, v55 row_shl:2 row_mask:0xf bank_mask:0xf bound_ctrl:1
	v_add_f32_dpp v48, v48, v48 row_shl:4 row_mask:0xf bank_mask:0xf bound_ctrl:1
	v_add_f32_dpp v49, v49, v49 row_shl:4 row_mask:0xf bank_mask:0xf bound_ctrl:1
	v_add_f32_dpp v50, v50, v50 row_shl:4 row_mask:0xf bank_mask:0xf bound_ctrl:1
	v_add_f32_dpp v51, v51, v51 row_shl:4 row_mask:0xf bank_mask:0xf bound_ctrl:1
	v_add_f32_dpp v52, v52, v52 row_shl:4 row_mask:0xf bank_mask:0xf bound_ctrl:1
	v_add_f32_dpp v53, v53, v53 row_shl:4 row_mask:0xf bank_mask:0xf bound_ctrl:1
	v_add_f32_dpp v54, v54, v54 row_shl:4 row_mask:0xf bank_mask:0xf bound_ctrl:1
	v_add_f32_dpp v55, v55, v55 row_shl:4 row_mask:0xf bank_mask:0xf bound_ctrl:1
	v_add_f32_dpp v48, v48, v48 row_shl:8 row_mask:0xf bank_mask:0xf bound_ctrl:1
	v_add_f32_dpp v49, v49, v49 row_shl:8 row_mask:0xf bank_mask:0xf bound_ctrl:1
	v_add_f32_dpp v50, v50, v50 row_shl:8 row_mask:0xf bank_mask:0xf bound_ctrl:1
	v_add_f32_dpp v51, v51, v51 row_shl:8 row_mask:0xf bank_mask:0xf bound_ctrl:1
	v_add_f32_dpp v52, v52, v52 row_shl:8 row_mask:0xf bank_mask:0xf bound_ctrl:1
	v_add_f32_dpp v53, v53, v53 row_shl:8 row_mask:0xf bank_mask:0xf bound_ctrl:1
	v_add_f32_dpp v54, v54, v54 row_shl:8 row_mask:0xf bank_mask:0xf bound_ctrl:1
	v_add_f32_dpp v55, v55, v55 row_shl:8 row_mask:0xf bank_mask:0xf bound_ctrl:1
	v_mov_b32_dpp v88, v48 row_newbcast:0 row_mask:0xf bank_mask:0xf
	v_mov_b32_dpp v89, v49 row_newbcast:0 row_mask:0xf bank_mask:0xf
	v_mov_b32_dpp v90, v50 row_newbcast:0 row_mask:0xf bank_mask:0xf
	v_mov_b32_dpp v91, v51 row_newbcast:0 row_mask:0xf bank_mask:0xf
	v_mov_b32_dpp v92, v52 row_newbcast:0 row_mask:0xf bank_mask:0xf
	v_mov_b32_dpp v93, v53 row_newbcast:0 row_mask:0xf bank_mask:0xf
	v_mov_b32_dpp v94, v54 row_newbcast:0 row_mask:0xf bank_mask:0xf
	v_mov_b32_dpp v95, v55 row_newbcast:0 row_mask:0xf bank_mask:0xf
	v_pk_add_f32 v[48:49], v[48:49], v[68:69]
	v_pk_add_f32 v[52:53], v[52:53], v[76:77]
	v_pk_add_f32 v[50:51], v[50:51], v[70:71]
	v_pk_add_f32 v[54:55], v[54:55], v[78:79]
	v_pk_mul_f32 v[132:133], v[48:49], v[150:151]
	v_pk_mul_f32 v[48:49], v[48:49], v[146:147]
	v_pk_fma_f32 v[48:49], v[52:53], v[150:151], v[48:49] neg_lo:[1,0,0] neg_hi:[1,0,0]
	v_pk_fma_f32 v[52:53], v[52:53], v[146:147], v[132:133]
	v_pk_mul_f32 v[132:133], v[50:51], v[152:153]
	v_pk_mul_f32 v[50:51], v[50:51], v[148:149]
	v_pk_fma_f32 v[50:51], v[54:55], v[152:153], v[50:51] neg_lo:[1,0,0] neg_hi:[1,0,0]
	v_pk_fma_f32 v[54:55], v[54:55], v[148:149], v[132:133]
	v_pk_add_f32 v[88:89], v[88:89], v[68:69]
	v_pk_add_f32 v[92:93], v[92:93], v[76:77]
	v_pk_mul_f32 v[132:133], v[92:93], v[158:159]
	v_pk_mul_f32 v[76:77], v[88:89], v[158:159]
	v_pk_fma_f32 v[68:69], v[88:89], v[154:155], v[132:133] neg_lo:[0,0,1] neg_hi:[0,0,1]
	v_pk_fma_f32 v[76:77], v[92:93], v[154:155], v[76:77]
	v_pk_add_f32 v[90:91], v[90:91], v[70:71]
	v_pk_add_f32 v[94:95], v[94:95], v[78:79]
	v_pk_mul_f32 v[132:133], v[94:95], v[160:161]
	v_pk_mul_f32 v[78:79], v[90:91], v[160:161]
	v_pk_fma_f32 v[70:71], v[90:91], v[156:157], v[132:133] neg_lo:[0,0,1] neg_hi:[0,0,1]
	v_pk_fma_f32 v[78:79], v[94:95], v[156:157], v[78:79]
	v_pk_mul_f32 v[132:133], v[40:41], v[142:143]
	v_pk_mul_f32 v[40:41], v[40:41], v[138:139]
	v_pk_fma_f32 v[40:41], v[44:45], v[142:143], v[40:41] neg_lo:[1,0,0] neg_hi:[1,0,0]
	v_pk_fma_f32 v[44:45], v[44:45], v[138:139], v[132:133]
	v_pk_mul_f32 v[132:133], v[42:43], v[144:145]
	v_pk_mul_f32 v[42:43], v[42:43], v[140:141]
	v_pk_fma_f32 v[42:43], v[46:47], v[144:145], v[42:43] neg_lo:[1,0,0] neg_hi:[1,0,0]
	v_pk_fma_f32 v[46:47], v[46:47], v[140:141], v[132:133]
	v_add_f32_dpp v40, v40, v40 row_shl:1 row_mask:0xf bank_mask:0xf bound_ctrl:1
	v_add_f32_dpp v41, v41, v41 row_shl:1 row_mask:0xf bank_mask:0xf bound_ctrl:1
	v_add_f32_dpp v42, v42, v42 row_shl:1 row_mask:0xf bank_mask:0xf bound_ctrl:1
	v_add_f32_dpp v43, v43, v43 row_shl:1 row_mask:0xf bank_mask:0xf bound_ctrl:1
	v_add_f32_dpp v44, v44, v44 row_shl:1 row_mask:0xf bank_mask:0xf bound_ctrl:1
	v_add_f32_dpp v45, v45, v45 row_shl:1 row_mask:0xf bank_mask:0xf bound_ctrl:1
	v_add_f32_dpp v46, v46, v46 row_shl:1 row_mask:0xf bank_mask:0xf bound_ctrl:1
	v_add_f32_dpp v47, v47, v47 row_shl:1 row_mask:0xf bank_mask:0xf bound_ctrl:1
	v_add_f32_dpp v40, v40, v40 row_shl:2 row_mask:0xf bank_mask:0xf bound_ctrl:1
	v_add_f32_dpp v41, v41, v41 row_shl:2 row_mask:0xf bank_mask:0xf bound_ctrl:1
	v_add_f32_dpp v42, v42, v42 row_shl:2 row_mask:0xf bank_mask:0xf bound_ctrl:1
	v_add_f32_dpp v43, v43, v43 row_shl:2 row_mask:0xf bank_mask:0xf bound_ctrl:1
	v_add_f32_dpp v44, v44, v44 row_shl:2 row_mask:0xf bank_mask:0xf bound_ctrl:1
	v_add_f32_dpp v45, v45, v45 row_shl:2 row_mask:0xf bank_mask:0xf bound_ctrl:1
	v_add_f32_dpp v46, v46, v46 row_shl:2 row_mask:0xf bank_mask:0xf bound_ctrl:1
	v_add_f32_dpp v47, v47, v47 row_shl:2 row_mask:0xf bank_mask:0xf bound_ctrl:1
	v_add_f32_dpp v40, v40, v40 row_shl:4 row_mask:0xf bank_mask:0xf bound_ctrl:1
	v_add_f32_dpp v41, v41, v41 row_shl:4 row_mask:0xf bank_mask:0xf bound_ctrl:1
	v_add_f32_dpp v42, v42, v42 row_shl:4 row_mask:0xf bank_mask:0xf bound_ctrl:1
	v_add_f32_dpp v43, v43, v43 row_shl:4 row_mask:0xf bank_mask:0xf bound_ctrl:1
	v_add_f32_dpp v44, v44, v44 row_shl:4 row_mask:0xf bank_mask:0xf bound_ctrl:1
	v_add_f32_dpp v45, v45, v45 row_shl:4 row_mask:0xf bank_mask:0xf bound_ctrl:1
	v_add_f32_dpp v46, v46, v46 row_shl:4 row_mask:0xf bank_mask:0xf bound_ctrl:1
	v_add_f32_dpp v47, v47, v47 row_shl:4 row_mask:0xf bank_mask:0xf bound_ctrl:1
	v_add_f32_dpp v40, v40, v40 row_shl:8 row_mask:0xf bank_mask:0xf bound_ctrl:1
	v_add_f32_dpp v41, v41, v41 row_shl:8 row_mask:0xf bank_mask:0xf bound_ctrl:1
	v_add_f32_dpp v42, v42, v42 row_shl:8 row_mask:0xf bank_mask:0xf bound_ctrl:1
	v_add_f32_dpp v43, v43, v43 row_shl:8 row_mask:0xf bank_mask:0xf bound_ctrl:1
	v_add_f32_dpp v44, v44, v44 row_shl:8 row_mask:0xf bank_mask:0xf bound_ctrl:1
	v_add_f32_dpp v45, v45, v45 row_shl:8 row_mask:0xf bank_mask:0xf bound_ctrl:1
	v_add_f32_dpp v46, v46, v46 row_shl:8 row_mask:0xf bank_mask:0xf bound_ctrl:1
	v_add_f32_dpp v47, v47, v47 row_shl:8 row_mask:0xf bank_mask:0xf bound_ctrl:1
	v_mov_b32_dpp v88, v40 row_newbcast:0 row_mask:0xf bank_mask:0xf
	v_mov_b32_dpp v89, v41 row_newbcast:0 row_mask:0xf bank_mask:0xf
	v_mov_b32_dpp v90, v42 row_newbcast:0 row_mask:0xf bank_mask:0xf
	v_mov_b32_dpp v91, v43 row_newbcast:0 row_mask:0xf bank_mask:0xf
	v_mov_b32_dpp v92, v44 row_newbcast:0 row_mask:0xf bank_mask:0xf
	v_mov_b32_dpp v93, v45 row_newbcast:0 row_mask:0xf bank_mask:0xf
	v_mov_b32_dpp v94, v46 row_newbcast:0 row_mask:0xf bank_mask:0xf
	v_mov_b32_dpp v95, v47 row_newbcast:0 row_mask:0xf bank_mask:0xf
	v_pk_add_f32 v[40:41], v[40:41], v[68:69]
	v_pk_add_f32 v[44:45], v[44:45], v[76:77]
	v_pk_add_f32 v[42:43], v[42:43], v[70:71]
	v_pk_add_f32 v[46:47], v[46:47], v[78:79]
	v_pk_mul_f32 v[132:133], v[40:41], v[150:151]
	v_pk_mul_f32 v[40:41], v[40:41], v[146:147]
	v_pk_fma_f32 v[40:41], v[44:45], v[150:151], v[40:41] neg_lo:[1,0,0] neg_hi:[1,0,0]
	v_pk_fma_f32 v[44:45], v[44:45], v[146:147], v[132:133]
	v_pk_mul_f32 v[132:133], v[42:43], v[152:153]
	v_pk_mul_f32 v[42:43], v[42:43], v[148:149]
	v_pk_fma_f32 v[42:43], v[46:47], v[152:153], v[42:43] neg_lo:[1,0,0] neg_hi:[1,0,0]
	v_pk_fma_f32 v[46:47], v[46:47], v[148:149], v[132:133]
	v_pk_add_f32 v[88:89], v[88:89], v[68:69]
	v_pk_add_f32 v[92:93], v[92:93], v[76:77]
	v_pk_mul_f32 v[132:133], v[92:93], v[158:159]
	v_pk_mul_f32 v[76:77], v[88:89], v[158:159]
	v_pk_fma_f32 v[68:69], v[88:89], v[154:155], v[132:133] neg_lo:[0,0,1] neg_hi:[0,0,1]
	v_pk_fma_f32 v[76:77], v[92:93], v[154:155], v[76:77]
	v_pk_add_f32 v[90:91], v[90:91], v[70:71]
	v_pk_add_f32 v[94:95], v[94:95], v[78:79]
	v_pk_mul_f32 v[132:133], v[94:95], v[160:161]
	v_pk_mul_f32 v[78:79], v[90:91], v[160:161]
	v_pk_fma_f32 v[70:71], v[90:91], v[156:157], v[132:133] neg_lo:[0,0,1] neg_hi:[0,0,1]
	v_pk_fma_f32 v[78:79], v[94:95], v[156:157], v[78:79]
	v_pk_mul_f32 v[132:133], v[32:33], v[142:143]
	v_pk_mul_f32 v[32:33], v[32:33], v[138:139]
	v_pk_fma_f32 v[32:33], v[36:37], v[142:143], v[32:33] neg_lo:[1,0,0] neg_hi:[1,0,0]
	v_pk_fma_f32 v[36:37], v[36:37], v[138:139], v[132:133]
	v_pk_mul_f32 v[132:133], v[34:35], v[144:145]
	v_pk_mul_f32 v[34:35], v[34:35], v[140:141]
	v_pk_fma_f32 v[34:35], v[38:39], v[144:145], v[34:35] neg_lo:[1,0,0] neg_hi:[1,0,0]
	v_pk_fma_f32 v[38:39], v[38:39], v[140:141], v[132:133]
	v_add_f32_dpp v32, v32, v32 row_shl:1 row_mask:0xf bank_mask:0xf bound_ctrl:1
	v_add_f32_dpp v33, v33, v33 row_shl:1 row_mask:0xf bank_mask:0xf bound_ctrl:1
	v_add_f32_dpp v34, v34, v34 row_shl:1 row_mask:0xf bank_mask:0xf bound_ctrl:1
	v_add_f32_dpp v35, v35, v35 row_shl:1 row_mask:0xf bank_mask:0xf bound_ctrl:1
	v_add_f32_dpp v36, v36, v36 row_shl:1 row_mask:0xf bank_mask:0xf bound_ctrl:1
	v_add_f32_dpp v37, v37, v37 row_shl:1 row_mask:0xf bank_mask:0xf bound_ctrl:1
	v_add_f32_dpp v38, v38, v38 row_shl:1 row_mask:0xf bank_mask:0xf bound_ctrl:1
	v_add_f32_dpp v39, v39, v39 row_shl:1 row_mask:0xf bank_mask:0xf bound_ctrl:1
	v_add_f32_dpp v32, v32, v32 row_shl:2 row_mask:0xf bank_mask:0xf bound_ctrl:1
	v_add_f32_dpp v33, v33, v33 row_shl:2 row_mask:0xf bank_mask:0xf bound_ctrl:1
	v_add_f32_dpp v34, v34, v34 row_shl:2 row_mask:0xf bank_mask:0xf bound_ctrl:1
	v_add_f32_dpp v35, v35, v35 row_shl:2 row_mask:0xf bank_mask:0xf bound_ctrl:1
	v_add_f32_dpp v36, v36, v36 row_shl:2 row_mask:0xf bank_mask:0xf bound_ctrl:1
	v_add_f32_dpp v37, v37, v37 row_shl:2 row_mask:0xf bank_mask:0xf bound_ctrl:1
	v_add_f32_dpp v38, v38, v38 row_shl:2 row_mask:0xf bank_mask:0xf bound_ctrl:1
	v_add_f32_dpp v39, v39, v39 row_shl:2 row_mask:0xf bank_mask:0xf bound_ctrl:1
	v_add_f32_dpp v32, v32, v32 row_shl:4 row_mask:0xf bank_mask:0xf bound_ctrl:1
	v_add_f32_dpp v33, v33, v33 row_shl:4 row_mask:0xf bank_mask:0xf bound_ctrl:1
	v_add_f32_dpp v34, v34, v34 row_shl:4 row_mask:0xf bank_mask:0xf bound_ctrl:1
	v_add_f32_dpp v35, v35, v35 row_shl:4 row_mask:0xf bank_mask:0xf bound_ctrl:1
	v_add_f32_dpp v36, v36, v36 row_shl:4 row_mask:0xf bank_mask:0xf bound_ctrl:1
	v_add_f32_dpp v37, v37, v37 row_shl:4 row_mask:0xf bank_mask:0xf bound_ctrl:1
	v_add_f32_dpp v38, v38, v38 row_shl:4 row_mask:0xf bank_mask:0xf bound_ctrl:1
	v_add_f32_dpp v39, v39, v39 row_shl:4 row_mask:0xf bank_mask:0xf bound_ctrl:1
	v_add_f32_dpp v32, v32, v32 row_shl:8 row_mask:0xf bank_mask:0xf bound_ctrl:1
	v_add_f32_dpp v33, v33, v33 row_shl:8 row_mask:0xf bank_mask:0xf bound_ctrl:1
	v_add_f32_dpp v34, v34, v34 row_shl:8 row_mask:0xf bank_mask:0xf bound_ctrl:1
	v_add_f32_dpp v35, v35, v35 row_shl:8 row_mask:0xf bank_mask:0xf bound_ctrl:1
	v_add_f32_dpp v36, v36, v36 row_shl:8 row_mask:0xf bank_mask:0xf bound_ctrl:1
	v_add_f32_dpp v37, v37, v37 row_shl:8 row_mask:0xf bank_mask:0xf bound_ctrl:1
	v_add_f32_dpp v38, v38, v38 row_shl:8 row_mask:0xf bank_mask:0xf bound_ctrl:1
	v_add_f32_dpp v39, v39, v39 row_shl:8 row_mask:0xf bank_mask:0xf bound_ctrl:1
	v_mov_b32_dpp v88, v32 row_newbcast:0 row_mask:0xf bank_mask:0xf
	v_mov_b32_dpp v89, v33 row_newbcast:0 row_mask:0xf bank_mask:0xf
	v_mov_b32_dpp v90, v34 row_newbcast:0 row_mask:0xf bank_mask:0xf
	v_mov_b32_dpp v91, v35 row_newbcast:0 row_mask:0xf bank_mask:0xf
	v_mov_b32_dpp v92, v36 row_newbcast:0 row_mask:0xf bank_mask:0xf
	v_mov_b32_dpp v93, v37 row_newbcast:0 row_mask:0xf bank_mask:0xf
	v_mov_b32_dpp v94, v38 row_newbcast:0 row_mask:0xf bank_mask:0xf
	v_mov_b32_dpp v95, v39 row_newbcast:0 row_mask:0xf bank_mask:0xf
	v_pk_add_f32 v[32:33], v[32:33], v[68:69]
	v_pk_add_f32 v[36:37], v[36:37], v[76:77]
	v_pk_add_f32 v[34:35], v[34:35], v[70:71]
	v_pk_add_f32 v[38:39], v[38:39], v[78:79]
	v_pk_mul_f32 v[132:133], v[32:33], v[150:151]
	v_pk_mul_f32 v[32:33], v[32:33], v[146:147]
	v_pk_fma_f32 v[32:33], v[36:37], v[150:151], v[32:33] neg_lo:[1,0,0] neg_hi:[1,0,0]
	v_pk_fma_f32 v[36:37], v[36:37], v[146:147], v[132:133]
	v_pk_mul_f32 v[132:133], v[34:35], v[152:153]
	v_pk_mul_f32 v[34:35], v[34:35], v[148:149]
	v_pk_fma_f32 v[34:35], v[38:39], v[152:153], v[34:35] neg_lo:[1,0,0] neg_hi:[1,0,0]
	v_pk_fma_f32 v[38:39], v[38:39], v[148:149], v[132:133]
	v_pk_add_f32 v[88:89], v[88:89], v[68:69]
	v_pk_add_f32 v[92:93], v[92:93], v[76:77]
	v_pk_mul_f32 v[132:133], v[92:93], v[158:159]
	v_pk_mul_f32 v[76:77], v[88:89], v[158:159]
	v_pk_fma_f32 v[68:69], v[88:89], v[154:155], v[132:133] neg_lo:[0,0,1] neg_hi:[0,0,1]
	v_pk_fma_f32 v[76:77], v[92:93], v[154:155], v[76:77]
	v_pk_add_f32 v[90:91], v[90:91], v[70:71]
	v_pk_add_f32 v[94:95], v[94:95], v[78:79]
	v_pk_mul_f32 v[132:133], v[94:95], v[160:161]
	v_pk_mul_f32 v[78:79], v[90:91], v[160:161]
	v_pk_fma_f32 v[70:71], v[90:91], v[156:157], v[132:133] neg_lo:[0,0,1] neg_hi:[0,0,1]
	v_pk_fma_f32 v[78:79], v[94:95], v[156:157], v[78:79]
	s_waitcnt vmcnt(12)
	v_cvt_pk_bf16_f32 v96, v32, v33
	v_cvt_pk_bf16_f32 v97, v34, v35
	v_cvt_pk_bf16_f32 v98, v36, v37
	v_cvt_pk_bf16_f32 v99, v38, v39
	s_nop 1
	v_mfma_f32_16x16x32_bf16 v[16:19], v[80:83], v[96:99], v[16:19]
	v_cvt_pk_bf16_f32 v96, v40, v41
	v_cvt_pk_bf16_f32 v97, v42, v43
	v_cvt_pk_bf16_f32 v98, v44, v45
	v_cvt_pk_bf16_f32 v99, v46, v47
	s_nop 1
	v_mfma_f32_16x16x32_bf16 v[20:23], v[80:83], v[96:99], v[20:23]
	v_cvt_pk_bf16_f32 v96, v48, v49
	v_cvt_pk_bf16_f32 v97, v50, v51
	v_cvt_pk_bf16_f32 v98, v52, v53
	v_cvt_pk_bf16_f32 v99, v54, v55
	s_nop 1
	v_mfma_f32_16x16x32_bf16 v[24:27], v[80:83], v[96:99], v[24:27]
	v_cvt_pk_bf16_f32 v96, v56, v57
	v_cvt_pk_bf16_f32 v97, v58, v59
	v_cvt_pk_bf16_f32 v98, v60, v61
	v_cvt_pk_bf16_f32 v99, v62, v63
	s_nop 1
	v_mfma_f32_16x16x32_bf16 v[28:31], v[80:83], v[96:99], v[28:31]
	s_waitcnt vmcnt(10)
	global_load_dwordx4 v[80:83], v134, s[38:39]
	v_mfma_f32_16x16x32_bf16 v[32:35], v[64:67], v[0:3], 0
	v_mfma_f32_16x16x32_bf16 v[36:39], v[72:75], v[0:3], 0
	v_mfma_f32_16x16x32_bf16 v[40:43], v[64:67], v[4:7], 0
	v_mfma_f32_16x16x32_bf16 v[44:47], v[72:75], v[4:7], 0
	v_mfma_f32_16x16x32_bf16 v[48:51], v[64:67], v[8:11], 0
	v_mfma_f32_16x16x32_bf16 v[52:55], v[72:75], v[8:11], 0
	v_mfma_f32_16x16x32_bf16 v[56:59], v[64:67], v[12:15], 0
	v_mfma_f32_16x16x32_bf16 v[60:63], v[72:75], v[12:15], 0
	s_waitcnt vmcnt(1)
	v_mul_f32_e32 v132, v179, v128
	v_mul_f32_e32 v133, v178, v128
	v_fma_f32 v68, v178, v124, -v132
	v_fma_f32 v76, v179, v124, v133
	v_mul_f32_e32 v132, v181, v129
	v_mul_f32_e32 v133, v180, v129
	v_fma_f32 v69, v180, v125, -v132
	v_fma_f32 v77, v181, v125, v133
	v_mul_f32_e32 v132, v183, v130
	v_mul_f32_e32 v133, v182, v130
	v_fma_f32 v70, v182, v126, -v132
	v_fma_f32 v78, v183, v126, v133
	v_mul_f32_e32 v132, v185, v131
	v_mul_f32_e32 v133, v184, v131
	v_fma_f32 v71, v184, v127, -v132
	v_fma_f32 v79, v185, v127, v133
	v_pk_mul_f32 v[132:133], v[56:57], v[104:105]
	v_pk_mul_f32 v[56:57], v[56:57], v[100:101]
	v_pk_fma_f32 v[56:57], v[60:61], v[104:105], v[56:57] neg_lo:[1,0,0] neg_hi:[1,0,0]
	v_pk_fma_f32 v[60:61], v[60:61], v[100:101], v[132:133]
	v_pk_mul_f32 v[132:133], v[58:59], v[106:107]
	v_pk_mul_f32 v[58:59], v[58:59], v[102:103]
	v_pk_fma_f32 v[58:59], v[62:63], v[106:107], v[58:59] neg_lo:[1,0,0] neg_hi:[1,0,0]
	v_pk_fma_f32 v[62:63], v[62:63], v[102:103], v[132:133]
	v_add_f32_dpp v56, v56, v56 row_shl:1 row_mask:0xf bank_mask:0xf bound_ctrl:1
	v_add_f32_dpp v57, v57, v57 row_shl:1 row_mask:0xf bank_mask:0xf bound_ctrl:1
	v_add_f32_dpp v58, v58, v58 row_shl:1 row_mask:0xf bank_mask:0xf bound_ctrl:1
	v_add_f32_dpp v59, v59, v59 row_shl:1 row_mask:0xf bank_mask:0xf bound_ctrl:1
	v_add_f32_dpp v60, v60, v60 row_shl:1 row_mask:0xf bank_mask:0xf bound_ctrl:1
	v_add_f32_dpp v61, v61, v61 row_shl:1 row_mask:0xf bank_mask:0xf bound_ctrl:1
	v_add_f32_dpp v62, v62, v62 row_shl:1 row_mask:0xf bank_mask:0xf bound_ctrl:1
	v_add_f32_dpp v63, v63, v63 row_shl:1 row_mask:0xf bank_mask:0xf bound_ctrl:1
	v_add_f32_dpp v56, v56, v56 row_shl:2 row_mask:0xf bank_mask:0xf bound_ctrl:1
	v_add_f32_dpp v57, v57, v57 row_shl:2 row_mask:0xf bank_mask:0xf bound_ctrl:1
	v_add_f32_dpp v58, v58, v58 row_shl:2 row_mask:0xf bank_mask:0xf bound_ctrl:1
	v_add_f32_dpp v59, v59, v59 row_shl:2 row_mask:0xf bank_mask:0xf bound_ctrl:1
	v_add_f32_dpp v60, v60, v60 row_shl:2 row_mask:0xf bank_mask:0xf bound_ctrl:1
	v_add_f32_dpp v61, v61, v61 row_shl:2 row_mask:0xf bank_mask:0xf bound_ctrl:1
	v_add_f32_dpp v62, v62, v62 row_shl:2 row_mask:0xf bank_mask:0xf bound_ctrl:1
	v_add_f32_dpp v63, v63, v63 row_shl:2 row_mask:0xf bank_mask:0xf bound_ctrl:1
	v_add_f32_dpp v56, v56, v56 row_shl:4 row_mask:0xf bank_mask:0xf bound_ctrl:1
	v_add_f32_dpp v57, v57, v57 row_shl:4 row_mask:0xf bank_mask:0xf bound_ctrl:1
	v_add_f32_dpp v58, v58, v58 row_shl:4 row_mask:0xf bank_mask:0xf bound_ctrl:1
	v_add_f32_dpp v59, v59, v59 row_shl:4 row_mask:0xf bank_mask:0xf bound_ctrl:1
	v_add_f32_dpp v60, v60, v60 row_shl:4 row_mask:0xf bank_mask:0xf bound_ctrl:1
	v_add_f32_dpp v61, v61, v61 row_shl:4 row_mask:0xf bank_mask:0xf bound_ctrl:1
	v_add_f32_dpp v62, v62, v62 row_shl:4 row_mask:0xf bank_mask:0xf bound_ctrl:1
	v_add_f32_dpp v63, v63, v63 row_shl:4 row_mask:0xf bank_mask:0xf bound_ctrl:1
	v_add_f32_dpp v56, v56, v56 row_shl:8 row_mask:0xf bank_mask:0xf bound_ctrl:1
	v_add_f32_dpp v57, v57, v57 row_shl:8 row_mask:0xf bank_mask:0xf bound_ctrl:1
	v_add_f32_dpp v58, v58, v58 row_shl:8 row_mask:0xf bank_mask:0xf bound_ctrl:1
	v_add_f32_dpp v59, v59, v59 row_shl:8 row_mask:0xf bank_mask:0xf bound_ctrl:1
	v_add_f32_dpp v60, v60, v60 row_shl:8 row_mask:0xf bank_mask:0xf bound_ctrl:1
	v_add_f32_dpp v61, v61, v61 row_shl:8 row_mask:0xf bank_mask:0xf bound_ctrl:1
	v_add_f32_dpp v62, v62, v62 row_shl:8 row_mask:0xf bank_mask:0xf bound_ctrl:1
	v_add_f32_dpp v63, v63, v63 row_shl:8 row_mask:0xf bank_mask:0xf bound_ctrl:1
	v_mov_b32_dpp v88, v56 row_newbcast:0 row_mask:0xf bank_mask:0xf
	v_mov_b32_dpp v89, v57 row_newbcast:0 row_mask:0xf bank_mask:0xf
	v_mov_b32_dpp v90, v58 row_newbcast:0 row_mask:0xf bank_mask:0xf
	v_mov_b32_dpp v91, v59 row_newbcast:0 row_mask:0xf bank_mask:0xf
	v_mov_b32_dpp v92, v60 row_newbcast:0 row_mask:0xf bank_mask:0xf
	v_mov_b32_dpp v93, v61 row_newbcast:0 row_mask:0xf bank_mask:0xf
	v_mov_b32_dpp v94, v62 row_newbcast:0 row_mask:0xf bank_mask:0xf
	v_mov_b32_dpp v95, v63 row_newbcast:0 row_mask:0xf bank_mask:0xf
	v_pk_add_f32 v[56:57], v[56:57], v[68:69]
	v_pk_add_f32 v[60:61], v[60:61], v[76:77]
	v_pk_add_f32 v[58:59], v[58:59], v[70:71]
	v_pk_add_f32 v[62:63], v[62:63], v[78:79]
	v_pk_mul_f32 v[132:133], v[56:57], v[112:113]
	v_pk_mul_f32 v[56:57], v[56:57], v[108:109]
	v_pk_fma_f32 v[56:57], v[60:61], v[112:113], v[56:57] neg_lo:[1,0,0] neg_hi:[1,0,0]
	v_pk_fma_f32 v[60:61], v[60:61], v[108:109], v[132:133]
	v_pk_mul_f32 v[132:133], v[58:59], v[114:115]
	v_pk_mul_f32 v[58:59], v[58:59], v[110:111]
	v_pk_fma_f32 v[58:59], v[62:63], v[114:115], v[58:59] neg_lo:[1,0,0] neg_hi:[1,0,0]
	v_pk_fma_f32 v[62:63], v[62:63], v[110:111], v[132:133]
	v_pk_add_f32 v[88:89], v[88:89], v[68:69]
	v_pk_add_f32 v[92:93], v[92:93], v[76:77]
	v_pk_mul_f32 v[132:133], v[92:93], v[120:121]
	v_pk_mul_f32 v[76:77], v[88:89], v[120:121]
	v_pk_fma_f32 v[68:69], v[88:89], v[116:117], v[132:133] neg_lo:[0,0,1] neg_hi:[0,0,1]
	v_pk_fma_f32 v[76:77], v[92:93], v[116:117], v[76:77]
	v_pk_add_f32 v[90:91], v[90:91], v[70:71]
	v_pk_add_f32 v[94:95], v[94:95], v[78:79]
	v_pk_mul_f32 v[132:133], v[94:95], v[122:123]
	v_pk_mul_f32 v[78:79], v[90:91], v[122:123]
	v_pk_fma_f32 v[70:71], v[90:91], v[118:119], v[132:133] neg_lo:[0,0,1] neg_hi:[0,0,1]
	v_pk_fma_f32 v[78:79], v[94:95], v[118:119], v[78:79]
	v_pk_mul_f32 v[132:133], v[48:49], v[104:105]
	v_pk_mul_f32 v[48:49], v[48:49], v[100:101]
	v_pk_fma_f32 v[48:49], v[52:53], v[104:105], v[48:49] neg_lo:[1,0,0] neg_hi:[1,0,0]
	v_pk_fma_f32 v[52:53], v[52:53], v[100:101], v[132:133]
	v_pk_mul_f32 v[132:133], v[50:51], v[106:107]
	v_pk_mul_f32 v[50:51], v[50:51], v[102:103]
	v_pk_fma_f32 v[50:51], v[54:55], v[106:107], v[50:51] neg_lo:[1,0,0] neg_hi:[1,0,0]
	v_pk_fma_f32 v[54:55], v[54:55], v[102:103], v[132:133]
	v_add_f32_dpp v48, v48, v48 row_shl:1 row_mask:0xf bank_mask:0xf bound_ctrl:1
	v_add_f32_dpp v49, v49, v49 row_shl:1 row_mask:0xf bank_mask:0xf bound_ctrl:1
	v_add_f32_dpp v50, v50, v50 row_shl:1 row_mask:0xf bank_mask:0xf bound_ctrl:1
	v_add_f32_dpp v51, v51, v51 row_shl:1 row_mask:0xf bank_mask:0xf bound_ctrl:1
	v_add_f32_dpp v52, v52, v52 row_shl:1 row_mask:0xf bank_mask:0xf bound_ctrl:1
	v_add_f32_dpp v53, v53, v53 row_shl:1 row_mask:0xf bank_mask:0xf bound_ctrl:1
	v_add_f32_dpp v54, v54, v54 row_shl:1 row_mask:0xf bank_mask:0xf bound_ctrl:1
	v_add_f32_dpp v55, v55, v55 row_shl:1 row_mask:0xf bank_mask:0xf bound_ctrl:1
	v_add_f32_dpp v48, v48, v48 row_shl:2 row_mask:0xf bank_mask:0xf bound_ctrl:1
	v_add_f32_dpp v49, v49, v49 row_shl:2 row_mask:0xf bank_mask:0xf bound_ctrl:1
	v_add_f32_dpp v50, v50, v50 row_shl:2 row_mask:0xf bank_mask:0xf bound_ctrl:1
	v_add_f32_dpp v51, v51, v51 row_shl:2 row_mask:0xf bank_mask:0xf bound_ctrl:1
	v_add_f32_dpp v52, v52, v52 row_shl:2 row_mask:0xf bank_mask:0xf bound_ctrl:1
	v_add_f32_dpp v53, v53, v53 row_shl:2 row_mask:0xf bank_mask:0xf bound_ctrl:1
	v_add_f32_dpp v54, v54, v54 row_shl:2 row_mask:0xf bank_mask:0xf bound_ctrl:1
	v_add_f32_dpp v55, v55, v55 row_shl:2 row_mask:0xf bank_mask:0xf bound_ctrl:1
	v_add_f32_dpp v48, v48, v48 row_shl:4 row_mask:0xf bank_mask:0xf bound_ctrl:1
	v_add_f32_dpp v49, v49, v49 row_shl:4 row_mask:0xf bank_mask:0xf bound_ctrl:1
	v_add_f32_dpp v50, v50, v50 row_shl:4 row_mask:0xf bank_mask:0xf bound_ctrl:1
	v_add_f32_dpp v51, v51, v51 row_shl:4 row_mask:0xf bank_mask:0xf bound_ctrl:1
	v_add_f32_dpp v52, v52, v52 row_shl:4 row_mask:0xf bank_mask:0xf bound_ctrl:1
	v_add_f32_dpp v53, v53, v53 row_shl:4 row_mask:0xf bank_mask:0xf bound_ctrl:1
	v_add_f32_dpp v54, v54, v54 row_shl:4 row_mask:0xf bank_mask:0xf bound_ctrl:1
	v_add_f32_dpp v55, v55, v55 row_shl:4 row_mask:0xf bank_mask:0xf bound_ctrl:1
	v_add_f32_dpp v48, v48, v48 row_shl:8 row_mask:0xf bank_mask:0xf bound_ctrl:1
	v_add_f32_dpp v49, v49, v49 row_shl:8 row_mask:0xf bank_mask:0xf bound_ctrl:1
	v_add_f32_dpp v50, v50, v50 row_shl:8 row_mask:0xf bank_mask:0xf bound_ctrl:1
	v_add_f32_dpp v51, v51, v51 row_shl:8 row_mask:0xf bank_mask:0xf bound_ctrl:1
	v_add_f32_dpp v52, v52, v52 row_shl:8 row_mask:0xf bank_mask:0xf bound_ctrl:1
	v_add_f32_dpp v53, v53, v53 row_shl:8 row_mask:0xf bank_mask:0xf bound_ctrl:1
	v_add_f32_dpp v54, v54, v54 row_shl:8 row_mask:0xf bank_mask:0xf bound_ctrl:1
	v_add_f32_dpp v55, v55, v55 row_shl:8 row_mask:0xf bank_mask:0xf bound_ctrl:1
	v_mov_b32_dpp v88, v48 row_newbcast:0 row_mask:0xf bank_mask:0xf
	v_mov_b32_dpp v89, v49 row_newbcast:0 row_mask:0xf bank_mask:0xf
	v_mov_b32_dpp v90, v50 row_newbcast:0 row_mask:0xf bank_mask:0xf
	v_mov_b32_dpp v91, v51 row_newbcast:0 row_mask:0xf bank_mask:0xf
	v_mov_b32_dpp v92, v52 row_newbcast:0 row_mask:0xf bank_mask:0xf
	v_mov_b32_dpp v93, v53 row_newbcast:0 row_mask:0xf bank_mask:0xf
	v_mov_b32_dpp v94, v54 row_newbcast:0 row_mask:0xf bank_mask:0xf
	v_mov_b32_dpp v95, v55 row_newbcast:0 row_mask:0xf bank_mask:0xf
	v_pk_add_f32 v[48:49], v[48:49], v[68:69]
	v_pk_add_f32 v[52:53], v[52:53], v[76:77]
	v_pk_add_f32 v[50:51], v[50:51], v[70:71]
	v_pk_add_f32 v[54:55], v[54:55], v[78:79]
	v_pk_mul_f32 v[132:133], v[48:49], v[112:113]
	v_pk_mul_f32 v[48:49], v[48:49], v[108:109]
	v_pk_fma_f32 v[48:49], v[52:53], v[112:113], v[48:49] neg_lo:[1,0,0] neg_hi:[1,0,0]
	v_pk_fma_f32 v[52:53], v[52:53], v[108:109], v[132:133]
	v_pk_mul_f32 v[132:133], v[50:51], v[114:115]
	v_pk_mul_f32 v[50:51], v[50:51], v[110:111]
	v_pk_fma_f32 v[50:51], v[54:55], v[114:115], v[50:51] neg_lo:[1,0,0] neg_hi:[1,0,0]
	v_pk_fma_f32 v[54:55], v[54:55], v[110:111], v[132:133]
	v_pk_add_f32 v[88:89], v[88:89], v[68:69]
	v_pk_add_f32 v[92:93], v[92:93], v[76:77]
	v_pk_mul_f32 v[132:133], v[92:93], v[120:121]
	v_pk_mul_f32 v[76:77], v[88:89], v[120:121]
	v_pk_fma_f32 v[68:69], v[88:89], v[116:117], v[132:133] neg_lo:[0,0,1] neg_hi:[0,0,1]
	v_pk_fma_f32 v[76:77], v[92:93], v[116:117], v[76:77]
	v_pk_add_f32 v[90:91], v[90:91], v[70:71]
	v_pk_add_f32 v[94:95], v[94:95], v[78:79]
	v_pk_mul_f32 v[132:133], v[94:95], v[122:123]
	v_pk_mul_f32 v[78:79], v[90:91], v[122:123]
	v_pk_fma_f32 v[70:71], v[90:91], v[118:119], v[132:133] neg_lo:[0,0,1] neg_hi:[0,0,1]
	v_pk_fma_f32 v[78:79], v[94:95], v[118:119], v[78:79]
	v_pk_mul_f32 v[132:133], v[40:41], v[104:105]
	v_pk_mul_f32 v[40:41], v[40:41], v[100:101]
	v_pk_fma_f32 v[40:41], v[44:45], v[104:105], v[40:41] neg_lo:[1,0,0] neg_hi:[1,0,0]
	v_pk_fma_f32 v[44:45], v[44:45], v[100:101], v[132:133]
	v_pk_mul_f32 v[132:133], v[42:43], v[106:107]
	v_pk_mul_f32 v[42:43], v[42:43], v[102:103]
	v_pk_fma_f32 v[42:43], v[46:47], v[106:107], v[42:43] neg_lo:[1,0,0] neg_hi:[1,0,0]
	v_pk_fma_f32 v[46:47], v[46:47], v[102:103], v[132:133]
	v_add_f32_dpp v40, v40, v40 row_shl:1 row_mask:0xf bank_mask:0xf bound_ctrl:1
	v_add_f32_dpp v41, v41, v41 row_shl:1 row_mask:0xf bank_mask:0xf bound_ctrl:1
	v_add_f32_dpp v42, v42, v42 row_shl:1 row_mask:0xf bank_mask:0xf bound_ctrl:1
	v_add_f32_dpp v43, v43, v43 row_shl:1 row_mask:0xf bank_mask:0xf bound_ctrl:1
	v_add_f32_dpp v44, v44, v44 row_shl:1 row_mask:0xf bank_mask:0xf bound_ctrl:1
	v_add_f32_dpp v45, v45, v45 row_shl:1 row_mask:0xf bank_mask:0xf bound_ctrl:1
	v_add_f32_dpp v46, v46, v46 row_shl:1 row_mask:0xf bank_mask:0xf bound_ctrl:1
	v_add_f32_dpp v47, v47, v47 row_shl:1 row_mask:0xf bank_mask:0xf bound_ctrl:1
	v_add_f32_dpp v40, v40, v40 row_shl:2 row_mask:0xf bank_mask:0xf bound_ctrl:1
	v_add_f32_dpp v41, v41, v41 row_shl:2 row_mask:0xf bank_mask:0xf bound_ctrl:1
	v_add_f32_dpp v42, v42, v42 row_shl:2 row_mask:0xf bank_mask:0xf bound_ctrl:1
	v_add_f32_dpp v43, v43, v43 row_shl:2 row_mask:0xf bank_mask:0xf bound_ctrl:1
	v_add_f32_dpp v44, v44, v44 row_shl:2 row_mask:0xf bank_mask:0xf bound_ctrl:1
	v_add_f32_dpp v45, v45, v45 row_shl:2 row_mask:0xf bank_mask:0xf bound_ctrl:1
	v_add_f32_dpp v46, v46, v46 row_shl:2 row_mask:0xf bank_mask:0xf bound_ctrl:1
	v_add_f32_dpp v47, v47, v47 row_shl:2 row_mask:0xf bank_mask:0xf bound_ctrl:1
	v_add_f32_dpp v40, v40, v40 row_shl:4 row_mask:0xf bank_mask:0xf bound_ctrl:1
	v_add_f32_dpp v41, v41, v41 row_shl:4 row_mask:0xf bank_mask:0xf bound_ctrl:1
	v_add_f32_dpp v42, v42, v42 row_shl:4 row_mask:0xf bank_mask:0xf bound_ctrl:1
	v_add_f32_dpp v43, v43, v43 row_shl:4 row_mask:0xf bank_mask:0xf bound_ctrl:1
	v_add_f32_dpp v44, v44, v44 row_shl:4 row_mask:0xf bank_mask:0xf bound_ctrl:1
	v_add_f32_dpp v45, v45, v45 row_shl:4 row_mask:0xf bank_mask:0xf bound_ctrl:1
	v_add_f32_dpp v46, v46, v46 row_shl:4 row_mask:0xf bank_mask:0xf bound_ctrl:1
	v_add_f32_dpp v47, v47, v47 row_shl:4 row_mask:0xf bank_mask:0xf bound_ctrl:1
	v_add_f32_dpp v40, v40, v40 row_shl:8 row_mask:0xf bank_mask:0xf bound_ctrl:1
	v_add_f32_dpp v41, v41, v41 row_shl:8 row_mask:0xf bank_mask:0xf bound_ctrl:1
	v_add_f32_dpp v42, v42, v42 row_shl:8 row_mask:0xf bank_mask:0xf bound_ctrl:1
	v_add_f32_dpp v43, v43, v43 row_shl:8 row_mask:0xf bank_mask:0xf bound_ctrl:1
	v_add_f32_dpp v44, v44, v44 row_shl:8 row_mask:0xf bank_mask:0xf bound_ctrl:1
	v_add_f32_dpp v45, v45, v45 row_shl:8 row_mask:0xf bank_mask:0xf bound_ctrl:1
	v_add_f32_dpp v46, v46, v46 row_shl:8 row_mask:0xf bank_mask:0xf bound_ctrl:1
	v_add_f32_dpp v47, v47, v47 row_shl:8 row_mask:0xf bank_mask:0xf bound_ctrl:1
	v_mov_b32_dpp v88, v40 row_newbcast:0 row_mask:0xf bank_mask:0xf
	v_mov_b32_dpp v89, v41 row_newbcast:0 row_mask:0xf bank_mask:0xf
	v_mov_b32_dpp v90, v42 row_newbcast:0 row_mask:0xf bank_mask:0xf
	v_mov_b32_dpp v91, v43 row_newbcast:0 row_mask:0xf bank_mask:0xf
	v_mov_b32_dpp v92, v44 row_newbcast:0 row_mask:0xf bank_mask:0xf
	v_mov_b32_dpp v93, v45 row_newbcast:0 row_mask:0xf bank_mask:0xf
	v_mov_b32_dpp v94, v46 row_newbcast:0 row_mask:0xf bank_mask:0xf
	v_mov_b32_dpp v95, v47 row_newbcast:0 row_mask:0xf bank_mask:0xf
	v_pk_add_f32 v[40:41], v[40:41], v[68:69]
	v_pk_add_f32 v[44:45], v[44:45], v[76:77]
	v_pk_add_f32 v[42:43], v[42:43], v[70:71]
	v_pk_add_f32 v[46:47], v[46:47], v[78:79]
	v_pk_mul_f32 v[132:133], v[40:41], v[112:113]
	v_pk_mul_f32 v[40:41], v[40:41], v[108:109]
	v_pk_fma_f32 v[40:41], v[44:45], v[112:113], v[40:41] neg_lo:[1,0,0] neg_hi:[1,0,0]
	v_pk_fma_f32 v[44:45], v[44:45], v[108:109], v[132:133]
	v_pk_mul_f32 v[132:133], v[42:43], v[114:115]
	v_pk_mul_f32 v[42:43], v[42:43], v[110:111]
	v_pk_fma_f32 v[42:43], v[46:47], v[114:115], v[42:43] neg_lo:[1,0,0] neg_hi:[1,0,0]
	v_pk_fma_f32 v[46:47], v[46:47], v[110:111], v[132:133]
	v_pk_add_f32 v[88:89], v[88:89], v[68:69]
	v_pk_add_f32 v[92:93], v[92:93], v[76:77]
	v_pk_mul_f32 v[132:133], v[92:93], v[120:121]
	v_pk_mul_f32 v[76:77], v[88:89], v[120:121]
	v_pk_fma_f32 v[68:69], v[88:89], v[116:117], v[132:133] neg_lo:[0,0,1] neg_hi:[0,0,1]
	v_pk_fma_f32 v[76:77], v[92:93], v[116:117], v[76:77]
	v_pk_add_f32 v[90:91], v[90:91], v[70:71]
	v_pk_add_f32 v[94:95], v[94:95], v[78:79]
	v_pk_mul_f32 v[132:133], v[94:95], v[122:123]
	v_pk_mul_f32 v[78:79], v[90:91], v[122:123]
	v_pk_fma_f32 v[70:71], v[90:91], v[118:119], v[132:133] neg_lo:[0,0,1] neg_hi:[0,0,1]
	v_pk_fma_f32 v[78:79], v[94:95], v[118:119], v[78:79]
	v_pk_mul_f32 v[132:133], v[32:33], v[104:105]
	v_pk_mul_f32 v[32:33], v[32:33], v[100:101]
	v_pk_fma_f32 v[32:33], v[36:37], v[104:105], v[32:33] neg_lo:[1,0,0] neg_hi:[1,0,0]
	v_pk_fma_f32 v[36:37], v[36:37], v[100:101], v[132:133]
	v_pk_mul_f32 v[132:133], v[34:35], v[106:107]
	v_pk_mul_f32 v[34:35], v[34:35], v[102:103]
	v_pk_fma_f32 v[34:35], v[38:39], v[106:107], v[34:35] neg_lo:[1,0,0] neg_hi:[1,0,0]
	v_pk_fma_f32 v[38:39], v[38:39], v[102:103], v[132:133]
	v_add_f32_dpp v32, v32, v32 row_shl:1 row_mask:0xf bank_mask:0xf bound_ctrl:1
	v_add_f32_dpp v33, v33, v33 row_shl:1 row_mask:0xf bank_mask:0xf bound_ctrl:1
	v_add_f32_dpp v34, v34, v34 row_shl:1 row_mask:0xf bank_mask:0xf bound_ctrl:1
	v_add_f32_dpp v35, v35, v35 row_shl:1 row_mask:0xf bank_mask:0xf bound_ctrl:1
	v_add_f32_dpp v36, v36, v36 row_shl:1 row_mask:0xf bank_mask:0xf bound_ctrl:1
	v_add_f32_dpp v37, v37, v37 row_shl:1 row_mask:0xf bank_mask:0xf bound_ctrl:1
	v_add_f32_dpp v38, v38, v38 row_shl:1 row_mask:0xf bank_mask:0xf bound_ctrl:1
	v_add_f32_dpp v39, v39, v39 row_shl:1 row_mask:0xf bank_mask:0xf bound_ctrl:1
	v_add_f32_dpp v32, v32, v32 row_shl:2 row_mask:0xf bank_mask:0xf bound_ctrl:1
	v_add_f32_dpp v33, v33, v33 row_shl:2 row_mask:0xf bank_mask:0xf bound_ctrl:1
	v_add_f32_dpp v34, v34, v34 row_shl:2 row_mask:0xf bank_mask:0xf bound_ctrl:1
	v_add_f32_dpp v35, v35, v35 row_shl:2 row_mask:0xf bank_mask:0xf bound_ctrl:1
	v_add_f32_dpp v36, v36, v36 row_shl:2 row_mask:0xf bank_mask:0xf bound_ctrl:1
	v_add_f32_dpp v37, v37, v37 row_shl:2 row_mask:0xf bank_mask:0xf bound_ctrl:1
	v_add_f32_dpp v38, v38, v38 row_shl:2 row_mask:0xf bank_mask:0xf bound_ctrl:1
	v_add_f32_dpp v39, v39, v39 row_shl:2 row_mask:0xf bank_mask:0xf bound_ctrl:1
	v_add_f32_dpp v32, v32, v32 row_shl:4 row_mask:0xf bank_mask:0xf bound_ctrl:1
	v_add_f32_dpp v33, v33, v33 row_shl:4 row_mask:0xf bank_mask:0xf bound_ctrl:1
	v_add_f32_dpp v34, v34, v34 row_shl:4 row_mask:0xf bank_mask:0xf bound_ctrl:1
	v_add_f32_dpp v35, v35, v35 row_shl:4 row_mask:0xf bank_mask:0xf bound_ctrl:1
	v_add_f32_dpp v36, v36, v36 row_shl:4 row_mask:0xf bank_mask:0xf bound_ctrl:1
	v_add_f32_dpp v37, v37, v37 row_shl:4 row_mask:0xf bank_mask:0xf bound_ctrl:1
	v_add_f32_dpp v38, v38, v38 row_shl:4 row_mask:0xf bank_mask:0xf bound_ctrl:1
	v_add_f32_dpp v39, v39, v39 row_shl:4 row_mask:0xf bank_mask:0xf bound_ctrl:1
	v_add_f32_dpp v32, v32, v32 row_shl:8 row_mask:0xf bank_mask:0xf bound_ctrl:1
	v_add_f32_dpp v33, v33, v33 row_shl:8 row_mask:0xf bank_mask:0xf bound_ctrl:1
	v_add_f32_dpp v34, v34, v34 row_shl:8 row_mask:0xf bank_mask:0xf bound_ctrl:1
	v_add_f32_dpp v35, v35, v35 row_shl:8 row_mask:0xf bank_mask:0xf bound_ctrl:1
	v_add_f32_dpp v36, v36, v36 row_shl:8 row_mask:0xf bank_mask:0xf bound_ctrl:1
	v_add_f32_dpp v37, v37, v37 row_shl:8 row_mask:0xf bank_mask:0xf bound_ctrl:1
	v_add_f32_dpp v38, v38, v38 row_shl:8 row_mask:0xf bank_mask:0xf bound_ctrl:1
	v_add_f32_dpp v39, v39, v39 row_shl:8 row_mask:0xf bank_mask:0xf bound_ctrl:1
	v_mov_b32_dpp v88, v32 row_newbcast:0 row_mask:0xf bank_mask:0xf
	v_mov_b32_dpp v89, v33 row_newbcast:0 row_mask:0xf bank_mask:0xf
	v_mov_b32_dpp v90, v34 row_newbcast:0 row_mask:0xf bank_mask:0xf
	v_mov_b32_dpp v91, v35 row_newbcast:0 row_mask:0xf bank_mask:0xf
	v_mov_b32_dpp v92, v36 row_newbcast:0 row_mask:0xf bank_mask:0xf
	v_mov_b32_dpp v93, v37 row_newbcast:0 row_mask:0xf bank_mask:0xf
	v_mov_b32_dpp v94, v38 row_newbcast:0 row_mask:0xf bank_mask:0xf
	v_mov_b32_dpp v95, v39 row_newbcast:0 row_mask:0xf bank_mask:0xf
	v_pk_add_f32 v[32:33], v[32:33], v[68:69]
	v_pk_add_f32 v[36:37], v[36:37], v[76:77]
	v_pk_add_f32 v[34:35], v[34:35], v[70:71]
	v_pk_add_f32 v[38:39], v[38:39], v[78:79]
	v_pk_mul_f32 v[132:133], v[32:33], v[112:113]
	v_pk_mul_f32 v[32:33], v[32:33], v[108:109]
	v_pk_fma_f32 v[32:33], v[36:37], v[112:113], v[32:33] neg_lo:[1,0,0] neg_hi:[1,0,0]
	v_pk_fma_f32 v[36:37], v[36:37], v[108:109], v[132:133]
	v_pk_mul_f32 v[132:133], v[34:35], v[114:115]
	v_pk_mul_f32 v[34:35], v[34:35], v[110:111]
	v_pk_fma_f32 v[34:35], v[38:39], v[114:115], v[34:35] neg_lo:[1,0,0] neg_hi:[1,0,0]
	v_pk_fma_f32 v[38:39], v[38:39], v[110:111], v[132:133]
	v_pk_add_f32 v[88:89], v[88:89], v[68:69]
	v_pk_add_f32 v[92:93], v[92:93], v[76:77]
	v_pk_mul_f32 v[132:133], v[92:93], v[120:121]
	v_pk_mul_f32 v[76:77], v[88:89], v[120:121]
	v_pk_fma_f32 v[68:69], v[88:89], v[116:117], v[132:133] neg_lo:[0,0,1] neg_hi:[0,0,1]
	v_pk_fma_f32 v[76:77], v[92:93], v[116:117], v[76:77]
	v_pk_add_f32 v[90:91], v[90:91], v[70:71]
	v_pk_add_f32 v[94:95], v[94:95], v[78:79]
	v_pk_mul_f32 v[132:133], v[94:95], v[122:123]
	v_pk_mul_f32 v[78:79], v[90:91], v[122:123]
	v_pk_fma_f32 v[70:71], v[90:91], v[118:119], v[132:133] neg_lo:[0,0,1] neg_hi:[0,0,1]
	v_pk_fma_f32 v[78:79], v[94:95], v[118:119], v[78:79]
	s_waitcnt vmcnt(0)
	v_cvt_pk_bf16_f32 v96, v32, v33
	v_cvt_pk_bf16_f32 v97, v34, v35
	v_cvt_pk_bf16_f32 v98, v36, v37
	v_cvt_pk_bf16_f32 v99, v38, v39
	s_nop 1
	v_mfma_f32_16x16x32_bf16 v[16:19], v[80:83], v[96:99], v[16:19]
	v_cvt_pk_bf16_f32 v96, v40, v41
	v_cvt_pk_bf16_f32 v97, v42, v43
	v_cvt_pk_bf16_f32 v98, v44, v45
	v_cvt_pk_bf16_f32 v99, v46, v47
	s_nop 1
	v_mfma_f32_16x16x32_bf16 v[20:23], v[80:83], v[96:99], v[20:23]
	v_cvt_pk_bf16_f32 v96, v48, v49
	v_cvt_pk_bf16_f32 v97, v50, v51
	v_cvt_pk_bf16_f32 v98, v52, v53
	v_cvt_pk_bf16_f32 v99, v54, v55
	s_nop 1
	v_mfma_f32_16x16x32_bf16 v[24:27], v[80:83], v[96:99], v[24:27]
	v_cvt_pk_bf16_f32 v96, v56, v57
	v_cvt_pk_bf16_f32 v97, v58, v59
	v_cvt_pk_bf16_f32 v98, v60, v61
	v_cvt_pk_bf16_f32 v99, v62, v63
	s_nop 1
	v_mfma_f32_16x16x32_bf16 v[28:31], v[80:83], v[96:99], v[28:31]
	v_and_b32_e32 v100, 15, v205
	v_lshrrev_b32_e32 v101, 4, v205
	v_mul_u32_u24_e32 v102, 0xe00, v100
	v_lshl_add_u32 v102, v101, 3, v102
	v_lshlrev_b32_e32 v103, 9, v100
	v_lshl_add_u32 v103, v101, 3, v103
	v_lshlrev_b32_e32 v104, 4, v101
	s_mul_i32 s18, s9, 0xe00
	s_lshl_b32 s19, s7, 5
	s_add_i32 s18, s18, s19
	s_add_u32 s18, s18, 0x5e00c00
	s_add_u32 s18, s4, s18
	s_addc_u32 s19, s5, 0
	global_load_dwordx2 v[108:109], v102, s[18:19]
	s_add_u32 s18, s18, 0xe000
	s_addc_u32 s19, s19, 0
	global_load_dwordx2 v[110:111], v102, s[18:19]
	s_add_u32 s18, s18, 0xe000
	s_addc_u32 s19, s19, 0
	global_load_dwordx2 v[112:113], v102, s[18:19]
	s_add_u32 s18, s18, 0xe000
	s_addc_u32 s19, s19, 0
	global_load_dwordx2 v[114:115], v102, s[18:19]
	v_readlane_b32 s10, v247, 28
	s_lshl_b32 s10, s10, 10
	s_lshl_b32 s11, s7, 6
	s_add_i32 s10, s10, s11
	s_add_u32 s10, s10, 0x21fb20
	s_add_u32 s20, s4, s10
	s_addc_u32 s21, s5, 0
	global_load_dwordx4 v[116:119], v104, s[20:21]
	s_lshl_b32 s10, s9, 9
	s_add_i32 s10, s10, s11
	s_lshr_b32 s11, s11, 1
	s_sub_i32 s10, s10, s11
	s_add_u32 s10, s10, 0xc500000
	s_add_u32 s22, s4, s10
	s_addc_u32 s23, s5, 0
	s_waitcnt vmcnt(0)
	s_nop 4
	v_lshlrev_b32_e32 v120, 16, v108
	v_and_b32_e32 v121, 0xffff0000, v108
	v_lshlrev_b32_e32 v122, 16, v109
	v_and_b32_e32 v123, 0xffff0000, v109
	v_fmac_f32_e32 v16, v116, v120
	v_fmac_f32_e32 v17, v117, v121
	v_fmac_f32_e32 v18, v118, v122
	v_fmac_f32_e32 v19, v119, v123
	v_cvt_pk_bf16_f32 v124, v16, v17
	v_cvt_pk_bf16_f32 v125, v18, v19
	global_store_dwordx2 v103, v[124:125], s[22:23] offset:0
	s_add_u32 s22, s22, 0x2000
	s_addc_u32 s23, s23, 0
	v_lshlrev_b32_e32 v120, 16, v110
	v_and_b32_e32 v121, 0xffff0000, v110
	v_lshlrev_b32_e32 v122, 16, v111
	v_and_b32_e32 v123, 0xffff0000, v111
	v_fmac_f32_e32 v20, v116, v120
	v_fmac_f32_e32 v21, v117, v121
	v_fmac_f32_e32 v22, v118, v122
	v_fmac_f32_e32 v23, v119, v123
	v_cvt_pk_bf16_f32 v124, v20, v21
	v_cvt_pk_bf16_f32 v125, v22, v23
	global_store_dwordx2 v103, v[124:125], s[22:23] offset:0
	s_add_u32 s22, s22, 0x2000
	s_addc_u32 s23, s23, 0
	v_lshlrev_b32_e32 v120, 16, v112
	v_and_b32_e32 v121, 0xffff0000, v112
	v_lshlrev_b32_e32 v122, 16, v113
	v_and_b32_e32 v123, 0xffff0000, v113
	v_fmac_f32_e32 v24, v116, v120
	v_fmac_f32_e32 v25, v117, v121
	v_fmac_f32_e32 v26, v118, v122
	v_fmac_f32_e32 v27, v119, v123
	v_cvt_pk_bf16_f32 v124, v24, v25
	v_cvt_pk_bf16_f32 v125, v26, v27
	global_store_dwordx2 v103, v[124:125], s[22:23] offset:0
	s_add_u32 s22, s22, 0x2000
	s_addc_u32 s23, s23, 0
	v_lshlrev_b32_e32 v120, 16, v114
	v_and_b32_e32 v121, 0xffff0000, v114
	v_lshlrev_b32_e32 v122, 16, v115
	v_and_b32_e32 v123, 0xffff0000, v115
	v_fmac_f32_e32 v28, v116, v120
	v_fmac_f32_e32 v29, v117, v121
	v_fmac_f32_e32 v30, v118, v122
	v_fmac_f32_e32 v31, v119, v123
	v_cvt_pk_bf16_f32 v124, v28, v29
	v_cvt_pk_bf16_f32 v125, v30, v31
	global_store_dwordx2 v103, v[124:125], s[22:23] offset:0
	s_cmp_eq_u32 s37, 1
	s_cbranch_scc1 .Lss3_done
	s_add_i32 s36, s36, s30
	s_branch .Lss3_top

.LBB0_449:
	s_andn2_b64 vcc, exec, s[0:1]
	s_cbranch_vccnz .LBB0_478
	s_sub_i32 s86, s12, s60
	s_mul_i32 s10, s86, 0xf0f1
	s_lshr_b32 s10, s10, 22
	s_mul_i32 s11, s10, 68
	s_sub_i32 s8, s86, s11
	s_and_b32 s7, s10, 15
	s_lshr_b32 s6, s10, 4
	s_lshl_b32 s10, s8, 6
	s_lshl_b32 s11, s6, 8
	s_add_i32 s9, s10, s11
	s_lshl_b32 s11, s6, 12
	s_add_i32 s11, s11, s10
	s_add_i32 s11, s11, 0x300
	s_cmp_lt_u32 s8, 4
	s_cselect_b32 s9, s9, s11
	v_mov_b32_e32 v0, 0
	v_mov_b32_e32 v1, 0
	v_mov_b32_e32 v2, 0
	v_mov_b32_e32 v3, 0
	v_mov_b32_e32 v4, 0
	v_mov_b32_e32 v5, 0
	v_mov_b32_e32 v6, 0
	v_mov_b32_e32 v7, 0
	v_mov_b32_e32 v8, 0
	v_mov_b32_e32 v9, 0
	v_mov_b32_e32 v10, 0
	v_mov_b32_e32 v11, 0
	v_mov_b32_e32 v12, 0
	v_mov_b32_e32 v13, 0
	v_mov_b32_e32 v14, 0
	v_mov_b32_e32 v15, 0
	v_and_b32_e32 v100, 15, v205
	v_mul_u32_u24_e32 v100, 0xe00, v100
	v_and_b32_e32 v101, 16, v205
	v_add_u32_e32 v100, v100, v101
	s_mul_i32 s18, s9, 0xe00
	s_lshl_b32 s19, s7, 5
	s_add_i32 s18, s18, s19
	s_add_u32 s18, s18, 0x5e00c00
	s_add_u32 s18, s4, s18
	s_addc_u32 s19, s5, 0
	s_mov_b32 exec_hi, 0
	global_load_dwordx4 v[0:3], v100, s[18:19]
	s_add_u32 s18, s18, 0xe000
	s_addc_u32 s19, s19, 0
	global_load_dwordx4 v[4:7], v100, s[18:19]
	s_add_u32 s18, s18, 0xe000
	s_addc_u32 s19, s19, 0
	global_load_dwordx4 v[8:11], v100, s[18:19]
	s_add_u32 s18, s18, 0xe000
	s_addc_u32 s19, s19, 0
	global_load_dwordx4 v[12:15], v100, s[18:19]
	s_mov_b64 exec, -1
	v_and_b32_e32 v112, 15, v205
	v_lshlrev_b32_e32 v112, 6, v112
	v_and_b32_e32 v113, 16, v205
	v_lshl_add_u32 v112, v113, 1, v112
	v_lshlrev_b32_e32 v113, 4, v205
	v_lshrrev_b32_e32 v114, 4, v205
	v_lshlrev_b32_e32 v114, 5, v114
	v_readlane_b32 s10, v247, 28
	s_mov_b32 s11, s8
	s_lshl_b32 s16, s10, 1
	s_add_i32 s16, s16, 0
	s_lshl_b32 s16, s16, 4
	s_add_i32 s16, s16, s7
	s_lshl_b32 s17, s6, 1
	s_add_i32 s17, s17, 0
	s_lshl_b32 s17, s17, 4
	s_add_i32 s17, s17, s7
	s_mul_i32 s17, s17, 68
	s_add_i32 s17, s17, s11
	s_lshl_b32 s17, s17, 6
	s_lshl_b32 s20, s16, 13
	s_add_u32 s20, s20, 0xfd00000
	s_add_u32 s20, s4, s20
	s_addc_u32 s21, s5, 0
	s_lshl_b32 s24, s16, 14
	s_add_u32 s24, s24, 0xfc00000
	s_add_u32 s24, s4, s24
	s_addc_u32 s25, s5, 0
	s_lshl_b32 s26, s17, 3
	s_add_u32 s26, s26, 0x300000
	s_add_u32 s26, s4, s26
	s_addc_u32 s27, s5, 0
	global_load_dwordx4 v[48:51], v113, s[20:21]
	global_load_dwordx4 v[56:59], v113, s[20:21] offset:1024
	global_load_dwordx4 v[80:83], v113, s[24:25] offset:0
	global_load_dwordx4 v[84:87], v113, s[24:25] offset:1024
	global_load_dwordx4 v[88:91], v113, s[24:25] offset:2048
	global_load_dwordx4 v[92:95], v113, s[24:25] offset:3072
	s_add_u32 s20, s20, 0x800
	s_addc_u32 s21, s21, 0
	s_add_u32 s24, s24, 0x1000
	s_addc_u32 s25, s25, 0
	s_waitcnt vmcnt(6)
	s_waitcnt vmcnt(4)
	global_load_dwordx4 v[64:67], v113, s[20:21]
	global_load_dwordx4 v[72:75], v113, s[20:21] offset:1024
	global_load_dwordx4 v[96:99], v113, s[24:25] offset:0
	global_load_dwordx4 v[100:103], v113, s[24:25] offset:1024
	global_load_dwordx4 v[104:107], v113, s[24:25] offset:2048
	global_load_dwordx4 v[108:111], v113, s[24:25] offset:3072
	s_add_u32 s20, s20, 0x800
	s_addc_u32 s21, s21, 0
	s_add_u32 s24, s24, 0x1000
	s_addc_u32 s25, s25, 0
	v_mfma_f32_16x16x32_bf16 v[16:19], v[48:51], v[0:3], 0
	v_mfma_f32_16x16x32_bf16 v[20:23], v[56:59], v[0:3], 0
	v_mfma_f32_16x16x32_bf16 v[24:27], v[48:51], v[4:7], 0
	v_mfma_f32_16x16x32_bf16 v[28:31], v[56:59], v[4:7], 0
	v_mfma_f32_16x16x32_bf16 v[32:35], v[48:51], v[8:11], 0
	v_mfma_f32_16x16x32_bf16 v[36:39], v[56:59], v[8:11], 0
	v_mfma_f32_16x16x32_bf16 v[40:43], v[48:51], v[12:15], 0
	v_mfma_f32_16x16x32_bf16 v[44:47], v[56:59], v[12:15], 0
	s_waitcnt vmcnt(6)
	s_nop 7
	v_pk_mul_f32 v[52:53], v[80:81], v[20:21]
	v_pk_mul_f32 v[120:121], v[80:81], v[16:17]
	v_pk_fma_f32 v[120:121], v[84:85], v[20:21], v[120:121] neg_lo:[1,0,0] neg_hi:[1,0,0]
	v_pk_fma_f32 v[124:125], v[84:85], v[16:17], v[52:53]
	v_pk_mul_f32 v[52:53], v[82:83], v[22:23]
	v_pk_mul_f32 v[122:123], v[82:83], v[18:19]
	v_pk_fma_f32 v[122:123], v[86:87], v[22:23], v[122:123] neg_lo:[1,0,0] neg_hi:[1,0,0]
	v_pk_fma_f32 v[126:127], v[86:87], v[18:19], v[52:53]
	v_pk_mul_f32 v[52:53], v[80:81], v[28:29]
	v_pk_mul_f32 v[60:61], v[80:81], v[24:25]
	v_pk_fma_f32 v[60:61], v[84:85], v[28:29], v[60:61] neg_lo:[1,0,0] neg_hi:[1,0,0]
	v_pk_fma_f32 v[62:63], v[84:85], v[24:25], v[52:53]
	v_pk_fma_f32 v[62:63], v[120:121], v[92:93], v[62:63]
	v_pk_fma_f32 v[60:61], v[120:121], v[88:89], v[60:61]
	v_pk_fma_f32 v[120:121], v[124:125], v[92:93], v[60:61] neg_lo:[1,0,0] neg_hi:[1,0,0]
	v_pk_fma_f32 v[124:125], v[124:125], v[88:89], v[62:63]
	v_pk_mul_f32 v[52:53], v[82:83], v[30:31]
	v_pk_mul_f32 v[60:61], v[82:83], v[26:27]
	v_pk_fma_f32 v[60:61], v[86:87], v[30:31], v[60:61] neg_lo:[1,0,0] neg_hi:[1,0,0]
	v_pk_fma_f32 v[62:63], v[86:87], v[26:27], v[52:53]
	v_pk_fma_f32 v[62:63], v[122:123], v[94:95], v[62:63]
	v_pk_fma_f32 v[60:61], v[122:123], v[90:91], v[60:61]
	v_pk_fma_f32 v[122:123], v[126:127], v[94:95], v[60:61] neg_lo:[1,0,0] neg_hi:[1,0,0]
	v_pk_fma_f32 v[126:127], v[126:127], v[90:91], v[62:63]
	v_pk_mul_f32 v[52:53], v[80:81], v[36:37]
	v_pk_mul_f32 v[60:61], v[80:81], v[32:33]
	v_pk_fma_f32 v[60:61], v[84:85], v[36:37], v[60:61] neg_lo:[1,0,0] neg_hi:[1,0,0]
	v_pk_fma_f32 v[62:63], v[84:85], v[32:33], v[52:53]
	v_pk_fma_f32 v[62:63], v[120:121], v[92:93], v[62:63]
	v_pk_fma_f32 v[60:61], v[120:121], v[88:89], v[60:61]
	v_pk_fma_f32 v[120:121], v[124:125], v[92:93], v[60:61] neg_lo:[1,0,0] neg_hi:[1,0,0]
	v_pk_fma_f32 v[124:125], v[124:125], v[88:89], v[62:63]
	v_pk_mul_f32 v[52:53], v[82:83], v[38:39]
	v_pk_mul_f32 v[60:61], v[82:83], v[34:35]
	v_pk_fma_f32 v[60:61], v[86:87], v[38:39], v[60:61] neg_lo:[1,0,0] neg_hi:[1,0,0]
	v_pk_fma_f32 v[62:63], v[86:87], v[34:35], v[52:53]
	v_pk_fma_f32 v[62:63], v[122:123], v[94:95], v[62:63]
	v_pk_fma_f32 v[60:61], v[122:123], v[90:91], v[60:61]
	v_pk_fma_f32 v[122:123], v[126:127], v[94:95], v[60:61] neg_lo:[1,0,0] neg_hi:[1,0,0]
	v_pk_fma_f32 v[126:127], v[126:127], v[90:91], v[62:63]
	v_pk_mul_f32 v[52:53], v[80:81], v[44:45]
	v_pk_mul_f32 v[60:61], v[80:81], v[40:41]
	v_pk_fma_f32 v[60:61], v[84:85], v[44:45], v[60:61] neg_lo:[1,0,0] neg_hi:[1,0,0]
	v_pk_fma_f32 v[62:63], v[84:85], v[40:41], v[52:53]
	v_pk_fma_f32 v[62:63], v[120:121], v[92:93], v[62:63]
	v_pk_fma_f32 v[60:61], v[120:121], v[88:89], v[60:61]
	v_pk_fma_f32 v[120:121], v[124:125], v[92:93], v[60:61] neg_lo:[1,0,0] neg_hi:[1,0,0]
	v_pk_fma_f32 v[124:125], v[124:125], v[88:89], v[62:63]
	v_pk_mul_f32 v[52:53], v[82:83], v[46:47]
	v_pk_mul_f32 v[60:61], v[82:83], v[42:43]
	v_pk_fma_f32 v[60:61], v[86:87], v[46:47], v[60:61] neg_lo:[1,0,0] neg_hi:[1,0,0]
	v_pk_fma_f32 v[62:63], v[86:87], v[42:43], v[52:53]
	v_pk_fma_f32 v[62:63], v[122:123], v[94:95], v[62:63]
	v_pk_fma_f32 v[60:61], v[122:123], v[90:91], v[60:61]
	v_pk_fma_f32 v[122:123], v[126:127], v[94:95], v[60:61] neg_lo:[1,0,0] neg_hi:[1,0,0]
	v_pk_fma_f32 v[126:127], v[126:127], v[90:91], v[62:63]
	v_add_f32_dpp v120, v120, v120 row_ror:8 row_mask:0xf bank_mask:0xf
	v_add_f32_dpp v121, v121, v121 row_ror:8 row_mask:0xf bank_mask:0xf
	v_add_f32_dpp v122, v122, v122 row_ror:8 row_mask:0xf bank_mask:0xf
	v_add_f32_dpp v123, v123, v123 row_ror:8 row_mask:0xf bank_mask:0xf
	v_add_f32_dpp v124, v124, v124 row_ror:8 row_mask:0xf bank_mask:0xf
	v_add_f32_dpp v125, v125, v125 row_ror:8 row_mask:0xf bank_mask:0xf
	v_add_f32_dpp v126, v126, v126 row_ror:8 row_mask:0xf bank_mask:0xf
	v_add_f32_dpp v127, v127, v127 row_ror:8 row_mask:0xf bank_mask:0xf
	v_add_f32_dpp v120, v120, v120 row_ror:4 row_mask:0xf bank_mask:0xf
	v_add_f32_dpp v121, v121, v121 row_ror:4 row_mask:0xf bank_mask:0xf
	v_add_f32_dpp v122, v122, v122 row_ror:4 row_mask:0xf bank_mask:0xf
	v_add_f32_dpp v123, v123, v123 row_ror:4 row_mask:0xf bank_mask:0xf
	v_add_f32_dpp v124, v124, v124 row_ror:4 row_mask:0xf bank_mask:0xf
	v_add_f32_dpp v125, v125, v125 row_ror:4 row_mask:0xf bank_mask:0xf
	v_add_f32_dpp v126, v126, v126 row_ror:4 row_mask:0xf bank_mask:0xf
	v_add_f32_dpp v127, v127, v127 row_ror:4 row_mask:0xf bank_mask:0xf
	v_add_f32_dpp v120, v120, v120 row_ror:2 row_mask:0xf bank_mask:0xf
	v_add_f32_dpp v121, v121, v121 row_ror:2 row_mask:0xf bank_mask:0xf
	v_add_f32_dpp v122, v122, v122 row_ror:2 row_mask:0xf bank_mask:0xf
	v_add_f32_dpp v123, v123, v123 row_ror:2 row_mask:0xf bank_mask:0xf
	v_add_f32_dpp v124, v124, v124 row_ror:2 row_mask:0xf bank_mask:0xf
	v_add_f32_dpp v125, v125, v125 row_ror:2 row_mask:0xf bank_mask:0xf
	v_add_f32_dpp v126, v126, v126 row_ror:2 row_mask:0xf bank_mask:0xf
	v_add_f32_dpp v127, v127, v127 row_ror:2 row_mask:0xf bank_mask:0xf
	v_add_f32_dpp v120, v120, v120 row_ror:1 row_mask:0xf bank_mask:0xf
	v_add_f32_dpp v121, v121, v121 row_ror:1 row_mask:0xf bank_mask:0xf
	v_add_f32_dpp v122, v122, v122 row_ror:1 row_mask:0xf bank_mask:0xf
	v_add_f32_dpp v123, v123, v123 row_ror:1 row_mask:0xf bank_mask:0xf
	v_add_f32_dpp v124, v124, v124 row_ror:1 row_mask:0xf bank_mask:0xf
	v_add_f32_dpp v125, v125, v125 row_ror:1 row_mask:0xf bank_mask:0xf
	v_add_f32_dpp v126, v126, v126 row_ror:1 row_mask:0xf bank_mask:0xf
	v_add_f32_dpp v127, v127, v127 row_ror:1 row_mask:0xf bank_mask:0xf
	s_add_u32 s18, s26, 0
	s_addc_u32 s19, s27, 0
	v_mov_b32_e32 v128, v120
	v_mov_b32_e32 v129, v124
	v_mov_b32_e32 v130, v121
	v_mov_b32_e32 v131, v125
	v_mov_b32_e32 v132, v122
	v_mov_b32_e32 v133, v126
	v_mov_b32_e32 v134, v123
	v_mov_b32_e32 v135, v127
	s_mov_b32 exec_lo, 0x10001
	s_mov_b32 exec_hi, 0x10001
	global_store_dwordx4 v114, v[128:131], s[18:19]
	global_store_dwordx4 v114, v[132:135], s[18:19] offset:16
	s_mov_b64 exec, -1
	s_nop 1
	s_waitcnt vmcnt(4)
	global_load_dwordx4 v[48:51], v113, s[20:21]
	global_load_dwordx4 v[56:59], v113, s[20:21] offset:1024
	global_load_dwordx4 v[80:83], v113, s[24:25] offset:0
	global_load_dwordx4 v[84:87], v113, s[24:25] offset:1024
	global_load_dwordx4 v[88:91], v113, s[24:25] offset:2048
	global_load_dwordx4 v[92:95], v113, s[24:25] offset:3072
	s_add_u32 s20, s20, 0x800
	s_addc_u32 s21, s21, 0
	s_add_u32 s24, s24, 0x1000
	s_addc_u32 s25, s25, 0
	v_mfma_f32_16x16x32_bf16 v[16:19], v[64:67], v[0:3], 0
	v_mfma_f32_16x16x32_bf16 v[20:23], v[72:75], v[0:3], 0
	v_mfma_f32_16x16x32_bf16 v[24:27], v[64:67], v[4:7], 0
	v_mfma_f32_16x16x32_bf16 v[28:31], v[72:75], v[4:7], 0
	v_mfma_f32_16x16x32_bf16 v[32:35], v[64:67], v[8:11], 0
	v_mfma_f32_16x16x32_bf16 v[36:39], v[72:75], v[8:11], 0
	v_mfma_f32_16x16x32_bf16 v[40:43], v[64:67], v[12:15], 0
	v_mfma_f32_16x16x32_bf16 v[44:47], v[72:75], v[12:15], 0
	s_waitcnt vmcnt(6)
	s_nop 7
	v_pk_mul_f32 v[52:53], v[96:97], v[20:21]
	v_pk_mul_f32 v[120:121], v[96:97], v[16:17]
	v_pk_fma_f32 v[120:121], v[100:101], v[20:21], v[120:121] neg_lo:[1,0,0] neg_hi:[1,0,0]
	v_pk_fma_f32 v[124:125], v[100:101], v[16:17], v[52:53]
	v_pk_mul_f32 v[52:53], v[98:99], v[22:23]
	v_pk_mul_f32 v[122:123], v[98:99], v[18:19]
	v_pk_fma_f32 v[122:123], v[102:103], v[22:23], v[122:123] neg_lo:[1,0,0] neg_hi:[1,0,0]
	v_pk_fma_f32 v[126:127], v[102:103], v[18:19], v[52:53]
	v_pk_mul_f32 v[52:53], v[96:97], v[28:29]
	v_pk_mul_f32 v[60:61], v[96:97], v[24:25]
	v_pk_fma_f32 v[60:61], v[100:101], v[28:29], v[60:61] neg_lo:[1,0,0] neg_hi:[1,0,0]
	v_pk_fma_f32 v[62:63], v[100:101], v[24:25], v[52:53]
	v_pk_fma_f32 v[62:63], v[120:121], v[108:109], v[62:63]
	v_pk_fma_f32 v[60:61], v[120:121], v[104:105], v[60:61]
	v_pk_fma_f32 v[120:121], v[124:125], v[108:109], v[60:61] neg_lo:[1,0,0] neg_hi:[1,0,0]
	v_pk_fma_f32 v[124:125], v[124:125], v[104:105], v[62:63]
	v_pk_mul_f32 v[52:53], v[98:99], v[30:31]
	v_pk_mul_f32 v[60:61], v[98:99], v[26:27]
	v_pk_fma_f32 v[60:61], v[102:103], v[30:31], v[60:61] neg_lo:[1,0,0] neg_hi:[1,0,0]
	v_pk_fma_f32 v[62:63], v[102:103], v[26:27], v[52:53]
	v_pk_fma_f32 v[62:63], v[122:123], v[110:111], v[62:63]
	v_pk_fma_f32 v[60:61], v[122:123], v[106:107], v[60:61]
	v_pk_fma_f32 v[122:123], v[126:127], v[110:111], v[60:61] neg_lo:[1,0,0] neg_hi:[1,0,0]
	v_pk_fma_f32 v[126:127], v[126:127], v[106:107], v[62:63]
	v_pk_mul_f32 v[52:53], v[96:97], v[36:37]
	v_pk_mul_f32 v[60:61], v[96:97], v[32:33]
	v_pk_fma_f32 v[60:61], v[100:101], v[36:37], v[60:61] neg_lo:[1,0,0] neg_hi:[1,0,0]
	v_pk_fma_f32 v[62:63], v[100:101], v[32:33], v[52:53]
	v_pk_fma_f32 v[62:63], v[120:121], v[108:109], v[62:63]
	v_pk_fma_f32 v[60:61], v[120:121], v[104:105], v[60:61]
	v_pk_fma_f32 v[120:121], v[124:125], v[108:109], v[60:61] neg_lo:[1,0,0] neg_hi:[1,0,0]
	v_pk_fma_f32 v[124:125], v[124:125], v[104:105], v[62:63]
	v_pk_mul_f32 v[52:53], v[98:99], v[38:39]
	v_pk_mul_f32 v[60:61], v[98:99], v[34:35]
	v_pk_fma_f32 v[60:61], v[102:103], v[38:39], v[60:61] neg_lo:[1,0,0] neg_hi:[1,0,0]
	v_pk_fma_f32 v[62:63], v[102:103], v[34:35], v[52:53]
	v_pk_fma_f32 v[62:63], v[122:123], v[110:111], v[62:63]
	v_pk_fma_f32 v[60:61], v[122:123], v[106:107], v[60:61]
	v_pk_fma_f32 v[122:123], v[126:127], v[110:111], v[60:61] neg_lo:[1,0,0] neg_hi:[1,0,0]
	v_pk_fma_f32 v[126:127], v[126:127], v[106:107], v[62:63]
	v_pk_mul_f32 v[52:53], v[96:97], v[44:45]
	v_pk_mul_f32 v[60:61], v[96:97], v[40:41]
	v_pk_fma_f32 v[60:61], v[100:101], v[44:45], v[60:61] neg_lo:[1,0,0] neg_hi:[1,0,0]
	v_pk_fma_f32 v[62:63], v[100:101], v[40:41], v[52:53]
	v_pk_fma_f32 v[62:63], v[120:121], v[108:109], v[62:63]
	v_pk_fma_f32 v[60:61], v[120:121], v[104:105], v[60:61]
	v_pk_fma_f32 v[120:121], v[124:125], v[108:109], v[60:61] neg_lo:[1,0,0] neg_hi:[1,0,0]
	v_pk_fma_f32 v[124:125], v[124:125], v[104:105], v[62:63]
	v_pk_mul_f32 v[52:53], v[98:99], v[46:47]
	v_pk_mul_f32 v[60:61], v[98:99], v[42:43]
	v_pk_fma_f32 v[60:61], v[102:103], v[46:47], v[60:61] neg_lo:[1,0,0] neg_hi:[1,0,0]
	v_pk_fma_f32 v[62:63], v[102:103], v[42:43], v[52:53]
	v_pk_fma_f32 v[62:63], v[122:123], v[110:111], v[62:63]
	v_pk_fma_f32 v[60:61], v[122:123], v[106:107], v[60:61]
	v_pk_fma_f32 v[122:123], v[126:127], v[110:111], v[60:61] neg_lo:[1,0,0] neg_hi:[1,0,0]
	v_pk_fma_f32 v[126:127], v[126:127], v[106:107], v[62:63]
	v_add_f32_dpp v120, v120, v120 row_ror:8 row_mask:0xf bank_mask:0xf
	v_add_f32_dpp v121, v121, v121 row_ror:8 row_mask:0xf bank_mask:0xf
	v_add_f32_dpp v122, v122, v122 row_ror:8 row_mask:0xf bank_mask:0xf
	v_add_f32_dpp v123, v123, v123 row_ror:8 row_mask:0xf bank_mask:0xf
	v_add_f32_dpp v124, v124, v124 row_ror:8 row_mask:0xf bank_mask:0xf
	v_add_f32_dpp v125, v125, v125 row_ror:8 row_mask:0xf bank_mask:0xf
	v_add_f32_dpp v126, v126, v126 row_ror:8 row_mask:0xf bank_mask:0xf
	v_add_f32_dpp v127, v127, v127 row_ror:8 row_mask:0xf bank_mask:0xf
	v_add_f32_dpp v120, v120, v120 row_ror:4 row_mask:0xf bank_mask:0xf
	v_add_f32_dpp v121, v121, v121 row_ror:4 row_mask:0xf bank_mask:0xf
	v_add_f32_dpp v122, v122, v122 row_ror:4 row_mask:0xf bank_mask:0xf
	v_add_f32_dpp v123, v123, v123 row_ror:4 row_mask:0xf bank_mask:0xf
	v_add_f32_dpp v124, v124, v124 row_ror:4 row_mask:0xf bank_mask:0xf
	v_add_f32_dpp v125, v125, v125 row_ror:4 row_mask:0xf bank_mask:0xf
	v_add_f32_dpp v126, v126, v126 row_ror:4 row_mask:0xf bank_mask:0xf
	v_add_f32_dpp v127, v127, v127 row_ror:4 row_mask:0xf bank_mask:0xf
	v_add_f32_dpp v120, v120, v120 row_ror:2 row_mask:0xf bank_mask:0xf
	v_add_f32_dpp v121, v121, v121 row_ror:2 row_mask:0xf bank_mask:0xf
	v_add_f32_dpp v122, v122, v122 row_ror:2 row_mask:0xf bank_mask:0xf
	v_add_f32_dpp v123, v123, v123 row_ror:2 row_mask:0xf bank_mask:0xf
	v_add_f32_dpp v124, v124, v124 row_ror:2 row_mask:0xf bank_mask:0xf
	v_add_f32_dpp v125, v125, v125 row_ror:2 row_mask:0xf bank_mask:0xf
	v_add_f32_dpp v126, v126, v126 row_ror:2 row_mask:0xf bank_mask:0xf
	v_add_f32_dpp v127, v127, v127 row_ror:2 row_mask:0xf bank_mask:0xf
	v_add_f32_dpp v120, v120, v120 row_ror:1 row_mask:0xf bank_mask:0xf
	v_add_f32_dpp v121, v121, v121 row_ror:1 row_mask:0xf bank_mask:0xf
	v_add_f32_dpp v122, v122, v122 row_ror:1 row_mask:0xf bank_mask:0xf
	v_add_f32_dpp v123, v123, v123 row_ror:1 row_mask:0xf bank_mask:0xf
	v_add_f32_dpp v124, v124, v124 row_ror:1 row_mask:0xf bank_mask:0xf
	v_add_f32_dpp v125, v125, v125 row_ror:1 row_mask:0xf bank_mask:0xf
	v_add_f32_dpp v126, v126, v126 row_ror:1 row_mask:0xf bank_mask:0xf
	v_add_f32_dpp v127, v127, v127 row_ror:1 row_mask:0xf bank_mask:0xf
	s_add_u32 s18, s26, 128
	s_addc_u32 s19, s27, 0
	v_mov_b32_e32 v128, v120
	v_mov_b32_e32 v129, v124
	v_mov_b32_e32 v130, v121
	v_mov_b32_e32 v131, v125
	v_mov_b32_e32 v132, v122
	v_mov_b32_e32 v133, v126
	v_mov_b32_e32 v134, v123
	v_mov_b32_e32 v135, v127
	s_mov_b32 exec_lo, 0x10001
	s_mov_b32 exec_hi, 0x10001
	global_store_dwordx4 v114, v[128:131], s[18:19]
	global_store_dwordx4 v114, v[132:135], s[18:19] offset:16
	s_mov_b64 exec, -1
	s_nop 1
	s_waitcnt vmcnt(4)
	global_load_dwordx4 v[64:67], v113, s[20:21]
	global_load_dwordx4 v[72:75], v113, s[20:21] offset:1024
	global_load_dwordx4 v[96:99], v113, s[24:25] offset:0
	global_load_dwordx4 v[100:103], v113, s[24:25] offset:1024
	global_load_dwordx4 v[104:107], v113, s[24:25] offset:2048
	global_load_dwordx4 v[108:111], v113, s[24:25] offset:3072
	v_mfma_f32_16x16x32_bf16 v[16:19], v[48:51], v[0:3], 0
	v_mfma_f32_16x16x32_bf16 v[20:23], v[56:59], v[0:3], 0
	v_mfma_f32_16x16x32_bf16 v[24:27], v[48:51], v[4:7], 0
	v_mfma_f32_16x16x32_bf16 v[28:31], v[56:59], v[4:7], 0
	v_mfma_f32_16x16x32_bf16 v[32:35], v[48:51], v[8:11], 0
	v_mfma_f32_16x16x32_bf16 v[36:39], v[56:59], v[8:11], 0
	v_mfma_f32_16x16x32_bf16 v[40:43], v[48:51], v[12:15], 0
	v_mfma_f32_16x16x32_bf16 v[44:47], v[56:59], v[12:15], 0
	s_waitcnt vmcnt(6)
	s_nop 7
	v_pk_mul_f32 v[52:53], v[80:81], v[20:21]
	v_pk_mul_f32 v[120:121], v[80:81], v[16:17]
	v_pk_fma_f32 v[120:121], v[84:85], v[20:21], v[120:121] neg_lo:[1,0,0] neg_hi:[1,0,0]
	v_pk_fma_f32 v[124:125], v[84:85], v[16:17], v[52:53]
	v_pk_mul_f32 v[52:53], v[82:83], v[22:23]
	v_pk_mul_f32 v[122:123], v[82:83], v[18:19]
	v_pk_fma_f32 v[122:123], v[86:87], v[22:23], v[122:123] neg_lo:[1,0,0] neg_hi:[1,0,0]
	v_pk_fma_f32 v[126:127], v[86:87], v[18:19], v[52:53]
	v_pk_mul_f32 v[52:53], v[80:81], v[28:29]
	v_pk_mul_f32 v[60:61], v[80:81], v[24:25]
	v_pk_fma_f32 v[60:61], v[84:85], v[28:29], v[60:61] neg_lo:[1,0,0] neg_hi:[1,0,0]
	v_pk_fma_f32 v[62:63], v[84:85], v[24:25], v[52:53]
	v_pk_fma_f32 v[62:63], v[120:121], v[92:93], v[62:63]
	v_pk_fma_f32 v[60:61], v[120:121], v[88:89], v[60:61]
	v_pk_fma_f32 v[120:121], v[124:125], v[92:93], v[60:61] neg_lo:[1,0,0] neg_hi:[1,0,0]
	v_pk_fma_f32 v[124:125], v[124:125], v[88:89], v[62:63]
	v_pk_mul_f32 v[52:53], v[82:83], v[30:31]
	v_pk_mul_f32 v[60:61], v[82:83], v[26:27]
	v_pk_fma_f32 v[60:61], v[86:87], v[30:31], v[60:61] neg_lo:[1,0,0] neg_hi:[1,0,0]
	v_pk_fma_f32 v[62:63], v[86:87], v[26:27], v[52:53]
	v_pk_fma_f32 v[62:63], v[122:123], v[94:95], v[62:63]
	v_pk_fma_f32 v[60:61], v[122:123], v[90:91], v[60:61]
	v_pk_fma_f32 v[122:123], v[126:127], v[94:95], v[60:61] neg_lo:[1,0,0] neg_hi:[1,0,0]
	v_pk_fma_f32 v[126:127], v[126:127], v[90:91], v[62:63]
	v_pk_mul_f32 v[52:53], v[80:81], v[36:37]
	v_pk_mul_f32 v[60:61], v[80:81], v[32:33]
	v_pk_fma_f32 v[60:61], v[84:85], v[36:37], v[60:61] neg_lo:[1,0,0] neg_hi:[1,0,0]
	v_pk_fma_f32 v[62:63], v[84:85], v[32:33], v[52:53]
	v_pk_fma_f32 v[62:63], v[120:121], v[92:93], v[62:63]
	v_pk_fma_f32 v[60:61], v[120:121], v[88:89], v[60:61]
	v_pk_fma_f32 v[120:121], v[124:125], v[92:93], v[60:61] neg_lo:[1,0,0] neg_hi:[1,0,0]
	v_pk_fma_f32 v[124:125], v[124:125], v[88:89], v[62:63]
	v_pk_mul_f32 v[52:53], v[82:83], v[38:39]
	v_pk_mul_f32 v[60:61], v[82:83], v[34:35]
	v_pk_fma_f32 v[60:61], v[86:87], v[38:39], v[60:61] neg_lo:[1,0,0] neg_hi:[1,0,0]
	v_pk_fma_f32 v[62:63], v[86:87], v[34:35], v[52:53]
	v_pk_fma_f32 v[62:63], v[122:123], v[94:95], v[62:63]
	v_pk_fma_f32 v[60:61], v[122:123], v[90:91], v[60:61]
	v_pk_fma_f32 v[122:123], v[126:127], v[94:95], v[60:61] neg_lo:[1,0,0] neg_hi:[1,0,0]
	v_pk_fma_f32 v[126:127], v[126:127], v[90:91], v[62:63]
	v_pk_mul_f32 v[52:53], v[80:81], v[44:45]
	v_pk_mul_f32 v[60:61], v[80:81], v[40:41]
	v_pk_fma_f32 v[60:61], v[84:85], v[44:45], v[60:61] neg_lo:[1,0,0] neg_hi:[1,0,0]
	v_pk_fma_f32 v[62:63], v[84:85], v[40:41], v[52:53]
	v_pk_fma_f32 v[62:63], v[120:121], v[92:93], v[62:63]
	v_pk_fma_f32 v[60:61], v[120:121], v[88:89], v[60:61]
	v_pk_fma_f32 v[120:121], v[124:125], v[92:93], v[60:61] neg_lo:[1,0,0] neg_hi:[1,0,0]
	v_pk_fma_f32 v[124:125], v[124:125], v[88:89], v[62:63]
	v_pk_mul_f32 v[52:53], v[82:83], v[46:47]
	v_pk_mul_f32 v[60:61], v[82:83], v[42:43]
	v_pk_fma_f32 v[60:61], v[86:87], v[46:47], v[60:61] neg_lo:[1,0,0] neg_hi:[1,0,0]
	v_pk_fma_f32 v[62:63], v[86:87], v[42:43], v[52:53]
	v_pk_fma_f32 v[62:63], v[122:123], v[94:95], v[62:63]
	v_pk_fma_f32 v[60:61], v[122:123], v[90:91], v[60:61]
	v_pk_fma_f32 v[122:123], v[126:127], v[94:95], v[60:61] neg_lo:[1,0,0] neg_hi:[1,0,0]
	v_pk_fma_f32 v[126:127], v[126:127], v[90:91], v[62:63]
	v_add_f32_dpp v120, v120, v120 row_ror:8 row_mask:0xf bank_mask:0xf
	v_add_f32_dpp v121, v121, v121 row_ror:8 row_mask:0xf bank_mask:0xf
	v_add_f32_dpp v122, v122, v122 row_ror:8 row_mask:0xf bank_mask:0xf
	v_add_f32_dpp v123, v123, v123 row_ror:8 row_mask:0xf bank_mask:0xf
	v_add_f32_dpp v124, v124, v124 row_ror:8 row_mask:0xf bank_mask:0xf
	v_add_f32_dpp v125, v125, v125 row_ror:8 row_mask:0xf bank_mask:0xf
	v_add_f32_dpp v126, v126, v126 row_ror:8 row_mask:0xf bank_mask:0xf
	v_add_f32_dpp v127, v127, v127 row_ror:8 row_mask:0xf bank_mask:0xf
	v_add_f32_dpp v120, v120, v120 row_ror:4 row_mask:0xf bank_mask:0xf
	v_add_f32_dpp v121, v121, v121 row_ror:4 row_mask:0xf bank_mask:0xf
	v_add_f32_dpp v122, v122, v122 row_ror:4 row_mask:0xf bank_mask:0xf
	v_add_f32_dpp v123, v123, v123 row_ror:4 row_mask:0xf bank_mask:0xf
	v_add_f32_dpp v124, v124, v124 row_ror:4 row_mask:0xf bank_mask:0xf
	v_add_f32_dpp v125, v125, v125 row_ror:4 row_mask:0xf bank_mask:0xf
	v_add_f32_dpp v126, v126, v126 row_ror:4 row_mask:0xf bank_mask:0xf
	v_add_f32_dpp v127, v127, v127 row_ror:4 row_mask:0xf bank_mask:0xf
	v_add_f32_dpp v120, v120, v120 row_ror:2 row_mask:0xf bank_mask:0xf
	v_add_f32_dpp v121, v121, v121 row_ror:2 row_mask:0xf bank_mask:0xf
	v_add_f32_dpp v122, v122, v122 row_ror:2 row_mask:0xf bank_mask:0xf
	v_add_f32_dpp v123, v123, v123 row_ror:2 row_mask:0xf bank_mask:0xf
	v_add_f32_dpp v124, v124, v124 row_ror:2 row_mask:0xf bank_mask:0xf
	v_add_f32_dpp v125, v125, v125 row_ror:2 row_mask:0xf bank_mask:0xf
	v_add_f32_dpp v126, v126, v126 row_ror:2 row_mask:0xf bank_mask:0xf
	v_add_f32_dpp v127, v127, v127 row_ror:2 row_mask:0xf bank_mask:0xf
	v_add_f32_dpp v120, v120, v120 row_ror:1 row_mask:0xf bank_mask:0xf
	v_add_f32_dpp v121, v121, v121 row_ror:1 row_mask:0xf bank_mask:0xf
	v_add_f32_dpp v122, v122, v122 row_ror:1 row_mask:0xf bank_mask:0xf
	v_add_f32_dpp v123, v123, v123 row_ror:1 row_mask:0xf bank_mask:0xf
	v_add_f32_dpp v124, v124, v124 row_ror:1 row_mask:0xf bank_mask:0xf
	v_add_f32_dpp v125, v125, v125 row_ror:1 row_mask:0xf bank_mask:0xf
	v_add_f32_dpp v126, v126, v126 row_ror:1 row_mask:0xf bank_mask:0xf
	v_add_f32_dpp v127, v127, v127 row_ror:1 row_mask:0xf bank_mask:0xf
	s_add_u32 s18, s26, 256
	s_addc_u32 s19, s27, 0
	v_mov_b32_e32 v128, v120
	v_mov_b32_e32 v129, v124
	v_mov_b32_e32 v130, v121
	v_mov_b32_e32 v131, v125
	v_mov_b32_e32 v132, v122
	v_mov_b32_e32 v133, v126
	v_mov_b32_e32 v134, v123
	v_mov_b32_e32 v135, v127
	s_mov_b32 exec_lo, 0x10001
	s_mov_b32 exec_hi, 0x10001
	global_store_dwordx4 v114, v[128:131], s[18:19]
	global_store_dwordx4 v114, v[132:135], s[18:19] offset:16
	s_mov_b64 exec, -1
	s_nop 1
	s_waitcnt vmcnt(4)
	v_readlane_b32 s10, v247, 28
	s_sub_i32 s11, 3, s8
	s_sub_i32 s17, 71, s8
	s_cmp_lt_u32 s8, 4
	s_cselect_b32 s11, s11, s17
	s_lshl_b32 s16, s10, 1
	s_add_i32 s16, s16, 1
	s_lshl_b32 s16, s16, 4
	s_add_i32 s16, s16, s7
	s_lshl_b32 s17, s6, 1
	s_add_i32 s17, s17, 1
	s_lshl_b32 s17, s17, 4
	s_add_i32 s17, s17, s7
	s_mul_i32 s17, s17, 68
	s_add_i32 s17, s17, s11
	s_lshl_b32 s17, s17, 6
	s_lshl_b32 s20, s16, 13
	s_add_u32 s20, s20, 0xfd00000
	s_add_u32 s20, s4, s20
	s_addc_u32 s21, s5, 0
	s_lshl_b32 s24, s16, 14
	s_add_u32 s24, s24, 0xfc00000
	s_add_u32 s24, s4, s24
	s_addc_u32 s25, s5, 0
	s_lshl_b32 s36, s17, 3
	s_add_u32 s36, s36, 0x300000
	s_add_u32 s36, s4, s36
	s_addc_u32 s37, s5, 0
	global_load_dwordx4 v[48:51], v113, s[20:21]
	global_load_dwordx4 v[56:59], v113, s[20:21] offset:1024
	global_load_dwordx4 v[80:83], v113, s[24:25] offset:0
	global_load_dwordx4 v[84:87], v113, s[24:25] offset:1024
	global_load_dwordx4 v[88:91], v113, s[24:25] offset:2048
	global_load_dwordx4 v[92:95], v113, s[24:25] offset:3072
	s_add_u32 s20, s20, 0x800
	s_addc_u32 s21, s21, 0
	s_add_u32 s24, s24, 0x1000
	s_addc_u32 s25, s25, 0
	v_mfma_f32_16x16x32_bf16 v[16:19], v[64:67], v[0:3], 0
	v_mfma_f32_16x16x32_bf16 v[20:23], v[72:75], v[0:3], 0
	v_mfma_f32_16x16x32_bf16 v[24:27], v[64:67], v[4:7], 0
	v_mfma_f32_16x16x32_bf16 v[28:31], v[72:75], v[4:7], 0
	v_mfma_f32_16x16x32_bf16 v[32:35], v[64:67], v[8:11], 0
	v_mfma_f32_16x16x32_bf16 v[36:39], v[72:75], v[8:11], 0
	v_mfma_f32_16x16x32_bf16 v[40:43], v[64:67], v[12:15], 0
	v_mfma_f32_16x16x32_bf16 v[44:47], v[72:75], v[12:15], 0
	s_waitcnt vmcnt(6)
	s_nop 7
	v_pk_mul_f32 v[52:53], v[96:97], v[20:21]
	v_pk_mul_f32 v[120:121], v[96:97], v[16:17]
	v_pk_fma_f32 v[120:121], v[100:101], v[20:21], v[120:121] neg_lo:[1,0,0] neg_hi:[1,0,0]
	v_pk_fma_f32 v[124:125], v[100:101], v[16:17], v[52:53]
	v_pk_mul_f32 v[52:53], v[98:99], v[22:23]
	v_pk_mul_f32 v[122:123], v[98:99], v[18:19]
	v_pk_fma_f32 v[122:123], v[102:103], v[22:23], v[122:123] neg_lo:[1,0,0] neg_hi:[1,0,0]
	v_pk_fma_f32 v[126:127], v[102:103], v[18:19], v[52:53]
	v_pk_mul_f32 v[52:53], v[96:97], v[28:29]
	v_pk_mul_f32 v[60:61], v[96:97], v[24:25]
	v_pk_fma_f32 v[60:61], v[100:101], v[28:29], v[60:61] neg_lo:[1,0,0] neg_hi:[1,0,0]
	v_pk_fma_f32 v[62:63], v[100:101], v[24:25], v[52:53]
	v_pk_fma_f32 v[62:63], v[120:121], v[108:109], v[62:63]
	v_pk_fma_f32 v[60:61], v[120:121], v[104:105], v[60:61]
	v_pk_fma_f32 v[120:121], v[124:125], v[108:109], v[60:61] neg_lo:[1,0,0] neg_hi:[1,0,0]
	v_pk_fma_f32 v[124:125], v[124:125], v[104:105], v[62:63]
	v_pk_mul_f32 v[52:53], v[98:99], v[30:31]
	v_pk_mul_f32 v[60:61], v[98:99], v[26:27]
	v_pk_fma_f32 v[60:61], v[102:103], v[30:31], v[60:61] neg_lo:[1,0,0] neg_hi:[1,0,0]
	v_pk_fma_f32 v[62:63], v[102:103], v[26:27], v[52:53]
	v_pk_fma_f32 v[62:63], v[122:123], v[110:111], v[62:63]
	v_pk_fma_f32 v[60:61], v[122:123], v[106:107], v[60:61]
	v_pk_fma_f32 v[122:123], v[126:127], v[110:111], v[60:61] neg_lo:[1,0,0] neg_hi:[1,0,0]
	v_pk_fma_f32 v[126:127], v[126:127], v[106:107], v[62:63]
	v_pk_mul_f32 v[52:53], v[96:97], v[36:37]
	v_pk_mul_f32 v[60:61], v[96:97], v[32:33]
	v_pk_fma_f32 v[60:61], v[100:101], v[36:37], v[60:61] neg_lo:[1,0,0] neg_hi:[1,0,0]
	v_pk_fma_f32 v[62:63], v[100:101], v[32:33], v[52:53]
	v_pk_fma_f32 v[62:63], v[120:121], v[108:109], v[62:63]
	v_pk_fma_f32 v[60:61], v[120:121], v[104:105], v[60:61]
	v_pk_fma_f32 v[120:121], v[124:125], v[108:109], v[60:61] neg_lo:[1,0,0] neg_hi:[1,0,0]
	v_pk_fma_f32 v[124:125], v[124:125], v[104:105], v[62:63]
	v_pk_mul_f32 v[52:53], v[98:99], v[38:39]
	v_pk_mul_f32 v[60:61], v[98:99], v[34:35]
	v_pk_fma_f32 v[60:61], v[102:103], v[38:39], v[60:61] neg_lo:[1,0,0] neg_hi:[1,0,0]
	v_pk_fma_f32 v[62:63], v[102:103], v[34:35], v[52:53]
	v_pk_fma_f32 v[62:63], v[122:123], v[110:111], v[62:63]
	v_pk_fma_f32 v[60:61], v[122:123], v[106:107], v[60:61]
	v_pk_fma_f32 v[122:123], v[126:127], v[110:111], v[60:61] neg_lo:[1,0,0] neg_hi:[1,0,0]
	v_pk_fma_f32 v[126:127], v[126:127], v[106:107], v[62:63]
	v_pk_mul_f32 v[52:53], v[96:97], v[44:45]
	v_pk_mul_f32 v[60:61], v[96:97], v[40:41]
	v_pk_fma_f32 v[60:61], v[100:101], v[44:45], v[60:61] neg_lo:[1,0,0] neg_hi:[1,0,0]
	v_pk_fma_f32 v[62:63], v[100:101], v[40:41], v[52:53]
	v_pk_fma_f32 v[62:63], v[120:121], v[108:109], v[62:63]
	v_pk_fma_f32 v[60:61], v[120:121], v[104:105], v[60:61]
	v_pk_fma_f32 v[120:121], v[124:125], v[108:109], v[60:61] neg_lo:[1,0,0] neg_hi:[1,0,0]
	v_pk_fma_f32 v[124:125], v[124:125], v[104:105], v[62:63]
	v_pk_mul_f32 v[52:53], v[98:99], v[46:47]
	v_pk_mul_f32 v[60:61], v[98:99], v[42:43]
	v_pk_fma_f32 v[60:61], v[102:103], v[46:47], v[60:61] neg_lo:[1,0,0] neg_hi:[1,0,0]
	v_pk_fma_f32 v[62:63], v[102:103], v[42:43], v[52:53]
	v_pk_fma_f32 v[62:63], v[122:123], v[110:111], v[62:63]
	v_pk_fma_f32 v[60:61], v[122:123], v[106:107], v[60:61]
	v_pk_fma_f32 v[122:123], v[126:127], v[110:111], v[60:61] neg_lo:[1,0,0] neg_hi:[1,0,0]
	v_pk_fma_f32 v[126:127], v[126:127], v[106:107], v[62:63]
	v_add_f32_dpp v120, v120, v120 row_ror:8 row_mask:0xf bank_mask:0xf
	v_add_f32_dpp v121, v121, v121 row_ror:8 row_mask:0xf bank_mask:0xf
	v_add_f32_dpp v122, v122, v122 row_ror:8 row_mask:0xf bank_mask:0xf
	v_add_f32_dpp v123, v123, v123 row_ror:8 row_mask:0xf bank_mask:0xf
	v_add_f32_dpp v124, v124, v124 row_ror:8 row_mask:0xf bank_mask:0xf
	v_add_f32_dpp v125, v125, v125 row_ror:8 row_mask:0xf bank_mask:0xf
	v_add_f32_dpp v126, v126, v126 row_ror:8 row_mask:0xf bank_mask:0xf
	v_add_f32_dpp v127, v127, v127 row_ror:8 row_mask:0xf bank_mask:0xf
	v_add_f32_dpp v120, v120, v120 row_ror:4 row_mask:0xf bank_mask:0xf
	v_add_f32_dpp v121, v121, v121 row_ror:4 row_mask:0xf bank_mask:0xf
	v_add_f32_dpp v122, v122, v122 row_ror:4 row_mask:0xf bank_mask:0xf
	v_add_f32_dpp v123, v123, v123 row_ror:4 row_mask:0xf bank_mask:0xf
	v_add_f32_dpp v124, v124, v124 row_ror:4 row_mask:0xf bank_mask:0xf
	v_add_f32_dpp v125, v125, v125 row_ror:4 row_mask:0xf bank_mask:0xf
	v_add_f32_dpp v126, v126, v126 row_ror:4 row_mask:0xf bank_mask:0xf
	v_add_f32_dpp v127, v127, v127 row_ror:4 row_mask:0xf bank_mask:0xf
	v_add_f32_dpp v120, v120, v120 row_ror:2 row_mask:0xf bank_mask:0xf
	v_add_f32_dpp v121, v121, v121 row_ror:2 row_mask:0xf bank_mask:0xf
	v_add_f32_dpp v122, v122, v122 row_ror:2 row_mask:0xf bank_mask:0xf
	v_add_f32_dpp v123, v123, v123 row_ror:2 row_mask:0xf bank_mask:0xf
	v_add_f32_dpp v124, v124, v124 row_ror:2 row_mask:0xf bank_mask:0xf
	v_add_f32_dpp v125, v125, v125 row_ror:2 row_mask:0xf bank_mask:0xf
	v_add_f32_dpp v126, v126, v126 row_ror:2 row_mask:0xf bank_mask:0xf
	v_add_f32_dpp v127, v127, v127 row_ror:2 row_mask:0xf bank_mask:0xf
	v_add_f32_dpp v120, v120, v120 row_ror:1 row_mask:0xf bank_mask:0xf
	v_add_f32_dpp v121, v121, v121 row_ror:1 row_mask:0xf bank_mask:0xf
	v_add_f32_dpp v122, v122, v122 row_ror:1 row_mask:0xf bank_mask:0xf
	v_add_f32_dpp v123, v123, v123 row_ror:1 row_mask:0xf bank_mask:0xf
	v_add_f32_dpp v124, v124, v124 row_ror:1 row_mask:0xf bank_mask:0xf
	v_add_f32_dpp v125, v125, v125 row_ror:1 row_mask:0xf bank_mask:0xf
	v_add_f32_dpp v126, v126, v126 row_ror:1 row_mask:0xf bank_mask:0xf
	v_add_f32_dpp v127, v127, v127 row_ror:1 row_mask:0xf bank_mask:0xf
	s_add_u32 s18, s26, 384
	s_addc_u32 s19, s27, 0
	v_mov_b32_e32 v128, v120
	v_mov_b32_e32 v129, v124
	v_mov_b32_e32 v130, v121
	v_mov_b32_e32 v131, v125
	v_mov_b32_e32 v132, v122
	v_mov_b32_e32 v133, v126
	v_mov_b32_e32 v134, v123
	v_mov_b32_e32 v135, v127
	s_mov_b32 exec_lo, 0x10001
	s_mov_b32 exec_hi, 0x10001
	global_store_dwordx4 v114, v[128:131], s[18:19]
	global_store_dwordx4 v114, v[132:135], s[18:19] offset:16
	s_mov_b64 exec, -1
	s_nop 1
	s_waitcnt vmcnt(4)
	global_load_dwordx4 v[64:67], v113, s[20:21]
	global_load_dwordx4 v[72:75], v113, s[20:21] offset:1024
	global_load_dwordx4 v[96:99], v113, s[24:25] offset:0
	global_load_dwordx4 v[100:103], v113, s[24:25] offset:1024
	global_load_dwordx4 v[104:107], v113, s[24:25] offset:2048
	global_load_dwordx4 v[108:111], v113, s[24:25] offset:3072
	s_add_u32 s20, s20, 0x800
	s_addc_u32 s21, s21, 0
	s_add_u32 s24, s24, 0x1000
	s_addc_u32 s25, s25, 0
	v_mfma_f32_16x16x32_bf16 v[16:19], v[48:51], v[0:3], 0
	v_mfma_f32_16x16x32_bf16 v[20:23], v[56:59], v[0:3], 0
	v_mfma_f32_16x16x32_bf16 v[24:27], v[48:51], v[4:7], 0
	v_mfma_f32_16x16x32_bf16 v[28:31], v[56:59], v[4:7], 0
	v_mfma_f32_16x16x32_bf16 v[32:35], v[48:51], v[8:11], 0
	v_mfma_f32_16x16x32_bf16 v[36:39], v[56:59], v[8:11], 0
	v_mfma_f32_16x16x32_bf16 v[40:43], v[48:51], v[12:15], 0
	v_mfma_f32_16x16x32_bf16 v[44:47], v[56:59], v[12:15], 0
	s_waitcnt vmcnt(6)
	s_nop 7
	v_pk_mul_f32 v[52:53], v[80:81], v[44:45]
	v_pk_mul_f32 v[120:121], v[80:81], v[40:41]
	v_pk_fma_f32 v[120:121], v[84:85], v[44:45], v[120:121] neg_lo:[1,0,0] neg_hi:[1,0,0]
	v_pk_fma_f32 v[124:125], v[84:85], v[40:41], v[52:53]
	v_pk_mul_f32 v[52:53], v[82:83], v[46:47]
	v_pk_mul_f32 v[122:123], v[82:83], v[42:43]
	v_pk_fma_f32 v[122:123], v[86:87], v[46:47], v[122:123] neg_lo:[1,0,0] neg_hi:[1,0,0]
	v_pk_fma_f32 v[126:127], v[86:87], v[42:43], v[52:53]
	v_pk_mul_f32 v[52:53], v[80:81], v[36:37]
	v_pk_mul_f32 v[60:61], v[80:81], v[32:33]
	v_pk_fma_f32 v[60:61], v[84:85], v[36:37], v[60:61] neg_lo:[1,0,0] neg_hi:[1,0,0]
	v_pk_fma_f32 v[62:63], v[84:85], v[32:33], v[52:53]
	v_pk_fma_f32 v[62:63], v[120:121], v[92:93], v[62:63]
	v_pk_fma_f32 v[60:61], v[120:121], v[88:89], v[60:61]
	v_pk_fma_f32 v[120:121], v[124:125], v[92:93], v[60:61] neg_lo:[1,0,0] neg_hi:[1,0,0]
	v_pk_fma_f32 v[124:125], v[124:125], v[88:89], v[62:63]
	v_pk_mul_f32 v[52:53], v[82:83], v[38:39]
	v_pk_mul_f32 v[60:61], v[82:83], v[34:35]
	v_pk_fma_f32 v[60:61], v[86:87], v[38:39], v[60:61] neg_lo:[1,0,0] neg_hi:[1,0,0]
	v_pk_fma_f32 v[62:63], v[86:87], v[34:35], v[52:53]
	v_pk_fma_f32 v[62:63], v[122:123], v[94:95], v[62:63]
	v_pk_fma_f32 v[60:61], v[122:123], v[90:91], v[60:61]
	v_pk_fma_f32 v[122:123], v[126:127], v[94:95], v[60:61] neg_lo:[1,0,0] neg_hi:[1,0,0]
	v_pk_fma_f32 v[126:127], v[126:127], v[90:91], v[62:63]
	v_pk_mul_f32 v[52:53], v[80:81], v[28:29]
	v_pk_mul_f32 v[60:61], v[80:81], v[24:25]
	v_pk_fma_f32 v[60:61], v[84:85], v[28:29], v[60:61] neg_lo:[1,0,0] neg_hi:[1,0,0]
	v_pk_fma_f32 v[62:63], v[84:85], v[24:25], v[52:53]
	v_pk_fma_f32 v[62:63], v[120:121], v[92:93], v[62:63]
	v_pk_fma_f32 v[60:61], v[120:121], v[88:89], v[60:61]
	v_pk_fma_f32 v[120:121], v[124:125], v[92:93], v[60:61] neg_lo:[1,0,0] neg_hi:[1,0,0]
	v_pk_fma_f32 v[124:125], v[124:125], v[88:89], v[62:63]
	v_pk_mul_f32 v[52:53], v[82:83], v[30:31]
	v_pk_mul_f32 v[60:61], v[82:83], v[26:27]
	v_pk_fma_f32 v[60:61], v[86:87], v[30:31], v[60:61] neg_lo:[1,0,0] neg_hi:[1,0,0]
	v_pk_fma_f32 v[62:63], v[86:87], v[26:27], v[52:53]
	v_pk_fma_f32 v[62:63], v[122:123], v[94:95], v[62:63]
	v_pk_fma_f32 v[60:61], v[122:123], v[90:91], v[60:61]
	v_pk_fma_f32 v[122:123], v[126:127], v[94:95], v[60:61] neg_lo:[1,0,0] neg_hi:[1,0,0]
	v_pk_fma_f32 v[126:127], v[126:127], v[90:91], v[62:63]
	v_pk_mul_f32 v[52:53], v[80:81], v[20:21]
	v_pk_mul_f32 v[60:61], v[80:81], v[16:17]
	v_pk_fma_f32 v[60:61], v[84:85], v[20:21], v[60:61] neg_lo:[1,0,0] neg_hi:[1,0,0]
	v_pk_fma_f32 v[62:63], v[84:85], v[16:17], v[52:53]
	v_pk_fma_f32 v[62:63], v[120:121], v[92:93], v[62:63]
	v_pk_fma_f32 v[60:61], v[120:121], v[88:89], v[60:61]
	v_pk_fma_f32 v[120:121], v[124:125], v[92:93], v[60:61] neg_lo:[1,0,0] neg_hi:[1,0,0]
	v_pk_fma_f32 v[124:125], v[124:125], v[88:89], v[62:63]
	v_pk_mul_f32 v[52:53], v[82:83], v[22:23]
	v_pk_mul_f32 v[60:61], v[82:83], v[18:19]
	v_pk_fma_f32 v[60:61], v[86:87], v[22:23], v[60:61] neg_lo:[1,0,0] neg_hi:[1,0,0]
	v_pk_fma_f32 v[62:63], v[86:87], v[18:19], v[52:53]
	v_pk_fma_f32 v[62:63], v[122:123], v[94:95], v[62:63]
	v_pk_fma_f32 v[60:61], v[122:123], v[90:91], v[60:61]
	v_pk_fma_f32 v[122:123], v[126:127], v[94:95], v[60:61] neg_lo:[1,0,0] neg_hi:[1,0,0]
	v_pk_fma_f32 v[126:127], v[126:127], v[90:91], v[62:63]
	v_add_f32_dpp v120, v120, v120 row_ror:8 row_mask:0xf bank_mask:0xf
	v_add_f32_dpp v121, v121, v121 row_ror:8 row_mask:0xf bank_mask:0xf
	v_add_f32_dpp v122, v122, v122 row_ror:8 row_mask:0xf bank_mask:0xf
	v_add_f32_dpp v123, v123, v123 row_ror:8 row_mask:0xf bank_mask:0xf
	v_add_f32_dpp v124, v124, v124 row_ror:8 row_mask:0xf bank_mask:0xf
	v_add_f32_dpp v125, v125, v125 row_ror:8 row_mask:0xf bank_mask:0xf
	v_add_f32_dpp v126, v126, v126 row_ror:8 row_mask:0xf bank_mask:0xf
	v_add_f32_dpp v127, v127, v127 row_ror:8 row_mask:0xf bank_mask:0xf
	v_add_f32_dpp v120, v120, v120 row_ror:4 row_mask:0xf bank_mask:0xf
	v_add_f32_dpp v121, v121, v121 row_ror:4 row_mask:0xf bank_mask:0xf
	v_add_f32_dpp v122, v122, v122 row_ror:4 row_mask:0xf bank_mask:0xf
	v_add_f32_dpp v123, v123, v123 row_ror:4 row_mask:0xf bank_mask:0xf
	v_add_f32_dpp v124, v124, v124 row_ror:4 row_mask:0xf bank_mask:0xf
	v_add_f32_dpp v125, v125, v125 row_ror:4 row_mask:0xf bank_mask:0xf
	v_add_f32_dpp v126, v126, v126 row_ror:4 row_mask:0xf bank_mask:0xf
	v_add_f32_dpp v127, v127, v127 row_ror:4 row_mask:0xf bank_mask:0xf
	v_add_f32_dpp v120, v120, v120 row_ror:2 row_mask:0xf bank_mask:0xf
	v_add_f32_dpp v121, v121, v121 row_ror:2 row_mask:0xf bank_mask:0xf
	v_add_f32_dpp v122, v122, v122 row_ror:2 row_mask:0xf bank_mask:0xf
	v_add_f32_dpp v123, v123, v123 row_ror:2 row_mask:0xf bank_mask:0xf
	v_add_f32_dpp v124, v124, v124 row_ror:2 row_mask:0xf bank_mask:0xf
	v_add_f32_dpp v125, v125, v125 row_ror:2 row_mask:0xf bank_mask:0xf
	v_add_f32_dpp v126, v126, v126 row_ror:2 row_mask:0xf bank_mask:0xf
	v_add_f32_dpp v127, v127, v127 row_ror:2 row_mask:0xf bank_mask:0xf
	v_add_f32_dpp v120, v120, v120 row_ror:1 row_mask:0xf bank_mask:0xf
	v_add_f32_dpp v121, v121, v121 row_ror:1 row_mask:0xf bank_mask:0xf
	v_add_f32_dpp v122, v122, v122 row_ror:1 row_mask:0xf bank_mask:0xf
	v_add_f32_dpp v123, v123, v123 row_ror:1 row_mask:0xf bank_mask:0xf
	v_add_f32_dpp v124, v124, v124 row_ror:1 row_mask:0xf bank_mask:0xf
	v_add_f32_dpp v125, v125, v125 row_ror:1 row_mask:0xf bank_mask:0xf
	v_add_f32_dpp v126, v126, v126 row_ror:1 row_mask:0xf bank_mask:0xf
	v_add_f32_dpp v127, v127, v127 row_ror:1 row_mask:0xf bank_mask:0xf
	s_add_u32 s18, s36, 0
	s_addc_u32 s19, s37, 0
	v_mov_b32_e32 v128, v120
	v_mov_b32_e32 v129, v124
	v_mov_b32_e32 v130, v121
	v_mov_b32_e32 v131, v125
	v_mov_b32_e32 v132, v122
	v_mov_b32_e32 v133, v126
	v_mov_b32_e32 v134, v123
	v_mov_b32_e32 v135, v127
	s_mov_b32 exec_lo, 0x10001
	s_mov_b32 exec_hi, 0x10001
	global_store_dwordx4 v114, v[128:131], s[18:19]
	global_store_dwordx4 v114, v[132:135], s[18:19] offset:16
	s_mov_b64 exec, -1
	s_nop 1
	s_waitcnt vmcnt(4)
	global_load_dwordx4 v[48:51], v113, s[20:21]
	global_load_dwordx4 v[56:59], v113, s[20:21] offset:1024
	global_load_dwordx4 v[80:83], v113, s[24:25] offset:0
	global_load_dwordx4 v[84:87], v113, s[24:25] offset:1024
	global_load_dwordx4 v[88:91], v113, s[24:25] offset:2048
	global_load_dwordx4 v[92:95], v113, s[24:25] offset:3072
	s_add_u32 s20, s20, 0x800
	s_addc_u32 s21, s21, 0
	s_add_u32 s24, s24, 0x1000
	s_addc_u32 s25, s25, 0
	v_mfma_f32_16x16x32_bf16 v[16:19], v[64:67], v[0:3], 0
	v_mfma_f32_16x16x32_bf16 v[20:23], v[72:75], v[0:3], 0
	v_mfma_f32_16x16x32_bf16 v[24:27], v[64:67], v[4:7], 0
	v_mfma_f32_16x16x32_bf16 v[28:31], v[72:75], v[4:7], 0
	v_mfma_f32_16x16x32_bf16 v[32:35], v[64:67], v[8:11], 0
	v_mfma_f32_16x16x32_bf16 v[36:39], v[72:75], v[8:11], 0
	v_mfma_f32_16x16x32_bf16 v[40:43], v[64:67], v[12:15], 0
	v_mfma_f32_16x16x32_bf16 v[44:47], v[72:75], v[12:15], 0
	s_waitcnt vmcnt(6)
	s_nop 7
	v_pk_mul_f32 v[52:53], v[96:97], v[44:45]
	v_pk_mul_f32 v[120:121], v[96:97], v[40:41]
	v_pk_fma_f32 v[120:121], v[100:101], v[44:45], v[120:121] neg_lo:[1,0,0] neg_hi:[1,0,0]
	v_pk_fma_f32 v[124:125], v[100:101], v[40:41], v[52:53]
	v_pk_mul_f32 v[52:53], v[98:99], v[46:47]
	v_pk_mul_f32 v[122:123], v[98:99], v[42:43]
	v_pk_fma_f32 v[122:123], v[102:103], v[46:47], v[122:123] neg_lo:[1,0,0] neg_hi:[1,0,0]
	v_pk_fma_f32 v[126:127], v[102:103], v[42:43], v[52:53]
	v_pk_mul_f32 v[52:53], v[96:97], v[36:37]
	v_pk_mul_f32 v[60:61], v[96:97], v[32:33]
	v_pk_fma_f32 v[60:61], v[100:101], v[36:37], v[60:61] neg_lo:[1,0,0] neg_hi:[1,0,0]
	v_pk_fma_f32 v[62:63], v[100:101], v[32:33], v[52:53]
	v_pk_fma_f32 v[62:63], v[120:121], v[108:109], v[62:63]
	v_pk_fma_f32 v[60:61], v[120:121], v[104:105], v[60:61]
	v_pk_fma_f32 v[120:121], v[124:125], v[108:109], v[60:61] neg_lo:[1,0,0] neg_hi:[1,0,0]
	v_pk_fma_f32 v[124:125], v[124:125], v[104:105], v[62:63]
	v_pk_mul_f32 v[52:53], v[98:99], v[38:39]
	v_pk_mul_f32 v[60:61], v[98:99], v[34:35]
	v_pk_fma_f32 v[60:61], v[102:103], v[38:39], v[60:61] neg_lo:[1,0,0] neg_hi:[1,0,0]
	v_pk_fma_f32 v[62:63], v[102:103], v[34:35], v[52:53]
	v_pk_fma_f32 v[62:63], v[122:123], v[110:111], v[62:63]
	v_pk_fma_f32 v[60:61], v[122:123], v[106:107], v[60:61]
	v_pk_fma_f32 v[122:123], v[126:127], v[110:111], v[60:61] neg_lo:[1,0,0] neg_hi:[1,0,0]
	v_pk_fma_f32 v[126:127], v[126:127], v[106:107], v[62:63]
	v_pk_mul_f32 v[52:53], v[96:97], v[28:29]
	v_pk_mul_f32 v[60:61], v[96:97], v[24:25]
	v_pk_fma_f32 v[60:61], v[100:101], v[28:29], v[60:61] neg_lo:[1,0,0] neg_hi:[1,0,0]
	v_pk_fma_f32 v[62:63], v[100:101], v[24:25], v[52:53]
	v_pk_fma_f32 v[62:63], v[120:121], v[108:109], v[62:63]
	v_pk_fma_f32 v[60:61], v[120:121], v[104:105], v[60:61]
	v_pk_fma_f32 v[120:121], v[124:125], v[108:109], v[60:61] neg_lo:[1,0,0] neg_hi:[1,0,0]
	v_pk_fma_f32 v[124:125], v[124:125], v[104:105], v[62:63]
	v_pk_mul_f32 v[52:53], v[98:99], v[30:31]
	v_pk_mul_f32 v[60:61], v[98:99], v[26:27]
	v_pk_fma_f32 v[60:61], v[102:103], v[30:31], v[60:61] neg_lo:[1,0,0] neg_hi:[1,0,0]
	v_pk_fma_f32 v[62:63], v[102:103], v[26:27], v[52:53]
	v_pk_fma_f32 v[62:63], v[122:123], v[110:111], v[62:63]
	v_pk_fma_f32 v[60:61], v[122:123], v[106:107], v[60:61]
	v_pk_fma_f32 v[122:123], v[126:127], v[110:111], v[60:61] neg_lo:[1,0,0] neg_hi:[1,0,0]
	v_pk_fma_f32 v[126:127], v[126:127], v[106:107], v[62:63]
	v_pk_mul_f32 v[52:53], v[96:97], v[20:21]
	v_pk_mul_f32 v[60:61], v[96:97], v[16:17]
	v_pk_fma_f32 v[60:61], v[100:101], v[20:21], v[60:61] neg_lo:[1,0,0] neg_hi:[1,0,0]
	v_pk_fma_f32 v[62:63], v[100:101], v[16:17], v[52:53]
	v_pk_fma_f32 v[62:63], v[120:121], v[108:109], v[62:63]
	v_pk_fma_f32 v[60:61], v[120:121], v[104:105], v[60:61]
	v_pk_fma_f32 v[120:121], v[124:125], v[108:109], v[60:61] neg_lo:[1,0,0] neg_hi:[1,0,0]
	v_pk_fma_f32 v[124:125], v[124:125], v[104:105], v[62:63]
	v_pk_mul_f32 v[52:53], v[98:99], v[22:23]
	v_pk_mul_f32 v[60:61], v[98:99], v[18:19]
	v_pk_fma_f32 v[60:61], v[102:103], v[22:23], v[60:61] neg_lo:[1,0,0] neg_hi:[1,0,0]
	v_pk_fma_f32 v[62:63], v[102:103], v[18:19], v[52:53]
	v_pk_fma_f32 v[62:63], v[122:123], v[110:111], v[62:63]
	v_pk_fma_f32 v[60:61], v[122:123], v[106:107], v[60:61]
	v_pk_fma_f32 v[122:123], v[126:127], v[110:111], v[60:61] neg_lo:[1,0,0] neg_hi:[1,0,0]
	v_pk_fma_f32 v[126:127], v[126:127], v[106:107], v[62:63]
	v_add_f32_dpp v120, v120, v120 row_ror:8 row_mask:0xf bank_mask:0xf
	v_add_f32_dpp v121, v121, v121 row_ror:8 row_mask:0xf bank_mask:0xf
	v_add_f32_dpp v122, v122, v122 row_ror:8 row_mask:0xf bank_mask:0xf
	v_add_f32_dpp v123, v123, v123 row_ror:8 row_mask:0xf bank_mask:0xf
	v_add_f32_dpp v124, v124, v124 row_ror:8 row_mask:0xf bank_mask:0xf
	v_add_f32_dpp v125, v125, v125 row_ror:8 row_mask:0xf bank_mask:0xf
	v_add_f32_dpp v126, v126, v126 row_ror:8 row_mask:0xf bank_mask:0xf
	v_add_f32_dpp v127, v127, v127 row_ror:8 row_mask:0xf bank_mask:0xf
	v_add_f32_dpp v120, v120, v120 row_ror:4 row_mask:0xf bank_mask:0xf
	v_add_f32_dpp v121, v121, v121 row_ror:4 row_mask:0xf bank_mask:0xf
	v_add_f32_dpp v122, v122, v122 row_ror:4 row_mask:0xf bank_mask:0xf
	v_add_f32_dpp v123, v123, v123 row_ror:4 row_mask:0xf bank_mask:0xf
	v_add_f32_dpp v124, v124, v124 row_ror:4 row_mask:0xf bank_mask:0xf
	v_add_f32_dpp v125, v125, v125 row_ror:4 row_mask:0xf bank_mask:0xf
	v_add_f32_dpp v126, v126, v126 row_ror:4 row_mask:0xf bank_mask:0xf
	v_add_f32_dpp v127, v127, v127 row_ror:4 row_mask:0xf bank_mask:0xf
	v_add_f32_dpp v120, v120, v120 row_ror:2 row_mask:0xf bank_mask:0xf
	v_add_f32_dpp v121, v121, v121 row_ror:2 row_mask:0xf bank_mask:0xf
	v_add_f32_dpp v122, v122, v122 row_ror:2 row_mask:0xf bank_mask:0xf
	v_add_f32_dpp v123, v123, v123 row_ror:2 row_mask:0xf bank_mask:0xf
	v_add_f32_dpp v124, v124, v124 row_ror:2 row_mask:0xf bank_mask:0xf
	v_add_f32_dpp v125, v125, v125 row_ror:2 row_mask:0xf bank_mask:0xf
	v_add_f32_dpp v126, v126, v126 row_ror:2 row_mask:0xf bank_mask:0xf
	v_add_f32_dpp v127, v127, v127 row_ror:2 row_mask:0xf bank_mask:0xf
	v_add_f32_dpp v120, v120, v120 row_ror:1 row_mask:0xf bank_mask:0xf
	v_add_f32_dpp v121, v121, v121 row_ror:1 row_mask:0xf bank_mask:0xf
	v_add_f32_dpp v122, v122, v122 row_ror:1 row_mask:0xf bank_mask:0xf
	v_add_f32_dpp v123, v123, v123 row_ror:1 row_mask:0xf bank_mask:0xf
	v_add_f32_dpp v124, v124, v124 row_ror:1 row_mask:0xf bank_mask:0xf
	v_add_f32_dpp v125, v125, v125 row_ror:1 row_mask:0xf bank_mask:0xf
	v_add_f32_dpp v126, v126, v126 row_ror:1 row_mask:0xf bank_mask:0xf
	v_add_f32_dpp v127, v127, v127 row_ror:1 row_mask:0xf bank_mask:0xf
	s_add_u32 s18, s36, 128
	s_addc_u32 s19, s37, 0
	v_mov_b32_e32 v128, v120
	v_mov_b32_e32 v129, v124
	v_mov_b32_e32 v130, v121
	v_mov_b32_e32 v131, v125
	v_mov_b32_e32 v132, v122
	v_mov_b32_e32 v133, v126
	v_mov_b32_e32 v134, v123
	v_mov_b32_e32 v135, v127
	s_mov_b32 exec_lo, 0x10001
	s_mov_b32 exec_hi, 0x10001
	global_store_dwordx4 v114, v[128:131], s[18:19]
	global_store_dwordx4 v114, v[132:135], s[18:19] offset:16
	s_mov_b64 exec, -1
	s_nop 1
	s_waitcnt vmcnt(4)
	global_load_dwordx4 v[64:67], v113, s[20:21]
	global_load_dwordx4 v[72:75], v113, s[20:21] offset:1024
	global_load_dwordx4 v[96:99], v113, s[24:25] offset:0
	global_load_dwordx4 v[100:103], v113, s[24:25] offset:1024
	global_load_dwordx4 v[104:107], v113, s[24:25] offset:2048
	global_load_dwordx4 v[108:111], v113, s[24:25] offset:3072
	v_mfma_f32_16x16x32_bf16 v[16:19], v[48:51], v[0:3], 0
	v_mfma_f32_16x16x32_bf16 v[20:23], v[56:59], v[0:3], 0
	v_mfma_f32_16x16x32_bf16 v[24:27], v[48:51], v[4:7], 0
	v_mfma_f32_16x16x32_bf16 v[28:31], v[56:59], v[4:7], 0
	v_mfma_f32_16x16x32_bf16 v[32:35], v[48:51], v[8:11], 0
	v_mfma_f32_16x16x32_bf16 v[36:39], v[56:59], v[8:11], 0
	v_mfma_f32_16x16x32_bf16 v[40:43], v[48:51], v[12:15], 0
	v_mfma_f32_16x16x32_bf16 v[44:47], v[56:59], v[12:15], 0
	s_waitcnt vmcnt(6)
	s_nop 7
	v_pk_mul_f32 v[52:53], v[80:81], v[44:45]
	v_pk_mul_f32 v[120:121], v[80:81], v[40:41]
	v_pk_fma_f32 v[120:121], v[84:85], v[44:45], v[120:121] neg_lo:[1,0,0] neg_hi:[1,0,0]
	v_pk_fma_f32 v[124:125], v[84:85], v[40:41], v[52:53]
	v_pk_mul_f32 v[52:53], v[82:83], v[46:47]
	v_pk_mul_f32 v[122:123], v[82:83], v[42:43]
	v_pk_fma_f32 v[122:123], v[86:87], v[46:47], v[122:123] neg_lo:[1,0,0] neg_hi:[1,0,0]
	v_pk_fma_f32 v[126:127], v[86:87], v[42:43], v[52:53]
	v_pk_mul_f32 v[52:53], v[80:81], v[36:37]
	v_pk_mul_f32 v[60:61], v[80:81], v[32:33]
	v_pk_fma_f32 v[60:61], v[84:85], v[36:37], v[60:61] neg_lo:[1,0,0] neg_hi:[1,0,0]
	v_pk_fma_f32 v[62:63], v[84:85], v[32:33], v[52:53]
	v_pk_fma_f32 v[62:63], v[120:121], v[92:93], v[62:63]
	v_pk_fma_f32 v[60:61], v[120:121], v[88:89], v[60:61]
	v_pk_fma_f32 v[120:121], v[124:125], v[92:93], v[60:61] neg_lo:[1,0,0] neg_hi:[1,0,0]
	v_pk_fma_f32 v[124:125], v[124:125], v[88:89], v[62:63]
	v_pk_mul_f32 v[52:53], v[82:83], v[38:39]
	v_pk_mul_f32 v[60:61], v[82:83], v[34:35]
	v_pk_fma_f32 v[60:61], v[86:87], v[38:39], v[60:61] neg_lo:[1,0,0] neg_hi:[1,0,0]
	v_pk_fma_f32 v[62:63], v[86:87], v[34:35], v[52:53]
	v_pk_fma_f32 v[62:63], v[122:123], v[94:95], v[62:63]
	v_pk_fma_f32 v[60:61], v[122:123], v[90:91], v[60:61]
	v_pk_fma_f32 v[122:123], v[126:127], v[94:95], v[60:61] neg_lo:[1,0,0] neg_hi:[1,0,0]
	v_pk_fma_f32 v[126:127], v[126:127], v[90:91], v[62:63]
	v_pk_mul_f32 v[52:53], v[80:81], v[28:29]
	v_pk_mul_f32 v[60:61], v[80:81], v[24:25]
	v_pk_fma_f32 v[60:61], v[84:85], v[28:29], v[60:61] neg_lo:[1,0,0] neg_hi:[1,0,0]
	v_pk_fma_f32 v[62:63], v[84:85], v[24:25], v[52:53]
	v_pk_fma_f32 v[62:63], v[120:121], v[92:93], v[62:63]
	v_pk_fma_f32 v[60:61], v[120:121], v[88:89], v[60:61]
	v_pk_fma_f32 v[120:121], v[124:125], v[92:93], v[60:61] neg_lo:[1,0,0] neg_hi:[1,0,0]
	v_pk_fma_f32 v[124:125], v[124:125], v[88:89], v[62:63]
	v_pk_mul_f32 v[52:53], v[82:83], v[30:31]
	v_pk_mul_f32 v[60:61], v[82:83], v[26:27]
	v_pk_fma_f32 v[60:61], v[86:87], v[30:31], v[60:61] neg_lo:[1,0,0] neg_hi:[1,0,0]
	v_pk_fma_f32 v[62:63], v[86:87], v[26:27], v[52:53]
	v_pk_fma_f32 v[62:63], v[122:123], v[94:95], v[62:63]
	v_pk_fma_f32 v[60:61], v[122:123], v[90:91], v[60:61]
	v_pk_fma_f32 v[122:123], v[126:127], v[94:95], v[60:61] neg_lo:[1,0,0] neg_hi:[1,0,0]
	v_pk_fma_f32 v[126:127], v[126:127], v[90:91], v[62:63]
	v_pk_mul_f32 v[52:53], v[80:81], v[20:21]
	v_pk_mul_f32 v[60:61], v[80:81], v[16:17]
	v_pk_fma_f32 v[60:61], v[84:85], v[20:21], v[60:61] neg_lo:[1,0,0] neg_hi:[1,0,0]
	v_pk_fma_f32 v[62:63], v[84:85], v[16:17], v[52:53]
	v_pk_fma_f32 v[62:63], v[120:121], v[92:93], v[62:63]
	v_pk_fma_f32 v[60:61], v[120:121], v[88:89], v[60:61]
	v_pk_fma_f32 v[120:121], v[124:125], v[92:93], v[60:61] neg_lo:[1,0,0] neg_hi:[1,0,0]
	v_pk_fma_f32 v[124:125], v[124:125], v[88:89], v[62:63]
	v_pk_mul_f32 v[52:53], v[82:83], v[22:23]
	v_pk_mul_f32 v[60:61], v[82:83], v[18:19]
	v_pk_fma_f32 v[60:61], v[86:87], v[22:23], v[60:61] neg_lo:[1,0,0] neg_hi:[1,0,0]
	v_pk_fma_f32 v[62:63], v[86:87], v[18:19], v[52:53]
	v_pk_fma_f32 v[62:63], v[122:123], v[94:95], v[62:63]
	v_pk_fma_f32 v[60:61], v[122:123], v[90:91], v[60:61]
	v_pk_fma_f32 v[122:123], v[126:127], v[94:95], v[60:61] neg_lo:[1,0,0] neg_hi:[1,0,0]
	v_pk_fma_f32 v[126:127], v[126:127], v[90:91], v[62:63]
	v_add_f32_dpp v120, v120, v120 row_ror:8 row_mask:0xf bank_mask:0xf
	v_add_f32_dpp v121, v121, v121 row_ror:8 row_mask:0xf bank_mask:0xf
	v_add_f32_dpp v122, v122, v122 row_ror:8 row_mask:0xf bank_mask:0xf
	v_add_f32_dpp v123, v123, v123 row_ror:8 row_mask:0xf bank_mask:0xf
	v_add_f32_dpp v124, v124, v124 row_ror:8 row_mask:0xf bank_mask:0xf
	v_add_f32_dpp v125, v125, v125 row_ror:8 row_mask:0xf bank_mask:0xf
	v_add_f32_dpp v126, v126, v126 row_ror:8 row_mask:0xf bank_mask:0xf
	v_add_f32_dpp v127, v127, v127 row_ror:8 row_mask:0xf bank_mask:0xf
	v_add_f32_dpp v120, v120, v120 row_ror:4 row_mask:0xf bank_mask:0xf
	v_add_f32_dpp v121, v121, v121 row_ror:4 row_mask:0xf bank_mask:0xf
	v_add_f32_dpp v122, v122, v122 row_ror:4 row_mask:0xf bank_mask:0xf
	v_add_f32_dpp v123, v123, v123 row_ror:4 row_mask:0xf bank_mask:0xf
	v_add_f32_dpp v124, v124, v124 row_ror:4 row_mask:0xf bank_mask:0xf
	v_add_f32_dpp v125, v125, v125 row_ror:4 row_mask:0xf bank_mask:0xf
	v_add_f32_dpp v126, v126, v126 row_ror:4 row_mask:0xf bank_mask:0xf
	v_add_f32_dpp v127, v127, v127 row_ror:4 row_mask:0xf bank_mask:0xf
	v_add_f32_dpp v120, v120, v120 row_ror:2 row_mask:0xf bank_mask:0xf
	v_add_f32_dpp v121, v121, v121 row_ror:2 row_mask:0xf bank_mask:0xf
	v_add_f32_dpp v122, v122, v122 row_ror:2 row_mask:0xf bank_mask:0xf
	v_add_f32_dpp v123, v123, v123 row_ror:2 row_mask:0xf bank_mask:0xf
	v_add_f32_dpp v124, v124, v124 row_ror:2 row_mask:0xf bank_mask:0xf
	v_add_f32_dpp v125, v125, v125 row_ror:2 row_mask:0xf bank_mask:0xf
	v_add_f32_dpp v126, v126, v126 row_ror:2 row_mask:0xf bank_mask:0xf
	v_add_f32_dpp v127, v127, v127 row_ror:2 row_mask:0xf bank_mask:0xf
	v_add_f32_dpp v120, v120, v120 row_ror:1 row_mask:0xf bank_mask:0xf
	v_add_f32_dpp v121, v121, v121 row_ror:1 row_mask:0xf bank_mask:0xf
	v_add_f32_dpp v122, v122, v122 row_ror:1 row_mask:0xf bank_mask:0xf
	v_add_f32_dpp v123, v123, v123 row_ror:1 row_mask:0xf bank_mask:0xf
	v_add_f32_dpp v124, v124, v124 row_ror:1 row_mask:0xf bank_mask:0xf
	v_add_f32_dpp v125, v125, v125 row_ror:1 row_mask:0xf bank_mask:0xf
	v_add_f32_dpp v126, v126, v126 row_ror:1 row_mask:0xf bank_mask:0xf
	v_add_f32_dpp v127, v127, v127 row_ror:1 row_mask:0xf bank_mask:0xf
	s_add_u32 s18, s36, 256
	s_addc_u32 s19, s37, 0
	v_mov_b32_e32 v128, v120
	v_mov_b32_e32 v129, v124
	v_mov_b32_e32 v130, v121
	v_mov_b32_e32 v131, v125
	v_mov_b32_e32 v132, v122
	v_mov_b32_e32 v133, v126
	v_mov_b32_e32 v134, v123
	v_mov_b32_e32 v135, v127
	s_mov_b32 exec_lo, 0x10001
	s_mov_b32 exec_hi, 0x10001
	global_store_dwordx4 v114, v[128:131], s[18:19]
	global_store_dwordx4 v114, v[132:135], s[18:19] offset:16
	s_mov_b64 exec, -1
	s_nop 1
	s_waitcnt vmcnt(4)
	v_mfma_f32_16x16x32_bf16 v[16:19], v[64:67], v[0:3], 0
	v_mfma_f32_16x16x32_bf16 v[20:23], v[72:75], v[0:3], 0
	v_mfma_f32_16x16x32_bf16 v[24:27], v[64:67], v[4:7], 0
	v_mfma_f32_16x16x32_bf16 v[28:31], v[72:75], v[4:7], 0
	v_mfma_f32_16x16x32_bf16 v[32:35], v[64:67], v[8:11], 0
	v_mfma_f32_16x16x32_bf16 v[36:39], v[72:75], v[8:11], 0
	v_mfma_f32_16x16x32_bf16 v[40:43], v[64:67], v[12:15], 0
	v_mfma_f32_16x16x32_bf16 v[44:47], v[72:75], v[12:15], 0
	s_waitcnt vmcnt(0)
	s_nop 7
	v_pk_mul_f32 v[52:53], v[96:97], v[44:45]
	v_pk_mul_f32 v[120:121], v[96:97], v[40:41]
	v_pk_fma_f32 v[120:121], v[100:101], v[44:45], v[120:121] neg_lo:[1,0,0] neg_hi:[1,0,0]
	v_pk_fma_f32 v[124:125], v[100:101], v[40:41], v[52:53]
	v_pk_mul_f32 v[52:53], v[98:99], v[46:47]
	v_pk_mul_f32 v[122:123], v[98:99], v[42:43]
	v_pk_fma_f32 v[122:123], v[102:103], v[46:47], v[122:123] neg_lo:[1,0,0] neg_hi:[1,0,0]
	v_pk_fma_f32 v[126:127], v[102:103], v[42:43], v[52:53]
	v_pk_mul_f32 v[52:53], v[96:97], v[36:37]
	v_pk_mul_f32 v[60:61], v[96:97], v[32:33]
	v_pk_fma_f32 v[60:61], v[100:101], v[36:37], v[60:61] neg_lo:[1,0,0] neg_hi:[1,0,0]
	v_pk_fma_f32 v[62:63], v[100:101], v[32:33], v[52:53]
	v_pk_fma_f32 v[62:63], v[120:121], v[108:109], v[62:63]
	v_pk_fma_f32 v[60:61], v[120:121], v[104:105], v[60:61]
	v_pk_fma_f32 v[120:121], v[124:125], v[108:109], v[60:61] neg_lo:[1,0,0] neg_hi:[1,0,0]
	v_pk_fma_f32 v[124:125], v[124:125], v[104:105], v[62:63]
	v_pk_mul_f32 v[52:53], v[98:99], v[38:39]
	v_pk_mul_f32 v[60:61], v[98:99], v[34:35]
	v_pk_fma_f32 v[60:61], v[102:103], v[38:39], v[60:61] neg_lo:[1,0,0] neg_hi:[1,0,0]
	v_pk_fma_f32 v[62:63], v[102:103], v[34:35], v[52:53]
	v_pk_fma_f32 v[62:63], v[122:123], v[110:111], v[62:63]
	v_pk_fma_f32 v[60:61], v[122:123], v[106:107], v[60:61]
	v_pk_fma_f32 v[122:123], v[126:127], v[110:111], v[60:61] neg_lo:[1,0,0] neg_hi:[1,0,0]
	v_pk_fma_f32 v[126:127], v[126:127], v[106:107], v[62:63]
	v_pk_mul_f32 v[52:53], v[96:97], v[28:29]
	v_pk_mul_f32 v[60:61], v[96:97], v[24:25]
	v_pk_fma_f32 v[60:61], v[100:101], v[28:29], v[60:61] neg_lo:[1,0,0] neg_hi:[1,0,0]
	v_pk_fma_f32 v[62:63], v[100:101], v[24:25], v[52:53]
	v_pk_fma_f32 v[62:63], v[120:121], v[108:109], v[62:63]
	v_pk_fma_f32 v[60:61], v[120:121], v[104:105], v[60:61]
	v_pk_fma_f32 v[120:121], v[124:125], v[108:109], v[60:61] neg_lo:[1,0,0] neg_hi:[1,0,0]
	v_pk_fma_f32 v[124:125], v[124:125], v[104:105], v[62:63]
	v_pk_mul_f32 v[52:53], v[98:99], v[30:31]
	v_pk_mul_f32 v[60:61], v[98:99], v[26:27]
	v_pk_fma_f32 v[60:61], v[102:103], v[30:31], v[60:61] neg_lo:[1,0,0] neg_hi:[1,0,0]
	v_pk_fma_f32 v[62:63], v[102:103], v[26:27], v[52:53]
	v_pk_fma_f32 v[62:63], v[122:123], v[110:111], v[62:63]
	v_pk_fma_f32 v[60:61], v[122:123], v[106:107], v[60:61]
	v_pk_fma_f32 v[122:123], v[126:127], v[110:111], v[60:61] neg_lo:[1,0,0] neg_hi:[1,0,0]
	v_pk_fma_f32 v[126:127], v[126:127], v[106:107], v[62:63]
	v_pk_mul_f32 v[52:53], v[96:97], v[20:21]
	v_pk_mul_f32 v[60:61], v[96:97], v[16:17]
	v_pk_fma_f32 v[60:61], v[100:101], v[20:21], v[60:61] neg_lo:[1,0,0] neg_hi:[1,0,0]
	v_pk_fma_f32 v[62:63], v[100:101], v[16:17], v[52:53]
	v_pk_fma_f32 v[62:63], v[120:121], v[108:109], v[62:63]
	v_pk_fma_f32 v[60:61], v[120:121], v[104:105], v[60:61]
	v_pk_fma_f32 v[120:121], v[124:125], v[108:109], v[60:61] neg_lo:[1,0,0] neg_hi:[1,0,0]
	v_pk_fma_f32 v[124:125], v[124:125], v[104:105], v[62:63]
	v_pk_mul_f32 v[52:53], v[98:99], v[22:23]
	v_pk_mul_f32 v[60:61], v[98:99], v[18:19]
	v_pk_fma_f32 v[60:61], v[102:103], v[22:23], v[60:61] neg_lo:[1,0,0] neg_hi:[1,0,0]
	v_pk_fma_f32 v[62:63], v[102:103], v[18:19], v[52:53]
	v_pk_fma_f32 v[62:63], v[122:123], v[110:111], v[62:63]
	v_pk_fma_f32 v[60:61], v[122:123], v[106:107], v[60:61]
	v_pk_fma_f32 v[122:123], v[126:127], v[110:111], v[60:61] neg_lo:[1,0,0] neg_hi:[1,0,0]
	v_pk_fma_f32 v[126:127], v[126:127], v[106:107], v[62:63]
	v_add_f32_dpp v120, v120, v120 row_ror:8 row_mask:0xf bank_mask:0xf
	v_add_f32_dpp v121, v121, v121 row_ror:8 row_mask:0xf bank_mask:0xf
	v_add_f32_dpp v122, v122, v122 row_ror:8 row_mask:0xf bank_mask:0xf
	v_add_f32_dpp v123, v123, v123 row_ror:8 row_mask:0xf bank_mask:0xf
	v_add_f32_dpp v124, v124, v124 row_ror:8 row_mask:0xf bank_mask:0xf
	v_add_f32_dpp v125, v125, v125 row_ror:8 row_mask:0xf bank_mask:0xf
	v_add_f32_dpp v126, v126, v126 row_ror:8 row_mask:0xf bank_mask:0xf
	v_add_f32_dpp v127, v127, v127 row_ror:8 row_mask:0xf bank_mask:0xf
	v_add_f32_dpp v120, v120, v120 row_ror:4 row_mask:0xf bank_mask:0xf
	v_add_f32_dpp v121, v121, v121 row_ror:4 row_mask:0xf bank_mask:0xf
	v_add_f32_dpp v122, v122, v122 row_ror:4 row_mask:0xf bank_mask:0xf
	v_add_f32_dpp v123, v123, v123 row_ror:4 row_mask:0xf bank_mask:0xf
	v_add_f32_dpp v124, v124, v124 row_ror:4 row_mask:0xf bank_mask:0xf
	v_add_f32_dpp v125, v125, v125 row_ror:4 row_mask:0xf bank_mask:0xf
	v_add_f32_dpp v126, v126, v126 row_ror:4 row_mask:0xf bank_mask:0xf
	v_add_f32_dpp v127, v127, v127 row_ror:4 row_mask:0xf bank_mask:0xf
	v_add_f32_dpp v120, v120, v120 row_ror:2 row_mask:0xf bank_mask:0xf
	v_add_f32_dpp v121, v121, v121 row_ror:2 row_mask:0xf bank_mask:0xf
	v_add_f32_dpp v122, v122, v122 row_ror:2 row_mask:0xf bank_mask:0xf
	v_add_f32_dpp v123, v123, v123 row_ror:2 row_mask:0xf bank_mask:0xf
	v_add_f32_dpp v124, v124, v124 row_ror:2 row_mask:0xf bank_mask:0xf
	v_add_f32_dpp v125, v125, v125 row_ror:2 row_mask:0xf bank_mask:0xf
	v_add_f32_dpp v126, v126, v126 row_ror:2 row_mask:0xf bank_mask:0xf
	v_add_f32_dpp v127, v127, v127 row_ror:2 row_mask:0xf bank_mask:0xf
	v_add_f32_dpp v120, v120, v120 row_ror:1 row_mask:0xf bank_mask:0xf
	v_add_f32_dpp v121, v121, v121 row_ror:1 row_mask:0xf bank_mask:0xf
	v_add_f32_dpp v122, v122, v122 row_ror:1 row_mask:0xf bank_mask:0xf
	v_add_f32_dpp v123, v123, v123 row_ror:1 row_mask:0xf bank_mask:0xf
	v_add_f32_dpp v124, v124, v124 row_ror:1 row_mask:0xf bank_mask:0xf
	v_add_f32_dpp v125, v125, v125 row_ror:1 row_mask:0xf bank_mask:0xf
	v_add_f32_dpp v126, v126, v126 row_ror:1 row_mask:0xf bank_mask:0xf
	v_add_f32_dpp v127, v127, v127 row_ror:1 row_mask:0xf bank_mask:0xf
	s_add_u32 s18, s36, 384
	s_addc_u32 s19, s37, 0
	v_mov_b32_e32 v128, v120
	v_mov_b32_e32 v129, v124
	v_mov_b32_e32 v130, v121
	v_mov_b32_e32 v131, v125
	v_mov_b32_e32 v132, v122
	v_mov_b32_e32 v133, v126
	v_mov_b32_e32 v134, v123
	v_mov_b32_e32 v135, v127
	s_mov_b32 exec_lo, 0x10001
	s_mov_b32 exec_hi, 0x10001
	global_store_dwordx4 v114, v[128:131], s[18:19]
	global_store_dwordx4 v114, v[132:135], s[18:19] offset:16
	s_mov_b64 exec, -1
	s_nop 1

.LBB0_612:
	v_readlane_b32 s78, v247, 22
	s_bitcmp0_b32 s94, 0
	v_readlane_b32 s79, v247, 23
	v_readlane_b32 s24, v247, 28
	v_readlane_b32 s25, v244, 30
	v_readlane_b32 s26, v244, 31
	v_readlane_b32 s27, v245, 40
	s_cbranch_scc1 .LBB0_620
	v_readlane_b32 s0, v246, 3
	v_readlane_b32 s1, v246, 4
	s_andn2_b64 vcc, exec, s[0:1]
	s_cbranch_vccnz .LBB0_620
	v_readlane_b32 s0, v245, 21
	s_nop 0
	s_sub_u32 s0, s0, 0x400
	s_cbranch_scc1 .Lstab_end
	s_and_b32 s1, s0, 7
	s_cmp_lg_u32 s1, 0
	s_cbranch_scc1 .Lstab_end
	s_lshr_b32 s0, s0, 3
	s_lshr_b32 s1, s0, 2
	s_and_b32 s6, s0, 3
	s_lshl_b32 s7, s24, 5
	s_add_i32 s7, s7, s1
	s_bfe_u32 s8, s1, 0x10004
	s_mul_i32 s9, s8, 15
	v_and_b32_e32 v0, 15, v205
	v_lshrrev_b32_e32 v1, 4, v205
	v_xor_b32_e32 v2, s9, v0
	v_and_b32_e32 v3, 1, v2
	v_cmp_ne_u32_e64 s[10:11], 0, v3
	v_and_b32_e32 v3, 2, v2
	v_cmp_ne_u32_e64 s[12:13], 0, v3
	v_and_b32_e32 v3, 4, v2
	v_cmp_ne_u32_e64 s[14:15], 0, v3
	v_and_b32_e32 v3, 8, v2
	v_cmp_ne_u32_e64 s[16:17], 0, v3
	s_lshl_b32 s18, s7, 6
	s_lshl_b32 s19, s6, 4
	s_add_i32 s18, s18, s19
	s_lshl_b32 s18, s18, 2
	s_add_u32 s18, s18, 0x117a20
	s_add_u32 s20, s4, s18
	s_addc_u32 s21, s5, 0
	s_add_u32 s22, s20, 0x4000
	s_addc_u32 s23, s21, 0
	v_lshlrev_b32_e32 v3, 4, v1
	global_load_dwordx4 v[4:7], v3, s[20:21]
	global_load_dwordx4 v[8:11], v3, s[22:23]
	s_lshl_b32 s19, s7, 2
	s_add_u32 s19, s19, 0x11fa20
	s_add_u32 s0, s4, s19
	s_addc_u32 s1, s5, 0
	global_load_dword v12, v137, s[0:1]
	s_lshl_b32 s18, s7, 2
	s_add_i32 s18, s18, s6
	s_lshl_b32 s19, s18, 13
	s_add_u32 s19, s19, 0xf900000
	s_add_u32 s20, s4, s19
	s_addc_u32 s21, s5, 0
	s_lshl_b32 s19, s18, 12
	s_add_u32 s19, s19, 0xfc00000
	s_add_u32 s22, s4, s19
	s_addc_u32 s23, s5, 0
	v_lshlrev_b32_e32 v13, 4, v205
	v_lshlrev_b32_e32 v14, 4, v205
	v_add_u32_e32 v44, 0x1000, v13
	s_waitcnt vmcnt(0)
	v_mul_f32_e32 v12, 0x3fb8aa3b, v12
	v_exp_f32_e32 v12, v12
	s_nop 0
	v_mul_f32_e32 v15, v12, v4
	v_mul_f32_e32 v16, 0x3fb8aa3b, v15
	v_mul_f32_e32 v17, 0xbfb8aa3b, v15
	v_exp_f32_e32 v16, v16
	v_exp_f32_e32 v17, v17
	v_mul_f32_e32 v18, v12, v8
	v_mul_f32_e32 v19, 0.15915494, v18
	v_rndne_f32_e32 v19, v19
	v_fma_f32 v18, v18, 0.15915494, -v19
	v_cos_f32_e32 v19, v18
	v_sin_f32_e32 v20, v18
	s_nop 0
	v_mul_f32_e32 v22, v16, v19
	v_mul_f32_e32 v23, v16, v20
	v_mul_f32_e32 v24, v17, v19
	v_mul_f32_e64 v25, -v17, v20
	v_add_f32_e32 v26, -1.0, v22
	v_mul_f32_e32 v27, v8, v8
	v_fmac_f32_e32 v27, v4, v4
	v_rcp_f32_e32 v27, v27
	v_mul_f32_e32 v28, v26, v4
	v_fmac_f32_e32 v28, v23, v8
	v_mul_f32_e32 v29, v23, v4
	v_fma_f32 v29, -v26, v8, v29
	v_mul_f32_e32 v28, v28, v27
	v_mul_f32_e32 v29, v29, v27
	v_mul_f32_e32 v42, v23, v23
	v_mul_f32_e32 v43, v22, v23
	v_fma_f32 v30, v22, v22, -v42
	v_add_f32_e32 v31, v43, v43
	v_mul_f32_e32 v42, v31, v31
	v_mul_f32_e32 v43, v30, v31
	v_fma_f32 v32, v30, v30, -v42
	v_add_f32_e32 v33, v43, v43
	v_mul_f32_e32 v42, v33, v33
	v_mul_f32_e32 v43, v32, v33
	v_fma_f32 v34, v32, v32, -v42
	v_add_f32_e32 v35, v43, v43
	v_mul_f32_e32 v42, v35, v35
	v_mul_f32_e32 v43, v34, v35
	v_fma_f32 v36, v34, v34, -v42
	v_add_f32_e32 v37, v43, v43
	v_mov_b32_e32 v38, 1.0
	v_mov_b32_e32 v39, 0
	v_mov_b32_e32 v40, 1.0
	v_mov_b32_e32 v41, 0
	v_mul_f32_e32 v15, v39, v23
	v_fma_f32 v42, v38, v22, -v15
	v_mul_f32_e32 v15, v38, v23
	v_fma_f32 v43, v39, v22, v15
	v_cndmask_b32_e64 v38, v38, v42, s[10:11]
	v_cndmask_b32_e64 v39, v39, v43, s[10:11]
	v_mul_f32_e32 v15, v41, v23
	v_fma_f32 v42, v40, v22, -v15
	v_mul_f32_e32 v15, v40, v23
	v_fma_f32 v43, v41, v22, v15
	v_cndmask_b32_e64 v40, v42, v40, s[10:11]
	v_cndmask_b32_e64 v41, v43, v41, s[10:11]
	v_mul_f32_e32 v15, v39, v31
	v_fma_f32 v42, v38, v30, -v15
	v_mul_f32_e32 v15, v38, v31
	v_fma_f32 v43, v39, v30, v15
	v_cndmask_b32_e64 v38, v38, v42, s[12:13]
	v_cndmask_b32_e64 v39, v39, v43, s[12:13]
	v_mul_f32_e32 v15, v41, v31
	v_fma_f32 v42, v40, v30, -v15
	v_mul_f32_e32 v15, v40, v31
	v_fma_f32 v43, v41, v30, v15
	v_cndmask_b32_e64 v40, v42, v40, s[12:13]
	v_cndmask_b32_e64 v41, v43, v41, s[12:13]
	v_mul_f32_e32 v15, v39, v33
	v_fma_f32 v42, v38, v32, -v15
	v_mul_f32_e32 v15, v38, v33
	v_fma_f32 v43, v39, v32, v15
	v_cndmask_b32_e64 v38, v38, v42, s[14:15]
	v_cndmask_b32_e64 v39, v39, v43, s[14:15]
	v_mul_f32_e32 v15, v41, v33
	v_fma_f32 v42, v40, v32, -v15
	v_mul_f32_e32 v15, v40, v33
	v_fma_f32 v43, v41, v32, v15
	v_cndmask_b32_e64 v40, v42, v40, s[14:15]
	v_cndmask_b32_e64 v41, v43, v41, s[14:15]
	v_mul_f32_e32 v15, v39, v35
	v_fma_f32 v42, v38, v34, -v15
	v_mul_f32_e32 v15, v38, v35
	v_fma_f32 v43, v39, v34, v15
	v_cndmask_b32_e64 v38, v38, v42, s[16:17]
	v_cndmask_b32_e64 v39, v39, v43, s[16:17]
	v_mul_f32_e32 v15, v41, v35
	v_fma_f32 v42, v40, v34, -v15
	v_mul_f32_e32 v15, v40, v35
	v_fma_f32 v43, v41, v34, v15
	v_cndmask_b32_e64 v40, v42, v40, s[16:17]
	v_cndmask_b32_e64 v41, v43, v41, s[16:17]
	v_mul_f32_e32 v42, v25, v25
	v_mul_f32_e32 v43, v24, v25
	v_fma_f32 v30, v24, v24, -v42
	v_add_f32_e32 v31, v43, v43
	v_mul_f32_e32 v42, v31, v31
	v_mul_f32_e32 v43, v30, v31
	v_fma_f32 v32, v30, v30, -v42
	v_add_f32_e32 v33, v43, v43
	v_mul_f32_e32 v42, v33, v33
	v_mul_f32_e32 v43, v32, v33
	v_fma_f32 v34, v32, v32, -v42
	v_add_f32_e32 v35, v43, v43
	v_mov_b32_e32 v16, 1.0
	v_mov_b32_e32 v17, 0
	v_mul_f32_e32 v15, v17, v25
	v_fma_f32 v42, v16, v24, -v15
	v_mul_f32_e32 v15, v16, v25
	v_fma_f32 v43, v17, v24, v15
	v_cndmask_b32_e64 v16, v16, v42, s[10:11]
	v_cndmask_b32_e64 v17, v17, v43, s[10:11]
	v_mul_f32_e32 v15, v17, v31
	v_fma_f32 v42, v16, v30, -v15
	v_mul_f32_e32 v15, v16, v31
	v_fma_f32 v43, v17, v30, v15
	v_cndmask_b32_e64 v16, v16, v42, s[12:13]
	v_cndmask_b32_e64 v17, v17, v43, s[12:13]
	v_mul_f32_e32 v15, v17, v33
	v_fma_f32 v42, v16, v32, -v15
	v_mul_f32_e32 v15, v16, v33
	v_fma_f32 v43, v17, v32, v15
	v_cndmask_b32_e64 v16, v16, v42, s[14:15]
	v_cndmask_b32_e64 v17, v17, v43, s[14:15]
	v_mul_f32_e32 v15, v17, v35
	v_fma_f32 v42, v16, v34, -v15
	v_mul_f32_e32 v15, v16, v35
	v_fma_f32 v43, v17, v34, v15
	v_cndmask_b32_e64 v16, v16, v42, s[16:17]
	v_cndmask_b32_e64 v17, v17, v43, s[16:17]
	v_mul_f32_e32 v15, v29, v17
	v_fma_f32 v18, v28, v16, -v15
	v_mul_f32_e32 v15, v28, v17
	v_fma_f32 v19, v29, v16, v15
	v_mul_f32_e32 v15, v29, v41
	v_fma_f32 v20, v28, v40, -v15
	v_mul_f32_e32 v15, v28, v41
	v_fma_f32 v21, v29, v40, v15
	global_store_dword v13, v18, s[20:21] offset:0
	global_store_dword v13, v19, s[20:21] offset:1024
	global_store_dword v13, v38, s[20:21] offset:2048
	global_store_dword v13, v39, s[20:21] offset:3072
	global_store_dword v44, v36, s[20:21] offset:0
	global_store_dword v44, v37, s[20:21] offset:1024
	global_store_dword v44, v22, s[20:21] offset:2048
	global_store_dword v44, v23, s[20:21] offset:3072
	global_store_dword v14, v20, s[22:23] offset:0
	global_store_dword v14, v21, s[22:23] offset:1024
	global_store_dword v14, v36, s[22:23] offset:2048
	global_store_dword v14, v37, s[22:23] offset:3072
	s_nop 1
	v_mul_f32_e32 v15, v12, v5
	v_mul_f32_e32 v16, 0x3fb8aa3b, v15
	v_mul_f32_e32 v17, 0xbfb8aa3b, v15
	v_exp_f32_e32 v16, v16
	v_exp_f32_e32 v17, v17
	v_mul_f32_e32 v18, v12, v9
	v_mul_f32_e32 v19, 0.15915494, v18
	v_rndne_f32_e32 v19, v19
	v_fma_f32 v18, v18, 0.15915494, -v19
	v_cos_f32_e32 v19, v18
	v_sin_f32_e32 v20, v18
	s_nop 0
	v_mul_f32_e32 v22, v16, v19
	v_mul_f32_e32 v23, v16, v20
	v_mul_f32_e32 v24, v17, v19
	v_mul_f32_e64 v25, -v17, v20
	v_add_f32_e32 v26, -1.0, v22
	v_mul_f32_e32 v27, v9, v9
	v_fmac_f32_e32 v27, v5, v5
	v_rcp_f32_e32 v27, v27
	v_mul_f32_e32 v28, v26, v5
	v_fmac_f32_e32 v28, v23, v9
	v_mul_f32_e32 v29, v23, v5
	v_fma_f32 v29, -v26, v9, v29
	v_mul_f32_e32 v28, v28, v27
	v_mul_f32_e32 v29, v29, v27
	v_mul_f32_e32 v42, v23, v23
	v_mul_f32_e32 v43, v22, v23
	v_fma_f32 v30, v22, v22, -v42
	v_add_f32_e32 v31, v43, v43
	v_mul_f32_e32 v42, v31, v31
	v_mul_f32_e32 v43, v30, v31
	v_fma_f32 v32, v30, v30, -v42
	v_add_f32_e32 v33, v43, v43
	v_mul_f32_e32 v42, v33, v33
	v_mul_f32_e32 v43, v32, v33
	v_fma_f32 v34, v32, v32, -v42
	v_add_f32_e32 v35, v43, v43
	v_mul_f32_e32 v42, v35, v35
	v_mul_f32_e32 v43, v34, v35
	v_fma_f32 v36, v34, v34, -v42
	v_add_f32_e32 v37, v43, v43
	v_mov_b32_e32 v38, 1.0
	v_mov_b32_e32 v39, 0
	v_mov_b32_e32 v40, 1.0
	v_mov_b32_e32 v41, 0
	v_mul_f32_e32 v15, v39, v23
	v_fma_f32 v42, v38, v22, -v15
	v_mul_f32_e32 v15, v38, v23
	v_fma_f32 v43, v39, v22, v15
	v_cndmask_b32_e64 v38, v38, v42, s[10:11]
	v_cndmask_b32_e64 v39, v39, v43, s[10:11]
	v_mul_f32_e32 v15, v41, v23
	v_fma_f32 v42, v40, v22, -v15
	v_mul_f32_e32 v15, v40, v23
	v_fma_f32 v43, v41, v22, v15
	v_cndmask_b32_e64 v40, v42, v40, s[10:11]
	v_cndmask_b32_e64 v41, v43, v41, s[10:11]
	v_mul_f32_e32 v15, v39, v31
	v_fma_f32 v42, v38, v30, -v15
	v_mul_f32_e32 v15, v38, v31
	v_fma_f32 v43, v39, v30, v15
	v_cndmask_b32_e64 v38, v38, v42, s[12:13]
	v_cndmask_b32_e64 v39, v39, v43, s[12:13]
	v_mul_f32_e32 v15, v41, v31
	v_fma_f32 v42, v40, v30, -v15
	v_mul_f32_e32 v15, v40, v31
	v_fma_f32 v43, v41, v30, v15
	v_cndmask_b32_e64 v40, v42, v40, s[12:13]
	v_cndmask_b32_e64 v41, v43, v41, s[12:13]
	v_mul_f32_e32 v15, v39, v33
	v_fma_f32 v42, v38, v32, -v15
	v_mul_f32_e32 v15, v38, v33
	v_fma_f32 v43, v39, v32, v15
	v_cndmask_b32_e64 v38, v38, v42, s[14:15]
	v_cndmask_b32_e64 v39, v39, v43, s[14:15]
	v_mul_f32_e32 v15, v41, v33
	v_fma_f32 v42, v40, v32, -v15
	v_mul_f32_e32 v15, v40, v33
	v_fma_f32 v43, v41, v32, v15
	v_cndmask_b32_e64 v40, v42, v40, s[14:15]
	v_cndmask_b32_e64 v41, v43, v41, s[14:15]
	v_mul_f32_e32 v15, v39, v35
	v_fma_f32 v42, v38, v34, -v15
	v_mul_f32_e32 v15, v38, v35
	v_fma_f32 v43, v39, v34, v15
	v_cndmask_b32_e64 v38, v38, v42, s[16:17]
	v_cndmask_b32_e64 v39, v39, v43, s[16:17]
	v_mul_f32_e32 v15, v41, v35
	v_fma_f32 v42, v40, v34, -v15
	v_mul_f32_e32 v15, v40, v35
	v_fma_f32 v43, v41, v34, v15
	v_cndmask_b32_e64 v40, v42, v40, s[16:17]
	v_cndmask_b32_e64 v41, v43, v41, s[16:17]
	v_mul_f32_e32 v42, v25, v25
	v_mul_f32_e32 v43, v24, v25
	v_fma_f32 v30, v24, v24, -v42
	v_add_f32_e32 v31, v43, v43
	v_mul_f32_e32 v42, v31, v31
	v_mul_f32_e32 v43, v30, v31
	v_fma_f32 v32, v30, v30, -v42
	v_add_f32_e32 v33, v43, v43
	v_mul_f32_e32 v42, v33, v33
	v_mul_f32_e32 v43, v32, v33
	v_fma_f32 v34, v32, v32, -v42
	v_add_f32_e32 v35, v43, v43
	v_mov_b32_e32 v16, 1.0
	v_mov_b32_e32 v17, 0
	v_mul_f32_e32 v15, v17, v25
	v_fma_f32 v42, v16, v24, -v15
	v_mul_f32_e32 v15, v16, v25
	v_fma_f32 v43, v17, v24, v15
	v_cndmask_b32_e64 v16, v16, v42, s[10:11]
	v_cndmask_b32_e64 v17, v17, v43, s[10:11]
	v_mul_f32_e32 v15, v17, v31
	v_fma_f32 v42, v16, v30, -v15
	v_mul_f32_e32 v15, v16, v31
	v_fma_f32 v43, v17, v30, v15
	v_cndmask_b32_e64 v16, v16, v42, s[12:13]
	v_cndmask_b32_e64 v17, v17, v43, s[12:13]
	v_mul_f32_e32 v15, v17, v33
	v_fma_f32 v42, v16, v32, -v15
	v_mul_f32_e32 v15, v16, v33
	v_fma_f32 v43, v17, v32, v15
	v_cndmask_b32_e64 v16, v16, v42, s[14:15]
	v_cndmask_b32_e64 v17, v17, v43, s[14:15]
	v_mul_f32_e32 v15, v17, v35
	v_fma_f32 v42, v16, v34, -v15
	v_mul_f32_e32 v15, v16, v35
	v_fma_f32 v43, v17, v34, v15
	v_cndmask_b32_e64 v16, v16, v42, s[16:17]
	v_cndmask_b32_e64 v17, v17, v43, s[16:17]
	v_mul_f32_e32 v15, v29, v17
	v_fma_f32 v18, v28, v16, -v15
	v_mul_f32_e32 v15, v28, v17
	v_fma_f32 v19, v29, v16, v15
	v_mul_f32_e32 v15, v29, v41
	v_fma_f32 v20, v28, v40, -v15
	v_mul_f32_e32 v15, v28, v41
	v_fma_f32 v21, v29, v40, v15
	global_store_dword v13, v18, s[20:21] offset:4
	global_store_dword v13, v19, s[20:21] offset:1028
	global_store_dword v13, v38, s[20:21] offset:2052
	global_store_dword v13, v39, s[20:21] offset:3076
	global_store_dword v44, v36, s[20:21] offset:4
	global_store_dword v44, v37, s[20:21] offset:1028
	global_store_dword v44, v22, s[20:21] offset:2052
	global_store_dword v44, v23, s[20:21] offset:3076
	global_store_dword v14, v20, s[22:23] offset:4
	global_store_dword v14, v21, s[22:23] offset:1028
	global_store_dword v14, v36, s[22:23] offset:2052
	global_store_dword v14, v37, s[22:23] offset:3076
	s_nop 1
	v_mul_f32_e32 v15, v12, v6
	v_mul_f32_e32 v16, 0x3fb8aa3b, v15
	v_mul_f32_e32 v17, 0xbfb8aa3b, v15
	v_exp_f32_e32 v16, v16
	v_exp_f32_e32 v17, v17
	v_mul_f32_e32 v18, v12, v10
	v_mul_f32_e32 v19, 0.15915494, v18
	v_rndne_f32_e32 v19, v19
	v_fma_f32 v18, v18, 0.15915494, -v19
	v_cos_f32_e32 v19, v18
	v_sin_f32_e32 v20, v18
	s_nop 0
	v_mul_f32_e32 v22, v16, v19
	v_mul_f32_e32 v23, v16, v20
	v_mul_f32_e32 v24, v17, v19
	v_mul_f32_e64 v25, -v17, v20
	v_add_f32_e32 v26, -1.0, v22
	v_mul_f32_e32 v27, v10, v10
	v_fmac_f32_e32 v27, v6, v6
	v_rcp_f32_e32 v27, v27
	v_mul_f32_e32 v28, v26, v6
	v_fmac_f32_e32 v28, v23, v10
	v_mul_f32_e32 v29, v23, v6
	v_fma_f32 v29, -v26, v10, v29
	v_mul_f32_e32 v28, v28, v27
	v_mul_f32_e32 v29, v29, v27
	v_mul_f32_e32 v42, v23, v23
	v_mul_f32_e32 v43, v22, v23
	v_fma_f32 v30, v22, v22, -v42
	v_add_f32_e32 v31, v43, v43
	v_mul_f32_e32 v42, v31, v31
	v_mul_f32_e32 v43, v30, v31
	v_fma_f32 v32, v30, v30, -v42
	v_add_f32_e32 v33, v43, v43
	v_mul_f32_e32 v42, v33, v33
	v_mul_f32_e32 v43, v32, v33
	v_fma_f32 v34, v32, v32, -v42
	v_add_f32_e32 v35, v43, v43
	v_mul_f32_e32 v42, v35, v35
	v_mul_f32_e32 v43, v34, v35
	v_fma_f32 v36, v34, v34, -v42
	v_add_f32_e32 v37, v43, v43
	v_mov_b32_e32 v38, 1.0
	v_mov_b32_e32 v39, 0
	v_mov_b32_e32 v40, 1.0
	v_mov_b32_e32 v41, 0
	v_mul_f32_e32 v15, v39, v23
	v_fma_f32 v42, v38, v22, -v15
	v_mul_f32_e32 v15, v38, v23
	v_fma_f32 v43, v39, v22, v15
	v_cndmask_b32_e64 v38, v38, v42, s[10:11]
	v_cndmask_b32_e64 v39, v39, v43, s[10:11]
	v_mul_f32_e32 v15, v41, v23
	v_fma_f32 v42, v40, v22, -v15
	v_mul_f32_e32 v15, v40, v23
	v_fma_f32 v43, v41, v22, v15
	v_cndmask_b32_e64 v40, v42, v40, s[10:11]
	v_cndmask_b32_e64 v41, v43, v41, s[10:11]
	v_mul_f32_e32 v15, v39, v31
	v_fma_f32 v42, v38, v30, -v15
	v_mul_f32_e32 v15, v38, v31
	v_fma_f32 v43, v39, v30, v15
	v_cndmask_b32_e64 v38, v38, v42, s[12:13]
	v_cndmask_b32_e64 v39, v39, v43, s[12:13]
	v_mul_f32_e32 v15, v41, v31
	v_fma_f32 v42, v40, v30, -v15
	v_mul_f32_e32 v15, v40, v31
	v_fma_f32 v43, v41, v30, v15
	v_cndmask_b32_e64 v40, v42, v40, s[12:13]
	v_cndmask_b32_e64 v41, v43, v41, s[12:13]
	v_mul_f32_e32 v15, v39, v33
	v_fma_f32 v42, v38, v32, -v15
	v_mul_f32_e32 v15, v38, v33
	v_fma_f32 v43, v39, v32, v15
	v_cndmask_b32_e64 v38, v38, v42, s[14:15]
	v_cndmask_b32_e64 v39, v39, v43, s[14:15]
	v_mul_f32_e32 v15, v41, v33
	v_fma_f32 v42, v40, v32, -v15
	v_mul_f32_e32 v15, v40, v33
	v_fma_f32 v43, v41, v32, v15
	v_cndmask_b32_e64 v40, v42, v40, s[14:15]
	v_cndmask_b32_e64 v41, v43, v41, s[14:15]
	v_mul_f32_e32 v15, v39, v35
	v_fma_f32 v42, v38, v34, -v15
	v_mul_f32_e32 v15, v38, v35
	v_fma_f32 v43, v39, v34, v15
	v_cndmask_b32_e64 v38, v38, v42, s[16:17]
	v_cndmask_b32_e64 v39, v39, v43, s[16:17]
	v_mul_f32_e32 v15, v41, v35
	v_fma_f32 v42, v40, v34, -v15
	v_mul_f32_e32 v15, v40, v35
	v_fma_f32 v43, v41, v34, v15
	v_cndmask_b32_e64 v40, v42, v40, s[16:17]
	v_cndmask_b32_e64 v41, v43, v41, s[16:17]
	v_mul_f32_e32 v42, v25, v25
	v_mul_f32_e32 v43, v24, v25
	v_fma_f32 v30, v24, v24, -v42
	v_add_f32_e32 v31, v43, v43
	v_mul_f32_e32 v42, v31, v31
	v_mul_f32_e32 v43, v30, v31
	v_fma_f32 v32, v30, v30, -v42
	v_add_f32_e32 v33, v43, v43
	v_mul_f32_e32 v42, v33, v33
	v_mul_f32_e32 v43, v32, v33
	v_fma_f32 v34, v32, v32, -v42
	v_add_f32_e32 v35, v43, v43
	v_mov_b32_e32 v16, 1.0
	v_mov_b32_e32 v17, 0
	v_mul_f32_e32 v15, v17, v25
	v_fma_f32 v42, v16, v24, -v15
	v_mul_f32_e32 v15, v16, v25
	v_fma_f32 v43, v17, v24, v15
	v_cndmask_b32_e64 v16, v16, v42, s[10:11]
	v_cndmask_b32_e64 v17, v17, v43, s[10:11]
	v_mul_f32_e32 v15, v17, v31
	v_fma_f32 v42, v16, v30, -v15
	v_mul_f32_e32 v15, v16, v31
	v_fma_f32 v43, v17, v30, v15
	v_cndmask_b32_e64 v16, v16, v42, s[12:13]
	v_cndmask_b32_e64 v17, v17, v43, s[12:13]
	v_mul_f32_e32 v15, v17, v33
	v_fma_f32 v42, v16, v32, -v15
	v_mul_f32_e32 v15, v16, v33
	v_fma_f32 v43, v17, v32, v15
	v_cndmask_b32_e64 v16, v16, v42, s[14:15]
	v_cndmask_b32_e64 v17, v17, v43, s[14:15]
	v_mul_f32_e32 v15, v17, v35
	v_fma_f32 v42, v16, v34, -v15
	v_mul_f32_e32 v15, v16, v35
	v_fma_f32 v43, v17, v34, v15
	v_cndmask_b32_e64 v16, v16, v42, s[16:17]
	v_cndmask_b32_e64 v17, v17, v43, s[16:17]
	v_mul_f32_e32 v15, v29, v17
	v_fma_f32 v18, v28, v16, -v15
	v_mul_f32_e32 v15, v28, v17
	v_fma_f32 v19, v29, v16, v15
	v_mul_f32_e32 v15, v29, v41
	v_fma_f32 v20, v28, v40, -v15
	v_mul_f32_e32 v15, v28, v41
	v_fma_f32 v21, v29, v40, v15
	global_store_dword v13, v18, s[20:21] offset:8
	global_store_dword v13, v19, s[20:21] offset:1032
	global_store_dword v13, v38, s[20:21] offset:2056
	global_store_dword v13, v39, s[20:21] offset:3080
	global_store_dword v44, v36, s[20:21] offset:8
	global_store_dword v44, v37, s[20:21] offset:1032
	global_store_dword v44, v22, s[20:21] offset:2056
	global_store_dword v44, v23, s[20:21] offset:3080
	global_store_dword v14, v20, s[22:23] offset:8
	global_store_dword v14, v21, s[22:23] offset:1032
	global_store_dword v14, v36, s[22:23] offset:2056
	global_store_dword v14, v37, s[22:23] offset:3080
	s_nop 1
	v_mul_f32_e32 v15, v12, v7
	v_mul_f32_e32 v16, 0x3fb8aa3b, v15
	v_mul_f32_e32 v17, 0xbfb8aa3b, v15
	v_exp_f32_e32 v16, v16
	v_exp_f32_e32 v17, v17
	v_mul_f32_e32 v18, v12, v11
	v_mul_f32_e32 v19, 0.15915494, v18
	v_rndne_f32_e32 v19, v19
	v_fma_f32 v18, v18, 0.15915494, -v19
	v_cos_f32_e32 v19, v18
	v_sin_f32_e32 v20, v18
	s_nop 0
	v_mul_f32_e32 v22, v16, v19
	v_mul_f32_e32 v23, v16, v20
	v_mul_f32_e32 v24, v17, v19
	v_mul_f32_e64 v25, -v17, v20
	v_add_f32_e32 v26, -1.0, v22
	v_mul_f32_e32 v27, v11, v11
	v_fmac_f32_e32 v27, v7, v7
	v_rcp_f32_e32 v27, v27
	v_mul_f32_e32 v28, v26, v7
	v_fmac_f32_e32 v28, v23, v11
	v_mul_f32_e32 v29, v23, v7
	v_fma_f32 v29, -v26, v11, v29
	v_mul_f32_e32 v28, v28, v27
	v_mul_f32_e32 v29, v29, v27
	v_mul_f32_e32 v42, v23, v23
	v_mul_f32_e32 v43, v22, v23
	v_fma_f32 v30, v22, v22, -v42
	v_add_f32_e32 v31, v43, v43
	v_mul_f32_e32 v42, v31, v31
	v_mul_f32_e32 v43, v30, v31
	v_fma_f32 v32, v30, v30, -v42
	v_add_f32_e32 v33, v43, v43
	v_mul_f32_e32 v42, v33, v33
	v_mul_f32_e32 v43, v32, v33
	v_fma_f32 v34, v32, v32, -v42
	v_add_f32_e32 v35, v43, v43
	v_mul_f32_e32 v42, v35, v35
	v_mul_f32_e32 v43, v34, v35
	v_fma_f32 v36, v34, v34, -v42
	v_add_f32_e32 v37, v43, v43
	v_mov_b32_e32 v38, 1.0
	v_mov_b32_e32 v39, 0
	v_mov_b32_e32 v40, 1.0
	v_mov_b32_e32 v41, 0
	v_mul_f32_e32 v15, v39, v23
	v_fma_f32 v42, v38, v22, -v15
	v_mul_f32_e32 v15, v38, v23
	v_fma_f32 v43, v39, v22, v15
	v_cndmask_b32_e64 v38, v38, v42, s[10:11]
	v_cndmask_b32_e64 v39, v39, v43, s[10:11]
	v_mul_f32_e32 v15, v41, v23
	v_fma_f32 v42, v40, v22, -v15
	v_mul_f32_e32 v15, v40, v23
	v_fma_f32 v43, v41, v22, v15
	v_cndmask_b32_e64 v40, v42, v40, s[10:11]
	v_cndmask_b32_e64 v41, v43, v41, s[10:11]
	v_mul_f32_e32 v15, v39, v31
	v_fma_f32 v42, v38, v30, -v15
	v_mul_f32_e32 v15, v38, v31
	v_fma_f32 v43, v39, v30, v15
	v_cndmask_b32_e64 v38, v38, v42, s[12:13]
	v_cndmask_b32_e64 v39, v39, v43, s[12:13]
	v_mul_f32_e32 v15, v41, v31
	v_fma_f32 v42, v40, v30, -v15
	v_mul_f32_e32 v15, v40, v31
	v_fma_f32 v43, v41, v30, v15
	v_cndmask_b32_e64 v40, v42, v40, s[12:13]
	v_cndmask_b32_e64 v41, v43, v41, s[12:13]
	v_mul_f32_e32 v15, v39, v33
	v_fma_f32 v42, v38, v32, -v15
	v_mul_f32_e32 v15, v38, v33
	v_fma_f32 v43, v39, v32, v15
	v_cndmask_b32_e64 v38, v38, v42, s[14:15]
	v_cndmask_b32_e64 v39, v39, v43, s[14:15]
	v_mul_f32_e32 v15, v41, v33
	v_fma_f32 v42, v40, v32, -v15
	v_mul_f32_e32 v15, v40, v33
	v_fma_f32 v43, v41, v32, v15
	v_cndmask_b32_e64 v40, v42, v40, s[14:15]
	v_cndmask_b32_e64 v41, v43, v41, s[14:15]
	v_mul_f32_e32 v15, v39, v35
	v_fma_f32 v42, v38, v34, -v15
	v_mul_f32_e32 v15, v38, v35
	v_fma_f32 v43, v39, v34, v15
	v_cndmask_b32_e64 v38, v38, v42, s[16:17]
	v_cndmask_b32_e64 v39, v39, v43, s[16:17]
	v_mul_f32_e32 v15, v41, v35
	v_fma_f32 v42, v40, v34, -v15
	v_mul_f32_e32 v15, v40, v35
	v_fma_f32 v43, v41, v34, v15
	v_cndmask_b32_e64 v40, v42, v40, s[16:17]
	v_cndmask_b32_e64 v41, v43, v41, s[16:17]
	v_mul_f32_e32 v42, v25, v25
	v_mul_f32_e32 v43, v24, v25
	v_fma_f32 v30, v24, v24, -v42
	v_add_f32_e32 v31, v43, v43
	v_mul_f32_e32 v42, v31, v31
	v_mul_f32_e32 v43, v30, v31
	v_fma_f32 v32, v30, v30, -v42
	v_add_f32_e32 v33, v43, v43
	v_mul_f32_e32 v42, v33, v33
	v_mul_f32_e32 v43, v32, v33
	v_fma_f32 v34, v32, v32, -v42
	v_add_f32_e32 v35, v43, v43
	v_mov_b32_e32 v16, 1.0
	v_mov_b32_e32 v17, 0
	v_mul_f32_e32 v15, v17, v25
	v_fma_f32 v42, v16, v24, -v15
	v_mul_f32_e32 v15, v16, v25
	v_fma_f32 v43, v17, v24, v15
	v_cndmask_b32_e64 v16, v16, v42, s[10:11]
	v_cndmask_b32_e64 v17, v17, v43, s[10:11]
	v_mul_f32_e32 v15, v17, v31
	v_fma_f32 v42, v16, v30, -v15
	v_mul_f32_e32 v15, v16, v31
	v_fma_f32 v43, v17, v30, v15
	v_cndmask_b32_e64 v16, v16, v42, s[12:13]
	v_cndmask_b32_e64 v17, v17, v43, s[12:13]
	v_mul_f32_e32 v15, v17, v33
	v_fma_f32 v42, v16, v32, -v15
	v_mul_f32_e32 v15, v16, v33
	v_fma_f32 v43, v17, v32, v15
	v_cndmask_b32_e64 v16, v16, v42, s[14:15]
	v_cndmask_b32_e64 v17, v17, v43, s[14:15]
	v_mul_f32_e32 v15, v17, v35
	v_fma_f32 v42, v16, v34, -v15
	v_mul_f32_e32 v15, v16, v35
	v_fma_f32 v43, v17, v34, v15
	v_cndmask_b32_e64 v16, v16, v42, s[16:17]
	v_cndmask_b32_e64 v17, v17, v43, s[16:17]
	v_mul_f32_e32 v15, v29, v17
	v_fma_f32 v18, v28, v16, -v15
	v_mul_f32_e32 v15, v28, v17
	v_fma_f32 v19, v29, v16, v15
	v_mul_f32_e32 v15, v29, v41
	v_fma_f32 v20, v28, v40, -v15
	v_mul_f32_e32 v15, v28, v41
	v_fma_f32 v21, v29, v40, v15
	global_store_dword v13, v18, s[20:21] offset:12
	global_store_dword v13, v19, s[20:21] offset:1036
	global_store_dword v13, v38, s[20:21] offset:2060
	global_store_dword v13, v39, s[20:21] offset:3084
	global_store_dword v44, v36, s[20:21] offset:12
	global_store_dword v44, v37, s[20:21] offset:1036
	global_store_dword v44, v22, s[20:21] offset:2060
	global_store_dword v44, v23, s[20:21] offset:3084
	global_store_dword v14, v20, s[22:23] offset:12
	global_store_dword v14, v21, s[22:23] offset:1036
	global_store_dword v14, v36, s[22:23] offset:2060
	global_store_dword v14, v37, s[22:23] offset:3084
	s_nop 1
	s_lshl_b32 s0, s7, 2
	s_add_i32 s0, s0, s6
	s_lshl_b32 s8, s7, 12
	s_lshl_b32 s9, s6, 10
	s_add_i32 s8, s8, s9
	s_add_u32 s8, s8, 0x11fb20
	s_add_u32 s8, s4, s8
	s_addc_u32 s9, s5, 0
	s_add_u32 s10, s8, 0x40000
	s_addc_u32 s11, s9, 0
	s_lshl_b32 s12, s7, 12
	s_lshl_b32 s13, s6, 6
	s_add_i32 s12, s12, s13
	s_add_u32 s12, s12, 0x19fb20
	s_add_u32 s12, s4, s12
	s_addc_u32 s13, s5, 0
	s_add_u32 s14, s12, 0x40000
	s_addc_u32 s15, s13, 0
	s_lshl_b32 s16, s0, 11
	s_add_u32 s16, s16, 0xfd00000
	s_add_u32 s16, s4, s16
	s_addc_u32 s17, s5, 0
	s_lshl_b32 s18, s0, 10
	s_add_u32 s18, s18, 0xfd80000
	s_add_u32 s18, s4, s18
	s_addc_u32 s19, s5, 0
	v_mov_b32_e32 v0, 0
	v_mov_b32_e32 v1, 0
	v_mov_b32_e32 v2, 0
	v_mov_b32_e32 v3, 0
	v_mov_b32_e32 v4, 0
	v_mov_b32_e32 v5, 0
	v_mov_b32_e32 v6, 0
	v_mov_b32_e32 v7, 0
	v_mov_b32_e32 v8, 0
	v_mov_b32_e32 v9, 0
	v_mov_b32_e32 v10, 0
	v_mov_b32_e32 v11, 0
	v_mov_b32_e32 v12, 0
	v_mov_b32_e32 v13, 0
	v_mov_b32_e32 v14, 0
	v_mov_b32_e32 v15, 0
	v_and_b32_e32 v24, 15, v205
	v_lshrrev_b32_e32 v26, 4, v205
	v_lshlrev_b32_e32 v25, 8, v24
	v_lshl_add_u32 v25, v26, 4, v25
	v_lshlrev_b32_e32 v24, 6, v24
	v_and_b32_e32 v26, 16, v205
	v_lshl_add_u32 v24, v26, 1, v24
	s_mov_b32 exec_hi, 0
	global_load_dwordx4 v[0:3], v24, s[8:9]
	global_load_dwordx4 v[4:7], v24, s[8:9] offset:16
	global_load_dwordx4 v[8:11], v24, s[10:11]
	global_load_dwordx4 v[12:15], v24, s[10:11] offset:16
	s_mov_b64 exec, -1
	global_load_dwordx4 v[16:19], v25, s[12:13]
	global_load_dwordx4 v[20:23], v25, s[14:15]
	s_waitcnt vmcnt(2)
	v_cvt_pk_bf16_f32 v0, v0, v1
	v_cvt_pk_bf16_f32 v1, v2, v3
	v_cvt_pk_bf16_f32 v2, v4, v5
	v_cvt_pk_bf16_f32 v3, v6, v7
	v_cvt_pk_bf16_f32 v8, v8, v9
	v_cvt_pk_bf16_f32 v9, v10, v11
	v_cvt_pk_bf16_f32 v10, v12, v13
	v_cvt_pk_bf16_f32 v11, v14, v15
	v_lshlrev_b32_e32 v27, 4, v205
	global_store_dwordx4 v27, v[0:3], s[16:17]
	global_store_dwordx4 v27, v[8:11], s[16:17] offset:1024
	s_waitcnt vmcnt(0)
	v_cvt_pk_bf16_f32 v16, v16, v17
	v_cvt_pk_bf16_f32 v17, v18, v19
	v_cvt_pk_bf16_f32 v18, -v20, -v21
	v_cvt_pk_bf16_f32 v19, -v22, -v23
	global_store_dwordx4 v27, v[16:19], s[18:19]
	s_nop 1
